# GEMM segment handoff: s_setprio 0 behind the closing barrier, s_setprio 1 ahead of the opening barrier, duplicate lgkmcnt(0) after the barrier removed (all 11 GEMM loops)
# speedup vs baseline: 1.0210x; 1.0210x over previous
.LBB0_504:
	s_mov_b32 s39, 0
	s_mov_b64 s[66:67], -1
	s_mov_b64 s[72:73], 0
	s_add_u32 s20, s62, s39
	s_addc_u32 s21, s63, 0
	s_add_u32 s22, s20, 0x100
	s_addc_u32 s23, s21, 0
	s_and_b64 s[18:19], s[72:73], exec
	s_cselect_b32 vcc_hi, s49, s23
	s_cselect_b32 vcc_lo, s48, s22
	s_add_u32 s18, s60, s39
	s_addc_u32 s19, s61, 0
	s_add_u32 s22, s18, 0x100
	s_addc_u32 s23, s19, 0
	s_add_i32 s24, 0, 0x10000
	s_and_b64 s[18:19], s[72:73], exec
	s_cselect_b32 s51, s59, s23
	s_cselect_b32 s50, s58, s22
	s_add_i32 s22, 0, 0x14000
	s_add_u32 s64, s20, 0x40080
	s_addc_u32 s65, s21, 0
	s_add_i32 s21, s24, s69
	s_add_i32 m0, s4, 0xc000
	s_add_i32 s25, s4, 0xe000
	s_add_i32 s18, s21, 0x2000
	s_add_u32 s78, s50, 0x10000
	v_add_u32_e32 v140, s24, v170
	v_add_u32_e32 v162, s22, v170
	s_addc_u32 s79, s51, 0
	s_add_i32 s19, s22, s69
	ds_read_b128 v[128:131], v140
	ds_read_b128 v[132:135], v140 offset:1024
	ds_read_b128 v[136:139], v140 offset:2048
	ds_read_b128 v[140:143], v140 offset:3072
	ds_read_b128 v[152:155], v162
	ds_read_b128 v[156:159], v162 offset:1024
	ds_read_b128 v[164:167], v162 offset:2048
	ds_read_b128 v[172:175], v162 offset:3072
	s_add_i32 s20, s19, 0x2000
	s_add_i32 s54, 0, 0x18000
	s_add_i32 s43, 0, 0x1c000
	s_add_u32 s74, vcc_lo, 0x40000
	s_addc_u32 s75, vcc_hi, 0
	s_add_i32 s41, s54, s69
	s_add_i32 s39, s41, 0x2000
	s_add_u32 s72, s50, 0x10080
	s_addc_u32 s73, s51, 0
	s_add_i32 s23, s43, s69
	s_add_i32 s22, s23, 0x2000
	v_lshl_add_u64 v[200:201], s[64:65], 0, v[150:151]
	ds_read_b128 v[176:179], v171
	ds_read_b128 v[180:183], v171 offset:1024
	ds_read_b128 v[184:187], v171 offset:2048
	ds_read_b128 v[188:191], v171 offset:3072
	ds_read_b128 v[192:195], v171 offset:4096
	ds_read_b128 v[196:199], v171 offset:5120
	ds_read_b128 v[206:209], v171 offset:6144
	ds_read_b128 v[210:213], v171 offset:7168
	global_load_lds_dwordx4 v[200:201], off
	v_lshl_add_u64 v[200:201], s[64:65], 0, v[146:147]
	s_mov_b32 m0, s25
	s_nop 0
	global_load_lds_dwordx4 v[200:201], off
	s_waitcnt vmcnt(8)
	s_waitcnt lgkmcnt(0)
	s_setprio 1
	s_barrier
	v_mfma_f32_16x16x32_bf16 v[124:127], v[128:131], v[176:179], 0
	v_mfma_f32_16x16x32_bf16 v[120:123], v[136:139], v[176:179], 0
	v_mfma_f32_16x16x32_bf16 v[112:115], v[128:131], v[184:187], 0
	v_mfma_f32_16x16x32_bf16 v[104:107], v[136:139], v[184:187], 0
	v_mfma_f32_16x16x32_bf16 v[96:99], v[128:131], v[192:195], 0
	v_mfma_f32_16x16x32_bf16 v[88:91], v[136:139], v[192:195], 0
	v_mfma_f32_16x16x32_bf16 v[80:83], v[128:131], v[206:209], 0
	v_mfma_f32_16x16x32_bf16 v[72:75], v[136:139], v[206:209], 0
	v_mfma_f32_16x16x32_bf16 v[124:127], v[132:135], v[180:183], v[124:127]
	v_mfma_f32_16x16x32_bf16 v[120:123], v[140:143], v[180:183], v[120:123]
	v_mfma_f32_16x16x32_bf16 v[112:115], v[132:135], v[188:191], v[112:115]
	v_mfma_f32_16x16x32_bf16 v[104:107], v[140:143], v[188:191], v[104:107]
	v_mfma_f32_16x16x32_bf16 v[96:99], v[132:135], v[196:199], v[96:99]
	v_mfma_f32_16x16x32_bf16 v[88:91], v[140:143], v[196:199], v[88:91]
	v_mfma_f32_16x16x32_bf16 v[80:83], v[132:135], v[210:213], v[80:83]
	v_mfma_f32_16x16x32_bf16 v[72:75], v[140:143], v[210:213], v[72:75]
	s_setprio 0
	s_setprio 1
	v_mfma_f32_16x16x32_bf16 v[116:119], v[152:155], v[176:179], 0
	v_mfma_f32_16x16x32_bf16 v[108:111], v[164:167], v[176:179], 0
	v_mfma_f32_16x16x32_bf16 v[100:103], v[152:155], v[184:187], 0
	v_mfma_f32_16x16x32_bf16 v[92:95], v[164:167], v[184:187], 0
	v_mfma_f32_16x16x32_bf16 v[84:87], v[152:155], v[192:195], 0
	v_mfma_f32_16x16x32_bf16 v[76:79], v[164:167], v[192:195], 0
	v_mfma_f32_16x16x32_bf16 v[68:71], v[152:155], v[206:209], 0
	v_mfma_f32_16x16x32_bf16 v[64:67], v[164:167], v[206:209], 0
	v_mfma_f32_16x16x32_bf16 v[116:119], v[156:159], v[180:183], v[116:119]
	v_mfma_f32_16x16x32_bf16 v[108:111], v[172:175], v[180:183], v[108:111]
	v_mfma_f32_16x16x32_bf16 v[100:103], v[156:159], v[188:191], v[100:103]
	v_mfma_f32_16x16x32_bf16 v[92:95], v[172:175], v[188:191], v[92:95]
	v_mfma_f32_16x16x32_bf16 v[84:87], v[156:159], v[196:199], v[84:87]
	v_mfma_f32_16x16x32_bf16 v[76:79], v[172:175], v[196:199], v[76:79]
	v_mfma_f32_16x16x32_bf16 v[68:71], v[156:159], v[210:213], v[68:71]
	v_mfma_f32_16x16x32_bf16 v[64:67], v[172:175], v[210:213], v[64:67]
	s_barrier
	s_setprio 0
	s_mov_b32 m0, s21
	v_lshl_add_u64 v[200:201], s[50:51], 0, v[148:149]
	ds_read_b128 v[176:179], v171 offset:16384
	ds_read_b128 v[180:183], v171 offset:17408
	ds_read_b128 v[184:187], v171 offset:18432
	ds_read_b128 v[188:191], v171 offset:19456
	ds_read_b128 v[192:195], v171 offset:20480
	ds_read_b128 v[196:199], v171 offset:21504
	ds_read_b128 v[206:209], v171 offset:22528
	ds_read_b128 v[210:213], v171 offset:23552
	global_load_lds_dwordx4 v[200:201], off
	v_lshl_add_u64 v[214:215], s[50:51], 0, v[144:145]
	s_mov_b32 m0, s18
	v_lshl_add_u64 v[216:217], s[78:79], 0, v[148:149]
	global_load_lds_dwordx4 v[214:215], off
	s_mov_b32 m0, s19
	v_lshl_add_u64 v[218:219], vcc, 0, v[146:147]
	global_load_lds_dwordx4 v[216:217], off
	v_lshl_add_u64 v[216:217], s[78:79], 0, v[144:145]
	s_mov_b32 m0, s20
	s_nop 0
	global_load_lds_dwordx4 v[216:217], off
	v_lshl_add_u64 v[216:217], vcc, 0, v[150:151]
	s_mov_b32 m0, s4
	s_nop 0
	global_load_lds_dwordx4 v[216:217], off
	s_mov_b32 m0, s5
	s_nop 0
	global_load_lds_dwordx4 v[218:219], off
	s_waitcnt vmcnt(8)
	s_waitcnt lgkmcnt(0)
	s_setprio 1
	s_barrier
	v_mfma_f32_16x16x32_bf16 v[60:63], v[128:131], v[176:179], 0
	v_mfma_f32_16x16x32_bf16 v[56:59], v[136:139], v[176:179], 0
	v_mfma_f32_16x16x32_bf16 v[48:51], v[128:131], v[184:187], 0
	v_mfma_f32_16x16x32_bf16 v[40:43], v[136:139], v[184:187], 0
	v_mfma_f32_16x16x32_bf16 v[32:35], v[128:131], v[192:195], 0
	v_mfma_f32_16x16x32_bf16 v[24:27], v[136:139], v[192:195], 0
	v_mfma_f32_16x16x32_bf16 v[16:19], v[128:131], v[206:209], 0
	v_mfma_f32_16x16x32_bf16 v[8:11], v[136:139], v[206:209], 0
	v_mfma_f32_16x16x32_bf16 v[60:63], v[132:135], v[180:183], v[60:63]
	v_mfma_f32_16x16x32_bf16 v[56:59], v[140:143], v[180:183], v[56:59]
	v_mfma_f32_16x16x32_bf16 v[48:51], v[132:135], v[188:191], v[48:51]
	v_mfma_f32_16x16x32_bf16 v[40:43], v[140:143], v[188:191], v[40:43]
	v_mfma_f32_16x16x32_bf16 v[32:35], v[132:135], v[196:199], v[32:35]
	v_mfma_f32_16x16x32_bf16 v[24:27], v[140:143], v[196:199], v[24:27]
	v_mfma_f32_16x16x32_bf16 v[16:19], v[132:135], v[210:213], v[16:19]
	v_mfma_f32_16x16x32_bf16 v[8:11], v[140:143], v[210:213], v[8:11]
	s_setprio 0
	s_setprio 1
	v_mfma_f32_16x16x32_bf16 v[52:55], v[152:155], v[176:179], 0
	v_mfma_f32_16x16x32_bf16 v[44:47], v[164:167], v[176:179], 0
	v_mfma_f32_16x16x32_bf16 v[36:39], v[152:155], v[184:187], 0
	v_mfma_f32_16x16x32_bf16 v[28:31], v[164:167], v[184:187], 0
	v_mfma_f32_16x16x32_bf16 v[20:23], v[152:155], v[192:195], 0
	v_mfma_f32_16x16x32_bf16 v[12:15], v[164:167], v[192:195], 0
	v_mfma_f32_16x16x32_bf16 v[4:7], v[152:155], v[206:209], 0
	v_mfma_f32_16x16x32_bf16 v[0:3], v[164:167], v[206:209], 0
	v_mfma_f32_16x16x32_bf16 v[52:55], v[156:159], v[180:183], v[52:55]
	v_mfma_f32_16x16x32_bf16 v[44:47], v[172:175], v[180:183], v[44:47]
	v_mfma_f32_16x16x32_bf16 v[36:39], v[156:159], v[188:191], v[36:39]
	v_mfma_f32_16x16x32_bf16 v[28:31], v[172:175], v[188:191], v[28:31]
	v_mfma_f32_16x16x32_bf16 v[20:23], v[156:159], v[196:199], v[20:23]
	v_mfma_f32_16x16x32_bf16 v[12:15], v[172:175], v[196:199], v[12:15]
	v_mfma_f32_16x16x32_bf16 v[4:7], v[156:159], v[210:213], v[4:7]
	v_mfma_f32_16x16x32_bf16 v[0:3], v[172:175], v[210:213], v[0:3]
	s_barrier
	s_setprio 0
	v_add_u32_e32 v140, s54, v170
	v_add_u32_e32 v162, s43, v170
	ds_read_b128 v[128:131], v140
	ds_read_b128 v[132:135], v140 offset:1024
	ds_read_b128 v[136:139], v140 offset:2048
	ds_read_b128 v[140:143], v140 offset:3072
	ds_read_b128 v[152:155], v162
	ds_read_b128 v[156:159], v162 offset:1024
	ds_read_b128 v[164:167], v162 offset:2048
	ds_read_b128 v[172:175], v162 offset:3072
	s_mov_b32 m0, s6
	v_lshl_add_u64 v[220:221], s[74:75], 0, v[150:151]
	ds_read_b128 v[176:179], v171 offset:32768
	ds_read_b128 v[180:183], v171 offset:33792
	ds_read_b128 v[184:187], v171 offset:34816
	ds_read_b128 v[188:191], v171 offset:35840
	ds_read_b128 v[192:195], v171 offset:36864
	ds_read_b128 v[196:199], v171 offset:37888
	ds_read_b128 v[206:209], v171 offset:38912
	ds_read_b128 v[210:213], v171 offset:39936
	global_load_lds_dwordx4 v[220:221], off
	v_lshl_add_u64 v[220:221], s[74:75], 0, v[146:147]
	s_mov_b32 m0, s7
	s_nop 0
	global_load_lds_dwordx4 v[220:221], off
	s_waitcnt vmcnt(8)
	s_waitcnt lgkmcnt(0)
	s_setprio 1
	s_barrier
	v_mfma_f32_16x16x32_bf16 v[124:127], v[128:131], v[176:179], v[124:127]
	v_mfma_f32_16x16x32_bf16 v[120:123], v[136:139], v[176:179], v[120:123]
	v_mfma_f32_16x16x32_bf16 v[112:115], v[128:131], v[184:187], v[112:115]
	v_mfma_f32_16x16x32_bf16 v[104:107], v[136:139], v[184:187], v[104:107]
	v_mfma_f32_16x16x32_bf16 v[96:99], v[128:131], v[192:195], v[96:99]
	v_mfma_f32_16x16x32_bf16 v[88:91], v[136:139], v[192:195], v[88:91]
	v_mfma_f32_16x16x32_bf16 v[80:83], v[128:131], v[206:209], v[80:83]
	v_mfma_f32_16x16x32_bf16 v[72:75], v[136:139], v[206:209], v[72:75]
	v_mfma_f32_16x16x32_bf16 v[124:127], v[132:135], v[180:183], v[124:127]
	v_mfma_f32_16x16x32_bf16 v[120:123], v[140:143], v[180:183], v[120:123]
	v_mfma_f32_16x16x32_bf16 v[112:115], v[132:135], v[188:191], v[112:115]
	v_mfma_f32_16x16x32_bf16 v[104:107], v[140:143], v[188:191], v[104:107]
	v_mfma_f32_16x16x32_bf16 v[96:99], v[132:135], v[196:199], v[96:99]
	v_mfma_f32_16x16x32_bf16 v[88:91], v[140:143], v[196:199], v[88:91]
	v_mfma_f32_16x16x32_bf16 v[80:83], v[132:135], v[210:213], v[80:83]
	v_mfma_f32_16x16x32_bf16 v[72:75], v[140:143], v[210:213], v[72:75]
	s_setprio 0
	s_setprio 1
	v_mfma_f32_16x16x32_bf16 v[116:119], v[152:155], v[176:179], v[116:119]
	v_mfma_f32_16x16x32_bf16 v[108:111], v[164:167], v[176:179], v[108:111]
	v_mfma_f32_16x16x32_bf16 v[100:103], v[152:155], v[184:187], v[100:103]
	v_mfma_f32_16x16x32_bf16 v[92:95], v[164:167], v[184:187], v[92:95]
	v_mfma_f32_16x16x32_bf16 v[84:87], v[152:155], v[192:195], v[84:87]
	v_mfma_f32_16x16x32_bf16 v[76:79], v[164:167], v[192:195], v[76:79]
	v_mfma_f32_16x16x32_bf16 v[68:71], v[152:155], v[206:209], v[68:71]
	v_mfma_f32_16x16x32_bf16 v[64:67], v[164:167], v[206:209], v[64:67]
	v_mfma_f32_16x16x32_bf16 v[116:119], v[156:159], v[180:183], v[116:119]
	v_mfma_f32_16x16x32_bf16 v[108:111], v[172:175], v[180:183], v[108:111]
	v_mfma_f32_16x16x32_bf16 v[100:103], v[156:159], v[188:191], v[100:103]
	v_mfma_f32_16x16x32_bf16 v[92:95], v[172:175], v[188:191], v[92:95]
	v_mfma_f32_16x16x32_bf16 v[84:87], v[156:159], v[196:199], v[84:87]
	v_mfma_f32_16x16x32_bf16 v[76:79], v[172:175], v[196:199], v[76:79]
	v_mfma_f32_16x16x32_bf16 v[68:71], v[156:159], v[210:213], v[68:71]
	v_mfma_f32_16x16x32_bf16 v[64:67], v[172:175], v[210:213], v[64:67]
	s_barrier
	s_setprio 0
	s_mov_b32 m0, s41
	v_lshl_add_u64 v[200:201], v[200:201], 0, s[76:77]
	ds_read_b128 v[176:179], v171 offset:49152
	ds_read_b128 v[180:183], v171 offset:50176
	ds_read_b128 v[184:187], v171 offset:51200
	ds_read_b128 v[188:191], v171 offset:52224
	ds_read_b128 v[192:195], v171 offset:53248
	ds_read_b128 v[196:199], v171 offset:54272
	ds_read_b128 v[206:209], v171 offset:55296
	ds_read_b128 v[210:213], v171 offset:56320
	global_load_lds_dwordx4 v[200:201], off
	v_lshl_add_u64 v[200:201], v[214:215], 0, s[76:77]
	s_mov_b32 m0, s39
	s_nop 0
	global_load_lds_dwordx4 v[200:201], off
	v_lshl_add_u64 v[200:201], s[72:73], 0, v[148:149]
	s_mov_b32 m0, s23
	s_nop 0
	global_load_lds_dwordx4 v[200:201], off
	v_lshl_add_u64 v[200:201], s[72:73], 0, v[144:145]
	s_mov_b32 m0, s22
	s_nop 0
	global_load_lds_dwordx4 v[200:201], off
	v_lshl_add_u64 v[200:201], v[216:217], 0, s[76:77]
	s_mov_b32 m0, s11
	s_nop 0
	global_load_lds_dwordx4 v[200:201], off
	v_lshl_add_u64 v[200:201], v[218:219], 0, s[76:77]
	s_mov_b32 m0, s12
	s_nop 0
	global_load_lds_dwordx4 v[200:201], off
	s_waitcnt vmcnt(8)
	s_waitcnt lgkmcnt(0)
	s_setprio 1
	s_barrier
	v_mfma_f32_16x16x32_bf16 v[60:63], v[128:131], v[176:179], v[60:63]
	v_mfma_f32_16x16x32_bf16 v[56:59], v[136:139], v[176:179], v[56:59]
	v_mfma_f32_16x16x32_bf16 v[48:51], v[128:131], v[184:187], v[48:51]
	v_mfma_f32_16x16x32_bf16 v[40:43], v[136:139], v[184:187], v[40:43]
	v_mfma_f32_16x16x32_bf16 v[32:35], v[128:131], v[192:195], v[32:35]
	v_mfma_f32_16x16x32_bf16 v[24:27], v[136:139], v[192:195], v[24:27]
	v_mfma_f32_16x16x32_bf16 v[16:19], v[128:131], v[206:209], v[16:19]
	v_mfma_f32_16x16x32_bf16 v[8:11], v[136:139], v[206:209], v[8:11]
	v_mfma_f32_16x16x32_bf16 v[60:63], v[132:135], v[180:183], v[60:63]
	v_mfma_f32_16x16x32_bf16 v[56:59], v[140:143], v[180:183], v[56:59]
	v_mfma_f32_16x16x32_bf16 v[48:51], v[132:135], v[188:191], v[48:51]
	v_mfma_f32_16x16x32_bf16 v[40:43], v[140:143], v[188:191], v[40:43]
	v_mfma_f32_16x16x32_bf16 v[32:35], v[132:135], v[196:199], v[32:35]
	v_mfma_f32_16x16x32_bf16 v[24:27], v[140:143], v[196:199], v[24:27]
	v_mfma_f32_16x16x32_bf16 v[16:19], v[132:135], v[210:213], v[16:19]
	v_mfma_f32_16x16x32_bf16 v[8:11], v[140:143], v[210:213], v[8:11]
	s_setprio 0
	s_setprio 1
	v_mfma_f32_16x16x32_bf16 v[52:55], v[152:155], v[176:179], v[52:55]
	v_mfma_f32_16x16x32_bf16 v[44:47], v[164:167], v[176:179], v[44:47]
	v_mfma_f32_16x16x32_bf16 v[36:39], v[152:155], v[184:187], v[36:39]
	v_mfma_f32_16x16x32_bf16 v[28:31], v[164:167], v[184:187], v[28:31]
	v_mfma_f32_16x16x32_bf16 v[20:23], v[152:155], v[192:195], v[20:23]
	v_mfma_f32_16x16x32_bf16 v[12:15], v[164:167], v[192:195], v[12:15]
	v_mfma_f32_16x16x32_bf16 v[4:7], v[152:155], v[206:209], v[4:7]
	v_mfma_f32_16x16x32_bf16 v[0:3], v[164:167], v[206:209], v[0:3]
	v_mfma_f32_16x16x32_bf16 v[52:55], v[156:159], v[180:183], v[52:55]
	v_mfma_f32_16x16x32_bf16 v[44:47], v[172:175], v[180:183], v[44:47]
	v_mfma_f32_16x16x32_bf16 v[36:39], v[156:159], v[188:191], v[36:39]
	v_mfma_f32_16x16x32_bf16 v[28:31], v[172:175], v[188:191], v[28:31]
	v_mfma_f32_16x16x32_bf16 v[20:23], v[156:159], v[196:199], v[20:23]
	v_mfma_f32_16x16x32_bf16 v[12:15], v[172:175], v[196:199], v[12:15]
	v_mfma_f32_16x16x32_bf16 v[4:7], v[156:159], v[210:213], v[4:7]
	v_mfma_f32_16x16x32_bf16 v[0:3], v[172:175], v[210:213], v[0:3]
	s_barrier
	s_setprio 0
	s_movk_i32 s39, 0x100
	s_andn2_b64 vcc, exec, s[66:67]
	s_mov_b64 s[72:73], -1
	s_mov_b64 s[66:67], 0
	s_cbranch_vccz .LBB0_505
	s_branch .Lpeel_x_505
.LBB0_505:
	s_add_u32 s20, s62, s39
	s_addc_u32 s21, s63, 0
	s_add_u32 s22, s20, 0x100
	s_addc_u32 s23, s21, 0
	s_and_b64 s[18:19], s[72:73], exec
	s_cselect_b32 vcc_hi, s49, s23
	s_cselect_b32 vcc_lo, s48, s22
	s_add_u32 s18, s60, s39
	s_addc_u32 s19, s61, 0
	s_add_u32 s22, s18, 0x100
	s_addc_u32 s23, s19, 0
	s_add_i32 s24, 0, 0x10000
	s_and_b64 s[18:19], s[72:73], exec
	s_cselect_b32 s51, s59, s23
	s_cselect_b32 s50, s58, s22
	s_add_i32 s22, 0, 0x14000
	s_add_u32 s64, s20, 0x40080
	s_addc_u32 s65, s21, 0
	s_add_i32 s21, s24, s69
	s_add_i32 m0, s4, 0xc000
	s_add_i32 s25, s4, 0xe000
	s_add_i32 s18, s21, 0x2000
	s_add_u32 s78, s50, 0x10000
	v_add_u32_e32 v140, s24, v170
	v_add_u32_e32 v162, s22, v170
	s_addc_u32 s79, s51, 0
	s_add_i32 s19, s22, s69
	ds_read_b128 v[128:131], v140
	ds_read_b128 v[132:135], v140 offset:1024
	ds_read_b128 v[136:139], v140 offset:2048
	ds_read_b128 v[140:143], v140 offset:3072
	ds_read_b128 v[152:155], v162
	ds_read_b128 v[156:159], v162 offset:1024
	ds_read_b128 v[164:167], v162 offset:2048
	ds_read_b128 v[172:175], v162 offset:3072
	s_add_i32 s20, s19, 0x2000
	s_add_i32 s54, 0, 0x18000
	s_add_i32 s43, 0, 0x1c000
	s_add_u32 s74, vcc_lo, 0x40000
	s_addc_u32 s75, vcc_hi, 0
	s_add_i32 s41, s54, s69
	s_add_i32 s39, s41, 0x2000
	s_add_u32 s72, s50, 0x10080
	s_addc_u32 s73, s51, 0
	s_add_i32 s23, s43, s69
	s_add_i32 s22, s23, 0x2000
	v_lshl_add_u64 v[200:201], s[64:65], 0, v[150:151]
	ds_read_b128 v[176:179], v171
	ds_read_b128 v[180:183], v171 offset:1024
	ds_read_b128 v[184:187], v171 offset:2048
	ds_read_b128 v[188:191], v171 offset:3072
	ds_read_b128 v[192:195], v171 offset:4096
	ds_read_b128 v[196:199], v171 offset:5120
	ds_read_b128 v[206:209], v171 offset:6144
	ds_read_b128 v[210:213], v171 offset:7168
	global_load_lds_dwordx4 v[200:201], off
	v_lshl_add_u64 v[200:201], s[64:65], 0, v[146:147]
	s_mov_b32 m0, s25
	s_nop 0
	global_load_lds_dwordx4 v[200:201], off
	s_waitcnt vmcnt(8)
	s_waitcnt lgkmcnt(0)
	s_setprio 1
	s_barrier
	v_mfma_f32_16x16x32_bf16 v[124:127], v[128:131], v[176:179], v[124:127]
	v_mfma_f32_16x16x32_bf16 v[120:123], v[136:139], v[176:179], v[120:123]
	v_mfma_f32_16x16x32_bf16 v[112:115], v[128:131], v[184:187], v[112:115]
	v_mfma_f32_16x16x32_bf16 v[104:107], v[136:139], v[184:187], v[104:107]
	v_mfma_f32_16x16x32_bf16 v[96:99], v[128:131], v[192:195], v[96:99]
	v_mfma_f32_16x16x32_bf16 v[88:91], v[136:139], v[192:195], v[88:91]
	v_mfma_f32_16x16x32_bf16 v[80:83], v[128:131], v[206:209], v[80:83]
	v_mfma_f32_16x16x32_bf16 v[72:75], v[136:139], v[206:209], v[72:75]
	v_mfma_f32_16x16x32_bf16 v[124:127], v[132:135], v[180:183], v[124:127]
	v_mfma_f32_16x16x32_bf16 v[120:123], v[140:143], v[180:183], v[120:123]
	v_mfma_f32_16x16x32_bf16 v[112:115], v[132:135], v[188:191], v[112:115]
	v_mfma_f32_16x16x32_bf16 v[104:107], v[140:143], v[188:191], v[104:107]
	v_mfma_f32_16x16x32_bf16 v[96:99], v[132:135], v[196:199], v[96:99]
	v_mfma_f32_16x16x32_bf16 v[88:91], v[140:143], v[196:199], v[88:91]
	v_mfma_f32_16x16x32_bf16 v[80:83], v[132:135], v[210:213], v[80:83]
	v_mfma_f32_16x16x32_bf16 v[72:75], v[140:143], v[210:213], v[72:75]
	s_setprio 0
	s_setprio 1
	v_mfma_f32_16x16x32_bf16 v[116:119], v[152:155], v[176:179], v[116:119]
	v_mfma_f32_16x16x32_bf16 v[108:111], v[164:167], v[176:179], v[108:111]
	v_mfma_f32_16x16x32_bf16 v[100:103], v[152:155], v[184:187], v[100:103]
	v_mfma_f32_16x16x32_bf16 v[92:95], v[164:167], v[184:187], v[92:95]
	v_mfma_f32_16x16x32_bf16 v[84:87], v[152:155], v[192:195], v[84:87]
	v_mfma_f32_16x16x32_bf16 v[76:79], v[164:167], v[192:195], v[76:79]
	v_mfma_f32_16x16x32_bf16 v[68:71], v[152:155], v[206:209], v[68:71]
	v_mfma_f32_16x16x32_bf16 v[64:67], v[164:167], v[206:209], v[64:67]
	v_mfma_f32_16x16x32_bf16 v[116:119], v[156:159], v[180:183], v[116:119]
	v_mfma_f32_16x16x32_bf16 v[108:111], v[172:175], v[180:183], v[108:111]
	v_mfma_f32_16x16x32_bf16 v[100:103], v[156:159], v[188:191], v[100:103]
	v_mfma_f32_16x16x32_bf16 v[92:95], v[172:175], v[188:191], v[92:95]
	v_mfma_f32_16x16x32_bf16 v[84:87], v[156:159], v[196:199], v[84:87]
	v_mfma_f32_16x16x32_bf16 v[76:79], v[172:175], v[196:199], v[76:79]
	v_mfma_f32_16x16x32_bf16 v[68:71], v[156:159], v[210:213], v[68:71]
	v_mfma_f32_16x16x32_bf16 v[64:67], v[172:175], v[210:213], v[64:67]
	s_barrier
	s_setprio 0
	s_mov_b32 m0, s21
	v_lshl_add_u64 v[200:201], s[50:51], 0, v[148:149]
	ds_read_b128 v[176:179], v171 offset:16384
	ds_read_b128 v[180:183], v171 offset:17408
	ds_read_b128 v[184:187], v171 offset:18432
	ds_read_b128 v[188:191], v171 offset:19456
	ds_read_b128 v[192:195], v171 offset:20480
	ds_read_b128 v[196:199], v171 offset:21504
	ds_read_b128 v[206:209], v171 offset:22528
	ds_read_b128 v[210:213], v171 offset:23552
	global_load_lds_dwordx4 v[200:201], off
	v_lshl_add_u64 v[214:215], s[50:51], 0, v[144:145]
	s_mov_b32 m0, s18
	v_lshl_add_u64 v[216:217], s[78:79], 0, v[148:149]
	global_load_lds_dwordx4 v[214:215], off
	s_mov_b32 m0, s19
	v_lshl_add_u64 v[218:219], vcc, 0, v[146:147]
	global_load_lds_dwordx4 v[216:217], off
	v_lshl_add_u64 v[216:217], s[78:79], 0, v[144:145]
	s_mov_b32 m0, s20
	s_nop 0
	global_load_lds_dwordx4 v[216:217], off
	v_lshl_add_u64 v[216:217], vcc, 0, v[150:151]
	s_mov_b32 m0, s4
	s_nop 0
	global_load_lds_dwordx4 v[216:217], off
	s_mov_b32 m0, s5
	s_nop 0
	global_load_lds_dwordx4 v[218:219], off
	s_waitcnt vmcnt(8)
	s_waitcnt lgkmcnt(0)
	s_setprio 1
	s_barrier
	v_mfma_f32_16x16x32_bf16 v[60:63], v[128:131], v[176:179], v[60:63]
	v_mfma_f32_16x16x32_bf16 v[56:59], v[136:139], v[176:179], v[56:59]
	v_mfma_f32_16x16x32_bf16 v[48:51], v[128:131], v[184:187], v[48:51]
	v_mfma_f32_16x16x32_bf16 v[40:43], v[136:139], v[184:187], v[40:43]
	v_mfma_f32_16x16x32_bf16 v[32:35], v[128:131], v[192:195], v[32:35]
	v_mfma_f32_16x16x32_bf16 v[24:27], v[136:139], v[192:195], v[24:27]
	v_mfma_f32_16x16x32_bf16 v[16:19], v[128:131], v[206:209], v[16:19]
	v_mfma_f32_16x16x32_bf16 v[8:11], v[136:139], v[206:209], v[8:11]
	v_mfma_f32_16x16x32_bf16 v[60:63], v[132:135], v[180:183], v[60:63]
	v_mfma_f32_16x16x32_bf16 v[56:59], v[140:143], v[180:183], v[56:59]
	v_mfma_f32_16x16x32_bf16 v[48:51], v[132:135], v[188:191], v[48:51]
	v_mfma_f32_16x16x32_bf16 v[40:43], v[140:143], v[188:191], v[40:43]
	v_mfma_f32_16x16x32_bf16 v[32:35], v[132:135], v[196:199], v[32:35]
	v_mfma_f32_16x16x32_bf16 v[24:27], v[140:143], v[196:199], v[24:27]
	v_mfma_f32_16x16x32_bf16 v[16:19], v[132:135], v[210:213], v[16:19]
	v_mfma_f32_16x16x32_bf16 v[8:11], v[140:143], v[210:213], v[8:11]
	s_setprio 0
	s_setprio 1
	v_mfma_f32_16x16x32_bf16 v[52:55], v[152:155], v[176:179], v[52:55]
	v_mfma_f32_16x16x32_bf16 v[44:47], v[164:167], v[176:179], v[44:47]
	v_mfma_f32_16x16x32_bf16 v[36:39], v[152:155], v[184:187], v[36:39]
	v_mfma_f32_16x16x32_bf16 v[28:31], v[164:167], v[184:187], v[28:31]
	v_mfma_f32_16x16x32_bf16 v[20:23], v[152:155], v[192:195], v[20:23]
	v_mfma_f32_16x16x32_bf16 v[12:15], v[164:167], v[192:195], v[12:15]
	v_mfma_f32_16x16x32_bf16 v[4:7], v[152:155], v[206:209], v[4:7]
	v_mfma_f32_16x16x32_bf16 v[0:3], v[164:167], v[206:209], v[0:3]
	v_mfma_f32_16x16x32_bf16 v[52:55], v[156:159], v[180:183], v[52:55]
	v_mfma_f32_16x16x32_bf16 v[44:47], v[172:175], v[180:183], v[44:47]
	v_mfma_f32_16x16x32_bf16 v[36:39], v[156:159], v[188:191], v[36:39]
	v_mfma_f32_16x16x32_bf16 v[28:31], v[172:175], v[188:191], v[28:31]
	v_mfma_f32_16x16x32_bf16 v[20:23], v[156:159], v[196:199], v[20:23]
	v_mfma_f32_16x16x32_bf16 v[12:15], v[172:175], v[196:199], v[12:15]
	v_mfma_f32_16x16x32_bf16 v[4:7], v[156:159], v[210:213], v[4:7]
	v_mfma_f32_16x16x32_bf16 v[0:3], v[172:175], v[210:213], v[0:3]
	s_barrier
	s_setprio 0
	v_add_u32_e32 v140, s54, v170
	v_add_u32_e32 v162, s43, v170
	ds_read_b128 v[128:131], v140
	ds_read_b128 v[132:135], v140 offset:1024
	ds_read_b128 v[136:139], v140 offset:2048
	ds_read_b128 v[140:143], v140 offset:3072
	ds_read_b128 v[152:155], v162
	ds_read_b128 v[156:159], v162 offset:1024
	ds_read_b128 v[164:167], v162 offset:2048
	ds_read_b128 v[172:175], v162 offset:3072
	s_mov_b32 m0, s6
	v_lshl_add_u64 v[220:221], s[74:75], 0, v[150:151]
	ds_read_b128 v[176:179], v171 offset:32768
	ds_read_b128 v[180:183], v171 offset:33792
	ds_read_b128 v[184:187], v171 offset:34816
	ds_read_b128 v[188:191], v171 offset:35840
	ds_read_b128 v[192:195], v171 offset:36864
	ds_read_b128 v[196:199], v171 offset:37888
	ds_read_b128 v[206:209], v171 offset:38912
	ds_read_b128 v[210:213], v171 offset:39936
	global_load_lds_dwordx4 v[220:221], off
	v_lshl_add_u64 v[220:221], s[74:75], 0, v[146:147]
	s_mov_b32 m0, s7
	s_nop 0
	global_load_lds_dwordx4 v[220:221], off
	s_waitcnt vmcnt(8)
	s_waitcnt lgkmcnt(0)
	s_setprio 1
	s_barrier
	v_mfma_f32_16x16x32_bf16 v[124:127], v[128:131], v[176:179], v[124:127]
	v_mfma_f32_16x16x32_bf16 v[120:123], v[136:139], v[176:179], v[120:123]
	v_mfma_f32_16x16x32_bf16 v[112:115], v[128:131], v[184:187], v[112:115]
	v_mfma_f32_16x16x32_bf16 v[104:107], v[136:139], v[184:187], v[104:107]
	v_mfma_f32_16x16x32_bf16 v[96:99], v[128:131], v[192:195], v[96:99]
	v_mfma_f32_16x16x32_bf16 v[88:91], v[136:139], v[192:195], v[88:91]
	v_mfma_f32_16x16x32_bf16 v[80:83], v[128:131], v[206:209], v[80:83]
	v_mfma_f32_16x16x32_bf16 v[72:75], v[136:139], v[206:209], v[72:75]
	v_mfma_f32_16x16x32_bf16 v[124:127], v[132:135], v[180:183], v[124:127]
	v_mfma_f32_16x16x32_bf16 v[120:123], v[140:143], v[180:183], v[120:123]
	v_mfma_f32_16x16x32_bf16 v[112:115], v[132:135], v[188:191], v[112:115]
	v_mfma_f32_16x16x32_bf16 v[104:107], v[140:143], v[188:191], v[104:107]
	v_mfma_f32_16x16x32_bf16 v[96:99], v[132:135], v[196:199], v[96:99]
	v_mfma_f32_16x16x32_bf16 v[88:91], v[140:143], v[196:199], v[88:91]
	v_mfma_f32_16x16x32_bf16 v[80:83], v[132:135], v[210:213], v[80:83]
	v_mfma_f32_16x16x32_bf16 v[72:75], v[140:143], v[210:213], v[72:75]
	s_setprio 0
	s_setprio 1
	v_mfma_f32_16x16x32_bf16 v[116:119], v[152:155], v[176:179], v[116:119]
	v_mfma_f32_16x16x32_bf16 v[108:111], v[164:167], v[176:179], v[108:111]
	v_mfma_f32_16x16x32_bf16 v[100:103], v[152:155], v[184:187], v[100:103]
	v_mfma_f32_16x16x32_bf16 v[92:95], v[164:167], v[184:187], v[92:95]
	v_mfma_f32_16x16x32_bf16 v[84:87], v[152:155], v[192:195], v[84:87]
	v_mfma_f32_16x16x32_bf16 v[76:79], v[164:167], v[192:195], v[76:79]
	v_mfma_f32_16x16x32_bf16 v[68:71], v[152:155], v[206:209], v[68:71]
	v_mfma_f32_16x16x32_bf16 v[64:67], v[164:167], v[206:209], v[64:67]
	v_mfma_f32_16x16x32_bf16 v[116:119], v[156:159], v[180:183], v[116:119]
	v_mfma_f32_16x16x32_bf16 v[108:111], v[172:175], v[180:183], v[108:111]
	v_mfma_f32_16x16x32_bf16 v[100:103], v[156:159], v[188:191], v[100:103]
	v_mfma_f32_16x16x32_bf16 v[92:95], v[172:175], v[188:191], v[92:95]
	v_mfma_f32_16x16x32_bf16 v[84:87], v[156:159], v[196:199], v[84:87]
	v_mfma_f32_16x16x32_bf16 v[76:79], v[172:175], v[196:199], v[76:79]
	v_mfma_f32_16x16x32_bf16 v[68:71], v[156:159], v[210:213], v[68:71]
	v_mfma_f32_16x16x32_bf16 v[64:67], v[172:175], v[210:213], v[64:67]
	s_barrier
	s_setprio 0
	s_mov_b32 m0, s41
	v_lshl_add_u64 v[200:201], v[200:201], 0, s[76:77]
	ds_read_b128 v[176:179], v171 offset:49152
	ds_read_b128 v[180:183], v171 offset:50176
	ds_read_b128 v[184:187], v171 offset:51200
	ds_read_b128 v[188:191], v171 offset:52224
	ds_read_b128 v[192:195], v171 offset:53248
	ds_read_b128 v[196:199], v171 offset:54272
	ds_read_b128 v[206:209], v171 offset:55296
	ds_read_b128 v[210:213], v171 offset:56320
	global_load_lds_dwordx4 v[200:201], off
	v_lshl_add_u64 v[200:201], v[214:215], 0, s[76:77]
	s_mov_b32 m0, s39
	s_nop 0
	global_load_lds_dwordx4 v[200:201], off
	v_lshl_add_u64 v[200:201], s[72:73], 0, v[148:149]
	s_mov_b32 m0, s23
	s_nop 0
	global_load_lds_dwordx4 v[200:201], off
	v_lshl_add_u64 v[200:201], s[72:73], 0, v[144:145]
	s_mov_b32 m0, s22
	s_nop 0
	global_load_lds_dwordx4 v[200:201], off
	v_lshl_add_u64 v[200:201], v[216:217], 0, s[76:77]
	s_mov_b32 m0, s11
	s_nop 0
	global_load_lds_dwordx4 v[200:201], off
	v_lshl_add_u64 v[200:201], v[218:219], 0, s[76:77]
	s_mov_b32 m0, s12
	s_nop 0
	global_load_lds_dwordx4 v[200:201], off
	s_waitcnt vmcnt(8)
	s_waitcnt lgkmcnt(0)
	s_setprio 1
	s_barrier
	v_mfma_f32_16x16x32_bf16 v[60:63], v[128:131], v[176:179], v[60:63]
	v_mfma_f32_16x16x32_bf16 v[56:59], v[136:139], v[176:179], v[56:59]
	v_mfma_f32_16x16x32_bf16 v[48:51], v[128:131], v[184:187], v[48:51]
	v_mfma_f32_16x16x32_bf16 v[40:43], v[136:139], v[184:187], v[40:43]
	v_mfma_f32_16x16x32_bf16 v[32:35], v[128:131], v[192:195], v[32:35]
	v_mfma_f32_16x16x32_bf16 v[24:27], v[136:139], v[192:195], v[24:27]
	v_mfma_f32_16x16x32_bf16 v[16:19], v[128:131], v[206:209], v[16:19]
	v_mfma_f32_16x16x32_bf16 v[8:11], v[136:139], v[206:209], v[8:11]
	v_mfma_f32_16x16x32_bf16 v[60:63], v[132:135], v[180:183], v[60:63]
	v_mfma_f32_16x16x32_bf16 v[56:59], v[140:143], v[180:183], v[56:59]
	v_mfma_f32_16x16x32_bf16 v[48:51], v[132:135], v[188:191], v[48:51]
	v_mfma_f32_16x16x32_bf16 v[40:43], v[140:143], v[188:191], v[40:43]
	v_mfma_f32_16x16x32_bf16 v[32:35], v[132:135], v[196:199], v[32:35]
	v_mfma_f32_16x16x32_bf16 v[24:27], v[140:143], v[196:199], v[24:27]
	v_mfma_f32_16x16x32_bf16 v[16:19], v[132:135], v[210:213], v[16:19]
	v_mfma_f32_16x16x32_bf16 v[8:11], v[140:143], v[210:213], v[8:11]
	s_setprio 0
	s_setprio 1
	v_mfma_f32_16x16x32_bf16 v[52:55], v[152:155], v[176:179], v[52:55]
	v_mfma_f32_16x16x32_bf16 v[44:47], v[164:167], v[176:179], v[44:47]
	v_mfma_f32_16x16x32_bf16 v[36:39], v[152:155], v[184:187], v[36:39]
	v_mfma_f32_16x16x32_bf16 v[28:31], v[164:167], v[184:187], v[28:31]
	v_mfma_f32_16x16x32_bf16 v[20:23], v[152:155], v[192:195], v[20:23]
	v_mfma_f32_16x16x32_bf16 v[12:15], v[164:167], v[192:195], v[12:15]
	v_mfma_f32_16x16x32_bf16 v[4:7], v[152:155], v[206:209], v[4:7]
	v_mfma_f32_16x16x32_bf16 v[0:3], v[164:167], v[206:209], v[0:3]
	v_mfma_f32_16x16x32_bf16 v[52:55], v[156:159], v[180:183], v[52:55]
	v_mfma_f32_16x16x32_bf16 v[44:47], v[172:175], v[180:183], v[44:47]
	v_mfma_f32_16x16x32_bf16 v[36:39], v[156:159], v[188:191], v[36:39]
	v_mfma_f32_16x16x32_bf16 v[28:31], v[172:175], v[188:191], v[28:31]
	v_mfma_f32_16x16x32_bf16 v[20:23], v[156:159], v[196:199], v[20:23]
	v_mfma_f32_16x16x32_bf16 v[12:15], v[172:175], v[196:199], v[12:15]
	v_mfma_f32_16x16x32_bf16 v[4:7], v[156:159], v[210:213], v[4:7]
	v_mfma_f32_16x16x32_bf16 v[0:3], v[172:175], v[210:213], v[0:3]
	s_barrier
	s_setprio 0
	s_movk_i32 s39, 0x100
	s_andn2_b64 vcc, exec, s[66:67]
	s_mov_b64 s[72:73], -1
	s_mov_b64 s[66:67], 0
	s_cbranch_vccz .LBB0_505

.LBB0_649:
	s_ashr_i32 s59, s58, 31
	s_lshl_b64 s[6:7], s[58:59], 19
	s_add_u32 s62, s96, s6
	s_addc_u32 s63, s97, s7
	s_and_b64 s[6:7], s[72:73], exec
	s_cselect_b32 s6, s63, s39
	s_cselect_b32 s7, s62, s38
	s_ashr_i32 s61, s60, 31
	s_lshl_b64 s[8:9], s[60:61], 19
	s_add_u32 s74, s50, s8
	s_addc_u32 s75, s51, s9
	s_and_b64 s[8:9], s[72:73], exec
	s_cselect_b32 s8, s75, s41
	s_cselect_b32 s9, s74, s40
	s_add_u32 s38, s38, 0x40080
	s_addc_u32 s39, s39, 0
	s_add_u32 s10, s40, 0x100
	s_addc_u32 s11, s41, 0
	s_mov_b32 s12, -2
	s_add_u32 s13, s38, 0xfffc0080
	s_addc_u32 s14, s39, -1
	s_add_i32 s15, 0, 0x10000
	s_cmp_eq_u32 s12, 12
	s_cselect_b32 s43, s6, s14
	s_cselect_b32 s42, s7, s13
	s_cselect_b32 s41, s8, s11
	s_cselect_b32 s40, s9, s10
	s_add_i32 s13, 0, 0x14000
	v_add_u32_e32 v140, s15, v181
	v_add_u32_e32 v156, s13, v181
	ds_read_b128 v[128:131], v140
	ds_read_b128 v[132:135], v140 offset:1024
	ds_read_b128 v[136:139], v140 offset:2048
	ds_read_b128 v[140:143], v140 offset:3072
	ds_read_b128 v[144:147], v156
	ds_read_b128 v[148:151], v156 offset:1024
	ds_read_b128 v[152:155], v156 offset:2048
	ds_read_b128 v[156:159], v156 offset:3072
	v_lshl_add_u64 v[178:179], s[38:39], 0, v[174:175]
	s_add_i32 m0, s66, 0xc000
	ds_read_b128 v[186:189], v185
	ds_read_b128 v[190:193], v185 offset:1024
	ds_read_b128 v[194:197], v185 offset:2048
	ds_read_b128 v[198:201], v185 offset:3072
	ds_read_b128 v[206:209], v185 offset:4096
	ds_read_b128 v[210:213], v185 offset:5120
	ds_read_b128 v[214:217], v185 offset:6144
	ds_read_b128 v[218:221], v185 offset:7168
	global_load_lds_dwordx4 v[178:179], off
	v_lshl_add_u64 v[178:179], s[38:39], 0, v[176:177]
	s_add_i32 m0, s66, 0xe000
	s_nop 0
	global_load_lds_dwordx4 v[178:179], off
	s_waitcnt vmcnt(8)
	s_waitcnt lgkmcnt(0)
	s_setprio 1
	s_barrier
	v_mfma_f32_16x16x32_bf16 v[120:123], v[128:131], v[186:189], 0
	v_mfma_f32_16x16x32_bf16 v[124:127], v[136:139], v[186:189], 0
	v_mfma_f32_16x16x32_bf16 v[104:107], v[128:131], v[194:197], 0
	v_mfma_f32_16x16x32_bf16 v[108:111], v[136:139], v[194:197], 0
	v_mfma_f32_16x16x32_bf16 v[88:91], v[128:131], v[206:209], 0
	v_mfma_f32_16x16x32_bf16 v[92:95], v[136:139], v[206:209], 0
	v_mfma_f32_16x16x32_bf16 v[72:75], v[128:131], v[214:217], 0
	v_mfma_f32_16x16x32_bf16 v[76:79], v[136:139], v[214:217], 0
	v_mfma_f32_16x16x32_bf16 v[120:123], v[132:135], v[190:193], v[120:123]
	v_mfma_f32_16x16x32_bf16 v[124:127], v[140:143], v[190:193], v[124:127]
	v_mfma_f32_16x16x32_bf16 v[104:107], v[132:135], v[198:201], v[104:107]
	v_mfma_f32_16x16x32_bf16 v[108:111], v[140:143], v[198:201], v[108:111]
	v_mfma_f32_16x16x32_bf16 v[88:91], v[132:135], v[210:213], v[88:91]
	v_mfma_f32_16x16x32_bf16 v[92:95], v[140:143], v[210:213], v[92:95]
	v_mfma_f32_16x16x32_bf16 v[72:75], v[132:135], v[218:221], v[72:75]
	v_mfma_f32_16x16x32_bf16 v[76:79], v[140:143], v[218:221], v[76:79]
	s_setprio 0
	s_setprio 1
	v_mfma_f32_16x16x32_bf16 v[116:119], v[144:147], v[186:189], 0
	v_mfma_f32_16x16x32_bf16 v[112:115], v[152:155], v[186:189], 0
	v_mfma_f32_16x16x32_bf16 v[100:103], v[144:147], v[194:197], 0
	v_mfma_f32_16x16x32_bf16 v[96:99], v[152:155], v[194:197], 0
	v_mfma_f32_16x16x32_bf16 v[84:87], v[144:147], v[206:209], 0
	v_mfma_f32_16x16x32_bf16 v[80:83], v[152:155], v[206:209], 0
	v_mfma_f32_16x16x32_bf16 v[68:71], v[144:147], v[214:217], 0
	v_mfma_f32_16x16x32_bf16 v[64:67], v[152:155], v[214:217], 0
	v_mfma_f32_16x16x32_bf16 v[116:119], v[148:151], v[190:193], v[116:119]
	v_mfma_f32_16x16x32_bf16 v[112:115], v[156:159], v[190:193], v[112:115]
	v_mfma_f32_16x16x32_bf16 v[100:103], v[148:151], v[198:201], v[100:103]
	v_mfma_f32_16x16x32_bf16 v[96:99], v[156:159], v[198:201], v[96:99]
	v_mfma_f32_16x16x32_bf16 v[84:87], v[148:151], v[210:213], v[84:87]
	v_mfma_f32_16x16x32_bf16 v[80:83], v[156:159], v[210:213], v[80:83]
	v_mfma_f32_16x16x32_bf16 v[68:71], v[148:151], v[218:221], v[68:71]
	v_mfma_f32_16x16x32_bf16 v[64:67], v[156:159], v[218:221], v[64:67]
	s_barrier
	s_setprio 0
	s_add_i32 s14, s15, s65
	v_lshl_add_u64 v[178:179], s[40:41], 0, v[168:169]
	s_mov_b32 m0, s14
	ds_read_b128 v[186:189], v185 offset:16384
	ds_read_b128 v[190:193], v185 offset:17408
	ds_read_b128 v[194:197], v185 offset:18432
	ds_read_b128 v[198:201], v185 offset:19456
	ds_read_b128 v[206:209], v185 offset:20480
	ds_read_b128 v[210:213], v185 offset:21504
	ds_read_b128 v[214:217], v185 offset:22528
	ds_read_b128 v[218:221], v185 offset:23552
	global_load_lds_dwordx4 v[178:179], off
	s_add_i32 m0, s14, 0x2000
	s_add_u32 s14, s40, 0x40000
	v_lshl_add_u64 v[222:223], s[40:41], 0, v[164:165]
	s_addc_u32 s15, s41, 0
	s_add_i32 s13, s13, s65
	global_load_lds_dwordx4 v[222:223], off
	v_lshl_add_u64 v[224:225], s[14:15], 0, v[168:169]
	s_mov_b32 m0, s13
	v_lshl_add_u64 v[226:227], s[42:43], 0, v[166:167]
	global_load_lds_dwordx4 v[224:225], off
	v_lshl_add_u64 v[224:225], s[14:15], 0, v[164:165]
	s_add_i32 m0, s13, 0x2000
	s_nop 0
	global_load_lds_dwordx4 v[224:225], off
	v_lshl_add_u64 v[224:225], s[42:43], 0, v[170:171]
	s_mov_b32 m0, s66
	s_nop 0
	global_load_lds_dwordx4 v[224:225], off
	s_mov_b32 m0, s67
	s_nop 0
	global_load_lds_dwordx4 v[226:227], off
	s_waitcnt vmcnt(8)
	s_waitcnt lgkmcnt(0)
	s_setprio 1
	s_barrier
	v_mfma_f32_16x16x32_bf16 v[56:59], v[128:131], v[186:189], 0
	v_mfma_f32_16x16x32_bf16 v[60:63], v[136:139], v[186:189], 0
	v_mfma_f32_16x16x32_bf16 v[40:43], v[128:131], v[194:197], 0
	v_mfma_f32_16x16x32_bf16 v[44:47], v[136:139], v[194:197], 0
	v_mfma_f32_16x16x32_bf16 v[24:27], v[128:131], v[206:209], 0
	v_mfma_f32_16x16x32_bf16 v[28:31], v[136:139], v[206:209], 0
	v_mfma_f32_16x16x32_bf16 v[8:11], v[128:131], v[214:217], 0
	v_mfma_f32_16x16x32_bf16 v[12:15], v[136:139], v[214:217], 0
	v_mfma_f32_16x16x32_bf16 v[56:59], v[132:135], v[190:193], v[56:59]
	v_mfma_f32_16x16x32_bf16 v[60:63], v[140:143], v[190:193], v[60:63]
	v_mfma_f32_16x16x32_bf16 v[40:43], v[132:135], v[198:201], v[40:43]
	v_mfma_f32_16x16x32_bf16 v[44:47], v[140:143], v[198:201], v[44:47]
	v_mfma_f32_16x16x32_bf16 v[24:27], v[132:135], v[210:213], v[24:27]
	v_mfma_f32_16x16x32_bf16 v[28:31], v[140:143], v[210:213], v[28:31]
	v_mfma_f32_16x16x32_bf16 v[8:11], v[132:135], v[218:221], v[8:11]
	v_mfma_f32_16x16x32_bf16 v[12:15], v[140:143], v[218:221], v[12:15]
	s_setprio 0
	s_setprio 1
	v_mfma_f32_16x16x32_bf16 v[52:55], v[144:147], v[186:189], 0
	v_mfma_f32_16x16x32_bf16 v[48:51], v[152:155], v[186:189], 0
	v_mfma_f32_16x16x32_bf16 v[36:39], v[144:147], v[194:197], 0
	v_mfma_f32_16x16x32_bf16 v[32:35], v[152:155], v[194:197], 0
	v_mfma_f32_16x16x32_bf16 v[20:23], v[144:147], v[206:209], 0
	v_mfma_f32_16x16x32_bf16 v[16:19], v[152:155], v[206:209], 0
	v_mfma_f32_16x16x32_bf16 v[4:7], v[144:147], v[214:217], 0
	v_mfma_f32_16x16x32_bf16 v[0:3], v[152:155], v[214:217], 0
	v_mfma_f32_16x16x32_bf16 v[52:55], v[148:151], v[190:193], v[52:55]
	v_mfma_f32_16x16x32_bf16 v[48:51], v[156:159], v[190:193], v[48:51]
	v_mfma_f32_16x16x32_bf16 v[36:39], v[148:151], v[198:201], v[36:39]
	v_mfma_f32_16x16x32_bf16 v[32:35], v[156:159], v[198:201], v[32:35]
	v_mfma_f32_16x16x32_bf16 v[20:23], v[148:151], v[210:213], v[20:23]
	v_mfma_f32_16x16x32_bf16 v[16:19], v[156:159], v[210:213], v[16:19]
	v_mfma_f32_16x16x32_bf16 v[4:7], v[148:151], v[218:221], v[4:7]
	v_mfma_f32_16x16x32_bf16 v[0:3], v[156:159], v[218:221], v[0:3]
	s_barrier
	s_setprio 0
	s_add_i32 s13, 0, 0x18000
	s_add_i32 s16, 0, 0x1c000
	v_add_u32_e32 v140, s13, v181
	v_add_u32_e32 v156, s16, v181
	ds_read_b128 v[128:131], v140
	ds_read_b128 v[132:135], v140 offset:1024
	ds_read_b128 v[136:139], v140 offset:2048
	ds_read_b128 v[140:143], v140 offset:3072
	ds_read_b128 v[144:147], v156
	ds_read_b128 v[148:151], v156 offset:1024
	ds_read_b128 v[152:155], v156 offset:2048
	ds_read_b128 v[156:159], v156 offset:3072
	s_add_u32 s14, s42, 0x40000
	s_addc_u32 s15, s43, 0
	s_mov_b32 m0, s68
	v_lshl_add_u64 v[228:229], s[14:15], 0, v[170:171]
	ds_read_b128 v[186:189], v185 offset:32768
	ds_read_b128 v[190:193], v185 offset:33792
	ds_read_b128 v[194:197], v185 offset:34816
	ds_read_b128 v[198:201], v185 offset:35840
	ds_read_b128 v[206:209], v185 offset:36864
	ds_read_b128 v[210:213], v185 offset:37888
	ds_read_b128 v[214:217], v185 offset:38912
	ds_read_b128 v[218:221], v185 offset:39936
	global_load_lds_dwordx4 v[228:229], off
	v_lshl_add_u64 v[228:229], s[14:15], 0, v[166:167]
	s_mov_b32 m0, s69
	s_nop 0
	global_load_lds_dwordx4 v[228:229], off
	s_waitcnt vmcnt(8)
	s_waitcnt lgkmcnt(0)
	s_setprio 1
	s_barrier
	v_mfma_f32_16x16x32_bf16 v[120:123], v[128:131], v[186:189], v[120:123]
	v_mfma_f32_16x16x32_bf16 v[124:127], v[136:139], v[186:189], v[124:127]
	v_mfma_f32_16x16x32_bf16 v[104:107], v[128:131], v[194:197], v[104:107]
	v_mfma_f32_16x16x32_bf16 v[108:111], v[136:139], v[194:197], v[108:111]
	v_mfma_f32_16x16x32_bf16 v[88:91], v[128:131], v[206:209], v[88:91]
	v_mfma_f32_16x16x32_bf16 v[92:95], v[136:139], v[206:209], v[92:95]
	v_mfma_f32_16x16x32_bf16 v[72:75], v[128:131], v[214:217], v[72:75]
	v_mfma_f32_16x16x32_bf16 v[76:79], v[136:139], v[214:217], v[76:79]
	v_mfma_f32_16x16x32_bf16 v[120:123], v[132:135], v[190:193], v[120:123]
	v_mfma_f32_16x16x32_bf16 v[124:127], v[140:143], v[190:193], v[124:127]
	v_mfma_f32_16x16x32_bf16 v[104:107], v[132:135], v[198:201], v[104:107]
	v_mfma_f32_16x16x32_bf16 v[108:111], v[140:143], v[198:201], v[108:111]
	v_mfma_f32_16x16x32_bf16 v[88:91], v[132:135], v[210:213], v[88:91]
	v_mfma_f32_16x16x32_bf16 v[92:95], v[140:143], v[210:213], v[92:95]
	v_mfma_f32_16x16x32_bf16 v[72:75], v[132:135], v[218:221], v[72:75]
	v_mfma_f32_16x16x32_bf16 v[76:79], v[140:143], v[218:221], v[76:79]
	s_setprio 0
	s_setprio 1
	v_mfma_f32_16x16x32_bf16 v[116:119], v[144:147], v[186:189], v[116:119]
	v_mfma_f32_16x16x32_bf16 v[112:115], v[152:155], v[186:189], v[112:115]
	v_mfma_f32_16x16x32_bf16 v[100:103], v[144:147], v[194:197], v[100:103]
	v_mfma_f32_16x16x32_bf16 v[96:99], v[152:155], v[194:197], v[96:99]
	v_mfma_f32_16x16x32_bf16 v[84:87], v[144:147], v[206:209], v[84:87]
	v_mfma_f32_16x16x32_bf16 v[80:83], v[152:155], v[206:209], v[80:83]
	v_mfma_f32_16x16x32_bf16 v[68:71], v[144:147], v[214:217], v[68:71]
	v_mfma_f32_16x16x32_bf16 v[64:67], v[152:155], v[214:217], v[64:67]
	v_mfma_f32_16x16x32_bf16 v[116:119], v[148:151], v[190:193], v[116:119]
	v_mfma_f32_16x16x32_bf16 v[112:115], v[156:159], v[190:193], v[112:115]
	v_mfma_f32_16x16x32_bf16 v[100:103], v[148:151], v[198:201], v[100:103]
	v_mfma_f32_16x16x32_bf16 v[96:99], v[156:159], v[198:201], v[96:99]
	v_mfma_f32_16x16x32_bf16 v[84:87], v[148:151], v[210:213], v[84:87]
	v_mfma_f32_16x16x32_bf16 v[80:83], v[156:159], v[210:213], v[80:83]
	v_mfma_f32_16x16x32_bf16 v[68:71], v[148:151], v[218:221], v[68:71]
	v_mfma_f32_16x16x32_bf16 v[64:67], v[156:159], v[218:221], v[64:67]
	s_barrier
	s_setprio 0
	s_add_i32 s13, s13, s65
	v_lshl_add_u64 v[178:179], v[178:179], 0, s[76:77]
	s_mov_b32 m0, s13
	ds_read_b128 v[186:189], v185 offset:49152
	ds_read_b128 v[190:193], v185 offset:50176
	ds_read_b128 v[194:197], v185 offset:51200
	ds_read_b128 v[198:201], v185 offset:52224
	ds_read_b128 v[206:209], v185 offset:53248
	ds_read_b128 v[210:213], v185 offset:54272
	ds_read_b128 v[214:217], v185 offset:55296
	ds_read_b128 v[218:221], v185 offset:56320
	global_load_lds_dwordx4 v[178:179], off
	s_add_i32 m0, s13, 0x2000
	s_add_u32 s14, s40, 0x40080
	v_lshl_add_u64 v[178:179], v[222:223], 0, s[76:77]
	s_addc_u32 s15, s41, 0
	s_add_i32 s13, s16, s65
	global_load_lds_dwordx4 v[178:179], off
	v_lshl_add_u64 v[178:179], s[14:15], 0, v[168:169]
	s_mov_b32 m0, s13
	s_nop 0
	global_load_lds_dwordx4 v[178:179], off
	v_lshl_add_u64 v[178:179], s[14:15], 0, v[164:165]
	s_add_i32 m0, s13, 0x2000
	s_nop 0
	global_load_lds_dwordx4 v[178:179], off
	v_lshl_add_u64 v[178:179], v[224:225], 0, s[76:77]
	s_mov_b32 m0, s79
	s_nop 0
	global_load_lds_dwordx4 v[178:179], off
	v_lshl_add_u64 v[178:179], v[226:227], 0, s[76:77]
	s_mov_b32 m0, s46
	s_nop 0
	global_load_lds_dwordx4 v[178:179], off
	s_waitcnt vmcnt(8)
	s_waitcnt lgkmcnt(0)
	s_setprio 1
	s_barrier
	v_mfma_f32_16x16x32_bf16 v[56:59], v[128:131], v[186:189], v[56:59]
	v_mfma_f32_16x16x32_bf16 v[60:63], v[136:139], v[186:189], v[60:63]
	v_mfma_f32_16x16x32_bf16 v[40:43], v[128:131], v[194:197], v[40:43]
	v_mfma_f32_16x16x32_bf16 v[44:47], v[136:139], v[194:197], v[44:47]
	v_mfma_f32_16x16x32_bf16 v[24:27], v[128:131], v[206:209], v[24:27]
	v_mfma_f32_16x16x32_bf16 v[28:31], v[136:139], v[206:209], v[28:31]
	v_mfma_f32_16x16x32_bf16 v[8:11], v[128:131], v[214:217], v[8:11]
	v_mfma_f32_16x16x32_bf16 v[12:15], v[136:139], v[214:217], v[12:15]
	v_mfma_f32_16x16x32_bf16 v[56:59], v[132:135], v[190:193], v[56:59]
	v_mfma_f32_16x16x32_bf16 v[60:63], v[140:143], v[190:193], v[60:63]
	v_mfma_f32_16x16x32_bf16 v[40:43], v[132:135], v[198:201], v[40:43]
	v_mfma_f32_16x16x32_bf16 v[44:47], v[140:143], v[198:201], v[44:47]
	v_mfma_f32_16x16x32_bf16 v[24:27], v[132:135], v[210:213], v[24:27]
	v_mfma_f32_16x16x32_bf16 v[28:31], v[140:143], v[210:213], v[28:31]
	v_mfma_f32_16x16x32_bf16 v[8:11], v[132:135], v[218:221], v[8:11]
	v_mfma_f32_16x16x32_bf16 v[12:15], v[140:143], v[218:221], v[12:15]
	s_setprio 0
	s_setprio 1
	v_mfma_f32_16x16x32_bf16 v[52:55], v[144:147], v[186:189], v[52:55]
	v_mfma_f32_16x16x32_bf16 v[48:51], v[152:155], v[186:189], v[48:51]
	v_mfma_f32_16x16x32_bf16 v[36:39], v[144:147], v[194:197], v[36:39]
	v_mfma_f32_16x16x32_bf16 v[32:35], v[152:155], v[194:197], v[32:35]
	v_mfma_f32_16x16x32_bf16 v[20:23], v[144:147], v[206:209], v[20:23]
	v_mfma_f32_16x16x32_bf16 v[16:19], v[152:155], v[206:209], v[16:19]
	v_mfma_f32_16x16x32_bf16 v[4:7], v[144:147], v[214:217], v[4:7]
	v_mfma_f32_16x16x32_bf16 v[0:3], v[152:155], v[214:217], v[0:3]
	v_mfma_f32_16x16x32_bf16 v[52:55], v[148:151], v[190:193], v[52:55]
	v_mfma_f32_16x16x32_bf16 v[48:51], v[156:159], v[190:193], v[48:51]
	v_mfma_f32_16x16x32_bf16 v[36:39], v[148:151], v[198:201], v[36:39]
	v_mfma_f32_16x16x32_bf16 v[32:35], v[156:159], v[198:201], v[32:35]
	v_mfma_f32_16x16x32_bf16 v[20:23], v[148:151], v[210:213], v[20:23]
	v_mfma_f32_16x16x32_bf16 v[16:19], v[156:159], v[210:213], v[16:19]
	v_mfma_f32_16x16x32_bf16 v[4:7], v[148:151], v[218:221], v[4:7]
	v_mfma_f32_16x16x32_bf16 v[0:3], v[156:159], v[218:221], v[0:3]
	s_barrier
	s_setprio 0
	s_add_i32 s12, s12, 2
	s_add_u32 s38, s38, 0x100
	s_addc_u32 s39, s39, 0
	s_add_u32 s10, s10, 0x100
	s_addc_u32 s11, s11, 0
	s_cmp_gt_u32 s12, 13
	s_cbranch_scc0 .LBB0_650
	s_branch .Lpeel_x_650
.LBB0_650:
	s_add_u32 s13, s38, 0xfffc0080
	s_addc_u32 s14, s39, -1
	s_add_i32 s15, 0, 0x10000
	s_cmp_eq_u32 s12, 12
	s_cselect_b32 s43, s6, s14
	s_cselect_b32 s42, s7, s13
	s_cselect_b32 s41, s8, s11
	s_cselect_b32 s40, s9, s10
	s_add_i32 s13, 0, 0x14000
	v_add_u32_e32 v140, s15, v181
	v_add_u32_e32 v156, s13, v181
	ds_read_b128 v[128:131], v140
	ds_read_b128 v[132:135], v140 offset:1024
	ds_read_b128 v[136:139], v140 offset:2048
	ds_read_b128 v[140:143], v140 offset:3072
	ds_read_b128 v[144:147], v156
	ds_read_b128 v[148:151], v156 offset:1024
	ds_read_b128 v[152:155], v156 offset:2048
	ds_read_b128 v[156:159], v156 offset:3072
	v_lshl_add_u64 v[178:179], s[38:39], 0, v[174:175]
	s_add_i32 m0, s66, 0xc000
	ds_read_b128 v[186:189], v185
	ds_read_b128 v[190:193], v185 offset:1024
	ds_read_b128 v[194:197], v185 offset:2048
	ds_read_b128 v[198:201], v185 offset:3072
	ds_read_b128 v[206:209], v185 offset:4096
	ds_read_b128 v[210:213], v185 offset:5120
	ds_read_b128 v[214:217], v185 offset:6144
	ds_read_b128 v[218:221], v185 offset:7168
	global_load_lds_dwordx4 v[178:179], off
	v_lshl_add_u64 v[178:179], s[38:39], 0, v[176:177]
	s_add_i32 m0, s66, 0xe000
	s_nop 0
	global_load_lds_dwordx4 v[178:179], off
	s_waitcnt vmcnt(8)
	s_waitcnt lgkmcnt(0)
	s_setprio 1
	s_barrier
	v_mfma_f32_16x16x32_bf16 v[120:123], v[128:131], v[186:189], v[120:123]
	v_mfma_f32_16x16x32_bf16 v[124:127], v[136:139], v[186:189], v[124:127]
	v_mfma_f32_16x16x32_bf16 v[104:107], v[128:131], v[194:197], v[104:107]
	v_mfma_f32_16x16x32_bf16 v[108:111], v[136:139], v[194:197], v[108:111]
	v_mfma_f32_16x16x32_bf16 v[88:91], v[128:131], v[206:209], v[88:91]
	v_mfma_f32_16x16x32_bf16 v[92:95], v[136:139], v[206:209], v[92:95]
	v_mfma_f32_16x16x32_bf16 v[72:75], v[128:131], v[214:217], v[72:75]
	v_mfma_f32_16x16x32_bf16 v[76:79], v[136:139], v[214:217], v[76:79]
	v_mfma_f32_16x16x32_bf16 v[120:123], v[132:135], v[190:193], v[120:123]
	v_mfma_f32_16x16x32_bf16 v[124:127], v[140:143], v[190:193], v[124:127]
	v_mfma_f32_16x16x32_bf16 v[104:107], v[132:135], v[198:201], v[104:107]
	v_mfma_f32_16x16x32_bf16 v[108:111], v[140:143], v[198:201], v[108:111]
	v_mfma_f32_16x16x32_bf16 v[88:91], v[132:135], v[210:213], v[88:91]
	v_mfma_f32_16x16x32_bf16 v[92:95], v[140:143], v[210:213], v[92:95]
	v_mfma_f32_16x16x32_bf16 v[72:75], v[132:135], v[218:221], v[72:75]
	v_mfma_f32_16x16x32_bf16 v[76:79], v[140:143], v[218:221], v[76:79]
	s_setprio 0
	s_setprio 1
	v_mfma_f32_16x16x32_bf16 v[116:119], v[144:147], v[186:189], v[116:119]
	v_mfma_f32_16x16x32_bf16 v[112:115], v[152:155], v[186:189], v[112:115]
	v_mfma_f32_16x16x32_bf16 v[100:103], v[144:147], v[194:197], v[100:103]
	v_mfma_f32_16x16x32_bf16 v[96:99], v[152:155], v[194:197], v[96:99]
	v_mfma_f32_16x16x32_bf16 v[84:87], v[144:147], v[206:209], v[84:87]
	v_mfma_f32_16x16x32_bf16 v[80:83], v[152:155], v[206:209], v[80:83]
	v_mfma_f32_16x16x32_bf16 v[68:71], v[144:147], v[214:217], v[68:71]
	v_mfma_f32_16x16x32_bf16 v[64:67], v[152:155], v[214:217], v[64:67]
	v_mfma_f32_16x16x32_bf16 v[116:119], v[148:151], v[190:193], v[116:119]
	v_mfma_f32_16x16x32_bf16 v[112:115], v[156:159], v[190:193], v[112:115]
	v_mfma_f32_16x16x32_bf16 v[100:103], v[148:151], v[198:201], v[100:103]
	v_mfma_f32_16x16x32_bf16 v[96:99], v[156:159], v[198:201], v[96:99]
	v_mfma_f32_16x16x32_bf16 v[84:87], v[148:151], v[210:213], v[84:87]
	v_mfma_f32_16x16x32_bf16 v[80:83], v[156:159], v[210:213], v[80:83]
	v_mfma_f32_16x16x32_bf16 v[68:71], v[148:151], v[218:221], v[68:71]
	v_mfma_f32_16x16x32_bf16 v[64:67], v[156:159], v[218:221], v[64:67]
	s_barrier
	s_setprio 0
	s_add_i32 s14, s15, s65
	v_lshl_add_u64 v[178:179], s[40:41], 0, v[168:169]
	s_mov_b32 m0, s14
	ds_read_b128 v[186:189], v185 offset:16384
	ds_read_b128 v[190:193], v185 offset:17408
	ds_read_b128 v[194:197], v185 offset:18432
	ds_read_b128 v[198:201], v185 offset:19456
	ds_read_b128 v[206:209], v185 offset:20480
	ds_read_b128 v[210:213], v185 offset:21504
	ds_read_b128 v[214:217], v185 offset:22528
	ds_read_b128 v[218:221], v185 offset:23552
	global_load_lds_dwordx4 v[178:179], off
	s_add_i32 m0, s14, 0x2000
	s_add_u32 s14, s40, 0x40000
	v_lshl_add_u64 v[222:223], s[40:41], 0, v[164:165]
	s_addc_u32 s15, s41, 0
	s_add_i32 s13, s13, s65
	global_load_lds_dwordx4 v[222:223], off
	v_lshl_add_u64 v[224:225], s[14:15], 0, v[168:169]
	s_mov_b32 m0, s13
	v_lshl_add_u64 v[226:227], s[42:43], 0, v[166:167]
	global_load_lds_dwordx4 v[224:225], off
	v_lshl_add_u64 v[224:225], s[14:15], 0, v[164:165]
	s_add_i32 m0, s13, 0x2000
	s_nop 0
	global_load_lds_dwordx4 v[224:225], off
	v_lshl_add_u64 v[224:225], s[42:43], 0, v[170:171]
	s_mov_b32 m0, s66
	s_nop 0
	global_load_lds_dwordx4 v[224:225], off
	s_mov_b32 m0, s67
	s_nop 0
	global_load_lds_dwordx4 v[226:227], off
	s_waitcnt vmcnt(8)
	s_waitcnt lgkmcnt(0)
	s_setprio 1
	s_barrier
	v_mfma_f32_16x16x32_bf16 v[56:59], v[128:131], v[186:189], v[56:59]
	v_mfma_f32_16x16x32_bf16 v[60:63], v[136:139], v[186:189], v[60:63]
	v_mfma_f32_16x16x32_bf16 v[40:43], v[128:131], v[194:197], v[40:43]
	v_mfma_f32_16x16x32_bf16 v[44:47], v[136:139], v[194:197], v[44:47]
	v_mfma_f32_16x16x32_bf16 v[24:27], v[128:131], v[206:209], v[24:27]
	v_mfma_f32_16x16x32_bf16 v[28:31], v[136:139], v[206:209], v[28:31]
	v_mfma_f32_16x16x32_bf16 v[8:11], v[128:131], v[214:217], v[8:11]
	v_mfma_f32_16x16x32_bf16 v[12:15], v[136:139], v[214:217], v[12:15]
	v_mfma_f32_16x16x32_bf16 v[56:59], v[132:135], v[190:193], v[56:59]
	v_mfma_f32_16x16x32_bf16 v[60:63], v[140:143], v[190:193], v[60:63]
	v_mfma_f32_16x16x32_bf16 v[40:43], v[132:135], v[198:201], v[40:43]
	v_mfma_f32_16x16x32_bf16 v[44:47], v[140:143], v[198:201], v[44:47]
	v_mfma_f32_16x16x32_bf16 v[24:27], v[132:135], v[210:213], v[24:27]
	v_mfma_f32_16x16x32_bf16 v[28:31], v[140:143], v[210:213], v[28:31]
	v_mfma_f32_16x16x32_bf16 v[8:11], v[132:135], v[218:221], v[8:11]
	v_mfma_f32_16x16x32_bf16 v[12:15], v[140:143], v[218:221], v[12:15]
	s_setprio 0
	s_setprio 1
	v_mfma_f32_16x16x32_bf16 v[52:55], v[144:147], v[186:189], v[52:55]
	v_mfma_f32_16x16x32_bf16 v[48:51], v[152:155], v[186:189], v[48:51]
	v_mfma_f32_16x16x32_bf16 v[36:39], v[144:147], v[194:197], v[36:39]
	v_mfma_f32_16x16x32_bf16 v[32:35], v[152:155], v[194:197], v[32:35]
	v_mfma_f32_16x16x32_bf16 v[20:23], v[144:147], v[206:209], v[20:23]
	v_mfma_f32_16x16x32_bf16 v[16:19], v[152:155], v[206:209], v[16:19]
	v_mfma_f32_16x16x32_bf16 v[4:7], v[144:147], v[214:217], v[4:7]
	v_mfma_f32_16x16x32_bf16 v[0:3], v[152:155], v[214:217], v[0:3]
	v_mfma_f32_16x16x32_bf16 v[52:55], v[148:151], v[190:193], v[52:55]
	v_mfma_f32_16x16x32_bf16 v[48:51], v[156:159], v[190:193], v[48:51]
	v_mfma_f32_16x16x32_bf16 v[36:39], v[148:151], v[198:201], v[36:39]
	v_mfma_f32_16x16x32_bf16 v[32:35], v[156:159], v[198:201], v[32:35]
	v_mfma_f32_16x16x32_bf16 v[20:23], v[148:151], v[210:213], v[20:23]
	v_mfma_f32_16x16x32_bf16 v[16:19], v[156:159], v[210:213], v[16:19]
	v_mfma_f32_16x16x32_bf16 v[4:7], v[148:151], v[218:221], v[4:7]
	v_mfma_f32_16x16x32_bf16 v[0:3], v[156:159], v[218:221], v[0:3]
	s_barrier
	s_setprio 0
	s_add_i32 s13, 0, 0x18000
	s_add_i32 s16, 0, 0x1c000
	v_add_u32_e32 v140, s13, v181
	v_add_u32_e32 v156, s16, v181
	ds_read_b128 v[128:131], v140
	ds_read_b128 v[132:135], v140 offset:1024
	ds_read_b128 v[136:139], v140 offset:2048
	ds_read_b128 v[140:143], v140 offset:3072
	ds_read_b128 v[144:147], v156
	ds_read_b128 v[148:151], v156 offset:1024
	ds_read_b128 v[152:155], v156 offset:2048
	ds_read_b128 v[156:159], v156 offset:3072
	s_add_u32 s14, s42, 0x40000
	s_addc_u32 s15, s43, 0
	s_mov_b32 m0, s68
	v_lshl_add_u64 v[228:229], s[14:15], 0, v[170:171]
	ds_read_b128 v[186:189], v185 offset:32768
	ds_read_b128 v[190:193], v185 offset:33792
	ds_read_b128 v[194:197], v185 offset:34816
	ds_read_b128 v[198:201], v185 offset:35840
	ds_read_b128 v[206:209], v185 offset:36864
	ds_read_b128 v[210:213], v185 offset:37888
	ds_read_b128 v[214:217], v185 offset:38912
	ds_read_b128 v[218:221], v185 offset:39936
	global_load_lds_dwordx4 v[228:229], off
	v_lshl_add_u64 v[228:229], s[14:15], 0, v[166:167]
	s_mov_b32 m0, s69
	s_nop 0
	global_load_lds_dwordx4 v[228:229], off
	s_waitcnt vmcnt(8)
	s_waitcnt lgkmcnt(0)
	s_setprio 1
	s_barrier
	v_mfma_f32_16x16x32_bf16 v[120:123], v[128:131], v[186:189], v[120:123]
	v_mfma_f32_16x16x32_bf16 v[124:127], v[136:139], v[186:189], v[124:127]
	v_mfma_f32_16x16x32_bf16 v[104:107], v[128:131], v[194:197], v[104:107]
	v_mfma_f32_16x16x32_bf16 v[108:111], v[136:139], v[194:197], v[108:111]
	v_mfma_f32_16x16x32_bf16 v[88:91], v[128:131], v[206:209], v[88:91]
	v_mfma_f32_16x16x32_bf16 v[92:95], v[136:139], v[206:209], v[92:95]
	v_mfma_f32_16x16x32_bf16 v[72:75], v[128:131], v[214:217], v[72:75]
	v_mfma_f32_16x16x32_bf16 v[76:79], v[136:139], v[214:217], v[76:79]
	v_mfma_f32_16x16x32_bf16 v[120:123], v[132:135], v[190:193], v[120:123]
	v_mfma_f32_16x16x32_bf16 v[124:127], v[140:143], v[190:193], v[124:127]
	v_mfma_f32_16x16x32_bf16 v[104:107], v[132:135], v[198:201], v[104:107]
	v_mfma_f32_16x16x32_bf16 v[108:111], v[140:143], v[198:201], v[108:111]
	v_mfma_f32_16x16x32_bf16 v[88:91], v[132:135], v[210:213], v[88:91]
	v_mfma_f32_16x16x32_bf16 v[92:95], v[140:143], v[210:213], v[92:95]
	v_mfma_f32_16x16x32_bf16 v[72:75], v[132:135], v[218:221], v[72:75]
	v_mfma_f32_16x16x32_bf16 v[76:79], v[140:143], v[218:221], v[76:79]
	s_setprio 0
	s_setprio 1
	v_mfma_f32_16x16x32_bf16 v[116:119], v[144:147], v[186:189], v[116:119]
	v_mfma_f32_16x16x32_bf16 v[112:115], v[152:155], v[186:189], v[112:115]
	v_mfma_f32_16x16x32_bf16 v[100:103], v[144:147], v[194:197], v[100:103]
	v_mfma_f32_16x16x32_bf16 v[96:99], v[152:155], v[194:197], v[96:99]
	v_mfma_f32_16x16x32_bf16 v[84:87], v[144:147], v[206:209], v[84:87]
	v_mfma_f32_16x16x32_bf16 v[80:83], v[152:155], v[206:209], v[80:83]
	v_mfma_f32_16x16x32_bf16 v[68:71], v[144:147], v[214:217], v[68:71]
	v_mfma_f32_16x16x32_bf16 v[64:67], v[152:155], v[214:217], v[64:67]
	v_mfma_f32_16x16x32_bf16 v[116:119], v[148:151], v[190:193], v[116:119]
	v_mfma_f32_16x16x32_bf16 v[112:115], v[156:159], v[190:193], v[112:115]
	v_mfma_f32_16x16x32_bf16 v[100:103], v[148:151], v[198:201], v[100:103]
	v_mfma_f32_16x16x32_bf16 v[96:99], v[156:159], v[198:201], v[96:99]
	v_mfma_f32_16x16x32_bf16 v[84:87], v[148:151], v[210:213], v[84:87]
	v_mfma_f32_16x16x32_bf16 v[80:83], v[156:159], v[210:213], v[80:83]
	v_mfma_f32_16x16x32_bf16 v[68:71], v[148:151], v[218:221], v[68:71]
	v_mfma_f32_16x16x32_bf16 v[64:67], v[156:159], v[218:221], v[64:67]
	s_barrier
	s_setprio 0
	s_add_i32 s13, s13, s65
	v_lshl_add_u64 v[178:179], v[178:179], 0, s[76:77]
	s_mov_b32 m0, s13
	ds_read_b128 v[186:189], v185 offset:49152
	ds_read_b128 v[190:193], v185 offset:50176
	ds_read_b128 v[194:197], v185 offset:51200
	ds_read_b128 v[198:201], v185 offset:52224
	ds_read_b128 v[206:209], v185 offset:53248
	ds_read_b128 v[210:213], v185 offset:54272
	ds_read_b128 v[214:217], v185 offset:55296
	ds_read_b128 v[218:221], v185 offset:56320
	global_load_lds_dwordx4 v[178:179], off
	s_add_i32 m0, s13, 0x2000
	s_add_u32 s14, s40, 0x40080
	v_lshl_add_u64 v[178:179], v[222:223], 0, s[76:77]
	s_addc_u32 s15, s41, 0
	s_add_i32 s13, s16, s65
	global_load_lds_dwordx4 v[178:179], off
	v_lshl_add_u64 v[178:179], s[14:15], 0, v[168:169]
	s_mov_b32 m0, s13
	s_nop 0
	global_load_lds_dwordx4 v[178:179], off
	v_lshl_add_u64 v[178:179], s[14:15], 0, v[164:165]
	s_add_i32 m0, s13, 0x2000
	s_nop 0
	global_load_lds_dwordx4 v[178:179], off
	v_lshl_add_u64 v[178:179], v[224:225], 0, s[76:77]
	s_mov_b32 m0, s79
	s_nop 0
	global_load_lds_dwordx4 v[178:179], off
	v_lshl_add_u64 v[178:179], v[226:227], 0, s[76:77]
	s_mov_b32 m0, s46
	s_nop 0
	global_load_lds_dwordx4 v[178:179], off
	s_waitcnt vmcnt(8)
	s_waitcnt lgkmcnt(0)
	s_setprio 1
	s_barrier
	v_mfma_f32_16x16x32_bf16 v[56:59], v[128:131], v[186:189], v[56:59]
	v_mfma_f32_16x16x32_bf16 v[60:63], v[136:139], v[186:189], v[60:63]
	v_mfma_f32_16x16x32_bf16 v[40:43], v[128:131], v[194:197], v[40:43]
	v_mfma_f32_16x16x32_bf16 v[44:47], v[136:139], v[194:197], v[44:47]
	v_mfma_f32_16x16x32_bf16 v[24:27], v[128:131], v[206:209], v[24:27]
	v_mfma_f32_16x16x32_bf16 v[28:31], v[136:139], v[206:209], v[28:31]
	v_mfma_f32_16x16x32_bf16 v[8:11], v[128:131], v[214:217], v[8:11]
	v_mfma_f32_16x16x32_bf16 v[12:15], v[136:139], v[214:217], v[12:15]
	v_mfma_f32_16x16x32_bf16 v[56:59], v[132:135], v[190:193], v[56:59]
	v_mfma_f32_16x16x32_bf16 v[60:63], v[140:143], v[190:193], v[60:63]
	v_mfma_f32_16x16x32_bf16 v[40:43], v[132:135], v[198:201], v[40:43]
	v_mfma_f32_16x16x32_bf16 v[44:47], v[140:143], v[198:201], v[44:47]
	v_mfma_f32_16x16x32_bf16 v[24:27], v[132:135], v[210:213], v[24:27]
	v_mfma_f32_16x16x32_bf16 v[28:31], v[140:143], v[210:213], v[28:31]
	v_mfma_f32_16x16x32_bf16 v[8:11], v[132:135], v[218:221], v[8:11]
	v_mfma_f32_16x16x32_bf16 v[12:15], v[140:143], v[218:221], v[12:15]
	s_setprio 0
	s_setprio 1
	v_mfma_f32_16x16x32_bf16 v[52:55], v[144:147], v[186:189], v[52:55]
	v_mfma_f32_16x16x32_bf16 v[48:51], v[152:155], v[186:189], v[48:51]
	v_mfma_f32_16x16x32_bf16 v[36:39], v[144:147], v[194:197], v[36:39]
	v_mfma_f32_16x16x32_bf16 v[32:35], v[152:155], v[194:197], v[32:35]
	v_mfma_f32_16x16x32_bf16 v[20:23], v[144:147], v[206:209], v[20:23]
	v_mfma_f32_16x16x32_bf16 v[16:19], v[152:155], v[206:209], v[16:19]
	v_mfma_f32_16x16x32_bf16 v[4:7], v[144:147], v[214:217], v[4:7]
	v_mfma_f32_16x16x32_bf16 v[0:3], v[152:155], v[214:217], v[0:3]
	v_mfma_f32_16x16x32_bf16 v[52:55], v[148:151], v[190:193], v[52:55]
	v_mfma_f32_16x16x32_bf16 v[48:51], v[156:159], v[190:193], v[48:51]
	v_mfma_f32_16x16x32_bf16 v[36:39], v[148:151], v[198:201], v[36:39]
	v_mfma_f32_16x16x32_bf16 v[32:35], v[156:159], v[198:201], v[32:35]
	v_mfma_f32_16x16x32_bf16 v[20:23], v[148:151], v[210:213], v[20:23]
	v_mfma_f32_16x16x32_bf16 v[16:19], v[156:159], v[210:213], v[16:19]
	v_mfma_f32_16x16x32_bf16 v[4:7], v[148:151], v[218:221], v[4:7]
	v_mfma_f32_16x16x32_bf16 v[0:3], v[156:159], v[218:221], v[0:3]
	s_barrier
	s_setprio 0
	s_add_i32 s12, s12, 2
	s_add_u32 s38, s38, 0x100
	s_addc_u32 s39, s39, 0
	s_add_u32 s10, s10, 0x100
	s_addc_u32 s11, s11, 0
	s_cmp_gt_u32 s12, 13
	s_cbranch_scc0 .LBB0_650

.LBB0_698:
	s_ashr_i32 s39, s38, 31
	s_lshl_b64 s[16:17], s[38:39], 19
	s_add_u32 s42, s4, s16
	s_addc_u32 s43, s5, s17
	s_and_b64 s[16:17], s[48:49], exec
	s_cselect_b32 s16, s43, s63
	s_cselect_b32 s17, s42, s62
	s_ashr_i32 s41, s40, 31
	s_lshl_b64 s[18:19], s[40:41], 19
	s_add_u32 s58, s96, s18
	s_addc_u32 s59, s97, s19
	s_and_b64 s[18:19], s[48:49], exec
	s_cselect_b32 s39, s59, s67
	s_cselect_b32 s41, s58, s66
	s_add_u32 s62, s62, 0x40080
	s_addc_u32 s63, s63, 0
	s_add_u32 s47, s66, 0x100
	s_addc_u32 s54, s67, 0
	s_mov_b32 s61, -2
	s_add_u32 s18, s62, 0xfffc0080
	s_addc_u32 s19, s63, -1
	s_add_i32 s20, 0, 0x10000
	s_cmp_eq_u32 s61, 12
	s_cselect_b32 s65, s16, s19
	s_cselect_b32 s64, s17, s18
	s_cselect_b32 s51, s39, s54
	s_cselect_b32 s50, s41, s47
	s_add_i32 s21, 0, 0x14000
	v_add_u32_e32 v156, s20, v141
	v_add_u32_e32 v162, s21, v141
	ds_read_b128 v[144:147], v156
	ds_read_b128 v[148:151], v156 offset:1024
	ds_read_b128 v[152:155], v156 offset:2048
	ds_read_b128 v[156:159], v156 offset:3072
	ds_read_b128 v[164:167], v162
	ds_read_b128 v[168:171], v162 offset:1024
	ds_read_b128 v[172:175], v162 offset:2048
	ds_read_b128 v[176:179], v162 offset:3072
	v_lshl_add_u64 v[200:201], s[62:63], 0, v[136:137]
	s_add_i32 m0, s8, 0xc000
	ds_read_b128 v[180:183], v143
	ds_read_b128 v[184:187], v143 offset:1024
	ds_read_b128 v[188:191], v143 offset:2048
	ds_read_b128 v[192:195], v143 offset:3072
	ds_read_b128 v[196:199], v143 offset:4096
	ds_read_b128 v[206:209], v143 offset:5120
	ds_read_b128 v[210:213], v143 offset:6144
	ds_read_b128 v[214:217], v143 offset:7168
	global_load_lds_dwordx4 v[200:201], off
	v_lshl_add_u64 v[200:201], s[62:63], 0, v[138:139]
	s_add_i32 m0, s8, 0xe000
	s_nop 0
	global_load_lds_dwordx4 v[200:201], off
	s_waitcnt vmcnt(8)
	s_waitcnt lgkmcnt(0)
	s_setprio 1
	s_barrier
	v_mfma_f32_16x16x32_bf16 v[124:127], v[144:147], v[180:183], 0
	v_mfma_f32_16x16x32_bf16 v[120:123], v[152:155], v[180:183], 0
	v_mfma_f32_16x16x32_bf16 v[116:119], v[144:147], v[188:191], 0
	v_mfma_f32_16x16x32_bf16 v[108:111], v[152:155], v[188:191], 0
	v_mfma_f32_16x16x32_bf16 v[100:103], v[144:147], v[196:199], 0
	v_mfma_f32_16x16x32_bf16 v[92:95], v[152:155], v[196:199], 0
	v_mfma_f32_16x16x32_bf16 v[84:87], v[144:147], v[210:213], 0
	v_mfma_f32_16x16x32_bf16 v[76:79], v[152:155], v[210:213], 0
	v_mfma_f32_16x16x32_bf16 v[124:127], v[148:151], v[184:187], v[124:127]
	v_mfma_f32_16x16x32_bf16 v[120:123], v[156:159], v[184:187], v[120:123]
	v_mfma_f32_16x16x32_bf16 v[116:119], v[148:151], v[192:195], v[116:119]
	v_mfma_f32_16x16x32_bf16 v[108:111], v[156:159], v[192:195], v[108:111]
	v_mfma_f32_16x16x32_bf16 v[100:103], v[148:151], v[206:209], v[100:103]
	v_mfma_f32_16x16x32_bf16 v[92:95], v[156:159], v[206:209], v[92:95]
	v_mfma_f32_16x16x32_bf16 v[84:87], v[148:151], v[214:217], v[84:87]
	v_mfma_f32_16x16x32_bf16 v[76:79], v[156:159], v[214:217], v[76:79]
	s_setprio 0
	s_setprio 1
	v_mfma_f32_16x16x32_bf16 v[112:115], v[164:167], v[180:183], 0
	v_mfma_f32_16x16x32_bf16 v[104:107], v[172:175], v[180:183], 0
	v_mfma_f32_16x16x32_bf16 v[96:99], v[164:167], v[188:191], 0
	v_mfma_f32_16x16x32_bf16 v[88:91], v[172:175], v[188:191], 0
	v_mfma_f32_16x16x32_bf16 v[80:83], v[164:167], v[196:199], 0
	v_mfma_f32_16x16x32_bf16 v[72:75], v[172:175], v[196:199], 0
	v_mfma_f32_16x16x32_bf16 v[68:71], v[164:167], v[210:213], 0
	v_mfma_f32_16x16x32_bf16 v[64:67], v[172:175], v[210:213], 0
	v_mfma_f32_16x16x32_bf16 v[112:115], v[168:171], v[184:187], v[112:115]
	v_mfma_f32_16x16x32_bf16 v[104:107], v[176:179], v[184:187], v[104:107]
	v_mfma_f32_16x16x32_bf16 v[96:99], v[168:171], v[192:195], v[96:99]
	v_mfma_f32_16x16x32_bf16 v[88:91], v[176:179], v[192:195], v[88:91]
	v_mfma_f32_16x16x32_bf16 v[80:83], v[168:171], v[206:209], v[80:83]
	v_mfma_f32_16x16x32_bf16 v[72:75], v[176:179], v[206:209], v[72:75]
	v_mfma_f32_16x16x32_bf16 v[68:71], v[168:171], v[214:217], v[68:71]
	v_mfma_f32_16x16x32_bf16 v[64:67], v[176:179], v[214:217], v[64:67]
	s_barrier
	s_setprio 0
	s_add_i32 s18, s20, s7
	v_lshl_add_u64 v[200:201], s[50:51], 0, v[132:133]
	s_mov_b32 m0, s18
	ds_read_b128 v[180:183], v143 offset:16384
	ds_read_b128 v[184:187], v143 offset:17408
	ds_read_b128 v[188:191], v143 offset:18432
	ds_read_b128 v[192:195], v143 offset:19456
	ds_read_b128 v[196:199], v143 offset:20480
	ds_read_b128 v[206:209], v143 offset:21504
	ds_read_b128 v[210:213], v143 offset:22528
	ds_read_b128 v[214:217], v143 offset:23552
	global_load_lds_dwordx4 v[200:201], off
	s_add_i32 m0, s18, 0x2000
	s_add_u32 s18, s50, 0x40000
	v_lshl_add_u64 v[218:219], s[50:51], 0, v[128:129]
	s_addc_u32 s19, s51, 0
	s_add_i32 s20, s21, s7
	global_load_lds_dwordx4 v[218:219], off
	v_lshl_add_u64 v[220:221], s[18:19], 0, v[132:133]
	s_mov_b32 m0, s20
	v_lshl_add_u64 v[222:223], s[64:65], 0, v[130:131]
	global_load_lds_dwordx4 v[220:221], off
	v_lshl_add_u64 v[220:221], s[18:19], 0, v[128:129]
	s_add_i32 m0, s20, 0x2000
	s_nop 0
	global_load_lds_dwordx4 v[220:221], off
	v_lshl_add_u64 v[220:221], s[64:65], 0, v[134:135]
	s_mov_b32 m0, s8
	s_nop 0
	global_load_lds_dwordx4 v[220:221], off
	s_mov_b32 m0, s9
	s_nop 0
	global_load_lds_dwordx4 v[222:223], off
	s_waitcnt vmcnt(8)
	s_waitcnt lgkmcnt(0)
	s_setprio 1
	s_barrier
	v_mfma_f32_16x16x32_bf16 v[60:63], v[144:147], v[180:183], 0
	v_mfma_f32_16x16x32_bf16 v[56:59], v[152:155], v[180:183], 0
	v_mfma_f32_16x16x32_bf16 v[52:55], v[144:147], v[188:191], 0
	v_mfma_f32_16x16x32_bf16 v[44:47], v[152:155], v[188:191], 0
	v_mfma_f32_16x16x32_bf16 v[36:39], v[144:147], v[196:199], 0
	v_mfma_f32_16x16x32_bf16 v[28:31], v[152:155], v[196:199], 0
	v_mfma_f32_16x16x32_bf16 v[20:23], v[144:147], v[210:213], 0
	v_mfma_f32_16x16x32_bf16 v[12:15], v[152:155], v[210:213], 0
	v_mfma_f32_16x16x32_bf16 v[60:63], v[148:151], v[184:187], v[60:63]
	v_mfma_f32_16x16x32_bf16 v[56:59], v[156:159], v[184:187], v[56:59]
	v_mfma_f32_16x16x32_bf16 v[52:55], v[148:151], v[192:195], v[52:55]
	v_mfma_f32_16x16x32_bf16 v[44:47], v[156:159], v[192:195], v[44:47]
	v_mfma_f32_16x16x32_bf16 v[36:39], v[148:151], v[206:209], v[36:39]
	v_mfma_f32_16x16x32_bf16 v[28:31], v[156:159], v[206:209], v[28:31]
	v_mfma_f32_16x16x32_bf16 v[20:23], v[148:151], v[214:217], v[20:23]
	v_mfma_f32_16x16x32_bf16 v[12:15], v[156:159], v[214:217], v[12:15]
	s_setprio 0
	s_setprio 1
	v_mfma_f32_16x16x32_bf16 v[48:51], v[164:167], v[180:183], 0
	v_mfma_f32_16x16x32_bf16 v[40:43], v[172:175], v[180:183], 0
	v_mfma_f32_16x16x32_bf16 v[32:35], v[164:167], v[188:191], 0
	v_mfma_f32_16x16x32_bf16 v[24:27], v[172:175], v[188:191], 0
	v_mfma_f32_16x16x32_bf16 v[16:19], v[164:167], v[196:199], 0
	v_mfma_f32_16x16x32_bf16 v[8:11], v[172:175], v[196:199], 0
	v_mfma_f32_16x16x32_bf16 v[4:7], v[164:167], v[210:213], 0
	v_mfma_f32_16x16x32_bf16 v[0:3], v[172:175], v[210:213], 0
	v_mfma_f32_16x16x32_bf16 v[48:51], v[168:171], v[184:187], v[48:51]
	v_mfma_f32_16x16x32_bf16 v[40:43], v[176:179], v[184:187], v[40:43]
	v_mfma_f32_16x16x32_bf16 v[32:35], v[168:171], v[192:195], v[32:35]
	v_mfma_f32_16x16x32_bf16 v[24:27], v[176:179], v[192:195], v[24:27]
	v_mfma_f32_16x16x32_bf16 v[16:19], v[168:171], v[206:209], v[16:19]
	v_mfma_f32_16x16x32_bf16 v[8:11], v[176:179], v[206:209], v[8:11]
	v_mfma_f32_16x16x32_bf16 v[4:7], v[168:171], v[214:217], v[4:7]
	v_mfma_f32_16x16x32_bf16 v[0:3], v[176:179], v[214:217], v[0:3]
	s_barrier
	s_setprio 0
	s_add_i32 s20, 0, 0x18000
	s_add_i32 s21, 0, 0x1c000
	v_add_u32_e32 v156, s20, v141
	v_add_u32_e32 v162, s21, v141
	ds_read_b128 v[144:147], v156
	ds_read_b128 v[148:151], v156 offset:1024
	ds_read_b128 v[152:155], v156 offset:2048
	ds_read_b128 v[156:159], v156 offset:3072
	ds_read_b128 v[164:167], v162
	ds_read_b128 v[168:171], v162 offset:1024
	ds_read_b128 v[172:175], v162 offset:2048
	ds_read_b128 v[176:179], v162 offset:3072
	s_add_u32 s18, s64, 0x40000
	s_addc_u32 s19, s65, 0
	s_mov_b32 m0, s10
	v_lshl_add_u64 v[224:225], s[18:19], 0, v[134:135]
	ds_read_b128 v[180:183], v143 offset:32768
	ds_read_b128 v[184:187], v143 offset:33792
	ds_read_b128 v[188:191], v143 offset:34816
	ds_read_b128 v[192:195], v143 offset:35840
	ds_read_b128 v[196:199], v143 offset:36864
	ds_read_b128 v[206:209], v143 offset:37888
	ds_read_b128 v[210:213], v143 offset:38912
	ds_read_b128 v[214:217], v143 offset:39936
	global_load_lds_dwordx4 v[224:225], off
	v_lshl_add_u64 v[224:225], s[18:19], 0, v[130:131]
	s_mov_b32 m0, s11
	s_nop 0
	global_load_lds_dwordx4 v[224:225], off
	s_waitcnt vmcnt(8)
	s_waitcnt lgkmcnt(0)
	s_setprio 1
	s_barrier
	v_mfma_f32_16x16x32_bf16 v[124:127], v[144:147], v[180:183], v[124:127]
	v_mfma_f32_16x16x32_bf16 v[120:123], v[152:155], v[180:183], v[120:123]
	v_mfma_f32_16x16x32_bf16 v[116:119], v[144:147], v[188:191], v[116:119]
	v_mfma_f32_16x16x32_bf16 v[108:111], v[152:155], v[188:191], v[108:111]
	v_mfma_f32_16x16x32_bf16 v[100:103], v[144:147], v[196:199], v[100:103]
	v_mfma_f32_16x16x32_bf16 v[92:95], v[152:155], v[196:199], v[92:95]
	v_mfma_f32_16x16x32_bf16 v[84:87], v[144:147], v[210:213], v[84:87]
	v_mfma_f32_16x16x32_bf16 v[76:79], v[152:155], v[210:213], v[76:79]
	v_mfma_f32_16x16x32_bf16 v[124:127], v[148:151], v[184:187], v[124:127]
	v_mfma_f32_16x16x32_bf16 v[120:123], v[156:159], v[184:187], v[120:123]
	v_mfma_f32_16x16x32_bf16 v[116:119], v[148:151], v[192:195], v[116:119]
	v_mfma_f32_16x16x32_bf16 v[108:111], v[156:159], v[192:195], v[108:111]
	v_mfma_f32_16x16x32_bf16 v[100:103], v[148:151], v[206:209], v[100:103]
	v_mfma_f32_16x16x32_bf16 v[92:95], v[156:159], v[206:209], v[92:95]
	v_mfma_f32_16x16x32_bf16 v[84:87], v[148:151], v[214:217], v[84:87]
	v_mfma_f32_16x16x32_bf16 v[76:79], v[156:159], v[214:217], v[76:79]
	s_setprio 0
	s_setprio 1
	v_mfma_f32_16x16x32_bf16 v[112:115], v[164:167], v[180:183], v[112:115]
	v_mfma_f32_16x16x32_bf16 v[104:107], v[172:175], v[180:183], v[104:107]
	v_mfma_f32_16x16x32_bf16 v[96:99], v[164:167], v[188:191], v[96:99]
	v_mfma_f32_16x16x32_bf16 v[88:91], v[172:175], v[188:191], v[88:91]
	v_mfma_f32_16x16x32_bf16 v[80:83], v[164:167], v[196:199], v[80:83]
	v_mfma_f32_16x16x32_bf16 v[72:75], v[172:175], v[196:199], v[72:75]
	v_mfma_f32_16x16x32_bf16 v[68:71], v[164:167], v[210:213], v[68:71]
	v_mfma_f32_16x16x32_bf16 v[64:67], v[172:175], v[210:213], v[64:67]
	v_mfma_f32_16x16x32_bf16 v[112:115], v[168:171], v[184:187], v[112:115]
	v_mfma_f32_16x16x32_bf16 v[104:107], v[176:179], v[184:187], v[104:107]
	v_mfma_f32_16x16x32_bf16 v[96:99], v[168:171], v[192:195], v[96:99]
	v_mfma_f32_16x16x32_bf16 v[88:91], v[176:179], v[192:195], v[88:91]
	v_mfma_f32_16x16x32_bf16 v[80:83], v[168:171], v[206:209], v[80:83]
	v_mfma_f32_16x16x32_bf16 v[72:75], v[176:179], v[206:209], v[72:75]
	v_mfma_f32_16x16x32_bf16 v[68:71], v[168:171], v[214:217], v[68:71]
	v_mfma_f32_16x16x32_bf16 v[64:67], v[176:179], v[214:217], v[64:67]
	s_barrier
	s_setprio 0
	s_add_i32 s18, s20, s7
	v_lshl_add_u64 v[200:201], v[200:201], 0, s[76:77]
	s_mov_b32 m0, s18
	ds_read_b128 v[180:183], v143 offset:49152
	ds_read_b128 v[184:187], v143 offset:50176
	ds_read_b128 v[188:191], v143 offset:51200
	ds_read_b128 v[192:195], v143 offset:52224
	ds_read_b128 v[196:199], v143 offset:53248
	ds_read_b128 v[206:209], v143 offset:54272
	ds_read_b128 v[210:213], v143 offset:55296
	ds_read_b128 v[214:217], v143 offset:56320
	global_load_lds_dwordx4 v[200:201], off
	s_add_i32 m0, s18, 0x2000
	s_add_u32 s18, s50, 0x40080
	v_lshl_add_u64 v[200:201], v[218:219], 0, s[76:77]
	s_addc_u32 s19, s51, 0
	s_add_i32 s20, s21, s7
	global_load_lds_dwordx4 v[200:201], off
	v_lshl_add_u64 v[200:201], s[18:19], 0, v[132:133]
	s_mov_b32 m0, s20
	s_nop 0
	global_load_lds_dwordx4 v[200:201], off
	v_lshl_add_u64 v[200:201], s[18:19], 0, v[128:129]
	s_add_i32 m0, s20, 0x2000
	s_nop 0
	global_load_lds_dwordx4 v[200:201], off
	v_lshl_add_u64 v[200:201], v[220:221], 0, s[76:77]
	s_mov_b32 m0, s13
	s_nop 0
	global_load_lds_dwordx4 v[200:201], off
	v_lshl_add_u64 v[200:201], v[222:223], 0, s[76:77]
	s_mov_b32 m0, s14
	s_nop 0
	global_load_lds_dwordx4 v[200:201], off
	s_waitcnt vmcnt(8)
	s_waitcnt lgkmcnt(0)
	s_setprio 1
	s_barrier
	v_mfma_f32_16x16x32_bf16 v[60:63], v[144:147], v[180:183], v[60:63]
	v_mfma_f32_16x16x32_bf16 v[56:59], v[152:155], v[180:183], v[56:59]
	v_mfma_f32_16x16x32_bf16 v[52:55], v[144:147], v[188:191], v[52:55]
	v_mfma_f32_16x16x32_bf16 v[44:47], v[152:155], v[188:191], v[44:47]
	v_mfma_f32_16x16x32_bf16 v[36:39], v[144:147], v[196:199], v[36:39]
	v_mfma_f32_16x16x32_bf16 v[28:31], v[152:155], v[196:199], v[28:31]
	v_mfma_f32_16x16x32_bf16 v[20:23], v[144:147], v[210:213], v[20:23]
	v_mfma_f32_16x16x32_bf16 v[12:15], v[152:155], v[210:213], v[12:15]
	v_mfma_f32_16x16x32_bf16 v[60:63], v[148:151], v[184:187], v[60:63]
	v_mfma_f32_16x16x32_bf16 v[56:59], v[156:159], v[184:187], v[56:59]
	v_mfma_f32_16x16x32_bf16 v[52:55], v[148:151], v[192:195], v[52:55]
	v_mfma_f32_16x16x32_bf16 v[44:47], v[156:159], v[192:195], v[44:47]
	v_mfma_f32_16x16x32_bf16 v[36:39], v[148:151], v[206:209], v[36:39]
	v_mfma_f32_16x16x32_bf16 v[28:31], v[156:159], v[206:209], v[28:31]
	v_mfma_f32_16x16x32_bf16 v[20:23], v[148:151], v[214:217], v[20:23]
	v_mfma_f32_16x16x32_bf16 v[12:15], v[156:159], v[214:217], v[12:15]
	s_setprio 0
	s_setprio 1
	v_mfma_f32_16x16x32_bf16 v[48:51], v[164:167], v[180:183], v[48:51]
	v_mfma_f32_16x16x32_bf16 v[40:43], v[172:175], v[180:183], v[40:43]
	v_mfma_f32_16x16x32_bf16 v[32:35], v[164:167], v[188:191], v[32:35]
	v_mfma_f32_16x16x32_bf16 v[24:27], v[172:175], v[188:191], v[24:27]
	v_mfma_f32_16x16x32_bf16 v[16:19], v[164:167], v[196:199], v[16:19]
	v_mfma_f32_16x16x32_bf16 v[8:11], v[172:175], v[196:199], v[8:11]
	v_mfma_f32_16x16x32_bf16 v[4:7], v[164:167], v[210:213], v[4:7]
	v_mfma_f32_16x16x32_bf16 v[0:3], v[172:175], v[210:213], v[0:3]
	v_mfma_f32_16x16x32_bf16 v[48:51], v[168:171], v[184:187], v[48:51]
	v_mfma_f32_16x16x32_bf16 v[40:43], v[176:179], v[184:187], v[40:43]
	v_mfma_f32_16x16x32_bf16 v[32:35], v[168:171], v[192:195], v[32:35]
	v_mfma_f32_16x16x32_bf16 v[24:27], v[176:179], v[192:195], v[24:27]
	v_mfma_f32_16x16x32_bf16 v[16:19], v[168:171], v[206:209], v[16:19]
	v_mfma_f32_16x16x32_bf16 v[8:11], v[176:179], v[206:209], v[8:11]
	v_mfma_f32_16x16x32_bf16 v[4:7], v[168:171], v[214:217], v[4:7]
	v_mfma_f32_16x16x32_bf16 v[0:3], v[176:179], v[214:217], v[0:3]
	s_barrier
	s_setprio 0
	s_add_i32 s61, s61, 2
	s_add_u32 s62, s62, 0x100
	s_addc_u32 s63, s63, 0
	s_add_u32 s47, s47, 0x100
	s_addc_u32 s54, s54, 0
	s_cmp_gt_u32 s61, 13
	s_cbranch_scc0 .LBB0_699
	s_branch .Lpeel_x_699
.LBB0_699:
	s_add_u32 s18, s62, 0xfffc0080
	s_addc_u32 s19, s63, -1
	s_add_i32 s20, 0, 0x10000
	s_cmp_eq_u32 s61, 12
	s_cselect_b32 s65, s16, s19
	s_cselect_b32 s64, s17, s18
	s_cselect_b32 s51, s39, s54
	s_cselect_b32 s50, s41, s47
	s_add_i32 s21, 0, 0x14000
	v_add_u32_e32 v156, s20, v141
	v_add_u32_e32 v162, s21, v141
	ds_read_b128 v[144:147], v156
	ds_read_b128 v[148:151], v156 offset:1024
	ds_read_b128 v[152:155], v156 offset:2048
	ds_read_b128 v[156:159], v156 offset:3072
	ds_read_b128 v[164:167], v162
	ds_read_b128 v[168:171], v162 offset:1024
	ds_read_b128 v[172:175], v162 offset:2048
	ds_read_b128 v[176:179], v162 offset:3072
	v_lshl_add_u64 v[200:201], s[62:63], 0, v[136:137]
	s_add_i32 m0, s8, 0xc000
	ds_read_b128 v[180:183], v143
	ds_read_b128 v[184:187], v143 offset:1024
	ds_read_b128 v[188:191], v143 offset:2048
	ds_read_b128 v[192:195], v143 offset:3072
	ds_read_b128 v[196:199], v143 offset:4096
	ds_read_b128 v[206:209], v143 offset:5120
	ds_read_b128 v[210:213], v143 offset:6144
	ds_read_b128 v[214:217], v143 offset:7168
	global_load_lds_dwordx4 v[200:201], off
	v_lshl_add_u64 v[200:201], s[62:63], 0, v[138:139]
	s_add_i32 m0, s8, 0xe000
	s_nop 0
	global_load_lds_dwordx4 v[200:201], off
	s_waitcnt vmcnt(8)
	s_waitcnt lgkmcnt(0)
	s_setprio 1
	s_barrier
	v_mfma_f32_16x16x32_bf16 v[124:127], v[144:147], v[180:183], v[124:127]
	v_mfma_f32_16x16x32_bf16 v[120:123], v[152:155], v[180:183], v[120:123]
	v_mfma_f32_16x16x32_bf16 v[116:119], v[144:147], v[188:191], v[116:119]
	v_mfma_f32_16x16x32_bf16 v[108:111], v[152:155], v[188:191], v[108:111]
	v_mfma_f32_16x16x32_bf16 v[100:103], v[144:147], v[196:199], v[100:103]
	v_mfma_f32_16x16x32_bf16 v[92:95], v[152:155], v[196:199], v[92:95]
	v_mfma_f32_16x16x32_bf16 v[84:87], v[144:147], v[210:213], v[84:87]
	v_mfma_f32_16x16x32_bf16 v[76:79], v[152:155], v[210:213], v[76:79]
	v_mfma_f32_16x16x32_bf16 v[124:127], v[148:151], v[184:187], v[124:127]
	v_mfma_f32_16x16x32_bf16 v[120:123], v[156:159], v[184:187], v[120:123]
	v_mfma_f32_16x16x32_bf16 v[116:119], v[148:151], v[192:195], v[116:119]
	v_mfma_f32_16x16x32_bf16 v[108:111], v[156:159], v[192:195], v[108:111]
	v_mfma_f32_16x16x32_bf16 v[100:103], v[148:151], v[206:209], v[100:103]
	v_mfma_f32_16x16x32_bf16 v[92:95], v[156:159], v[206:209], v[92:95]
	v_mfma_f32_16x16x32_bf16 v[84:87], v[148:151], v[214:217], v[84:87]
	v_mfma_f32_16x16x32_bf16 v[76:79], v[156:159], v[214:217], v[76:79]
	s_setprio 0
	s_setprio 1
	v_mfma_f32_16x16x32_bf16 v[112:115], v[164:167], v[180:183], v[112:115]
	v_mfma_f32_16x16x32_bf16 v[104:107], v[172:175], v[180:183], v[104:107]
	v_mfma_f32_16x16x32_bf16 v[96:99], v[164:167], v[188:191], v[96:99]
	v_mfma_f32_16x16x32_bf16 v[88:91], v[172:175], v[188:191], v[88:91]
	v_mfma_f32_16x16x32_bf16 v[80:83], v[164:167], v[196:199], v[80:83]
	v_mfma_f32_16x16x32_bf16 v[72:75], v[172:175], v[196:199], v[72:75]
	v_mfma_f32_16x16x32_bf16 v[68:71], v[164:167], v[210:213], v[68:71]
	v_mfma_f32_16x16x32_bf16 v[64:67], v[172:175], v[210:213], v[64:67]
	v_mfma_f32_16x16x32_bf16 v[112:115], v[168:171], v[184:187], v[112:115]
	v_mfma_f32_16x16x32_bf16 v[104:107], v[176:179], v[184:187], v[104:107]
	v_mfma_f32_16x16x32_bf16 v[96:99], v[168:171], v[192:195], v[96:99]
	v_mfma_f32_16x16x32_bf16 v[88:91], v[176:179], v[192:195], v[88:91]
	v_mfma_f32_16x16x32_bf16 v[80:83], v[168:171], v[206:209], v[80:83]
	v_mfma_f32_16x16x32_bf16 v[72:75], v[176:179], v[206:209], v[72:75]
	v_mfma_f32_16x16x32_bf16 v[68:71], v[168:171], v[214:217], v[68:71]
	v_mfma_f32_16x16x32_bf16 v[64:67], v[176:179], v[214:217], v[64:67]
	s_barrier
	s_setprio 0
	s_add_i32 s18, s20, s7
	v_lshl_add_u64 v[200:201], s[50:51], 0, v[132:133]
	s_mov_b32 m0, s18
	ds_read_b128 v[180:183], v143 offset:16384
	ds_read_b128 v[184:187], v143 offset:17408
	ds_read_b128 v[188:191], v143 offset:18432
	ds_read_b128 v[192:195], v143 offset:19456
	ds_read_b128 v[196:199], v143 offset:20480
	ds_read_b128 v[206:209], v143 offset:21504
	ds_read_b128 v[210:213], v143 offset:22528
	ds_read_b128 v[214:217], v143 offset:23552
	global_load_lds_dwordx4 v[200:201], off
	s_add_i32 m0, s18, 0x2000
	s_add_u32 s18, s50, 0x40000
	v_lshl_add_u64 v[218:219], s[50:51], 0, v[128:129]
	s_addc_u32 s19, s51, 0
	s_add_i32 s20, s21, s7
	global_load_lds_dwordx4 v[218:219], off
	v_lshl_add_u64 v[220:221], s[18:19], 0, v[132:133]
	s_mov_b32 m0, s20
	v_lshl_add_u64 v[222:223], s[64:65], 0, v[130:131]
	global_load_lds_dwordx4 v[220:221], off
	v_lshl_add_u64 v[220:221], s[18:19], 0, v[128:129]
	s_add_i32 m0, s20, 0x2000
	s_nop 0
	global_load_lds_dwordx4 v[220:221], off
	v_lshl_add_u64 v[220:221], s[64:65], 0, v[134:135]
	s_mov_b32 m0, s8
	s_nop 0
	global_load_lds_dwordx4 v[220:221], off
	s_mov_b32 m0, s9
	s_nop 0
	global_load_lds_dwordx4 v[222:223], off
	s_waitcnt vmcnt(8)
	s_waitcnt lgkmcnt(0)
	s_setprio 1
	s_barrier
	v_mfma_f32_16x16x32_bf16 v[60:63], v[144:147], v[180:183], v[60:63]
	v_mfma_f32_16x16x32_bf16 v[56:59], v[152:155], v[180:183], v[56:59]
	v_mfma_f32_16x16x32_bf16 v[52:55], v[144:147], v[188:191], v[52:55]
	v_mfma_f32_16x16x32_bf16 v[44:47], v[152:155], v[188:191], v[44:47]
	v_mfma_f32_16x16x32_bf16 v[36:39], v[144:147], v[196:199], v[36:39]
	v_mfma_f32_16x16x32_bf16 v[28:31], v[152:155], v[196:199], v[28:31]
	v_mfma_f32_16x16x32_bf16 v[20:23], v[144:147], v[210:213], v[20:23]
	v_mfma_f32_16x16x32_bf16 v[12:15], v[152:155], v[210:213], v[12:15]
	v_mfma_f32_16x16x32_bf16 v[60:63], v[148:151], v[184:187], v[60:63]
	v_mfma_f32_16x16x32_bf16 v[56:59], v[156:159], v[184:187], v[56:59]
	v_mfma_f32_16x16x32_bf16 v[52:55], v[148:151], v[192:195], v[52:55]
	v_mfma_f32_16x16x32_bf16 v[44:47], v[156:159], v[192:195], v[44:47]
	v_mfma_f32_16x16x32_bf16 v[36:39], v[148:151], v[206:209], v[36:39]
	v_mfma_f32_16x16x32_bf16 v[28:31], v[156:159], v[206:209], v[28:31]
	v_mfma_f32_16x16x32_bf16 v[20:23], v[148:151], v[214:217], v[20:23]
	v_mfma_f32_16x16x32_bf16 v[12:15], v[156:159], v[214:217], v[12:15]
	s_setprio 0
	s_setprio 1
	v_mfma_f32_16x16x32_bf16 v[48:51], v[164:167], v[180:183], v[48:51]
	v_mfma_f32_16x16x32_bf16 v[40:43], v[172:175], v[180:183], v[40:43]
	v_mfma_f32_16x16x32_bf16 v[32:35], v[164:167], v[188:191], v[32:35]
	v_mfma_f32_16x16x32_bf16 v[24:27], v[172:175], v[188:191], v[24:27]
	v_mfma_f32_16x16x32_bf16 v[16:19], v[164:167], v[196:199], v[16:19]
	v_mfma_f32_16x16x32_bf16 v[8:11], v[172:175], v[196:199], v[8:11]
	v_mfma_f32_16x16x32_bf16 v[4:7], v[164:167], v[210:213], v[4:7]
	v_mfma_f32_16x16x32_bf16 v[0:3], v[172:175], v[210:213], v[0:3]
	v_mfma_f32_16x16x32_bf16 v[48:51], v[168:171], v[184:187], v[48:51]
	v_mfma_f32_16x16x32_bf16 v[40:43], v[176:179], v[184:187], v[40:43]
	v_mfma_f32_16x16x32_bf16 v[32:35], v[168:171], v[192:195], v[32:35]
	v_mfma_f32_16x16x32_bf16 v[24:27], v[176:179], v[192:195], v[24:27]
	v_mfma_f32_16x16x32_bf16 v[16:19], v[168:171], v[206:209], v[16:19]
	v_mfma_f32_16x16x32_bf16 v[8:11], v[176:179], v[206:209], v[8:11]
	v_mfma_f32_16x16x32_bf16 v[4:7], v[168:171], v[214:217], v[4:7]
	v_mfma_f32_16x16x32_bf16 v[0:3], v[176:179], v[214:217], v[0:3]
	s_barrier
	s_setprio 0
	s_add_i32 s20, 0, 0x18000
	s_add_i32 s21, 0, 0x1c000
	v_add_u32_e32 v156, s20, v141
	v_add_u32_e32 v162, s21, v141
	ds_read_b128 v[144:147], v156
	ds_read_b128 v[148:151], v156 offset:1024
	ds_read_b128 v[152:155], v156 offset:2048
	ds_read_b128 v[156:159], v156 offset:3072
	ds_read_b128 v[164:167], v162
	ds_read_b128 v[168:171], v162 offset:1024
	ds_read_b128 v[172:175], v162 offset:2048
	ds_read_b128 v[176:179], v162 offset:3072
	s_add_u32 s18, s64, 0x40000
	s_addc_u32 s19, s65, 0
	s_mov_b32 m0, s10
	v_lshl_add_u64 v[224:225], s[18:19], 0, v[134:135]
	ds_read_b128 v[180:183], v143 offset:32768
	ds_read_b128 v[184:187], v143 offset:33792
	ds_read_b128 v[188:191], v143 offset:34816
	ds_read_b128 v[192:195], v143 offset:35840
	ds_read_b128 v[196:199], v143 offset:36864
	ds_read_b128 v[206:209], v143 offset:37888
	ds_read_b128 v[210:213], v143 offset:38912
	ds_read_b128 v[214:217], v143 offset:39936
	global_load_lds_dwordx4 v[224:225], off
	v_lshl_add_u64 v[224:225], s[18:19], 0, v[130:131]
	s_mov_b32 m0, s11
	s_nop 0
	global_load_lds_dwordx4 v[224:225], off
	s_waitcnt vmcnt(8)
	s_waitcnt lgkmcnt(0)
	s_setprio 1
	s_barrier
	v_mfma_f32_16x16x32_bf16 v[124:127], v[144:147], v[180:183], v[124:127]
	v_mfma_f32_16x16x32_bf16 v[120:123], v[152:155], v[180:183], v[120:123]
	v_mfma_f32_16x16x32_bf16 v[116:119], v[144:147], v[188:191], v[116:119]
	v_mfma_f32_16x16x32_bf16 v[108:111], v[152:155], v[188:191], v[108:111]
	v_mfma_f32_16x16x32_bf16 v[100:103], v[144:147], v[196:199], v[100:103]
	v_mfma_f32_16x16x32_bf16 v[92:95], v[152:155], v[196:199], v[92:95]
	v_mfma_f32_16x16x32_bf16 v[84:87], v[144:147], v[210:213], v[84:87]
	v_mfma_f32_16x16x32_bf16 v[76:79], v[152:155], v[210:213], v[76:79]
	v_mfma_f32_16x16x32_bf16 v[124:127], v[148:151], v[184:187], v[124:127]
	v_mfma_f32_16x16x32_bf16 v[120:123], v[156:159], v[184:187], v[120:123]
	v_mfma_f32_16x16x32_bf16 v[116:119], v[148:151], v[192:195], v[116:119]
	v_mfma_f32_16x16x32_bf16 v[108:111], v[156:159], v[192:195], v[108:111]
	v_mfma_f32_16x16x32_bf16 v[100:103], v[148:151], v[206:209], v[100:103]
	v_mfma_f32_16x16x32_bf16 v[92:95], v[156:159], v[206:209], v[92:95]
	v_mfma_f32_16x16x32_bf16 v[84:87], v[148:151], v[214:217], v[84:87]
	v_mfma_f32_16x16x32_bf16 v[76:79], v[156:159], v[214:217], v[76:79]
	s_setprio 0
	s_setprio 1
	v_mfma_f32_16x16x32_bf16 v[112:115], v[164:167], v[180:183], v[112:115]
	v_mfma_f32_16x16x32_bf16 v[104:107], v[172:175], v[180:183], v[104:107]
	v_mfma_f32_16x16x32_bf16 v[96:99], v[164:167], v[188:191], v[96:99]
	v_mfma_f32_16x16x32_bf16 v[88:91], v[172:175], v[188:191], v[88:91]
	v_mfma_f32_16x16x32_bf16 v[80:83], v[164:167], v[196:199], v[80:83]
	v_mfma_f32_16x16x32_bf16 v[72:75], v[172:175], v[196:199], v[72:75]
	v_mfma_f32_16x16x32_bf16 v[68:71], v[164:167], v[210:213], v[68:71]
	v_mfma_f32_16x16x32_bf16 v[64:67], v[172:175], v[210:213], v[64:67]
	v_mfma_f32_16x16x32_bf16 v[112:115], v[168:171], v[184:187], v[112:115]
	v_mfma_f32_16x16x32_bf16 v[104:107], v[176:179], v[184:187], v[104:107]
	v_mfma_f32_16x16x32_bf16 v[96:99], v[168:171], v[192:195], v[96:99]
	v_mfma_f32_16x16x32_bf16 v[88:91], v[176:179], v[192:195], v[88:91]
	v_mfma_f32_16x16x32_bf16 v[80:83], v[168:171], v[206:209], v[80:83]
	v_mfma_f32_16x16x32_bf16 v[72:75], v[176:179], v[206:209], v[72:75]
	v_mfma_f32_16x16x32_bf16 v[68:71], v[168:171], v[214:217], v[68:71]
	v_mfma_f32_16x16x32_bf16 v[64:67], v[176:179], v[214:217], v[64:67]
	s_barrier
	s_setprio 0
	s_add_i32 s18, s20, s7
	v_lshl_add_u64 v[200:201], v[200:201], 0, s[76:77]
	s_mov_b32 m0, s18
	ds_read_b128 v[180:183], v143 offset:49152
	ds_read_b128 v[184:187], v143 offset:50176
	ds_read_b128 v[188:191], v143 offset:51200
	ds_read_b128 v[192:195], v143 offset:52224
	ds_read_b128 v[196:199], v143 offset:53248
	ds_read_b128 v[206:209], v143 offset:54272
	ds_read_b128 v[210:213], v143 offset:55296
	ds_read_b128 v[214:217], v143 offset:56320
	global_load_lds_dwordx4 v[200:201], off
	s_add_i32 m0, s18, 0x2000
	s_add_u32 s18, s50, 0x40080
	v_lshl_add_u64 v[200:201], v[218:219], 0, s[76:77]
	s_addc_u32 s19, s51, 0
	s_add_i32 s20, s21, s7
	global_load_lds_dwordx4 v[200:201], off
	v_lshl_add_u64 v[200:201], s[18:19], 0, v[132:133]
	s_mov_b32 m0, s20
	s_nop 0
	global_load_lds_dwordx4 v[200:201], off
	v_lshl_add_u64 v[200:201], s[18:19], 0, v[128:129]
	s_add_i32 m0, s20, 0x2000
	s_nop 0
	global_load_lds_dwordx4 v[200:201], off
	v_lshl_add_u64 v[200:201], v[220:221], 0, s[76:77]
	s_mov_b32 m0, s13
	s_nop 0
	global_load_lds_dwordx4 v[200:201], off
	v_lshl_add_u64 v[200:201], v[222:223], 0, s[76:77]
	s_mov_b32 m0, s14
	s_nop 0
	global_load_lds_dwordx4 v[200:201], off
	s_waitcnt vmcnt(8)
	s_waitcnt lgkmcnt(0)
	s_setprio 1
	s_barrier
	v_mfma_f32_16x16x32_bf16 v[60:63], v[144:147], v[180:183], v[60:63]
	v_mfma_f32_16x16x32_bf16 v[56:59], v[152:155], v[180:183], v[56:59]
	v_mfma_f32_16x16x32_bf16 v[52:55], v[144:147], v[188:191], v[52:55]
	v_mfma_f32_16x16x32_bf16 v[44:47], v[152:155], v[188:191], v[44:47]
	v_mfma_f32_16x16x32_bf16 v[36:39], v[144:147], v[196:199], v[36:39]
	v_mfma_f32_16x16x32_bf16 v[28:31], v[152:155], v[196:199], v[28:31]
	v_mfma_f32_16x16x32_bf16 v[20:23], v[144:147], v[210:213], v[20:23]
	v_mfma_f32_16x16x32_bf16 v[12:15], v[152:155], v[210:213], v[12:15]
	v_mfma_f32_16x16x32_bf16 v[60:63], v[148:151], v[184:187], v[60:63]
	v_mfma_f32_16x16x32_bf16 v[56:59], v[156:159], v[184:187], v[56:59]
	v_mfma_f32_16x16x32_bf16 v[52:55], v[148:151], v[192:195], v[52:55]
	v_mfma_f32_16x16x32_bf16 v[44:47], v[156:159], v[192:195], v[44:47]
	v_mfma_f32_16x16x32_bf16 v[36:39], v[148:151], v[206:209], v[36:39]
	v_mfma_f32_16x16x32_bf16 v[28:31], v[156:159], v[206:209], v[28:31]
	v_mfma_f32_16x16x32_bf16 v[20:23], v[148:151], v[214:217], v[20:23]
	v_mfma_f32_16x16x32_bf16 v[12:15], v[156:159], v[214:217], v[12:15]
	s_setprio 0
	s_setprio 1
	v_mfma_f32_16x16x32_bf16 v[48:51], v[164:167], v[180:183], v[48:51]
	v_mfma_f32_16x16x32_bf16 v[40:43], v[172:175], v[180:183], v[40:43]
	v_mfma_f32_16x16x32_bf16 v[32:35], v[164:167], v[188:191], v[32:35]
	v_mfma_f32_16x16x32_bf16 v[24:27], v[172:175], v[188:191], v[24:27]
	v_mfma_f32_16x16x32_bf16 v[16:19], v[164:167], v[196:199], v[16:19]
	v_mfma_f32_16x16x32_bf16 v[8:11], v[172:175], v[196:199], v[8:11]
	v_mfma_f32_16x16x32_bf16 v[4:7], v[164:167], v[210:213], v[4:7]
	v_mfma_f32_16x16x32_bf16 v[0:3], v[172:175], v[210:213], v[0:3]
	v_mfma_f32_16x16x32_bf16 v[48:51], v[168:171], v[184:187], v[48:51]
	v_mfma_f32_16x16x32_bf16 v[40:43], v[176:179], v[184:187], v[40:43]
	v_mfma_f32_16x16x32_bf16 v[32:35], v[168:171], v[192:195], v[32:35]
	v_mfma_f32_16x16x32_bf16 v[24:27], v[176:179], v[192:195], v[24:27]
	v_mfma_f32_16x16x32_bf16 v[16:19], v[168:171], v[206:209], v[16:19]
	v_mfma_f32_16x16x32_bf16 v[8:11], v[176:179], v[206:209], v[8:11]
	v_mfma_f32_16x16x32_bf16 v[4:7], v[168:171], v[214:217], v[4:7]
	v_mfma_f32_16x16x32_bf16 v[0:3], v[176:179], v[214:217], v[0:3]
	s_barrier
	s_setprio 0
	s_add_i32 s61, s61, 2
	s_add_u32 s62, s62, 0x100
	s_addc_u32 s63, s63, 0
	s_add_u32 s47, s47, 0x100
	s_addc_u32 s54, s54, 0
	s_cmp_gt_u32 s61, 13
	s_cbranch_scc0 .LBB0_699

.LBB0_778:
	s_add_i32 s11, s11, 1
	s_mov_b32 s14, s12
	s_mul_i32 s12, s11, s86
	v_readlane_b32 s15, v245, 26
	s_add_i32 s12, s12, s15
	s_cmp_lt_u32 s12, 16
	s_mov_b32 s26, s40
	s_cselect_b64 s[48:49], -1, 0
	s_lshr_b32 s40, s12, 1
	s_and_b32 s12, s12, 1
	s_and_b64 s[16:17], s[48:49], exec
	s_mov_b32 s41, s27
	s_cselect_b32 s15, s89, s51
	s_cselect_b32 s16, s88, s50
	s_lshl_b64 s[20:21], s[40:41], 19
	v_readlane_b32 s17, v244, 0
	s_add_u32 s17, s17, s20
	v_readlane_b32 s20, v244, 1
	s_addc_u32 s20, s20, s21
	s_lshl_b32 s21, s12, 18
	s_add_u32 s17, s17, s21
	s_addc_u32 s22, s20, 0
	s_mov_b64 s[18:19], s[42:43]
	s_and_b64 s[20:21], s[48:49], exec
	s_cselect_b32 s43, s22, s19
	s_cselect_b32 s42, s17, s18
	s_add_u32 s58, s50, 0x20080
	s_addc_u32 s59, s51, 0
	s_add_u32 s17, s18, 0x100
	s_addc_u32 s39, s19, 0
	s_mov_b32 s41, -2
	s_add_u32 s18, s58, 0xfffe0080
	s_addc_u32 s19, s59, -1
	s_add_i32 s20, 0, 0x10000
	s_cmp_eq_u32 s41, 4
	s_cselect_b32 s61, s15, s19
	s_cselect_b32 s60, s16, s18
	v_add_u32_e32 v140, s20, v143
	s_cselect_b32 s51, s43, s39
	s_cselect_b32 s50, s42, s17
	s_add_i32 s21, 0, 0x14000
	ds_read_b128 v[146:149], v140
	ds_read_b128 v[150:153], v140 offset:1024
	ds_read_b128 v[154:157], v140 offset:2048
	ds_read_b128 v[164:167], v140 offset:3072
	v_add_u32_e32 v140, s21, v143
	ds_read_b128 v[168:171], v140
	ds_read_b128 v[172:175], v140 offset:1024
	ds_read_b128 v[176:179], v140 offset:2048
	ds_read_b128 v[180:183], v140 offset:3072
	v_lshl_add_u64 v[140:141], s[58:59], 0, v[136:137]
	s_add_i32 m0, s5, 0xc000
	ds_read_b128 v[184:187], v144
	ds_read_b128 v[188:191], v144 offset:1024
	ds_read_b128 v[192:195], v144 offset:2048
	ds_read_b128 v[196:199], v144 offset:3072
	ds_read_b128 v[206:209], v144 offset:4096
	ds_read_b128 v[210:213], v144 offset:5120
	ds_read_b128 v[214:217], v144 offset:6144
	ds_read_b128 v[218:221], v144 offset:7168
	global_load_lds_dwordx4 v[140:141], off
	v_lshl_add_u64 v[140:141], s[58:59], 0, v[138:139]
	s_add_i32 m0, s5, 0xe000
	s_nop 0
	global_load_lds_dwordx4 v[140:141], off
	s_waitcnt vmcnt(8)
	s_waitcnt lgkmcnt(0)
	s_setprio 1
	s_barrier
	v_mfma_f32_16x16x32_bf16 v[124:127], v[146:149], v[184:187], 0
	v_mfma_f32_16x16x32_bf16 v[120:123], v[154:157], v[184:187], 0
	v_mfma_f32_16x16x32_bf16 v[116:119], v[146:149], v[192:195], 0
	v_mfma_f32_16x16x32_bf16 v[108:111], v[154:157], v[192:195], 0
	v_mfma_f32_16x16x32_bf16 v[100:103], v[146:149], v[206:209], 0
	v_mfma_f32_16x16x32_bf16 v[92:95], v[154:157], v[206:209], 0
	v_mfma_f32_16x16x32_bf16 v[84:87], v[146:149], v[214:217], 0
	v_mfma_f32_16x16x32_bf16 v[76:79], v[154:157], v[214:217], 0
	v_mfma_f32_16x16x32_bf16 v[124:127], v[150:153], v[188:191], v[124:127]
	v_mfma_f32_16x16x32_bf16 v[120:123], v[164:167], v[188:191], v[120:123]
	v_mfma_f32_16x16x32_bf16 v[116:119], v[150:153], v[196:199], v[116:119]
	v_mfma_f32_16x16x32_bf16 v[108:111], v[164:167], v[196:199], v[108:111]
	v_mfma_f32_16x16x32_bf16 v[100:103], v[150:153], v[210:213], v[100:103]
	v_mfma_f32_16x16x32_bf16 v[92:95], v[164:167], v[210:213], v[92:95]
	v_mfma_f32_16x16x32_bf16 v[84:87], v[150:153], v[218:221], v[84:87]
	v_mfma_f32_16x16x32_bf16 v[76:79], v[164:167], v[218:221], v[76:79]
	s_setprio 0
	s_setprio 1
	v_mfma_f32_16x16x32_bf16 v[112:115], v[168:171], v[184:187], 0
	v_mfma_f32_16x16x32_bf16 v[104:107], v[176:179], v[184:187], 0
	v_mfma_f32_16x16x32_bf16 v[96:99], v[168:171], v[192:195], 0
	v_mfma_f32_16x16x32_bf16 v[88:91], v[176:179], v[192:195], 0
	v_mfma_f32_16x16x32_bf16 v[80:83], v[168:171], v[206:209], 0
	v_mfma_f32_16x16x32_bf16 v[72:75], v[176:179], v[206:209], 0
	v_mfma_f32_16x16x32_bf16 v[68:71], v[168:171], v[214:217], 0
	v_mfma_f32_16x16x32_bf16 v[64:67], v[176:179], v[214:217], 0
	v_mfma_f32_16x16x32_bf16 v[112:115], v[172:175], v[188:191], v[112:115]
	v_mfma_f32_16x16x32_bf16 v[104:107], v[180:183], v[188:191], v[104:107]
	v_mfma_f32_16x16x32_bf16 v[96:99], v[172:175], v[196:199], v[96:99]
	v_mfma_f32_16x16x32_bf16 v[88:91], v[180:183], v[196:199], v[88:91]
	v_mfma_f32_16x16x32_bf16 v[80:83], v[172:175], v[210:213], v[80:83]
	v_mfma_f32_16x16x32_bf16 v[72:75], v[180:183], v[210:213], v[72:75]
	v_mfma_f32_16x16x32_bf16 v[68:71], v[172:175], v[218:221], v[68:71]
	v_mfma_f32_16x16x32_bf16 v[64:67], v[180:183], v[218:221], v[64:67]
	s_barrier
	s_setprio 0
	s_add_i32 s18, s20, s4
	v_lshl_add_u64 v[140:141], s[50:51], 0, v[130:131]
	s_mov_b32 m0, s18
	ds_read_b128 v[184:187], v144 offset:16384
	ds_read_b128 v[188:191], v144 offset:17408
	ds_read_b128 v[192:195], v144 offset:18432
	ds_read_b128 v[196:199], v144 offset:19456
	ds_read_b128 v[206:209], v144 offset:20480
	ds_read_b128 v[210:213], v144 offset:21504
	ds_read_b128 v[214:217], v144 offset:22528
	ds_read_b128 v[218:221], v144 offset:23552
	global_load_lds_dwordx4 v[140:141], off
	s_add_i32 m0, s18, 0x2000
	s_add_u32 s18, s50, 0x20000
	v_lshl_add_u64 v[158:159], s[50:51], 0, v[134:135]
	s_addc_u32 s19, s51, 0
	s_add_i32 s20, s21, s4
	global_load_lds_dwordx4 v[158:159], off
	v_lshl_add_u64 v[200:201], s[18:19], 0, v[130:131]
	s_mov_b32 m0, s20
	v_lshl_add_u64 v[222:223], s[60:61], 0, v[132:133]
	global_load_lds_dwordx4 v[200:201], off
	v_lshl_add_u64 v[200:201], s[18:19], 0, v[134:135]
	s_add_i32 m0, s20, 0x2000
	s_nop 0
	global_load_lds_dwordx4 v[200:201], off
	v_lshl_add_u64 v[200:201], s[60:61], 0, v[128:129]
	s_mov_b32 m0, s5
	s_nop 0
	global_load_lds_dwordx4 v[200:201], off
	s_mov_b32 m0, s6
	s_nop 0
	global_load_lds_dwordx4 v[222:223], off
	s_waitcnt vmcnt(8)
	s_waitcnt lgkmcnt(0)
	s_setprio 1
	s_barrier
	v_mfma_f32_16x16x32_bf16 v[60:63], v[146:149], v[184:187], 0
	v_mfma_f32_16x16x32_bf16 v[56:59], v[154:157], v[184:187], 0
	v_mfma_f32_16x16x32_bf16 v[52:55], v[146:149], v[192:195], 0
	v_mfma_f32_16x16x32_bf16 v[44:47], v[154:157], v[192:195], 0
	v_mfma_f32_16x16x32_bf16 v[36:39], v[146:149], v[206:209], 0
	v_mfma_f32_16x16x32_bf16 v[28:31], v[154:157], v[206:209], 0
	v_mfma_f32_16x16x32_bf16 v[20:23], v[146:149], v[214:217], 0
	v_mfma_f32_16x16x32_bf16 v[12:15], v[154:157], v[214:217], 0
	v_mfma_f32_16x16x32_bf16 v[60:63], v[150:153], v[188:191], v[60:63]
	v_mfma_f32_16x16x32_bf16 v[56:59], v[164:167], v[188:191], v[56:59]
	v_mfma_f32_16x16x32_bf16 v[52:55], v[150:153], v[196:199], v[52:55]
	v_mfma_f32_16x16x32_bf16 v[44:47], v[164:167], v[196:199], v[44:47]
	v_mfma_f32_16x16x32_bf16 v[36:39], v[150:153], v[210:213], v[36:39]
	v_mfma_f32_16x16x32_bf16 v[28:31], v[164:167], v[210:213], v[28:31]
	v_mfma_f32_16x16x32_bf16 v[20:23], v[150:153], v[218:221], v[20:23]
	v_mfma_f32_16x16x32_bf16 v[12:15], v[164:167], v[218:221], v[12:15]
	s_setprio 0
	s_setprio 1
	v_mfma_f32_16x16x32_bf16 v[48:51], v[168:171], v[184:187], 0
	v_mfma_f32_16x16x32_bf16 v[40:43], v[176:179], v[184:187], 0
	v_mfma_f32_16x16x32_bf16 v[32:35], v[168:171], v[192:195], 0
	v_mfma_f32_16x16x32_bf16 v[24:27], v[176:179], v[192:195], 0
	v_mfma_f32_16x16x32_bf16 v[16:19], v[168:171], v[206:209], 0
	v_mfma_f32_16x16x32_bf16 v[8:11], v[176:179], v[206:209], 0
	v_mfma_f32_16x16x32_bf16 v[4:7], v[168:171], v[214:217], 0
	v_mfma_f32_16x16x32_bf16 v[0:3], v[176:179], v[214:217], 0
	v_mfma_f32_16x16x32_bf16 v[48:51], v[172:175], v[188:191], v[48:51]
	v_mfma_f32_16x16x32_bf16 v[40:43], v[180:183], v[188:191], v[40:43]
	v_mfma_f32_16x16x32_bf16 v[32:35], v[172:175], v[196:199], v[32:35]
	v_mfma_f32_16x16x32_bf16 v[24:27], v[180:183], v[196:199], v[24:27]
	v_mfma_f32_16x16x32_bf16 v[16:19], v[172:175], v[210:213], v[16:19]
	v_mfma_f32_16x16x32_bf16 v[8:11], v[180:183], v[210:213], v[8:11]
	v_mfma_f32_16x16x32_bf16 v[4:7], v[172:175], v[218:221], v[4:7]
	v_mfma_f32_16x16x32_bf16 v[0:3], v[180:183], v[218:221], v[0:3]
	s_barrier
	s_setprio 0
	s_add_i32 s20, 0, 0x18000
	v_add_u32_e32 v145, s20, v143
	s_add_i32 s21, 0, 0x1c000
	ds_read_b128 v[146:149], v145
	ds_read_b128 v[150:153], v145 offset:1024
	ds_read_b128 v[154:157], v145 offset:2048
	ds_read_b128 v[164:167], v145 offset:3072
	v_add_u32_e32 v145, s21, v143
	ds_read_b128 v[168:171], v145
	ds_read_b128 v[172:175], v145 offset:1024
	ds_read_b128 v[176:179], v145 offset:2048
	ds_read_b128 v[180:183], v145 offset:3072
	s_add_u32 s18, s60, 0x20000
	s_addc_u32 s19, s61, 0
	s_mov_b32 m0, s7
	v_lshl_add_u64 v[224:225], s[18:19], 0, v[128:129]
	ds_read_b128 v[184:187], v144 offset:32768
	ds_read_b128 v[188:191], v144 offset:33792
	ds_read_b128 v[192:195], v144 offset:34816
	ds_read_b128 v[196:199], v144 offset:35840
	ds_read_b128 v[206:209], v144 offset:36864
	ds_read_b128 v[210:213], v144 offset:37888
	ds_read_b128 v[214:217], v144 offset:38912
	ds_read_b128 v[218:221], v144 offset:39936
	global_load_lds_dwordx4 v[224:225], off
	v_lshl_add_u64 v[224:225], s[18:19], 0, v[132:133]
	s_mov_b32 m0, s8
	s_nop 0
	global_load_lds_dwordx4 v[224:225], off
	s_waitcnt vmcnt(8)
	s_waitcnt lgkmcnt(0)
	s_setprio 1
	s_barrier
	v_mfma_f32_16x16x32_bf16 v[124:127], v[146:149], v[184:187], v[124:127]
	v_mfma_f32_16x16x32_bf16 v[120:123], v[154:157], v[184:187], v[120:123]
	v_mfma_f32_16x16x32_bf16 v[116:119], v[146:149], v[192:195], v[116:119]
	v_mfma_f32_16x16x32_bf16 v[108:111], v[154:157], v[192:195], v[108:111]
	v_mfma_f32_16x16x32_bf16 v[100:103], v[146:149], v[206:209], v[100:103]
	v_mfma_f32_16x16x32_bf16 v[92:95], v[154:157], v[206:209], v[92:95]
	v_mfma_f32_16x16x32_bf16 v[84:87], v[146:149], v[214:217], v[84:87]
	v_mfma_f32_16x16x32_bf16 v[76:79], v[154:157], v[214:217], v[76:79]
	v_mfma_f32_16x16x32_bf16 v[124:127], v[150:153], v[188:191], v[124:127]
	v_mfma_f32_16x16x32_bf16 v[120:123], v[164:167], v[188:191], v[120:123]
	v_mfma_f32_16x16x32_bf16 v[116:119], v[150:153], v[196:199], v[116:119]
	v_mfma_f32_16x16x32_bf16 v[108:111], v[164:167], v[196:199], v[108:111]
	v_mfma_f32_16x16x32_bf16 v[100:103], v[150:153], v[210:213], v[100:103]
	v_mfma_f32_16x16x32_bf16 v[92:95], v[164:167], v[210:213], v[92:95]
	v_mfma_f32_16x16x32_bf16 v[84:87], v[150:153], v[218:221], v[84:87]
	v_mfma_f32_16x16x32_bf16 v[76:79], v[164:167], v[218:221], v[76:79]
	s_setprio 0
	s_setprio 1
	v_mfma_f32_16x16x32_bf16 v[112:115], v[168:171], v[184:187], v[112:115]
	v_mfma_f32_16x16x32_bf16 v[104:107], v[176:179], v[184:187], v[104:107]
	v_mfma_f32_16x16x32_bf16 v[96:99], v[168:171], v[192:195], v[96:99]
	v_mfma_f32_16x16x32_bf16 v[88:91], v[176:179], v[192:195], v[88:91]
	v_mfma_f32_16x16x32_bf16 v[80:83], v[168:171], v[206:209], v[80:83]
	v_mfma_f32_16x16x32_bf16 v[72:75], v[176:179], v[206:209], v[72:75]
	v_mfma_f32_16x16x32_bf16 v[68:71], v[168:171], v[214:217], v[68:71]
	v_mfma_f32_16x16x32_bf16 v[64:67], v[176:179], v[214:217], v[64:67]
	v_mfma_f32_16x16x32_bf16 v[112:115], v[172:175], v[188:191], v[112:115]
	v_mfma_f32_16x16x32_bf16 v[104:107], v[180:183], v[188:191], v[104:107]
	v_mfma_f32_16x16x32_bf16 v[96:99], v[172:175], v[196:199], v[96:99]
	v_mfma_f32_16x16x32_bf16 v[88:91], v[180:183], v[196:199], v[88:91]
	v_mfma_f32_16x16x32_bf16 v[80:83], v[172:175], v[210:213], v[80:83]
	v_mfma_f32_16x16x32_bf16 v[72:75], v[180:183], v[210:213], v[72:75]
	v_mfma_f32_16x16x32_bf16 v[68:71], v[172:175], v[218:221], v[68:71]
	v_mfma_f32_16x16x32_bf16 v[64:67], v[180:183], v[218:221], v[64:67]
	s_barrier
	s_setprio 0
	s_add_i32 s18, s20, s4
	v_lshl_add_u64 v[140:141], v[140:141], 0, s[76:77]
	s_mov_b32 m0, s18
	ds_read_b128 v[184:187], v144 offset:49152
	ds_read_b128 v[188:191], v144 offset:50176
	ds_read_b128 v[192:195], v144 offset:51200
	ds_read_b128 v[196:199], v144 offset:52224
	ds_read_b128 v[206:209], v144 offset:53248
	ds_read_b128 v[210:213], v144 offset:54272
	ds_read_b128 v[214:217], v144 offset:55296
	ds_read_b128 v[218:221], v144 offset:56320
	global_load_lds_dwordx4 v[140:141], off
	s_add_i32 m0, s18, 0x2000
	s_add_u32 s18, s50, 0x20080
	v_lshl_add_u64 v[140:141], v[158:159], 0, s[76:77]
	s_addc_u32 s19, s51, 0
	s_add_i32 s20, s21, s4
	global_load_lds_dwordx4 v[140:141], off
	v_lshl_add_u64 v[140:141], s[18:19], 0, v[130:131]
	s_mov_b32 m0, s20
	s_nop 0
	global_load_lds_dwordx4 v[140:141], off
	v_lshl_add_u64 v[140:141], s[18:19], 0, v[134:135]
	s_add_i32 m0, s20, 0x2000
	s_nop 0
	global_load_lds_dwordx4 v[140:141], off
	v_lshl_add_u64 v[140:141], v[200:201], 0, s[76:77]
	s_mov_b32 m0, s9
	s_nop 0
	global_load_lds_dwordx4 v[140:141], off
	v_lshl_add_u64 v[140:141], v[222:223], 0, s[76:77]
	s_mov_b32 m0, s10
	s_nop 0
	global_load_lds_dwordx4 v[140:141], off
	s_waitcnt vmcnt(8)
	s_waitcnt lgkmcnt(0)
	s_setprio 1
	s_barrier
	v_mfma_f32_16x16x32_bf16 v[60:63], v[146:149], v[184:187], v[60:63]
	v_mfma_f32_16x16x32_bf16 v[56:59], v[154:157], v[184:187], v[56:59]
	v_mfma_f32_16x16x32_bf16 v[52:55], v[146:149], v[192:195], v[52:55]
	v_mfma_f32_16x16x32_bf16 v[44:47], v[154:157], v[192:195], v[44:47]
	v_mfma_f32_16x16x32_bf16 v[36:39], v[146:149], v[206:209], v[36:39]
	v_mfma_f32_16x16x32_bf16 v[28:31], v[154:157], v[206:209], v[28:31]
	v_mfma_f32_16x16x32_bf16 v[20:23], v[146:149], v[214:217], v[20:23]
	v_mfma_f32_16x16x32_bf16 v[12:15], v[154:157], v[214:217], v[12:15]
	v_mfma_f32_16x16x32_bf16 v[60:63], v[150:153], v[188:191], v[60:63]
	v_mfma_f32_16x16x32_bf16 v[56:59], v[164:167], v[188:191], v[56:59]
	v_mfma_f32_16x16x32_bf16 v[52:55], v[150:153], v[196:199], v[52:55]
	v_mfma_f32_16x16x32_bf16 v[44:47], v[164:167], v[196:199], v[44:47]
	v_mfma_f32_16x16x32_bf16 v[36:39], v[150:153], v[210:213], v[36:39]
	v_mfma_f32_16x16x32_bf16 v[28:31], v[164:167], v[210:213], v[28:31]
	v_mfma_f32_16x16x32_bf16 v[20:23], v[150:153], v[218:221], v[20:23]
	v_mfma_f32_16x16x32_bf16 v[12:15], v[164:167], v[218:221], v[12:15]
	s_setprio 0
	s_setprio 1
	v_mfma_f32_16x16x32_bf16 v[48:51], v[168:171], v[184:187], v[48:51]
	v_mfma_f32_16x16x32_bf16 v[40:43], v[176:179], v[184:187], v[40:43]
	v_mfma_f32_16x16x32_bf16 v[32:35], v[168:171], v[192:195], v[32:35]
	v_mfma_f32_16x16x32_bf16 v[24:27], v[176:179], v[192:195], v[24:27]
	v_mfma_f32_16x16x32_bf16 v[16:19], v[168:171], v[206:209], v[16:19]
	v_mfma_f32_16x16x32_bf16 v[8:11], v[176:179], v[206:209], v[8:11]
	v_mfma_f32_16x16x32_bf16 v[4:7], v[168:171], v[214:217], v[4:7]
	v_mfma_f32_16x16x32_bf16 v[0:3], v[176:179], v[214:217], v[0:3]
	v_mfma_f32_16x16x32_bf16 v[48:51], v[172:175], v[188:191], v[48:51]
	v_mfma_f32_16x16x32_bf16 v[40:43], v[180:183], v[188:191], v[40:43]
	v_mfma_f32_16x16x32_bf16 v[32:35], v[172:175], v[196:199], v[32:35]
	v_mfma_f32_16x16x32_bf16 v[24:27], v[180:183], v[196:199], v[24:27]
	v_mfma_f32_16x16x32_bf16 v[16:19], v[172:175], v[210:213], v[16:19]
	v_mfma_f32_16x16x32_bf16 v[8:11], v[180:183], v[210:213], v[8:11]
	v_mfma_f32_16x16x32_bf16 v[4:7], v[172:175], v[218:221], v[4:7]
	v_mfma_f32_16x16x32_bf16 v[0:3], v[180:183], v[218:221], v[0:3]
	s_barrier
	s_setprio 0
	s_add_i32 s41, s41, 2
	s_add_u32 s58, s58, 0x100
	s_addc_u32 s59, s59, 0
	s_add_u32 s17, s17, 0x100
	s_addc_u32 s39, s39, 0
	s_cmp_gt_u32 s41, 5
	s_cbranch_scc0 .LBB0_779
	s_branch .Lpeel_x_779
.LBB0_779:
	s_add_u32 s18, s58, 0xfffe0080
	s_addc_u32 s19, s59, -1
	s_add_i32 s20, 0, 0x10000
	s_cmp_eq_u32 s41, 4
	s_cselect_b32 s61, s15, s19
	s_cselect_b32 s60, s16, s18
	v_add_u32_e32 v140, s20, v143
	s_cselect_b32 s51, s43, s39
	s_cselect_b32 s50, s42, s17
	s_add_i32 s21, 0, 0x14000
	ds_read_b128 v[146:149], v140
	ds_read_b128 v[150:153], v140 offset:1024
	ds_read_b128 v[154:157], v140 offset:2048
	ds_read_b128 v[164:167], v140 offset:3072
	v_add_u32_e32 v140, s21, v143
	ds_read_b128 v[168:171], v140
	ds_read_b128 v[172:175], v140 offset:1024
	ds_read_b128 v[176:179], v140 offset:2048
	ds_read_b128 v[180:183], v140 offset:3072
	v_lshl_add_u64 v[140:141], s[58:59], 0, v[136:137]
	s_add_i32 m0, s5, 0xc000
	ds_read_b128 v[184:187], v144
	ds_read_b128 v[188:191], v144 offset:1024
	ds_read_b128 v[192:195], v144 offset:2048
	ds_read_b128 v[196:199], v144 offset:3072
	ds_read_b128 v[206:209], v144 offset:4096
	ds_read_b128 v[210:213], v144 offset:5120
	ds_read_b128 v[214:217], v144 offset:6144
	ds_read_b128 v[218:221], v144 offset:7168
	global_load_lds_dwordx4 v[140:141], off
	v_lshl_add_u64 v[140:141], s[58:59], 0, v[138:139]
	s_add_i32 m0, s5, 0xe000
	s_nop 0
	global_load_lds_dwordx4 v[140:141], off
	s_waitcnt vmcnt(8)
	s_waitcnt lgkmcnt(0)
	s_setprio 1
	s_barrier
	v_mfma_f32_16x16x32_bf16 v[124:127], v[146:149], v[184:187], v[124:127]
	v_mfma_f32_16x16x32_bf16 v[120:123], v[154:157], v[184:187], v[120:123]
	v_mfma_f32_16x16x32_bf16 v[116:119], v[146:149], v[192:195], v[116:119]
	v_mfma_f32_16x16x32_bf16 v[108:111], v[154:157], v[192:195], v[108:111]
	v_mfma_f32_16x16x32_bf16 v[100:103], v[146:149], v[206:209], v[100:103]
	v_mfma_f32_16x16x32_bf16 v[92:95], v[154:157], v[206:209], v[92:95]
	v_mfma_f32_16x16x32_bf16 v[84:87], v[146:149], v[214:217], v[84:87]
	v_mfma_f32_16x16x32_bf16 v[76:79], v[154:157], v[214:217], v[76:79]
	v_mfma_f32_16x16x32_bf16 v[124:127], v[150:153], v[188:191], v[124:127]
	v_mfma_f32_16x16x32_bf16 v[120:123], v[164:167], v[188:191], v[120:123]
	v_mfma_f32_16x16x32_bf16 v[116:119], v[150:153], v[196:199], v[116:119]
	v_mfma_f32_16x16x32_bf16 v[108:111], v[164:167], v[196:199], v[108:111]
	v_mfma_f32_16x16x32_bf16 v[100:103], v[150:153], v[210:213], v[100:103]
	v_mfma_f32_16x16x32_bf16 v[92:95], v[164:167], v[210:213], v[92:95]
	v_mfma_f32_16x16x32_bf16 v[84:87], v[150:153], v[218:221], v[84:87]
	v_mfma_f32_16x16x32_bf16 v[76:79], v[164:167], v[218:221], v[76:79]
	s_setprio 0
	s_setprio 1
	v_mfma_f32_16x16x32_bf16 v[112:115], v[168:171], v[184:187], v[112:115]
	v_mfma_f32_16x16x32_bf16 v[104:107], v[176:179], v[184:187], v[104:107]
	v_mfma_f32_16x16x32_bf16 v[96:99], v[168:171], v[192:195], v[96:99]
	v_mfma_f32_16x16x32_bf16 v[88:91], v[176:179], v[192:195], v[88:91]
	v_mfma_f32_16x16x32_bf16 v[80:83], v[168:171], v[206:209], v[80:83]
	v_mfma_f32_16x16x32_bf16 v[72:75], v[176:179], v[206:209], v[72:75]
	v_mfma_f32_16x16x32_bf16 v[68:71], v[168:171], v[214:217], v[68:71]
	v_mfma_f32_16x16x32_bf16 v[64:67], v[176:179], v[214:217], v[64:67]
	v_mfma_f32_16x16x32_bf16 v[112:115], v[172:175], v[188:191], v[112:115]
	v_mfma_f32_16x16x32_bf16 v[104:107], v[180:183], v[188:191], v[104:107]
	v_mfma_f32_16x16x32_bf16 v[96:99], v[172:175], v[196:199], v[96:99]
	v_mfma_f32_16x16x32_bf16 v[88:91], v[180:183], v[196:199], v[88:91]
	v_mfma_f32_16x16x32_bf16 v[80:83], v[172:175], v[210:213], v[80:83]
	v_mfma_f32_16x16x32_bf16 v[72:75], v[180:183], v[210:213], v[72:75]
	v_mfma_f32_16x16x32_bf16 v[68:71], v[172:175], v[218:221], v[68:71]
	v_mfma_f32_16x16x32_bf16 v[64:67], v[180:183], v[218:221], v[64:67]
	s_barrier
	s_setprio 0
	s_add_i32 s18, s20, s4
	v_lshl_add_u64 v[140:141], s[50:51], 0, v[130:131]
	s_mov_b32 m0, s18
	ds_read_b128 v[184:187], v144 offset:16384
	ds_read_b128 v[188:191], v144 offset:17408
	ds_read_b128 v[192:195], v144 offset:18432
	ds_read_b128 v[196:199], v144 offset:19456
	ds_read_b128 v[206:209], v144 offset:20480
	ds_read_b128 v[210:213], v144 offset:21504
	ds_read_b128 v[214:217], v144 offset:22528
	ds_read_b128 v[218:221], v144 offset:23552
	global_load_lds_dwordx4 v[140:141], off
	s_add_i32 m0, s18, 0x2000
	s_add_u32 s18, s50, 0x20000
	v_lshl_add_u64 v[158:159], s[50:51], 0, v[134:135]
	s_addc_u32 s19, s51, 0
	s_add_i32 s20, s21, s4
	global_load_lds_dwordx4 v[158:159], off
	v_lshl_add_u64 v[200:201], s[18:19], 0, v[130:131]
	s_mov_b32 m0, s20
	v_lshl_add_u64 v[222:223], s[60:61], 0, v[132:133]
	global_load_lds_dwordx4 v[200:201], off
	v_lshl_add_u64 v[200:201], s[18:19], 0, v[134:135]
	s_add_i32 m0, s20, 0x2000
	s_nop 0
	global_load_lds_dwordx4 v[200:201], off
	v_lshl_add_u64 v[200:201], s[60:61], 0, v[128:129]
	s_mov_b32 m0, s5
	s_nop 0
	global_load_lds_dwordx4 v[200:201], off
	s_mov_b32 m0, s6
	s_nop 0
	global_load_lds_dwordx4 v[222:223], off
	s_waitcnt vmcnt(8)
	s_waitcnt lgkmcnt(0)
	s_setprio 1
	s_barrier
	v_mfma_f32_16x16x32_bf16 v[60:63], v[146:149], v[184:187], v[60:63]
	v_mfma_f32_16x16x32_bf16 v[56:59], v[154:157], v[184:187], v[56:59]
	v_mfma_f32_16x16x32_bf16 v[52:55], v[146:149], v[192:195], v[52:55]
	v_mfma_f32_16x16x32_bf16 v[44:47], v[154:157], v[192:195], v[44:47]
	v_mfma_f32_16x16x32_bf16 v[36:39], v[146:149], v[206:209], v[36:39]
	v_mfma_f32_16x16x32_bf16 v[28:31], v[154:157], v[206:209], v[28:31]
	v_mfma_f32_16x16x32_bf16 v[20:23], v[146:149], v[214:217], v[20:23]
	v_mfma_f32_16x16x32_bf16 v[12:15], v[154:157], v[214:217], v[12:15]
	v_mfma_f32_16x16x32_bf16 v[60:63], v[150:153], v[188:191], v[60:63]
	v_mfma_f32_16x16x32_bf16 v[56:59], v[164:167], v[188:191], v[56:59]
	v_mfma_f32_16x16x32_bf16 v[52:55], v[150:153], v[196:199], v[52:55]
	v_mfma_f32_16x16x32_bf16 v[44:47], v[164:167], v[196:199], v[44:47]
	v_mfma_f32_16x16x32_bf16 v[36:39], v[150:153], v[210:213], v[36:39]
	v_mfma_f32_16x16x32_bf16 v[28:31], v[164:167], v[210:213], v[28:31]
	v_mfma_f32_16x16x32_bf16 v[20:23], v[150:153], v[218:221], v[20:23]
	v_mfma_f32_16x16x32_bf16 v[12:15], v[164:167], v[218:221], v[12:15]
	s_setprio 0
	s_setprio 1
	v_mfma_f32_16x16x32_bf16 v[48:51], v[168:171], v[184:187], v[48:51]
	v_mfma_f32_16x16x32_bf16 v[40:43], v[176:179], v[184:187], v[40:43]
	v_mfma_f32_16x16x32_bf16 v[32:35], v[168:171], v[192:195], v[32:35]
	v_mfma_f32_16x16x32_bf16 v[24:27], v[176:179], v[192:195], v[24:27]
	v_mfma_f32_16x16x32_bf16 v[16:19], v[168:171], v[206:209], v[16:19]
	v_mfma_f32_16x16x32_bf16 v[8:11], v[176:179], v[206:209], v[8:11]
	v_mfma_f32_16x16x32_bf16 v[4:7], v[168:171], v[214:217], v[4:7]
	v_mfma_f32_16x16x32_bf16 v[0:3], v[176:179], v[214:217], v[0:3]
	v_mfma_f32_16x16x32_bf16 v[48:51], v[172:175], v[188:191], v[48:51]
	v_mfma_f32_16x16x32_bf16 v[40:43], v[180:183], v[188:191], v[40:43]
	v_mfma_f32_16x16x32_bf16 v[32:35], v[172:175], v[196:199], v[32:35]
	v_mfma_f32_16x16x32_bf16 v[24:27], v[180:183], v[196:199], v[24:27]
	v_mfma_f32_16x16x32_bf16 v[16:19], v[172:175], v[210:213], v[16:19]
	v_mfma_f32_16x16x32_bf16 v[8:11], v[180:183], v[210:213], v[8:11]
	v_mfma_f32_16x16x32_bf16 v[4:7], v[172:175], v[218:221], v[4:7]
	v_mfma_f32_16x16x32_bf16 v[0:3], v[180:183], v[218:221], v[0:3]
	s_barrier
	s_setprio 0
	s_add_i32 s20, 0, 0x18000
	v_add_u32_e32 v145, s20, v143
	s_add_i32 s21, 0, 0x1c000
	ds_read_b128 v[146:149], v145
	ds_read_b128 v[150:153], v145 offset:1024
	ds_read_b128 v[154:157], v145 offset:2048
	ds_read_b128 v[164:167], v145 offset:3072
	v_add_u32_e32 v145, s21, v143
	ds_read_b128 v[168:171], v145
	ds_read_b128 v[172:175], v145 offset:1024
	ds_read_b128 v[176:179], v145 offset:2048
	ds_read_b128 v[180:183], v145 offset:3072
	s_add_u32 s18, s60, 0x20000
	s_addc_u32 s19, s61, 0
	s_mov_b32 m0, s7
	v_lshl_add_u64 v[224:225], s[18:19], 0, v[128:129]
	ds_read_b128 v[184:187], v144 offset:32768
	ds_read_b128 v[188:191], v144 offset:33792
	ds_read_b128 v[192:195], v144 offset:34816
	ds_read_b128 v[196:199], v144 offset:35840
	ds_read_b128 v[206:209], v144 offset:36864
	ds_read_b128 v[210:213], v144 offset:37888
	ds_read_b128 v[214:217], v144 offset:38912
	ds_read_b128 v[218:221], v144 offset:39936
	global_load_lds_dwordx4 v[224:225], off
	v_lshl_add_u64 v[224:225], s[18:19], 0, v[132:133]
	s_mov_b32 m0, s8
	s_nop 0
	global_load_lds_dwordx4 v[224:225], off
	s_waitcnt vmcnt(8)
	s_waitcnt lgkmcnt(0)
	s_setprio 1
	s_barrier
	v_mfma_f32_16x16x32_bf16 v[124:127], v[146:149], v[184:187], v[124:127]
	v_mfma_f32_16x16x32_bf16 v[120:123], v[154:157], v[184:187], v[120:123]
	v_mfma_f32_16x16x32_bf16 v[116:119], v[146:149], v[192:195], v[116:119]
	v_mfma_f32_16x16x32_bf16 v[108:111], v[154:157], v[192:195], v[108:111]
	v_mfma_f32_16x16x32_bf16 v[100:103], v[146:149], v[206:209], v[100:103]
	v_mfma_f32_16x16x32_bf16 v[92:95], v[154:157], v[206:209], v[92:95]
	v_mfma_f32_16x16x32_bf16 v[84:87], v[146:149], v[214:217], v[84:87]
	v_mfma_f32_16x16x32_bf16 v[76:79], v[154:157], v[214:217], v[76:79]
	v_mfma_f32_16x16x32_bf16 v[124:127], v[150:153], v[188:191], v[124:127]
	v_mfma_f32_16x16x32_bf16 v[120:123], v[164:167], v[188:191], v[120:123]
	v_mfma_f32_16x16x32_bf16 v[116:119], v[150:153], v[196:199], v[116:119]
	v_mfma_f32_16x16x32_bf16 v[108:111], v[164:167], v[196:199], v[108:111]
	v_mfma_f32_16x16x32_bf16 v[100:103], v[150:153], v[210:213], v[100:103]
	v_mfma_f32_16x16x32_bf16 v[92:95], v[164:167], v[210:213], v[92:95]
	v_mfma_f32_16x16x32_bf16 v[84:87], v[150:153], v[218:221], v[84:87]
	v_mfma_f32_16x16x32_bf16 v[76:79], v[164:167], v[218:221], v[76:79]
	s_setprio 0
	s_setprio 1
	v_mfma_f32_16x16x32_bf16 v[112:115], v[168:171], v[184:187], v[112:115]
	v_mfma_f32_16x16x32_bf16 v[104:107], v[176:179], v[184:187], v[104:107]
	v_mfma_f32_16x16x32_bf16 v[96:99], v[168:171], v[192:195], v[96:99]
	v_mfma_f32_16x16x32_bf16 v[88:91], v[176:179], v[192:195], v[88:91]
	v_mfma_f32_16x16x32_bf16 v[80:83], v[168:171], v[206:209], v[80:83]
	v_mfma_f32_16x16x32_bf16 v[72:75], v[176:179], v[206:209], v[72:75]
	v_mfma_f32_16x16x32_bf16 v[68:71], v[168:171], v[214:217], v[68:71]
	v_mfma_f32_16x16x32_bf16 v[64:67], v[176:179], v[214:217], v[64:67]
	v_mfma_f32_16x16x32_bf16 v[112:115], v[172:175], v[188:191], v[112:115]
	v_mfma_f32_16x16x32_bf16 v[104:107], v[180:183], v[188:191], v[104:107]
	v_mfma_f32_16x16x32_bf16 v[96:99], v[172:175], v[196:199], v[96:99]
	v_mfma_f32_16x16x32_bf16 v[88:91], v[180:183], v[196:199], v[88:91]
	v_mfma_f32_16x16x32_bf16 v[80:83], v[172:175], v[210:213], v[80:83]
	v_mfma_f32_16x16x32_bf16 v[72:75], v[180:183], v[210:213], v[72:75]
	v_mfma_f32_16x16x32_bf16 v[68:71], v[172:175], v[218:221], v[68:71]
	v_mfma_f32_16x16x32_bf16 v[64:67], v[180:183], v[218:221], v[64:67]
	s_barrier
	s_setprio 0
	s_add_i32 s18, s20, s4
	v_lshl_add_u64 v[140:141], v[140:141], 0, s[76:77]
	s_mov_b32 m0, s18
	ds_read_b128 v[184:187], v144 offset:49152
	ds_read_b128 v[188:191], v144 offset:50176
	ds_read_b128 v[192:195], v144 offset:51200
	ds_read_b128 v[196:199], v144 offset:52224
	ds_read_b128 v[206:209], v144 offset:53248
	ds_read_b128 v[210:213], v144 offset:54272
	ds_read_b128 v[214:217], v144 offset:55296
	ds_read_b128 v[218:221], v144 offset:56320
	global_load_lds_dwordx4 v[140:141], off
	s_add_i32 m0, s18, 0x2000
	s_add_u32 s18, s50, 0x20080
	v_lshl_add_u64 v[140:141], v[158:159], 0, s[76:77]
	s_addc_u32 s19, s51, 0
	s_add_i32 s20, s21, s4
	global_load_lds_dwordx4 v[140:141], off
	v_lshl_add_u64 v[140:141], s[18:19], 0, v[130:131]
	s_mov_b32 m0, s20
	s_nop 0
	global_load_lds_dwordx4 v[140:141], off
	v_lshl_add_u64 v[140:141], s[18:19], 0, v[134:135]
	s_add_i32 m0, s20, 0x2000
	s_nop 0
	global_load_lds_dwordx4 v[140:141], off
	v_lshl_add_u64 v[140:141], v[200:201], 0, s[76:77]
	s_mov_b32 m0, s9
	s_nop 0
	global_load_lds_dwordx4 v[140:141], off
	v_lshl_add_u64 v[140:141], v[222:223], 0, s[76:77]
	s_mov_b32 m0, s10
	s_nop 0
	global_load_lds_dwordx4 v[140:141], off
	s_waitcnt vmcnt(8)
	s_waitcnt lgkmcnt(0)
	s_setprio 1
	s_barrier
	v_mfma_f32_16x16x32_bf16 v[60:63], v[146:149], v[184:187], v[60:63]
	v_mfma_f32_16x16x32_bf16 v[56:59], v[154:157], v[184:187], v[56:59]
	v_mfma_f32_16x16x32_bf16 v[52:55], v[146:149], v[192:195], v[52:55]
	v_mfma_f32_16x16x32_bf16 v[44:47], v[154:157], v[192:195], v[44:47]
	v_mfma_f32_16x16x32_bf16 v[36:39], v[146:149], v[206:209], v[36:39]
	v_mfma_f32_16x16x32_bf16 v[28:31], v[154:157], v[206:209], v[28:31]
	v_mfma_f32_16x16x32_bf16 v[20:23], v[146:149], v[214:217], v[20:23]
	v_mfma_f32_16x16x32_bf16 v[12:15], v[154:157], v[214:217], v[12:15]
	v_mfma_f32_16x16x32_bf16 v[60:63], v[150:153], v[188:191], v[60:63]
	v_mfma_f32_16x16x32_bf16 v[56:59], v[164:167], v[188:191], v[56:59]
	v_mfma_f32_16x16x32_bf16 v[52:55], v[150:153], v[196:199], v[52:55]
	v_mfma_f32_16x16x32_bf16 v[44:47], v[164:167], v[196:199], v[44:47]
	v_mfma_f32_16x16x32_bf16 v[36:39], v[150:153], v[210:213], v[36:39]
	v_mfma_f32_16x16x32_bf16 v[28:31], v[164:167], v[210:213], v[28:31]
	v_mfma_f32_16x16x32_bf16 v[20:23], v[150:153], v[218:221], v[20:23]
	v_mfma_f32_16x16x32_bf16 v[12:15], v[164:167], v[218:221], v[12:15]
	s_setprio 0
	s_setprio 1
	v_mfma_f32_16x16x32_bf16 v[48:51], v[168:171], v[184:187], v[48:51]
	v_mfma_f32_16x16x32_bf16 v[40:43], v[176:179], v[184:187], v[40:43]
	v_mfma_f32_16x16x32_bf16 v[32:35], v[168:171], v[192:195], v[32:35]
	v_mfma_f32_16x16x32_bf16 v[24:27], v[176:179], v[192:195], v[24:27]
	v_mfma_f32_16x16x32_bf16 v[16:19], v[168:171], v[206:209], v[16:19]
	v_mfma_f32_16x16x32_bf16 v[8:11], v[176:179], v[206:209], v[8:11]
	v_mfma_f32_16x16x32_bf16 v[4:7], v[168:171], v[214:217], v[4:7]
	v_mfma_f32_16x16x32_bf16 v[0:3], v[176:179], v[214:217], v[0:3]
	v_mfma_f32_16x16x32_bf16 v[48:51], v[172:175], v[188:191], v[48:51]
	v_mfma_f32_16x16x32_bf16 v[40:43], v[180:183], v[188:191], v[40:43]
	v_mfma_f32_16x16x32_bf16 v[32:35], v[172:175], v[196:199], v[32:35]
	v_mfma_f32_16x16x32_bf16 v[24:27], v[180:183], v[196:199], v[24:27]
	v_mfma_f32_16x16x32_bf16 v[16:19], v[172:175], v[210:213], v[16:19]
	v_mfma_f32_16x16x32_bf16 v[8:11], v[180:183], v[210:213], v[8:11]
	v_mfma_f32_16x16x32_bf16 v[4:7], v[172:175], v[218:221], v[4:7]
	v_mfma_f32_16x16x32_bf16 v[0:3], v[180:183], v[218:221], v[0:3]
	s_barrier
	s_setprio 0
	s_add_i32 s41, s41, 2
	s_add_u32 s58, s58, 0x100
	s_addc_u32 s59, s59, 0
	s_add_u32 s17, s17, 0x100
	s_addc_u32 s39, s39, 0
	s_cmp_gt_u32 s41, 5
	s_cbranch_scc0 .LBB0_779

.LBB0_890:
	s_ashr_i32 s49, s48, 31
	s_lshl_b64 s[16:17], s[48:49], 20
	s_add_u32 s60, s24, s16
	s_addc_u32 s61, s25, s17
	s_and_b64 s[16:17], s[66:67], exec
	s_cselect_b32 s16, s61, s65
	s_cselect_b32 s17, s60, s64
	s_add_u32 s66, s64, 0x1080
	s_addc_u32 s67, s65, 0
	s_add_u32 s41, s50, 0x100
	s_addc_u32 s43, s51, 0
	s_mov_b32 s46, -2
	s_add_u32 s18, s66, 0xfffff080
	s_addc_u32 s19, s67, -1
	s_add_i32 s20, 0, 0x10000
	s_cmp_eq_u32 s46, 28
	s_cselect_b32 s65, s16, s19
	s_cselect_b32 s64, s17, s18
	s_cselect_b32 s51, s59, s43
	s_cselect_b32 s50, s58, s41
	s_add_i32 s21, 0, 0x14000
	v_add_u32_e32 v90, s20, v88
	v_add_u32_e32 v106, s21, v88
	ds_read_b128 v[74:77], v90
	ds_read_b128 v[78:81], v90 offset:1024
	ds_read_b128 v[82:85], v90 offset:2048
	ds_read_b128 v[90:93], v90 offset:3072
	ds_read_b128 v[94:97], v106
	ds_read_b128 v[98:101], v106 offset:1024
	ds_read_b128 v[102:105], v106 offset:2048
	ds_read_b128 v[106:109], v106 offset:3072
	v_lshl_add_u64 v[142:143], s[66:67], 0, v[70:71]
	s_add_i32 m0, s5, 0xc000
	ds_read_b128 v[110:113], v89
	ds_read_b128 v[114:117], v89 offset:1024
	ds_read_b128 v[118:121], v89 offset:2048
	ds_read_b128 v[122:125], v89 offset:3072
	ds_read_b128 v[126:129], v89 offset:4096
	ds_read_b128 v[130:133], v89 offset:5120
	ds_read_b128 v[134:137], v89 offset:6144
	ds_read_b128 v[138:141], v89 offset:7168
	global_load_lds_dwordx4 v[142:143], off
	v_lshl_add_u64 v[142:143], s[66:67], 0, v[72:73]
	s_add_i32 m0, s5, 0xe000
	s_nop 0
	global_load_lds_dwordx4 v[142:143], off
	s_waitcnt vmcnt(8)
	s_waitcnt lgkmcnt(0)
	s_setprio 1
	s_barrier
	v_mfma_f32_16x16x32_bf16 v[60:63], v[74:77], v[110:113], 0
	v_mfma_f32_16x16x32_bf16 v[56:59], v[82:85], v[110:113], 0
	v_mfma_f32_16x16x32_bf16 v[44:47], v[74:77], v[118:121], 0
	v_mfma_f32_16x16x32_bf16 v[40:43], v[82:85], v[118:121], 0
	v_mfma_f32_16x16x32_bf16 v[28:31], v[74:77], v[126:129], 0
	v_mfma_f32_16x16x32_bf16 v[24:27], v[82:85], v[126:129], 0
	v_mfma_f32_16x16x32_bf16 v[12:15], v[74:77], v[134:137], 0
	v_mfma_f32_16x16x32_bf16 v[8:11], v[82:85], v[134:137], 0
	v_mfma_f32_16x16x32_bf16 v[60:63], v[78:81], v[114:117], v[60:63]
	v_mfma_f32_16x16x32_bf16 v[56:59], v[90:93], v[114:117], v[56:59]
	v_mfma_f32_16x16x32_bf16 v[44:47], v[78:81], v[122:125], v[44:47]
	v_mfma_f32_16x16x32_bf16 v[40:43], v[90:93], v[122:125], v[40:43]
	v_mfma_f32_16x16x32_bf16 v[28:31], v[78:81], v[130:133], v[28:31]
	v_mfma_f32_16x16x32_bf16 v[24:27], v[90:93], v[130:133], v[24:27]
	v_mfma_f32_16x16x32_bf16 v[12:15], v[78:81], v[138:141], v[12:15]
	v_mfma_f32_16x16x32_bf16 v[8:11], v[90:93], v[138:141], v[8:11]
	s_barrier
	s_setprio 0
	s_add_i32 s18, s20, s4
	v_lshl_add_u64 v[142:143], s[50:51], 0, v[162:163]
	s_mov_b32 m0, s18
	ds_read_b128 v[74:77], v89 offset:16384
	ds_read_b128 v[78:81], v89 offset:17408
	ds_read_b128 v[82:85], v89 offset:18432
	ds_read_b128 v[90:93], v89 offset:19456
	ds_read_b128 v[110:113], v89 offset:20480
	ds_read_b128 v[114:117], v89 offset:21504
	ds_read_b128 v[118:121], v89 offset:22528
	ds_read_b128 v[122:125], v89 offset:23552
	global_load_lds_dwordx4 v[142:143], off
	s_add_i32 m0, s18, 0x2000
	s_add_u32 s18, s50, 0x1000
	v_lshl_add_u64 v[144:145], s[50:51], 0, v[64:65]
	s_addc_u32 s19, s51, 0
	s_add_i32 s20, s21, s4
	global_load_lds_dwordx4 v[144:145], off
	v_lshl_add_u64 v[126:127], s[18:19], 0, v[162:163]
	s_mov_b32 m0, s20
	v_lshl_add_u64 v[146:147], s[64:65], 0, v[68:69]
	global_load_lds_dwordx4 v[126:127], off
	v_lshl_add_u64 v[126:127], s[18:19], 0, v[64:65]
	s_add_i32 m0, s20, 0x2000
	v_lshl_add_u64 v[148:149], s[64:65], 0, v[66:67]
	global_load_lds_dwordx4 v[126:127], off
	s_mov_b32 m0, s5
	s_nop 0
	global_load_lds_dwordx4 v[146:147], off
	s_mov_b32 m0, s6
	s_nop 0
	global_load_lds_dwordx4 v[148:149], off
	s_waitcnt vmcnt(8)
	s_waitcnt lgkmcnt(0)
	s_setprio 1
	s_barrier
	v_mfma_f32_16x16x32_bf16 v[52:55], v[94:97], v[74:77], 0
	v_mfma_f32_16x16x32_bf16 v[48:51], v[102:105], v[74:77], 0
	v_mfma_f32_16x16x32_bf16 v[36:39], v[94:97], v[82:85], 0
	v_mfma_f32_16x16x32_bf16 v[32:35], v[102:105], v[82:85], 0
	v_mfma_f32_16x16x32_bf16 v[20:23], v[94:97], v[110:113], 0
	v_mfma_f32_16x16x32_bf16 v[16:19], v[102:105], v[110:113], 0
	v_mfma_f32_16x16x32_bf16 v[4:7], v[94:97], v[118:121], 0
	v_mfma_f32_16x16x32_bf16 v[0:3], v[102:105], v[118:121], 0
	v_mfma_f32_16x16x32_bf16 v[52:55], v[98:101], v[78:81], v[52:55]
	v_mfma_f32_16x16x32_bf16 v[48:51], v[106:109], v[78:81], v[48:51]
	v_mfma_f32_16x16x32_bf16 v[36:39], v[98:101], v[90:93], v[36:39]
	v_mfma_f32_16x16x32_bf16 v[32:35], v[106:109], v[90:93], v[32:35]
	v_mfma_f32_16x16x32_bf16 v[20:23], v[98:101], v[114:117], v[20:23]
	v_mfma_f32_16x16x32_bf16 v[16:19], v[106:109], v[114:117], v[16:19]
	v_mfma_f32_16x16x32_bf16 v[4:7], v[98:101], v[122:125], v[4:7]
	v_mfma_f32_16x16x32_bf16 v[0:3], v[106:109], v[122:125], v[0:3]
	s_barrier
	s_setprio 0
	s_add_i32 s20, 0, 0x18000
	s_add_i32 s21, 0, 0x1c000
	v_add_u32_e32 v90, s20, v88
	v_add_u32_e32 v106, s21, v88
	ds_read_b128 v[74:77], v90
	ds_read_b128 v[78:81], v90 offset:1024
	ds_read_b128 v[82:85], v90 offset:2048
	ds_read_b128 v[90:93], v90 offset:3072
	ds_read_b128 v[94:97], v106
	ds_read_b128 v[98:101], v106 offset:1024
	ds_read_b128 v[102:105], v106 offset:2048
	ds_read_b128 v[106:109], v106 offset:3072
	s_add_u32 s18, s64, 0x1000
	s_addc_u32 s19, s65, 0
	s_mov_b32 m0, s7
	v_lshl_add_u64 v[150:151], s[18:19], 0, v[68:69]
	ds_read_b128 v[110:113], v89 offset:32768
	ds_read_b128 v[114:117], v89 offset:33792
	ds_read_b128 v[118:121], v89 offset:34816
	ds_read_b128 v[122:125], v89 offset:35840
	ds_read_b128 v[126:129], v89 offset:36864
	ds_read_b128 v[130:133], v89 offset:37888
	ds_read_b128 v[134:137], v89 offset:38912
	ds_read_b128 v[138:141], v89 offset:39936
	global_load_lds_dwordx4 v[150:151], off
	v_lshl_add_u64 v[150:151], s[18:19], 0, v[66:67]
	s_mov_b32 m0, s8
	s_nop 0
	global_load_lds_dwordx4 v[150:151], off
	s_waitcnt vmcnt(8)
	s_waitcnt lgkmcnt(0)
	s_setprio 1
	s_barrier
	v_mfma_f32_16x16x32_bf16 v[60:63], v[74:77], v[110:113], v[60:63]
	v_mfma_f32_16x16x32_bf16 v[56:59], v[82:85], v[110:113], v[56:59]
	v_mfma_f32_16x16x32_bf16 v[44:47], v[74:77], v[118:121], v[44:47]
	v_mfma_f32_16x16x32_bf16 v[40:43], v[82:85], v[118:121], v[40:43]
	v_mfma_f32_16x16x32_bf16 v[28:31], v[74:77], v[126:129], v[28:31]
	v_mfma_f32_16x16x32_bf16 v[24:27], v[82:85], v[126:129], v[24:27]
	v_mfma_f32_16x16x32_bf16 v[12:15], v[74:77], v[134:137], v[12:15]
	v_mfma_f32_16x16x32_bf16 v[8:11], v[82:85], v[134:137], v[8:11]
	v_mfma_f32_16x16x32_bf16 v[60:63], v[78:81], v[114:117], v[60:63]
	v_mfma_f32_16x16x32_bf16 v[56:59], v[90:93], v[114:117], v[56:59]
	v_mfma_f32_16x16x32_bf16 v[44:47], v[78:81], v[122:125], v[44:47]
	v_mfma_f32_16x16x32_bf16 v[40:43], v[90:93], v[122:125], v[40:43]
	v_mfma_f32_16x16x32_bf16 v[28:31], v[78:81], v[130:133], v[28:31]
	v_mfma_f32_16x16x32_bf16 v[24:27], v[90:93], v[130:133], v[24:27]
	v_mfma_f32_16x16x32_bf16 v[12:15], v[78:81], v[138:141], v[12:15]
	v_mfma_f32_16x16x32_bf16 v[8:11], v[90:93], v[138:141], v[8:11]
	s_barrier
	s_setprio 0
	s_add_i32 s18, s20, s4
	v_lshl_add_u64 v[126:127], v[142:143], 0, s[76:77]
	s_mov_b32 m0, s18
	ds_read_b128 v[74:77], v89 offset:49152
	ds_read_b128 v[78:81], v89 offset:50176
	ds_read_b128 v[82:85], v89 offset:51200
	ds_read_b128 v[90:93], v89 offset:52224
	ds_read_b128 v[110:113], v89 offset:53248
	ds_read_b128 v[114:117], v89 offset:54272
	ds_read_b128 v[118:121], v89 offset:55296
	ds_read_b128 v[122:125], v89 offset:56320
	global_load_lds_dwordx4 v[126:127], off
	s_add_i32 m0, s18, 0x2000
	s_add_u32 s18, s50, 0x1080
	v_lshl_add_u64 v[126:127], v[144:145], 0, s[76:77]
	s_addc_u32 s19, s51, 0
	s_add_i32 s20, s21, s4
	global_load_lds_dwordx4 v[126:127], off
	v_lshl_add_u64 v[126:127], s[18:19], 0, v[162:163]
	s_mov_b32 m0, s20
	s_nop 0
	global_load_lds_dwordx4 v[126:127], off
	v_lshl_add_u64 v[126:127], s[18:19], 0, v[64:65]
	s_add_i32 m0, s20, 0x2000
	s_nop 0
	global_load_lds_dwordx4 v[126:127], off
	v_lshl_add_u64 v[126:127], v[146:147], 0, s[76:77]
	s_mov_b32 m0, s11
	s_nop 0
	global_load_lds_dwordx4 v[126:127], off
	v_lshl_add_u64 v[126:127], v[148:149], 0, s[76:77]
	s_mov_b32 m0, s12
	s_nop 0
	global_load_lds_dwordx4 v[126:127], off
	s_waitcnt vmcnt(8)
	s_waitcnt lgkmcnt(0)
	s_setprio 1
	s_barrier
	v_mfma_f32_16x16x32_bf16 v[52:55], v[94:97], v[74:77], v[52:55]
	v_mfma_f32_16x16x32_bf16 v[48:51], v[102:105], v[74:77], v[48:51]
	v_mfma_f32_16x16x32_bf16 v[36:39], v[94:97], v[82:85], v[36:39]
	v_mfma_f32_16x16x32_bf16 v[32:35], v[102:105], v[82:85], v[32:35]
	v_mfma_f32_16x16x32_bf16 v[20:23], v[94:97], v[110:113], v[20:23]
	v_mfma_f32_16x16x32_bf16 v[16:19], v[102:105], v[110:113], v[16:19]
	v_mfma_f32_16x16x32_bf16 v[4:7], v[94:97], v[118:121], v[4:7]
	v_mfma_f32_16x16x32_bf16 v[0:3], v[102:105], v[118:121], v[0:3]
	v_mfma_f32_16x16x32_bf16 v[52:55], v[98:101], v[78:81], v[52:55]
	v_mfma_f32_16x16x32_bf16 v[48:51], v[106:109], v[78:81], v[48:51]
	v_mfma_f32_16x16x32_bf16 v[36:39], v[98:101], v[90:93], v[36:39]
	v_mfma_f32_16x16x32_bf16 v[32:35], v[106:109], v[90:93], v[32:35]
	v_mfma_f32_16x16x32_bf16 v[20:23], v[98:101], v[114:117], v[20:23]
	v_mfma_f32_16x16x32_bf16 v[16:19], v[106:109], v[114:117], v[16:19]
	v_mfma_f32_16x16x32_bf16 v[4:7], v[98:101], v[122:125], v[4:7]
	v_mfma_f32_16x16x32_bf16 v[0:3], v[106:109], v[122:125], v[0:3]
	s_barrier
	s_setprio 0
	s_add_i32 s46, s46, 2
	s_add_u32 s66, s66, 0x100
	s_addc_u32 s67, s67, 0
	s_add_u32 s41, s41, 0x100
	s_addc_u32 s43, s43, 0
	s_cmp_gt_u32 s46, 29
	s_cbranch_scc0 .LBB0_891
	s_branch .Lpeel_x_891
.LBB0_891:
	s_add_u32 s18, s66, 0xfffff080
	s_addc_u32 s19, s67, -1
	s_add_i32 s20, 0, 0x10000
	s_cmp_eq_u32 s46, 28
	s_cselect_b32 s65, s16, s19
	s_cselect_b32 s64, s17, s18
	s_cselect_b32 s51, s59, s43
	s_cselect_b32 s50, s58, s41
	s_add_i32 s21, 0, 0x14000
	v_add_u32_e32 v90, s20, v88
	v_add_u32_e32 v106, s21, v88
	ds_read_b128 v[74:77], v90
	ds_read_b128 v[78:81], v90 offset:1024
	ds_read_b128 v[82:85], v90 offset:2048
	ds_read_b128 v[90:93], v90 offset:3072
	ds_read_b128 v[94:97], v106
	ds_read_b128 v[98:101], v106 offset:1024
	ds_read_b128 v[102:105], v106 offset:2048
	ds_read_b128 v[106:109], v106 offset:3072
	v_lshl_add_u64 v[142:143], s[66:67], 0, v[70:71]
	s_add_i32 m0, s5, 0xc000
	ds_read_b128 v[110:113], v89
	ds_read_b128 v[114:117], v89 offset:1024
	ds_read_b128 v[118:121], v89 offset:2048
	ds_read_b128 v[122:125], v89 offset:3072
	ds_read_b128 v[126:129], v89 offset:4096
	ds_read_b128 v[130:133], v89 offset:5120
	ds_read_b128 v[134:137], v89 offset:6144
	ds_read_b128 v[138:141], v89 offset:7168
	global_load_lds_dwordx4 v[142:143], off
	v_lshl_add_u64 v[142:143], s[66:67], 0, v[72:73]
	s_add_i32 m0, s5, 0xe000
	s_nop 0
	global_load_lds_dwordx4 v[142:143], off
	s_waitcnt vmcnt(8)
	s_waitcnt lgkmcnt(0)
	s_setprio 1
	s_barrier
	v_mfma_f32_16x16x32_bf16 v[60:63], v[74:77], v[110:113], v[60:63]
	v_mfma_f32_16x16x32_bf16 v[56:59], v[82:85], v[110:113], v[56:59]
	v_mfma_f32_16x16x32_bf16 v[44:47], v[74:77], v[118:121], v[44:47]
	v_mfma_f32_16x16x32_bf16 v[40:43], v[82:85], v[118:121], v[40:43]
	v_mfma_f32_16x16x32_bf16 v[28:31], v[74:77], v[126:129], v[28:31]
	v_mfma_f32_16x16x32_bf16 v[24:27], v[82:85], v[126:129], v[24:27]
	v_mfma_f32_16x16x32_bf16 v[12:15], v[74:77], v[134:137], v[12:15]
	v_mfma_f32_16x16x32_bf16 v[8:11], v[82:85], v[134:137], v[8:11]
	v_mfma_f32_16x16x32_bf16 v[60:63], v[78:81], v[114:117], v[60:63]
	v_mfma_f32_16x16x32_bf16 v[56:59], v[90:93], v[114:117], v[56:59]
	v_mfma_f32_16x16x32_bf16 v[44:47], v[78:81], v[122:125], v[44:47]
	v_mfma_f32_16x16x32_bf16 v[40:43], v[90:93], v[122:125], v[40:43]
	v_mfma_f32_16x16x32_bf16 v[28:31], v[78:81], v[130:133], v[28:31]
	v_mfma_f32_16x16x32_bf16 v[24:27], v[90:93], v[130:133], v[24:27]
	v_mfma_f32_16x16x32_bf16 v[12:15], v[78:81], v[138:141], v[12:15]
	v_mfma_f32_16x16x32_bf16 v[8:11], v[90:93], v[138:141], v[8:11]
	s_barrier
	s_setprio 0
	s_add_i32 s18, s20, s4
	v_lshl_add_u64 v[142:143], s[50:51], 0, v[162:163]
	s_mov_b32 m0, s18
	ds_read_b128 v[74:77], v89 offset:16384
	ds_read_b128 v[78:81], v89 offset:17408
	ds_read_b128 v[82:85], v89 offset:18432
	ds_read_b128 v[90:93], v89 offset:19456
	ds_read_b128 v[110:113], v89 offset:20480
	ds_read_b128 v[114:117], v89 offset:21504
	ds_read_b128 v[118:121], v89 offset:22528
	ds_read_b128 v[122:125], v89 offset:23552
	global_load_lds_dwordx4 v[142:143], off
	s_add_i32 m0, s18, 0x2000
	s_add_u32 s18, s50, 0x1000
	v_lshl_add_u64 v[144:145], s[50:51], 0, v[64:65]
	s_addc_u32 s19, s51, 0
	s_add_i32 s20, s21, s4
	global_load_lds_dwordx4 v[144:145], off
	v_lshl_add_u64 v[126:127], s[18:19], 0, v[162:163]
	s_mov_b32 m0, s20
	v_lshl_add_u64 v[146:147], s[64:65], 0, v[68:69]
	global_load_lds_dwordx4 v[126:127], off
	v_lshl_add_u64 v[126:127], s[18:19], 0, v[64:65]
	s_add_i32 m0, s20, 0x2000
	v_lshl_add_u64 v[148:149], s[64:65], 0, v[66:67]
	global_load_lds_dwordx4 v[126:127], off
	s_mov_b32 m0, s5
	s_nop 0
	global_load_lds_dwordx4 v[146:147], off
	s_mov_b32 m0, s6
	s_nop 0
	global_load_lds_dwordx4 v[148:149], off
	s_waitcnt vmcnt(8)
	s_waitcnt lgkmcnt(0)
	s_setprio 1
	s_barrier
	v_mfma_f32_16x16x32_bf16 v[52:55], v[94:97], v[74:77], v[52:55]
	v_mfma_f32_16x16x32_bf16 v[48:51], v[102:105], v[74:77], v[48:51]
	v_mfma_f32_16x16x32_bf16 v[36:39], v[94:97], v[82:85], v[36:39]
	v_mfma_f32_16x16x32_bf16 v[32:35], v[102:105], v[82:85], v[32:35]
	v_mfma_f32_16x16x32_bf16 v[20:23], v[94:97], v[110:113], v[20:23]
	v_mfma_f32_16x16x32_bf16 v[16:19], v[102:105], v[110:113], v[16:19]
	v_mfma_f32_16x16x32_bf16 v[4:7], v[94:97], v[118:121], v[4:7]
	v_mfma_f32_16x16x32_bf16 v[0:3], v[102:105], v[118:121], v[0:3]
	v_mfma_f32_16x16x32_bf16 v[52:55], v[98:101], v[78:81], v[52:55]
	v_mfma_f32_16x16x32_bf16 v[48:51], v[106:109], v[78:81], v[48:51]
	v_mfma_f32_16x16x32_bf16 v[36:39], v[98:101], v[90:93], v[36:39]
	v_mfma_f32_16x16x32_bf16 v[32:35], v[106:109], v[90:93], v[32:35]
	v_mfma_f32_16x16x32_bf16 v[20:23], v[98:101], v[114:117], v[20:23]
	v_mfma_f32_16x16x32_bf16 v[16:19], v[106:109], v[114:117], v[16:19]
	v_mfma_f32_16x16x32_bf16 v[4:7], v[98:101], v[122:125], v[4:7]
	v_mfma_f32_16x16x32_bf16 v[0:3], v[106:109], v[122:125], v[0:3]
	s_barrier
	s_setprio 0
	s_add_i32 s20, 0, 0x18000
	s_add_i32 s21, 0, 0x1c000
	v_add_u32_e32 v90, s20, v88
	v_add_u32_e32 v106, s21, v88
	ds_read_b128 v[74:77], v90
	ds_read_b128 v[78:81], v90 offset:1024
	ds_read_b128 v[82:85], v90 offset:2048
	ds_read_b128 v[90:93], v90 offset:3072
	ds_read_b128 v[94:97], v106
	ds_read_b128 v[98:101], v106 offset:1024
	ds_read_b128 v[102:105], v106 offset:2048
	ds_read_b128 v[106:109], v106 offset:3072
	s_add_u32 s18, s64, 0x1000
	s_addc_u32 s19, s65, 0
	s_mov_b32 m0, s7
	v_lshl_add_u64 v[150:151], s[18:19], 0, v[68:69]
	ds_read_b128 v[110:113], v89 offset:32768
	ds_read_b128 v[114:117], v89 offset:33792
	ds_read_b128 v[118:121], v89 offset:34816
	ds_read_b128 v[122:125], v89 offset:35840
	ds_read_b128 v[126:129], v89 offset:36864
	ds_read_b128 v[130:133], v89 offset:37888
	ds_read_b128 v[134:137], v89 offset:38912
	ds_read_b128 v[138:141], v89 offset:39936
	global_load_lds_dwordx4 v[150:151], off
	v_lshl_add_u64 v[150:151], s[18:19], 0, v[66:67]
	s_mov_b32 m0, s8
	s_nop 0
	global_load_lds_dwordx4 v[150:151], off
	s_waitcnt vmcnt(8)
	s_waitcnt lgkmcnt(0)
	s_setprio 1
	s_barrier
	v_mfma_f32_16x16x32_bf16 v[60:63], v[74:77], v[110:113], v[60:63]
	v_mfma_f32_16x16x32_bf16 v[56:59], v[82:85], v[110:113], v[56:59]
	v_mfma_f32_16x16x32_bf16 v[44:47], v[74:77], v[118:121], v[44:47]
	v_mfma_f32_16x16x32_bf16 v[40:43], v[82:85], v[118:121], v[40:43]
	v_mfma_f32_16x16x32_bf16 v[28:31], v[74:77], v[126:129], v[28:31]
	v_mfma_f32_16x16x32_bf16 v[24:27], v[82:85], v[126:129], v[24:27]
	v_mfma_f32_16x16x32_bf16 v[12:15], v[74:77], v[134:137], v[12:15]
	v_mfma_f32_16x16x32_bf16 v[8:11], v[82:85], v[134:137], v[8:11]
	v_mfma_f32_16x16x32_bf16 v[60:63], v[78:81], v[114:117], v[60:63]
	v_mfma_f32_16x16x32_bf16 v[56:59], v[90:93], v[114:117], v[56:59]
	v_mfma_f32_16x16x32_bf16 v[44:47], v[78:81], v[122:125], v[44:47]
	v_mfma_f32_16x16x32_bf16 v[40:43], v[90:93], v[122:125], v[40:43]
	v_mfma_f32_16x16x32_bf16 v[28:31], v[78:81], v[130:133], v[28:31]
	v_mfma_f32_16x16x32_bf16 v[24:27], v[90:93], v[130:133], v[24:27]
	v_mfma_f32_16x16x32_bf16 v[12:15], v[78:81], v[138:141], v[12:15]
	v_mfma_f32_16x16x32_bf16 v[8:11], v[90:93], v[138:141], v[8:11]
	s_barrier
	s_setprio 0
	s_add_i32 s18, s20, s4
	v_lshl_add_u64 v[126:127], v[142:143], 0, s[76:77]
	s_mov_b32 m0, s18
	ds_read_b128 v[74:77], v89 offset:49152
	ds_read_b128 v[78:81], v89 offset:50176
	ds_read_b128 v[82:85], v89 offset:51200
	ds_read_b128 v[90:93], v89 offset:52224
	ds_read_b128 v[110:113], v89 offset:53248
	ds_read_b128 v[114:117], v89 offset:54272
	ds_read_b128 v[118:121], v89 offset:55296
	ds_read_b128 v[122:125], v89 offset:56320
	global_load_lds_dwordx4 v[126:127], off
	s_add_i32 m0, s18, 0x2000
	s_add_u32 s18, s50, 0x1080
	v_lshl_add_u64 v[126:127], v[144:145], 0, s[76:77]
	s_addc_u32 s19, s51, 0
	s_add_i32 s20, s21, s4
	global_load_lds_dwordx4 v[126:127], off
	v_lshl_add_u64 v[126:127], s[18:19], 0, v[162:163]
	s_mov_b32 m0, s20
	s_nop 0
	global_load_lds_dwordx4 v[126:127], off
	v_lshl_add_u64 v[126:127], s[18:19], 0, v[64:65]
	s_add_i32 m0, s20, 0x2000
	s_nop 0
	global_load_lds_dwordx4 v[126:127], off
	v_lshl_add_u64 v[126:127], v[146:147], 0, s[76:77]
	s_mov_b32 m0, s11
	s_nop 0
	global_load_lds_dwordx4 v[126:127], off
	v_lshl_add_u64 v[126:127], v[148:149], 0, s[76:77]
	s_mov_b32 m0, s12
	s_nop 0
	global_load_lds_dwordx4 v[126:127], off
	s_waitcnt vmcnt(8)
	s_waitcnt lgkmcnt(0)
	s_setprio 1
	s_barrier
	v_mfma_f32_16x16x32_bf16 v[52:55], v[94:97], v[74:77], v[52:55]
	v_mfma_f32_16x16x32_bf16 v[48:51], v[102:105], v[74:77], v[48:51]
	v_mfma_f32_16x16x32_bf16 v[36:39], v[94:97], v[82:85], v[36:39]
	v_mfma_f32_16x16x32_bf16 v[32:35], v[102:105], v[82:85], v[32:35]
	v_mfma_f32_16x16x32_bf16 v[20:23], v[94:97], v[110:113], v[20:23]
	v_mfma_f32_16x16x32_bf16 v[16:19], v[102:105], v[110:113], v[16:19]
	v_mfma_f32_16x16x32_bf16 v[4:7], v[94:97], v[118:121], v[4:7]
	v_mfma_f32_16x16x32_bf16 v[0:3], v[102:105], v[118:121], v[0:3]
	v_mfma_f32_16x16x32_bf16 v[52:55], v[98:101], v[78:81], v[52:55]
	v_mfma_f32_16x16x32_bf16 v[48:51], v[106:109], v[78:81], v[48:51]
	v_mfma_f32_16x16x32_bf16 v[36:39], v[98:101], v[90:93], v[36:39]
	v_mfma_f32_16x16x32_bf16 v[32:35], v[106:109], v[90:93], v[32:35]
	v_mfma_f32_16x16x32_bf16 v[20:23], v[98:101], v[114:117], v[20:23]
	v_mfma_f32_16x16x32_bf16 v[16:19], v[106:109], v[114:117], v[16:19]
	v_mfma_f32_16x16x32_bf16 v[4:7], v[98:101], v[122:125], v[4:7]
	v_mfma_f32_16x16x32_bf16 v[0:3], v[106:109], v[122:125], v[0:3]
	s_barrier
	s_setprio 0
	s_add_i32 s46, s46, 2
	s_add_u32 s66, s66, 0x100
	s_addc_u32 s67, s67, 0
	s_add_u32 s41, s41, 0x100
	s_addc_u32 s43, s43, 0
	s_cmp_gt_u32 s46, 29
	s_cbranch_scc0 .LBB0_891

.LBB0_913:
	s_add_i32 s11, s11, 1
	s_mov_b32 s13, s12
	s_mul_i32 s12, s11, s86
	s_add_i32 s12, s12, s45
	s_cmp_lt_u32 s12, 16
	s_mov_b32 s26, s40
	s_cselect_b64 s[48:49], -1, 0
	s_lshr_b32 s40, s12, 1
	s_mov_b32 s41, s27
	s_and_b32 s12, s12, 1
	s_lshl_b64 s[16:17], s[40:41], 19
	s_add_u32 s16, s21, s16
	s_addc_u32 s17, s22, s17
	s_lshl_b32 s18, s12, 18
	s_add_u32 s18, s16, s18
	s_addc_u32 s19, s17, 0
	s_mov_b64 s[14:15], s[42:43]
	s_and_b64 s[16:17], s[48:49], exec
	s_cselect_b32 s43, s19, s15
	s_cselect_b32 s42, s18, s14
	s_add_u32 s14, s14, 0x100
	s_addc_u32 s15, s15, 0
	s_mov_b32 s16, -2
	s_mov_b64 s[58:59], 0
	s_add_u32 s60, s58, 0x100
	s_addc_u32 s61, s59, 0
	s_add_u32 s17, s14, s58
	s_addc_u32 s18, s15, s59
	s_cmp_eq_u32 s16, 4
	s_cselect_b32 s20, 0, s60
	s_cselect_b32 s19, 0, s61
	s_cselect_b32 s50, s42, s17
	s_cselect_b32 s51, s43, s18
	s_add_u32 s62, s88, s20
	s_addc_u32 s63, s89, s19
	s_add_i32 s17, 0, 0x10000
	v_add_u32_e32 v142, s17, v144
	s_add_i32 s20, 0, 0x14000
	ds_read_b128 v[146:149], v142
	ds_read_b128 v[150:153], v142 offset:1024
	ds_read_b128 v[154:157], v142 offset:2048
	ds_read_b128 v[164:167], v142 offset:3072
	v_add_u32_e32 v142, s20, v144
	ds_read_b128 v[168:171], v142
	ds_read_b128 v[172:175], v142 offset:1024
	ds_read_b128 v[176:179], v142 offset:2048
	ds_read_b128 v[180:183], v142 offset:3072
	v_lshl_add_u64 v[142:143], v[138:139], 0, s[58:59]
	s_add_i32 m0, s5, 0xc000
	ds_read_b128 v[184:187], v145
	ds_read_b128 v[188:191], v145 offset:1024
	ds_read_b128 v[192:195], v145 offset:2048
	ds_read_b128 v[196:199], v145 offset:3072
	ds_read_b128 v[206:209], v145 offset:4096
	ds_read_b128 v[210:213], v145 offset:5120
	ds_read_b128 v[214:217], v145 offset:6144
	ds_read_b128 v[218:221], v145 offset:7168
	global_load_lds_dwordx4 v[142:143], off
	v_lshl_add_u64 v[142:143], v[140:141], 0, s[58:59]
	s_add_i32 m0, s5, 0xe000
	s_nop 0
	global_load_lds_dwordx4 v[142:143], off
	s_waitcnt vmcnt(8)
	s_waitcnt lgkmcnt(0)
	s_setprio 1
	s_barrier
	v_mfma_f32_16x16x32_bf16 v[124:127], v[146:149], v[184:187], 0
	v_mfma_f32_16x16x32_bf16 v[120:123], v[154:157], v[184:187], 0
	v_mfma_f32_16x16x32_bf16 v[116:119], v[146:149], v[192:195], 0
	v_mfma_f32_16x16x32_bf16 v[108:111], v[154:157], v[192:195], 0
	v_mfma_f32_16x16x32_bf16 v[100:103], v[146:149], v[206:209], 0
	v_mfma_f32_16x16x32_bf16 v[92:95], v[154:157], v[206:209], 0
	v_mfma_f32_16x16x32_bf16 v[84:87], v[146:149], v[214:217], 0
	v_mfma_f32_16x16x32_bf16 v[76:79], v[154:157], v[214:217], 0
	v_mfma_f32_16x16x32_bf16 v[124:127], v[150:153], v[188:191], v[124:127]
	v_mfma_f32_16x16x32_bf16 v[120:123], v[164:167], v[188:191], v[120:123]
	v_mfma_f32_16x16x32_bf16 v[116:119], v[150:153], v[196:199], v[116:119]
	v_mfma_f32_16x16x32_bf16 v[108:111], v[164:167], v[196:199], v[108:111]
	v_mfma_f32_16x16x32_bf16 v[100:103], v[150:153], v[210:213], v[100:103]
	v_mfma_f32_16x16x32_bf16 v[92:95], v[164:167], v[210:213], v[92:95]
	v_mfma_f32_16x16x32_bf16 v[84:87], v[150:153], v[218:221], v[84:87]
	v_mfma_f32_16x16x32_bf16 v[76:79], v[164:167], v[218:221], v[76:79]
	s_setprio 0
	s_setprio 1
	v_mfma_f32_16x16x32_bf16 v[112:115], v[168:171], v[184:187], 0
	v_mfma_f32_16x16x32_bf16 v[104:107], v[176:179], v[184:187], 0
	v_mfma_f32_16x16x32_bf16 v[96:99], v[168:171], v[192:195], 0
	v_mfma_f32_16x16x32_bf16 v[88:91], v[176:179], v[192:195], 0
	v_mfma_f32_16x16x32_bf16 v[80:83], v[168:171], v[206:209], 0
	v_mfma_f32_16x16x32_bf16 v[72:75], v[176:179], v[206:209], 0
	v_mfma_f32_16x16x32_bf16 v[68:71], v[168:171], v[214:217], 0
	v_mfma_f32_16x16x32_bf16 v[64:67], v[176:179], v[214:217], 0
	v_mfma_f32_16x16x32_bf16 v[112:115], v[172:175], v[188:191], v[112:115]
	v_mfma_f32_16x16x32_bf16 v[104:107], v[180:183], v[188:191], v[104:107]
	v_mfma_f32_16x16x32_bf16 v[96:99], v[172:175], v[196:199], v[96:99]
	v_mfma_f32_16x16x32_bf16 v[88:91], v[180:183], v[196:199], v[88:91]
	v_mfma_f32_16x16x32_bf16 v[80:83], v[172:175], v[210:213], v[80:83]
	v_mfma_f32_16x16x32_bf16 v[72:75], v[180:183], v[210:213], v[72:75]
	v_mfma_f32_16x16x32_bf16 v[68:71], v[172:175], v[218:221], v[68:71]
	v_mfma_f32_16x16x32_bf16 v[64:67], v[180:183], v[218:221], v[64:67]
	s_barrier
	s_setprio 0
	s_add_i32 s17, s17, s4
	v_lshl_add_u64 v[142:143], s[50:51], 0, v[132:133]
	s_mov_b32 m0, s17
	ds_read_b128 v[184:187], v145 offset:16384
	ds_read_b128 v[188:191], v145 offset:17408
	ds_read_b128 v[192:195], v145 offset:18432
	ds_read_b128 v[196:199], v145 offset:19456
	ds_read_b128 v[206:209], v145 offset:20480
	ds_read_b128 v[210:213], v145 offset:21504
	ds_read_b128 v[214:217], v145 offset:22528
	ds_read_b128 v[218:221], v145 offset:23552
	global_load_lds_dwordx4 v[142:143], off
	s_add_i32 m0, s17, 0x2000
	s_add_u32 s18, s50, 0x20000
	v_lshl_add_u64 v[158:159], s[50:51], 0, v[128:129]
	s_addc_u32 s19, s51, 0
	s_add_i32 s17, s20, s4
	global_load_lds_dwordx4 v[158:159], off
	v_lshl_add_u64 v[200:201], s[18:19], 0, v[132:133]
	s_mov_b32 m0, s17
	v_lshl_add_u64 v[222:223], s[62:63], 0, v[130:131]
	global_load_lds_dwordx4 v[200:201], off
	v_lshl_add_u64 v[200:201], s[18:19], 0, v[128:129]
	s_add_i32 m0, s17, 0x2000
	s_nop 0
	global_load_lds_dwordx4 v[200:201], off
	v_lshl_add_u64 v[200:201], s[62:63], 0, v[134:135]
	s_mov_b32 m0, s5
	s_nop 0
	global_load_lds_dwordx4 v[200:201], off
	s_mov_b32 m0, s6
	s_nop 0
	global_load_lds_dwordx4 v[222:223], off
	s_waitcnt vmcnt(8)
	s_waitcnt lgkmcnt(0)
	s_setprio 1
	s_barrier
	v_mfma_f32_16x16x32_bf16 v[60:63], v[146:149], v[184:187], 0
	v_mfma_f32_16x16x32_bf16 v[56:59], v[154:157], v[184:187], 0
	v_mfma_f32_16x16x32_bf16 v[52:55], v[146:149], v[192:195], 0
	v_mfma_f32_16x16x32_bf16 v[44:47], v[154:157], v[192:195], 0
	v_mfma_f32_16x16x32_bf16 v[36:39], v[146:149], v[206:209], 0
	v_mfma_f32_16x16x32_bf16 v[28:31], v[154:157], v[206:209], 0
	v_mfma_f32_16x16x32_bf16 v[20:23], v[146:149], v[214:217], 0
	v_mfma_f32_16x16x32_bf16 v[12:15], v[154:157], v[214:217], 0
	v_mfma_f32_16x16x32_bf16 v[60:63], v[150:153], v[188:191], v[60:63]
	v_mfma_f32_16x16x32_bf16 v[56:59], v[164:167], v[188:191], v[56:59]
	v_mfma_f32_16x16x32_bf16 v[52:55], v[150:153], v[196:199], v[52:55]
	v_mfma_f32_16x16x32_bf16 v[44:47], v[164:167], v[196:199], v[44:47]
	v_mfma_f32_16x16x32_bf16 v[36:39], v[150:153], v[210:213], v[36:39]
	v_mfma_f32_16x16x32_bf16 v[28:31], v[164:167], v[210:213], v[28:31]
	v_mfma_f32_16x16x32_bf16 v[20:23], v[150:153], v[218:221], v[20:23]
	v_mfma_f32_16x16x32_bf16 v[12:15], v[164:167], v[218:221], v[12:15]
	s_setprio 0
	s_setprio 1
	v_mfma_f32_16x16x32_bf16 v[48:51], v[168:171], v[184:187], 0
	v_mfma_f32_16x16x32_bf16 v[40:43], v[176:179], v[184:187], 0
	v_mfma_f32_16x16x32_bf16 v[32:35], v[168:171], v[192:195], 0
	v_mfma_f32_16x16x32_bf16 v[24:27], v[176:179], v[192:195], 0
	v_mfma_f32_16x16x32_bf16 v[16:19], v[168:171], v[206:209], 0
	v_mfma_f32_16x16x32_bf16 v[8:11], v[176:179], v[206:209], 0
	v_mfma_f32_16x16x32_bf16 v[4:7], v[168:171], v[214:217], 0
	v_mfma_f32_16x16x32_bf16 v[0:3], v[176:179], v[214:217], 0
	v_mfma_f32_16x16x32_bf16 v[48:51], v[172:175], v[188:191], v[48:51]
	v_mfma_f32_16x16x32_bf16 v[40:43], v[180:183], v[188:191], v[40:43]
	v_mfma_f32_16x16x32_bf16 v[32:35], v[172:175], v[196:199], v[32:35]
	v_mfma_f32_16x16x32_bf16 v[24:27], v[180:183], v[196:199], v[24:27]
	v_mfma_f32_16x16x32_bf16 v[16:19], v[172:175], v[210:213], v[16:19]
	v_mfma_f32_16x16x32_bf16 v[8:11], v[180:183], v[210:213], v[8:11]
	v_mfma_f32_16x16x32_bf16 v[4:7], v[172:175], v[218:221], v[4:7]
	v_mfma_f32_16x16x32_bf16 v[0:3], v[180:183], v[218:221], v[0:3]
	s_barrier
	s_setprio 0
	s_add_i32 s17, 0, 0x18000
	s_add_i32 s20, 0, 0x1c000
	v_add_u32_e32 v164, s17, v144
	v_add_u32_e32 v180, s20, v144
	ds_read_b128 v[146:149], v164
	ds_read_b128 v[150:153], v164 offset:1024
	ds_read_b128 v[154:157], v164 offset:2048
	ds_read_b128 v[164:167], v164 offset:3072
	ds_read_b128 v[168:171], v180
	ds_read_b128 v[172:175], v180 offset:1024
	ds_read_b128 v[176:179], v180 offset:2048
	ds_read_b128 v[180:183], v180 offset:3072
	s_add_u32 s18, s62, 0x20000
	s_addc_u32 s19, s63, 0
	s_mov_b32 m0, s7
	v_lshl_add_u64 v[224:225], s[18:19], 0, v[134:135]
	ds_read_b128 v[184:187], v145 offset:32768
	ds_read_b128 v[188:191], v145 offset:33792
	ds_read_b128 v[192:195], v145 offset:34816
	ds_read_b128 v[196:199], v145 offset:35840
	ds_read_b128 v[206:209], v145 offset:36864
	ds_read_b128 v[210:213], v145 offset:37888
	ds_read_b128 v[214:217], v145 offset:38912
	ds_read_b128 v[218:221], v145 offset:39936
	global_load_lds_dwordx4 v[224:225], off
	v_lshl_add_u64 v[224:225], s[18:19], 0, v[130:131]
	s_mov_b32 m0, s8
	s_nop 0
	global_load_lds_dwordx4 v[224:225], off
	s_waitcnt vmcnt(8)
	s_waitcnt lgkmcnt(0)
	s_setprio 1
	s_barrier
	v_mfma_f32_16x16x32_bf16 v[124:127], v[146:149], v[184:187], v[124:127]
	v_mfma_f32_16x16x32_bf16 v[120:123], v[154:157], v[184:187], v[120:123]
	v_mfma_f32_16x16x32_bf16 v[116:119], v[146:149], v[192:195], v[116:119]
	v_mfma_f32_16x16x32_bf16 v[108:111], v[154:157], v[192:195], v[108:111]
	v_mfma_f32_16x16x32_bf16 v[100:103], v[146:149], v[206:209], v[100:103]
	v_mfma_f32_16x16x32_bf16 v[92:95], v[154:157], v[206:209], v[92:95]
	v_mfma_f32_16x16x32_bf16 v[84:87], v[146:149], v[214:217], v[84:87]
	v_mfma_f32_16x16x32_bf16 v[76:79], v[154:157], v[214:217], v[76:79]
	v_mfma_f32_16x16x32_bf16 v[124:127], v[150:153], v[188:191], v[124:127]
	v_mfma_f32_16x16x32_bf16 v[120:123], v[164:167], v[188:191], v[120:123]
	v_mfma_f32_16x16x32_bf16 v[116:119], v[150:153], v[196:199], v[116:119]
	v_mfma_f32_16x16x32_bf16 v[108:111], v[164:167], v[196:199], v[108:111]
	v_mfma_f32_16x16x32_bf16 v[100:103], v[150:153], v[210:213], v[100:103]
	v_mfma_f32_16x16x32_bf16 v[92:95], v[164:167], v[210:213], v[92:95]
	v_mfma_f32_16x16x32_bf16 v[84:87], v[150:153], v[218:221], v[84:87]
	v_mfma_f32_16x16x32_bf16 v[76:79], v[164:167], v[218:221], v[76:79]
	s_setprio 0
	s_setprio 1
	v_mfma_f32_16x16x32_bf16 v[112:115], v[168:171], v[184:187], v[112:115]
	v_mfma_f32_16x16x32_bf16 v[104:107], v[176:179], v[184:187], v[104:107]
	v_mfma_f32_16x16x32_bf16 v[96:99], v[168:171], v[192:195], v[96:99]
	v_mfma_f32_16x16x32_bf16 v[88:91], v[176:179], v[192:195], v[88:91]
	v_mfma_f32_16x16x32_bf16 v[80:83], v[168:171], v[206:209], v[80:83]
	v_mfma_f32_16x16x32_bf16 v[72:75], v[176:179], v[206:209], v[72:75]
	v_mfma_f32_16x16x32_bf16 v[68:71], v[168:171], v[214:217], v[68:71]
	v_mfma_f32_16x16x32_bf16 v[64:67], v[176:179], v[214:217], v[64:67]
	v_mfma_f32_16x16x32_bf16 v[112:115], v[172:175], v[188:191], v[112:115]
	v_mfma_f32_16x16x32_bf16 v[104:107], v[180:183], v[188:191], v[104:107]
	v_mfma_f32_16x16x32_bf16 v[96:99], v[172:175], v[196:199], v[96:99]
	v_mfma_f32_16x16x32_bf16 v[88:91], v[180:183], v[196:199], v[88:91]
	v_mfma_f32_16x16x32_bf16 v[80:83], v[172:175], v[210:213], v[80:83]
	v_mfma_f32_16x16x32_bf16 v[72:75], v[180:183], v[210:213], v[72:75]
	v_mfma_f32_16x16x32_bf16 v[68:71], v[172:175], v[218:221], v[68:71]
	v_mfma_f32_16x16x32_bf16 v[64:67], v[180:183], v[218:221], v[64:67]
	s_barrier
	s_setprio 0
	s_add_i32 s17, s17, s4
	v_lshl_add_u64 v[142:143], v[142:143], 0, s[76:77]
	s_mov_b32 m0, s17
	ds_read_b128 v[184:187], v145 offset:49152
	ds_read_b128 v[188:191], v145 offset:50176
	ds_read_b128 v[192:195], v145 offset:51200
	ds_read_b128 v[196:199], v145 offset:52224
	ds_read_b128 v[206:209], v145 offset:53248
	ds_read_b128 v[210:213], v145 offset:54272
	ds_read_b128 v[214:217], v145 offset:55296
	ds_read_b128 v[218:221], v145 offset:56320
	global_load_lds_dwordx4 v[142:143], off
	s_add_i32 m0, s17, 0x2000
	s_add_u32 s18, s50, 0x20080
	v_lshl_add_u64 v[142:143], v[158:159], 0, s[76:77]
	s_addc_u32 s19, s51, 0
	s_add_i32 s17, s20, s4
	global_load_lds_dwordx4 v[142:143], off
	v_lshl_add_u64 v[142:143], s[18:19], 0, v[132:133]
	s_mov_b32 m0, s17
	s_nop 0
	global_load_lds_dwordx4 v[142:143], off
	v_lshl_add_u64 v[142:143], s[18:19], 0, v[128:129]
	s_add_i32 m0, s17, 0x2000
	s_nop 0
	global_load_lds_dwordx4 v[142:143], off
	v_lshl_add_u64 v[142:143], v[200:201], 0, s[76:77]
	s_mov_b32 m0, s9
	s_nop 0
	global_load_lds_dwordx4 v[142:143], off
	v_lshl_add_u64 v[142:143], v[222:223], 0, s[76:77]
	s_mov_b32 m0, s10
	s_nop 0
	global_load_lds_dwordx4 v[142:143], off
	s_waitcnt vmcnt(8)
	s_waitcnt lgkmcnt(0)
	s_setprio 1
	s_barrier
	v_mfma_f32_16x16x32_bf16 v[60:63], v[146:149], v[184:187], v[60:63]
	v_mfma_f32_16x16x32_bf16 v[56:59], v[154:157], v[184:187], v[56:59]
	v_mfma_f32_16x16x32_bf16 v[52:55], v[146:149], v[192:195], v[52:55]
	v_mfma_f32_16x16x32_bf16 v[44:47], v[154:157], v[192:195], v[44:47]
	v_mfma_f32_16x16x32_bf16 v[36:39], v[146:149], v[206:209], v[36:39]
	v_mfma_f32_16x16x32_bf16 v[28:31], v[154:157], v[206:209], v[28:31]
	v_mfma_f32_16x16x32_bf16 v[20:23], v[146:149], v[214:217], v[20:23]
	v_mfma_f32_16x16x32_bf16 v[12:15], v[154:157], v[214:217], v[12:15]
	v_mfma_f32_16x16x32_bf16 v[60:63], v[150:153], v[188:191], v[60:63]
	v_mfma_f32_16x16x32_bf16 v[56:59], v[164:167], v[188:191], v[56:59]
	v_mfma_f32_16x16x32_bf16 v[52:55], v[150:153], v[196:199], v[52:55]
	v_mfma_f32_16x16x32_bf16 v[44:47], v[164:167], v[196:199], v[44:47]
	v_mfma_f32_16x16x32_bf16 v[36:39], v[150:153], v[210:213], v[36:39]
	v_mfma_f32_16x16x32_bf16 v[28:31], v[164:167], v[210:213], v[28:31]
	v_mfma_f32_16x16x32_bf16 v[20:23], v[150:153], v[218:221], v[20:23]
	v_mfma_f32_16x16x32_bf16 v[12:15], v[164:167], v[218:221], v[12:15]
	s_setprio 0
	s_setprio 1
	v_mfma_f32_16x16x32_bf16 v[48:51], v[168:171], v[184:187], v[48:51]
	v_mfma_f32_16x16x32_bf16 v[40:43], v[176:179], v[184:187], v[40:43]
	v_mfma_f32_16x16x32_bf16 v[32:35], v[168:171], v[192:195], v[32:35]
	v_mfma_f32_16x16x32_bf16 v[24:27], v[176:179], v[192:195], v[24:27]
	v_mfma_f32_16x16x32_bf16 v[16:19], v[168:171], v[206:209], v[16:19]
	v_mfma_f32_16x16x32_bf16 v[8:11], v[176:179], v[206:209], v[8:11]
	v_mfma_f32_16x16x32_bf16 v[4:7], v[168:171], v[214:217], v[4:7]
	v_mfma_f32_16x16x32_bf16 v[0:3], v[176:179], v[214:217], v[0:3]
	v_mfma_f32_16x16x32_bf16 v[48:51], v[172:175], v[188:191], v[48:51]
	v_mfma_f32_16x16x32_bf16 v[40:43], v[180:183], v[188:191], v[40:43]
	v_mfma_f32_16x16x32_bf16 v[32:35], v[172:175], v[196:199], v[32:35]
	v_mfma_f32_16x16x32_bf16 v[24:27], v[180:183], v[196:199], v[24:27]
	v_mfma_f32_16x16x32_bf16 v[16:19], v[172:175], v[210:213], v[16:19]
	v_mfma_f32_16x16x32_bf16 v[8:11], v[180:183], v[210:213], v[8:11]
	v_mfma_f32_16x16x32_bf16 v[4:7], v[172:175], v[218:221], v[4:7]
	v_mfma_f32_16x16x32_bf16 v[0:3], v[180:183], v[218:221], v[0:3]
	s_barrier
	s_setprio 0
	s_add_i32 s16, s16, 2
	s_cmp_gt_u32 s16, 5
	s_mov_b64 s[58:59], s[60:61]
	s_cbranch_scc0 .LBB0_914
	s_branch .Lpeel_x_914
.LBB0_914:
	s_add_u32 s60, s58, 0x100
	s_addc_u32 s61, s59, 0
	s_add_u32 s17, s14, s58
	s_addc_u32 s18, s15, s59
	s_cmp_eq_u32 s16, 4
	s_cselect_b32 s20, 0, s60
	s_cselect_b32 s19, 0, s61
	s_cselect_b32 s50, s42, s17
	s_cselect_b32 s51, s43, s18
	s_add_u32 s62, s88, s20
	s_addc_u32 s63, s89, s19
	s_add_i32 s17, 0, 0x10000
	v_add_u32_e32 v142, s17, v144
	s_add_i32 s20, 0, 0x14000
	ds_read_b128 v[146:149], v142
	ds_read_b128 v[150:153], v142 offset:1024
	ds_read_b128 v[154:157], v142 offset:2048
	ds_read_b128 v[164:167], v142 offset:3072
	v_add_u32_e32 v142, s20, v144
	ds_read_b128 v[168:171], v142
	ds_read_b128 v[172:175], v142 offset:1024
	ds_read_b128 v[176:179], v142 offset:2048
	ds_read_b128 v[180:183], v142 offset:3072
	v_lshl_add_u64 v[142:143], v[138:139], 0, s[58:59]
	s_add_i32 m0, s5, 0xc000
	ds_read_b128 v[184:187], v145
	ds_read_b128 v[188:191], v145 offset:1024
	ds_read_b128 v[192:195], v145 offset:2048
	ds_read_b128 v[196:199], v145 offset:3072
	ds_read_b128 v[206:209], v145 offset:4096
	ds_read_b128 v[210:213], v145 offset:5120
	ds_read_b128 v[214:217], v145 offset:6144
	ds_read_b128 v[218:221], v145 offset:7168
	global_load_lds_dwordx4 v[142:143], off
	v_lshl_add_u64 v[142:143], v[140:141], 0, s[58:59]
	s_add_i32 m0, s5, 0xe000
	s_nop 0
	global_load_lds_dwordx4 v[142:143], off
	s_waitcnt vmcnt(8)
	s_waitcnt lgkmcnt(0)
	s_setprio 1
	s_barrier
	v_mfma_f32_16x16x32_bf16 v[124:127], v[146:149], v[184:187], v[124:127]
	v_mfma_f32_16x16x32_bf16 v[120:123], v[154:157], v[184:187], v[120:123]
	v_mfma_f32_16x16x32_bf16 v[116:119], v[146:149], v[192:195], v[116:119]
	v_mfma_f32_16x16x32_bf16 v[108:111], v[154:157], v[192:195], v[108:111]
	v_mfma_f32_16x16x32_bf16 v[100:103], v[146:149], v[206:209], v[100:103]
	v_mfma_f32_16x16x32_bf16 v[92:95], v[154:157], v[206:209], v[92:95]
	v_mfma_f32_16x16x32_bf16 v[84:87], v[146:149], v[214:217], v[84:87]
	v_mfma_f32_16x16x32_bf16 v[76:79], v[154:157], v[214:217], v[76:79]
	v_mfma_f32_16x16x32_bf16 v[124:127], v[150:153], v[188:191], v[124:127]
	v_mfma_f32_16x16x32_bf16 v[120:123], v[164:167], v[188:191], v[120:123]
	v_mfma_f32_16x16x32_bf16 v[116:119], v[150:153], v[196:199], v[116:119]
	v_mfma_f32_16x16x32_bf16 v[108:111], v[164:167], v[196:199], v[108:111]
	v_mfma_f32_16x16x32_bf16 v[100:103], v[150:153], v[210:213], v[100:103]
	v_mfma_f32_16x16x32_bf16 v[92:95], v[164:167], v[210:213], v[92:95]
	v_mfma_f32_16x16x32_bf16 v[84:87], v[150:153], v[218:221], v[84:87]
	v_mfma_f32_16x16x32_bf16 v[76:79], v[164:167], v[218:221], v[76:79]
	s_setprio 0
	s_setprio 1
	v_mfma_f32_16x16x32_bf16 v[112:115], v[168:171], v[184:187], v[112:115]
	v_mfma_f32_16x16x32_bf16 v[104:107], v[176:179], v[184:187], v[104:107]
	v_mfma_f32_16x16x32_bf16 v[96:99], v[168:171], v[192:195], v[96:99]
	v_mfma_f32_16x16x32_bf16 v[88:91], v[176:179], v[192:195], v[88:91]
	v_mfma_f32_16x16x32_bf16 v[80:83], v[168:171], v[206:209], v[80:83]
	v_mfma_f32_16x16x32_bf16 v[72:75], v[176:179], v[206:209], v[72:75]
	v_mfma_f32_16x16x32_bf16 v[68:71], v[168:171], v[214:217], v[68:71]
	v_mfma_f32_16x16x32_bf16 v[64:67], v[176:179], v[214:217], v[64:67]
	v_mfma_f32_16x16x32_bf16 v[112:115], v[172:175], v[188:191], v[112:115]
	v_mfma_f32_16x16x32_bf16 v[104:107], v[180:183], v[188:191], v[104:107]
	v_mfma_f32_16x16x32_bf16 v[96:99], v[172:175], v[196:199], v[96:99]
	v_mfma_f32_16x16x32_bf16 v[88:91], v[180:183], v[196:199], v[88:91]
	v_mfma_f32_16x16x32_bf16 v[80:83], v[172:175], v[210:213], v[80:83]
	v_mfma_f32_16x16x32_bf16 v[72:75], v[180:183], v[210:213], v[72:75]
	v_mfma_f32_16x16x32_bf16 v[68:71], v[172:175], v[218:221], v[68:71]
	v_mfma_f32_16x16x32_bf16 v[64:67], v[180:183], v[218:221], v[64:67]
	s_barrier
	s_setprio 0
	s_add_i32 s17, s17, s4
	v_lshl_add_u64 v[142:143], s[50:51], 0, v[132:133]
	s_mov_b32 m0, s17
	ds_read_b128 v[184:187], v145 offset:16384
	ds_read_b128 v[188:191], v145 offset:17408
	ds_read_b128 v[192:195], v145 offset:18432
	ds_read_b128 v[196:199], v145 offset:19456
	ds_read_b128 v[206:209], v145 offset:20480
	ds_read_b128 v[210:213], v145 offset:21504
	ds_read_b128 v[214:217], v145 offset:22528
	ds_read_b128 v[218:221], v145 offset:23552
	global_load_lds_dwordx4 v[142:143], off
	s_add_i32 m0, s17, 0x2000
	s_add_u32 s18, s50, 0x20000
	v_lshl_add_u64 v[158:159], s[50:51], 0, v[128:129]
	s_addc_u32 s19, s51, 0
	s_add_i32 s17, s20, s4
	global_load_lds_dwordx4 v[158:159], off
	v_lshl_add_u64 v[200:201], s[18:19], 0, v[132:133]
	s_mov_b32 m0, s17
	v_lshl_add_u64 v[222:223], s[62:63], 0, v[130:131]
	global_load_lds_dwordx4 v[200:201], off
	v_lshl_add_u64 v[200:201], s[18:19], 0, v[128:129]
	s_add_i32 m0, s17, 0x2000
	s_nop 0
	global_load_lds_dwordx4 v[200:201], off
	v_lshl_add_u64 v[200:201], s[62:63], 0, v[134:135]
	s_mov_b32 m0, s5
	s_nop 0
	global_load_lds_dwordx4 v[200:201], off
	s_mov_b32 m0, s6
	s_nop 0
	global_load_lds_dwordx4 v[222:223], off
	s_waitcnt vmcnt(8)
	s_waitcnt lgkmcnt(0)
	s_setprio 1
	s_barrier
	v_mfma_f32_16x16x32_bf16 v[60:63], v[146:149], v[184:187], v[60:63]
	v_mfma_f32_16x16x32_bf16 v[56:59], v[154:157], v[184:187], v[56:59]
	v_mfma_f32_16x16x32_bf16 v[52:55], v[146:149], v[192:195], v[52:55]
	v_mfma_f32_16x16x32_bf16 v[44:47], v[154:157], v[192:195], v[44:47]
	v_mfma_f32_16x16x32_bf16 v[36:39], v[146:149], v[206:209], v[36:39]
	v_mfma_f32_16x16x32_bf16 v[28:31], v[154:157], v[206:209], v[28:31]
	v_mfma_f32_16x16x32_bf16 v[20:23], v[146:149], v[214:217], v[20:23]
	v_mfma_f32_16x16x32_bf16 v[12:15], v[154:157], v[214:217], v[12:15]
	v_mfma_f32_16x16x32_bf16 v[60:63], v[150:153], v[188:191], v[60:63]
	v_mfma_f32_16x16x32_bf16 v[56:59], v[164:167], v[188:191], v[56:59]
	v_mfma_f32_16x16x32_bf16 v[52:55], v[150:153], v[196:199], v[52:55]
	v_mfma_f32_16x16x32_bf16 v[44:47], v[164:167], v[196:199], v[44:47]
	v_mfma_f32_16x16x32_bf16 v[36:39], v[150:153], v[210:213], v[36:39]
	v_mfma_f32_16x16x32_bf16 v[28:31], v[164:167], v[210:213], v[28:31]
	v_mfma_f32_16x16x32_bf16 v[20:23], v[150:153], v[218:221], v[20:23]
	v_mfma_f32_16x16x32_bf16 v[12:15], v[164:167], v[218:221], v[12:15]
	s_setprio 0
	s_setprio 1
	v_mfma_f32_16x16x32_bf16 v[48:51], v[168:171], v[184:187], v[48:51]
	v_mfma_f32_16x16x32_bf16 v[40:43], v[176:179], v[184:187], v[40:43]
	v_mfma_f32_16x16x32_bf16 v[32:35], v[168:171], v[192:195], v[32:35]
	v_mfma_f32_16x16x32_bf16 v[24:27], v[176:179], v[192:195], v[24:27]
	v_mfma_f32_16x16x32_bf16 v[16:19], v[168:171], v[206:209], v[16:19]
	v_mfma_f32_16x16x32_bf16 v[8:11], v[176:179], v[206:209], v[8:11]
	v_mfma_f32_16x16x32_bf16 v[4:7], v[168:171], v[214:217], v[4:7]
	v_mfma_f32_16x16x32_bf16 v[0:3], v[176:179], v[214:217], v[0:3]
	v_mfma_f32_16x16x32_bf16 v[48:51], v[172:175], v[188:191], v[48:51]
	v_mfma_f32_16x16x32_bf16 v[40:43], v[180:183], v[188:191], v[40:43]
	v_mfma_f32_16x16x32_bf16 v[32:35], v[172:175], v[196:199], v[32:35]
	v_mfma_f32_16x16x32_bf16 v[24:27], v[180:183], v[196:199], v[24:27]
	v_mfma_f32_16x16x32_bf16 v[16:19], v[172:175], v[210:213], v[16:19]
	v_mfma_f32_16x16x32_bf16 v[8:11], v[180:183], v[210:213], v[8:11]
	v_mfma_f32_16x16x32_bf16 v[4:7], v[172:175], v[218:221], v[4:7]
	v_mfma_f32_16x16x32_bf16 v[0:3], v[180:183], v[218:221], v[0:3]
	s_barrier
	s_setprio 0
	s_add_i32 s17, 0, 0x18000
	s_add_i32 s20, 0, 0x1c000
	v_add_u32_e32 v164, s17, v144
	v_add_u32_e32 v180, s20, v144
	ds_read_b128 v[146:149], v164
	ds_read_b128 v[150:153], v164 offset:1024
	ds_read_b128 v[154:157], v164 offset:2048
	ds_read_b128 v[164:167], v164 offset:3072
	ds_read_b128 v[168:171], v180
	ds_read_b128 v[172:175], v180 offset:1024
	ds_read_b128 v[176:179], v180 offset:2048
	ds_read_b128 v[180:183], v180 offset:3072
	s_add_u32 s18, s62, 0x20000
	s_addc_u32 s19, s63, 0
	s_mov_b32 m0, s7
	v_lshl_add_u64 v[224:225], s[18:19], 0, v[134:135]
	ds_read_b128 v[184:187], v145 offset:32768
	ds_read_b128 v[188:191], v145 offset:33792
	ds_read_b128 v[192:195], v145 offset:34816
	ds_read_b128 v[196:199], v145 offset:35840
	ds_read_b128 v[206:209], v145 offset:36864
	ds_read_b128 v[210:213], v145 offset:37888
	ds_read_b128 v[214:217], v145 offset:38912
	ds_read_b128 v[218:221], v145 offset:39936
	global_load_lds_dwordx4 v[224:225], off
	v_lshl_add_u64 v[224:225], s[18:19], 0, v[130:131]
	s_mov_b32 m0, s8
	s_nop 0
	global_load_lds_dwordx4 v[224:225], off
	s_waitcnt vmcnt(8)
	s_waitcnt lgkmcnt(0)
	s_setprio 1
	s_barrier
	v_mfma_f32_16x16x32_bf16 v[124:127], v[146:149], v[184:187], v[124:127]
	v_mfma_f32_16x16x32_bf16 v[120:123], v[154:157], v[184:187], v[120:123]
	v_mfma_f32_16x16x32_bf16 v[116:119], v[146:149], v[192:195], v[116:119]
	v_mfma_f32_16x16x32_bf16 v[108:111], v[154:157], v[192:195], v[108:111]
	v_mfma_f32_16x16x32_bf16 v[100:103], v[146:149], v[206:209], v[100:103]
	v_mfma_f32_16x16x32_bf16 v[92:95], v[154:157], v[206:209], v[92:95]
	v_mfma_f32_16x16x32_bf16 v[84:87], v[146:149], v[214:217], v[84:87]
	v_mfma_f32_16x16x32_bf16 v[76:79], v[154:157], v[214:217], v[76:79]
	v_mfma_f32_16x16x32_bf16 v[124:127], v[150:153], v[188:191], v[124:127]
	v_mfma_f32_16x16x32_bf16 v[120:123], v[164:167], v[188:191], v[120:123]
	v_mfma_f32_16x16x32_bf16 v[116:119], v[150:153], v[196:199], v[116:119]
	v_mfma_f32_16x16x32_bf16 v[108:111], v[164:167], v[196:199], v[108:111]
	v_mfma_f32_16x16x32_bf16 v[100:103], v[150:153], v[210:213], v[100:103]
	v_mfma_f32_16x16x32_bf16 v[92:95], v[164:167], v[210:213], v[92:95]
	v_mfma_f32_16x16x32_bf16 v[84:87], v[150:153], v[218:221], v[84:87]
	v_mfma_f32_16x16x32_bf16 v[76:79], v[164:167], v[218:221], v[76:79]
	s_setprio 0
	s_setprio 1
	v_mfma_f32_16x16x32_bf16 v[112:115], v[168:171], v[184:187], v[112:115]
	v_mfma_f32_16x16x32_bf16 v[104:107], v[176:179], v[184:187], v[104:107]
	v_mfma_f32_16x16x32_bf16 v[96:99], v[168:171], v[192:195], v[96:99]
	v_mfma_f32_16x16x32_bf16 v[88:91], v[176:179], v[192:195], v[88:91]
	v_mfma_f32_16x16x32_bf16 v[80:83], v[168:171], v[206:209], v[80:83]
	v_mfma_f32_16x16x32_bf16 v[72:75], v[176:179], v[206:209], v[72:75]
	v_mfma_f32_16x16x32_bf16 v[68:71], v[168:171], v[214:217], v[68:71]
	v_mfma_f32_16x16x32_bf16 v[64:67], v[176:179], v[214:217], v[64:67]
	v_mfma_f32_16x16x32_bf16 v[112:115], v[172:175], v[188:191], v[112:115]
	v_mfma_f32_16x16x32_bf16 v[104:107], v[180:183], v[188:191], v[104:107]
	v_mfma_f32_16x16x32_bf16 v[96:99], v[172:175], v[196:199], v[96:99]
	v_mfma_f32_16x16x32_bf16 v[88:91], v[180:183], v[196:199], v[88:91]
	v_mfma_f32_16x16x32_bf16 v[80:83], v[172:175], v[210:213], v[80:83]
	v_mfma_f32_16x16x32_bf16 v[72:75], v[180:183], v[210:213], v[72:75]
	v_mfma_f32_16x16x32_bf16 v[68:71], v[172:175], v[218:221], v[68:71]
	v_mfma_f32_16x16x32_bf16 v[64:67], v[180:183], v[218:221], v[64:67]
	s_barrier
	s_setprio 0
	s_add_i32 s17, s17, s4
	v_lshl_add_u64 v[142:143], v[142:143], 0, s[76:77]
	s_mov_b32 m0, s17
	ds_read_b128 v[184:187], v145 offset:49152
	ds_read_b128 v[188:191], v145 offset:50176
	ds_read_b128 v[192:195], v145 offset:51200
	ds_read_b128 v[196:199], v145 offset:52224
	ds_read_b128 v[206:209], v145 offset:53248
	ds_read_b128 v[210:213], v145 offset:54272
	ds_read_b128 v[214:217], v145 offset:55296
	ds_read_b128 v[218:221], v145 offset:56320
	global_load_lds_dwordx4 v[142:143], off
	s_add_i32 m0, s17, 0x2000
	s_add_u32 s18, s50, 0x20080
	v_lshl_add_u64 v[142:143], v[158:159], 0, s[76:77]
	s_addc_u32 s19, s51, 0
	s_add_i32 s17, s20, s4
	global_load_lds_dwordx4 v[142:143], off
	v_lshl_add_u64 v[142:143], s[18:19], 0, v[132:133]
	s_mov_b32 m0, s17
	s_nop 0
	global_load_lds_dwordx4 v[142:143], off
	v_lshl_add_u64 v[142:143], s[18:19], 0, v[128:129]
	s_add_i32 m0, s17, 0x2000
	s_nop 0
	global_load_lds_dwordx4 v[142:143], off
	v_lshl_add_u64 v[142:143], v[200:201], 0, s[76:77]
	s_mov_b32 m0, s9
	s_nop 0
	global_load_lds_dwordx4 v[142:143], off
	v_lshl_add_u64 v[142:143], v[222:223], 0, s[76:77]
	s_mov_b32 m0, s10
	s_nop 0
	global_load_lds_dwordx4 v[142:143], off
	s_waitcnt vmcnt(8)
	s_waitcnt lgkmcnt(0)
	s_setprio 1
	s_barrier
	v_mfma_f32_16x16x32_bf16 v[60:63], v[146:149], v[184:187], v[60:63]
	v_mfma_f32_16x16x32_bf16 v[56:59], v[154:157], v[184:187], v[56:59]
	v_mfma_f32_16x16x32_bf16 v[52:55], v[146:149], v[192:195], v[52:55]
	v_mfma_f32_16x16x32_bf16 v[44:47], v[154:157], v[192:195], v[44:47]
	v_mfma_f32_16x16x32_bf16 v[36:39], v[146:149], v[206:209], v[36:39]
	v_mfma_f32_16x16x32_bf16 v[28:31], v[154:157], v[206:209], v[28:31]
	v_mfma_f32_16x16x32_bf16 v[20:23], v[146:149], v[214:217], v[20:23]
	v_mfma_f32_16x16x32_bf16 v[12:15], v[154:157], v[214:217], v[12:15]
	v_mfma_f32_16x16x32_bf16 v[60:63], v[150:153], v[188:191], v[60:63]
	v_mfma_f32_16x16x32_bf16 v[56:59], v[164:167], v[188:191], v[56:59]
	v_mfma_f32_16x16x32_bf16 v[52:55], v[150:153], v[196:199], v[52:55]
	v_mfma_f32_16x16x32_bf16 v[44:47], v[164:167], v[196:199], v[44:47]
	v_mfma_f32_16x16x32_bf16 v[36:39], v[150:153], v[210:213], v[36:39]
	v_mfma_f32_16x16x32_bf16 v[28:31], v[164:167], v[210:213], v[28:31]
	v_mfma_f32_16x16x32_bf16 v[20:23], v[150:153], v[218:221], v[20:23]
	v_mfma_f32_16x16x32_bf16 v[12:15], v[164:167], v[218:221], v[12:15]
	s_setprio 0
	s_setprio 1
	v_mfma_f32_16x16x32_bf16 v[48:51], v[168:171], v[184:187], v[48:51]
	v_mfma_f32_16x16x32_bf16 v[40:43], v[176:179], v[184:187], v[40:43]
	v_mfma_f32_16x16x32_bf16 v[32:35], v[168:171], v[192:195], v[32:35]
	v_mfma_f32_16x16x32_bf16 v[24:27], v[176:179], v[192:195], v[24:27]
	v_mfma_f32_16x16x32_bf16 v[16:19], v[168:171], v[206:209], v[16:19]
	v_mfma_f32_16x16x32_bf16 v[8:11], v[176:179], v[206:209], v[8:11]
	v_mfma_f32_16x16x32_bf16 v[4:7], v[168:171], v[214:217], v[4:7]
	v_mfma_f32_16x16x32_bf16 v[0:3], v[176:179], v[214:217], v[0:3]
	v_mfma_f32_16x16x32_bf16 v[48:51], v[172:175], v[188:191], v[48:51]
	v_mfma_f32_16x16x32_bf16 v[40:43], v[180:183], v[188:191], v[40:43]
	v_mfma_f32_16x16x32_bf16 v[32:35], v[172:175], v[196:199], v[32:35]
	v_mfma_f32_16x16x32_bf16 v[24:27], v[180:183], v[196:199], v[24:27]
	v_mfma_f32_16x16x32_bf16 v[16:19], v[172:175], v[210:213], v[16:19]
	v_mfma_f32_16x16x32_bf16 v[8:11], v[180:183], v[210:213], v[8:11]
	v_mfma_f32_16x16x32_bf16 v[4:7], v[172:175], v[218:221], v[4:7]
	v_mfma_f32_16x16x32_bf16 v[0:3], v[180:183], v[218:221], v[0:3]
	s_barrier
	s_setprio 0
	s_add_i32 s16, s16, 2
	s_cmp_gt_u32 s16, 5
	s_mov_b64 s[58:59], s[60:61]
	s_cbranch_scc0 .LBB0_914

.LBB0_982:
	s_ashr_i32 s37, s36, 31
	s_lshl_b64 s[16:17], s[36:37], 19
	s_add_u32 s40, s94, s16
	s_addc_u32 s41, s95, s17
	s_and_b64 s[16:17], s[42:43], exec
	s_cselect_b32 s15, s41, s51
	s_cselect_b32 s16, s40, s50
	s_ashr_i32 s39, s38, 31
	s_lshl_b64 s[18:19], s[38:39], 19
	s_add_u32 s48, s22, s18
	s_addc_u32 s49, s23, s19
	s_and_b64 s[18:19], s[42:43], exec
	s_cselect_b32 s17, s49, s61
	s_cselect_b32 s37, s48, s60
	s_add_u32 s58, s50, 0x40080
	s_addc_u32 s59, s51, 0
	s_add_u32 s39, s60, 0x100
	s_addc_u32 s47, s61, 0
	s_mov_b32 s54, -2
	s_add_u32 s18, s58, 0xfffc0080
	s_addc_u32 s19, s59, -1
	s_add_i32 s20, 0, 0x10000
	s_cmp_eq_u32 s54, 12
	s_cselect_b32 s61, s15, s19
	s_cselect_b32 s60, s16, s18
	s_cselect_b32 s51, s17, s47
	s_cselect_b32 s50, s37, s39
	s_add_i32 s21, 0, 0x14000
	v_add_u32_e32 v140, s20, v174
	v_add_u32_e32 v162, s21, v174
	ds_read_b128 v[128:131], v140
	ds_read_b128 v[132:135], v140 offset:1024
	ds_read_b128 v[136:139], v140 offset:2048
	ds_read_b128 v[140:143], v140 offset:3072
	ds_read_b128 v[156:159], v162
	ds_read_b128 v[164:167], v162 offset:1024
	ds_read_b128 v[168:171], v162 offset:2048
	ds_read_b128 v[176:179], v162 offset:3072
	v_lshl_add_u64 v[200:201], s[58:59], 0, v[152:153]
	s_add_i32 m0, s4, 0xc000
	ds_read_b128 v[180:183], v175
	ds_read_b128 v[184:187], v175 offset:1024
	ds_read_b128 v[188:191], v175 offset:2048
	ds_read_b128 v[192:195], v175 offset:3072
	ds_read_b128 v[196:199], v175 offset:4096
	ds_read_b128 v[206:209], v175 offset:5120
	ds_read_b128 v[210:213], v175 offset:6144
	ds_read_b128 v[214:217], v175 offset:7168
	global_load_lds_dwordx4 v[200:201], off
	v_lshl_add_u64 v[200:201], s[58:59], 0, v[154:155]
	s_add_i32 m0, s4, 0xe000
	s_nop 0
	global_load_lds_dwordx4 v[200:201], off
	s_waitcnt vmcnt(8)
	s_waitcnt lgkmcnt(0)
	s_setprio 1
	s_barrier
	v_mfma_f32_16x16x32_bf16 v[124:127], v[128:131], v[180:183], 0
	v_mfma_f32_16x16x32_bf16 v[120:123], v[136:139], v[180:183], 0
	v_mfma_f32_16x16x32_bf16 v[112:115], v[128:131], v[188:191], 0
	v_mfma_f32_16x16x32_bf16 v[104:107], v[136:139], v[188:191], 0
	v_mfma_f32_16x16x32_bf16 v[96:99], v[128:131], v[196:199], 0
	v_mfma_f32_16x16x32_bf16 v[88:91], v[136:139], v[196:199], 0
	v_mfma_f32_16x16x32_bf16 v[80:83], v[128:131], v[210:213], 0
	v_mfma_f32_16x16x32_bf16 v[72:75], v[136:139], v[210:213], 0
	v_mfma_f32_16x16x32_bf16 v[124:127], v[132:135], v[184:187], v[124:127]
	v_mfma_f32_16x16x32_bf16 v[120:123], v[140:143], v[184:187], v[120:123]
	v_mfma_f32_16x16x32_bf16 v[112:115], v[132:135], v[192:195], v[112:115]
	v_mfma_f32_16x16x32_bf16 v[104:107], v[140:143], v[192:195], v[104:107]
	v_mfma_f32_16x16x32_bf16 v[96:99], v[132:135], v[206:209], v[96:99]
	v_mfma_f32_16x16x32_bf16 v[88:91], v[140:143], v[206:209], v[88:91]
	v_mfma_f32_16x16x32_bf16 v[80:83], v[132:135], v[214:217], v[80:83]
	v_mfma_f32_16x16x32_bf16 v[72:75], v[140:143], v[214:217], v[72:75]
	s_setprio 0
	s_setprio 1
	v_mfma_f32_16x16x32_bf16 v[116:119], v[156:159], v[180:183], 0
	v_mfma_f32_16x16x32_bf16 v[108:111], v[168:171], v[180:183], 0
	v_mfma_f32_16x16x32_bf16 v[100:103], v[156:159], v[188:191], 0
	v_mfma_f32_16x16x32_bf16 v[92:95], v[168:171], v[188:191], 0
	v_mfma_f32_16x16x32_bf16 v[84:87], v[156:159], v[196:199], 0
	v_mfma_f32_16x16x32_bf16 v[76:79], v[168:171], v[196:199], 0
	v_mfma_f32_16x16x32_bf16 v[68:71], v[156:159], v[210:213], 0
	v_mfma_f32_16x16x32_bf16 v[64:67], v[168:171], v[210:213], 0
	v_mfma_f32_16x16x32_bf16 v[116:119], v[164:167], v[184:187], v[116:119]
	v_mfma_f32_16x16x32_bf16 v[108:111], v[176:179], v[184:187], v[108:111]
	v_mfma_f32_16x16x32_bf16 v[100:103], v[164:167], v[192:195], v[100:103]
	v_mfma_f32_16x16x32_bf16 v[92:95], v[176:179], v[192:195], v[92:95]
	v_mfma_f32_16x16x32_bf16 v[84:87], v[164:167], v[206:209], v[84:87]
	v_mfma_f32_16x16x32_bf16 v[76:79], v[176:179], v[206:209], v[76:79]
	v_mfma_f32_16x16x32_bf16 v[68:71], v[164:167], v[214:217], v[68:71]
	v_mfma_f32_16x16x32_bf16 v[64:67], v[176:179], v[214:217], v[64:67]
	s_barrier
	s_setprio 0
	s_add_i32 s18, s20, s46
	v_lshl_add_u64 v[200:201], s[50:51], 0, v[148:149]
	s_mov_b32 m0, s18
	ds_read_b128 v[180:183], v175 offset:16384
	ds_read_b128 v[184:187], v175 offset:17408
	ds_read_b128 v[188:191], v175 offset:18432
	ds_read_b128 v[192:195], v175 offset:19456
	ds_read_b128 v[196:199], v175 offset:20480
	ds_read_b128 v[206:209], v175 offset:21504
	ds_read_b128 v[210:213], v175 offset:22528
	ds_read_b128 v[214:217], v175 offset:23552
	global_load_lds_dwordx4 v[200:201], off
	s_add_i32 m0, s18, 0x2000
	s_add_u32 s18, s50, 0x40000
	v_lshl_add_u64 v[218:219], s[50:51], 0, v[144:145]
	s_addc_u32 s19, s51, 0
	s_add_i32 s20, s21, s46
	global_load_lds_dwordx4 v[218:219], off
	v_lshl_add_u64 v[220:221], s[18:19], 0, v[148:149]
	s_mov_b32 m0, s20
	v_lshl_add_u64 v[222:223], s[60:61], 0, v[146:147]
	global_load_lds_dwordx4 v[220:221], off
	v_lshl_add_u64 v[220:221], s[18:19], 0, v[144:145]
	s_add_i32 m0, s20, 0x2000
	s_nop 0
	global_load_lds_dwordx4 v[220:221], off
	v_lshl_add_u64 v[220:221], s[60:61], 0, v[150:151]
	s_mov_b32 m0, s4
	s_nop 0
	global_load_lds_dwordx4 v[220:221], off
	s_mov_b32 m0, s5
	s_nop 0
	global_load_lds_dwordx4 v[222:223], off
	s_waitcnt vmcnt(8)
	s_waitcnt lgkmcnt(0)
	s_setprio 1
	s_barrier
	v_mfma_f32_16x16x32_bf16 v[60:63], v[128:131], v[180:183], 0
	v_mfma_f32_16x16x32_bf16 v[56:59], v[136:139], v[180:183], 0
	v_mfma_f32_16x16x32_bf16 v[48:51], v[128:131], v[188:191], 0
	v_mfma_f32_16x16x32_bf16 v[40:43], v[136:139], v[188:191], 0
	v_mfma_f32_16x16x32_bf16 v[32:35], v[128:131], v[196:199], 0
	v_mfma_f32_16x16x32_bf16 v[24:27], v[136:139], v[196:199], 0
	v_mfma_f32_16x16x32_bf16 v[16:19], v[128:131], v[210:213], 0
	v_mfma_f32_16x16x32_bf16 v[8:11], v[136:139], v[210:213], 0
	v_mfma_f32_16x16x32_bf16 v[60:63], v[132:135], v[184:187], v[60:63]
	v_mfma_f32_16x16x32_bf16 v[56:59], v[140:143], v[184:187], v[56:59]
	v_mfma_f32_16x16x32_bf16 v[48:51], v[132:135], v[192:195], v[48:51]
	v_mfma_f32_16x16x32_bf16 v[40:43], v[140:143], v[192:195], v[40:43]
	v_mfma_f32_16x16x32_bf16 v[32:35], v[132:135], v[206:209], v[32:35]
	v_mfma_f32_16x16x32_bf16 v[24:27], v[140:143], v[206:209], v[24:27]
	v_mfma_f32_16x16x32_bf16 v[16:19], v[132:135], v[214:217], v[16:19]
	v_mfma_f32_16x16x32_bf16 v[8:11], v[140:143], v[214:217], v[8:11]
	s_setprio 0
	s_setprio 1
	v_mfma_f32_16x16x32_bf16 v[52:55], v[156:159], v[180:183], 0
	v_mfma_f32_16x16x32_bf16 v[44:47], v[168:171], v[180:183], 0
	v_mfma_f32_16x16x32_bf16 v[36:39], v[156:159], v[188:191], 0
	v_mfma_f32_16x16x32_bf16 v[28:31], v[168:171], v[188:191], 0
	v_mfma_f32_16x16x32_bf16 v[20:23], v[156:159], v[196:199], 0
	v_mfma_f32_16x16x32_bf16 v[12:15], v[168:171], v[196:199], 0
	v_mfma_f32_16x16x32_bf16 v[4:7], v[156:159], v[210:213], 0
	v_mfma_f32_16x16x32_bf16 v[0:3], v[168:171], v[210:213], 0
	v_mfma_f32_16x16x32_bf16 v[52:55], v[164:167], v[184:187], v[52:55]
	v_mfma_f32_16x16x32_bf16 v[44:47], v[176:179], v[184:187], v[44:47]
	v_mfma_f32_16x16x32_bf16 v[36:39], v[164:167], v[192:195], v[36:39]
	v_mfma_f32_16x16x32_bf16 v[28:31], v[176:179], v[192:195], v[28:31]
	v_mfma_f32_16x16x32_bf16 v[20:23], v[164:167], v[206:209], v[20:23]
	v_mfma_f32_16x16x32_bf16 v[12:15], v[176:179], v[206:209], v[12:15]
	v_mfma_f32_16x16x32_bf16 v[4:7], v[164:167], v[214:217], v[4:7]
	v_mfma_f32_16x16x32_bf16 v[0:3], v[176:179], v[214:217], v[0:3]
	s_barrier
	s_setprio 0
	s_add_i32 s20, 0, 0x18000
	s_add_i32 s21, 0, 0x1c000
	v_add_u32_e32 v140, s20, v174
	v_add_u32_e32 v162, s21, v174
	ds_read_b128 v[128:131], v140
	ds_read_b128 v[132:135], v140 offset:1024
	ds_read_b128 v[136:139], v140 offset:2048
	ds_read_b128 v[140:143], v140 offset:3072
	ds_read_b128 v[156:159], v162
	ds_read_b128 v[164:167], v162 offset:1024
	ds_read_b128 v[168:171], v162 offset:2048
	ds_read_b128 v[176:179], v162 offset:3072
	s_add_u32 s18, s60, 0x40000
	s_addc_u32 s19, s61, 0
	s_mov_b32 m0, s6
	v_lshl_add_u64 v[224:225], s[18:19], 0, v[150:151]
	ds_read_b128 v[180:183], v175 offset:32768
	ds_read_b128 v[184:187], v175 offset:33792
	ds_read_b128 v[188:191], v175 offset:34816
	ds_read_b128 v[192:195], v175 offset:35840
	ds_read_b128 v[196:199], v175 offset:36864
	ds_read_b128 v[206:209], v175 offset:37888
	ds_read_b128 v[210:213], v175 offset:38912
	ds_read_b128 v[214:217], v175 offset:39936
	global_load_lds_dwordx4 v[224:225], off
	v_lshl_add_u64 v[224:225], s[18:19], 0, v[146:147]
	s_mov_b32 m0, s7
	s_nop 0
	global_load_lds_dwordx4 v[224:225], off
	s_waitcnt vmcnt(8)
	s_waitcnt lgkmcnt(0)
	s_setprio 1
	s_barrier
	v_mfma_f32_16x16x32_bf16 v[124:127], v[128:131], v[180:183], v[124:127]
	v_mfma_f32_16x16x32_bf16 v[120:123], v[136:139], v[180:183], v[120:123]
	v_mfma_f32_16x16x32_bf16 v[112:115], v[128:131], v[188:191], v[112:115]
	v_mfma_f32_16x16x32_bf16 v[104:107], v[136:139], v[188:191], v[104:107]
	v_mfma_f32_16x16x32_bf16 v[96:99], v[128:131], v[196:199], v[96:99]
	v_mfma_f32_16x16x32_bf16 v[88:91], v[136:139], v[196:199], v[88:91]
	v_mfma_f32_16x16x32_bf16 v[80:83], v[128:131], v[210:213], v[80:83]
	v_mfma_f32_16x16x32_bf16 v[72:75], v[136:139], v[210:213], v[72:75]
	v_mfma_f32_16x16x32_bf16 v[124:127], v[132:135], v[184:187], v[124:127]
	v_mfma_f32_16x16x32_bf16 v[120:123], v[140:143], v[184:187], v[120:123]
	v_mfma_f32_16x16x32_bf16 v[112:115], v[132:135], v[192:195], v[112:115]
	v_mfma_f32_16x16x32_bf16 v[104:107], v[140:143], v[192:195], v[104:107]
	v_mfma_f32_16x16x32_bf16 v[96:99], v[132:135], v[206:209], v[96:99]
	v_mfma_f32_16x16x32_bf16 v[88:91], v[140:143], v[206:209], v[88:91]
	v_mfma_f32_16x16x32_bf16 v[80:83], v[132:135], v[214:217], v[80:83]
	v_mfma_f32_16x16x32_bf16 v[72:75], v[140:143], v[214:217], v[72:75]
	s_setprio 0
	s_setprio 1
	v_mfma_f32_16x16x32_bf16 v[116:119], v[156:159], v[180:183], v[116:119]
	v_mfma_f32_16x16x32_bf16 v[108:111], v[168:171], v[180:183], v[108:111]
	v_mfma_f32_16x16x32_bf16 v[100:103], v[156:159], v[188:191], v[100:103]
	v_mfma_f32_16x16x32_bf16 v[92:95], v[168:171], v[188:191], v[92:95]
	v_mfma_f32_16x16x32_bf16 v[84:87], v[156:159], v[196:199], v[84:87]
	v_mfma_f32_16x16x32_bf16 v[76:79], v[168:171], v[196:199], v[76:79]
	v_mfma_f32_16x16x32_bf16 v[68:71], v[156:159], v[210:213], v[68:71]
	v_mfma_f32_16x16x32_bf16 v[64:67], v[168:171], v[210:213], v[64:67]
	v_mfma_f32_16x16x32_bf16 v[116:119], v[164:167], v[184:187], v[116:119]
	v_mfma_f32_16x16x32_bf16 v[108:111], v[176:179], v[184:187], v[108:111]
	v_mfma_f32_16x16x32_bf16 v[100:103], v[164:167], v[192:195], v[100:103]
	v_mfma_f32_16x16x32_bf16 v[92:95], v[176:179], v[192:195], v[92:95]
	v_mfma_f32_16x16x32_bf16 v[84:87], v[164:167], v[206:209], v[84:87]
	v_mfma_f32_16x16x32_bf16 v[76:79], v[176:179], v[206:209], v[76:79]
	v_mfma_f32_16x16x32_bf16 v[68:71], v[164:167], v[214:217], v[68:71]
	v_mfma_f32_16x16x32_bf16 v[64:67], v[176:179], v[214:217], v[64:67]
	s_barrier
	s_setprio 0
	s_add_i32 s18, s20, s46
	v_lshl_add_u64 v[200:201], v[200:201], 0, s[76:77]
	s_mov_b32 m0, s18
	ds_read_b128 v[180:183], v175 offset:49152
	ds_read_b128 v[184:187], v175 offset:50176
	ds_read_b128 v[188:191], v175 offset:51200
	ds_read_b128 v[192:195], v175 offset:52224
	ds_read_b128 v[196:199], v175 offset:53248
	ds_read_b128 v[206:209], v175 offset:54272
	ds_read_b128 v[210:213], v175 offset:55296
	ds_read_b128 v[214:217], v175 offset:56320
	global_load_lds_dwordx4 v[200:201], off
	s_add_i32 m0, s18, 0x2000
	s_add_u32 s18, s50, 0x40080
	v_lshl_add_u64 v[200:201], v[218:219], 0, s[76:77]
	s_addc_u32 s19, s51, 0
	s_add_i32 s20, s21, s46
	global_load_lds_dwordx4 v[200:201], off
	v_lshl_add_u64 v[200:201], s[18:19], 0, v[148:149]
	s_mov_b32 m0, s20
	s_nop 0
	global_load_lds_dwordx4 v[200:201], off
	v_lshl_add_u64 v[200:201], s[18:19], 0, v[144:145]
	s_add_i32 m0, s20, 0x2000
	s_nop 0
	global_load_lds_dwordx4 v[200:201], off
	v_lshl_add_u64 v[200:201], v[220:221], 0, s[76:77]
	s_mov_b32 m0, s9
	s_nop 0
	global_load_lds_dwordx4 v[200:201], off
	v_lshl_add_u64 v[200:201], v[222:223], 0, s[76:77]
	s_mov_b32 m0, s10
	s_nop 0
	global_load_lds_dwordx4 v[200:201], off
	s_waitcnt vmcnt(8)
	s_waitcnt lgkmcnt(0)
	s_setprio 1
	s_barrier
	v_mfma_f32_16x16x32_bf16 v[60:63], v[128:131], v[180:183], v[60:63]
	v_mfma_f32_16x16x32_bf16 v[56:59], v[136:139], v[180:183], v[56:59]
	v_mfma_f32_16x16x32_bf16 v[48:51], v[128:131], v[188:191], v[48:51]
	v_mfma_f32_16x16x32_bf16 v[40:43], v[136:139], v[188:191], v[40:43]
	v_mfma_f32_16x16x32_bf16 v[32:35], v[128:131], v[196:199], v[32:35]
	v_mfma_f32_16x16x32_bf16 v[24:27], v[136:139], v[196:199], v[24:27]
	v_mfma_f32_16x16x32_bf16 v[16:19], v[128:131], v[210:213], v[16:19]
	v_mfma_f32_16x16x32_bf16 v[8:11], v[136:139], v[210:213], v[8:11]
	v_mfma_f32_16x16x32_bf16 v[60:63], v[132:135], v[184:187], v[60:63]
	v_mfma_f32_16x16x32_bf16 v[56:59], v[140:143], v[184:187], v[56:59]
	v_mfma_f32_16x16x32_bf16 v[48:51], v[132:135], v[192:195], v[48:51]
	v_mfma_f32_16x16x32_bf16 v[40:43], v[140:143], v[192:195], v[40:43]
	v_mfma_f32_16x16x32_bf16 v[32:35], v[132:135], v[206:209], v[32:35]
	v_mfma_f32_16x16x32_bf16 v[24:27], v[140:143], v[206:209], v[24:27]
	v_mfma_f32_16x16x32_bf16 v[16:19], v[132:135], v[214:217], v[16:19]
	v_mfma_f32_16x16x32_bf16 v[8:11], v[140:143], v[214:217], v[8:11]
	s_setprio 0
	s_setprio 1
	v_mfma_f32_16x16x32_bf16 v[52:55], v[156:159], v[180:183], v[52:55]
	v_mfma_f32_16x16x32_bf16 v[44:47], v[168:171], v[180:183], v[44:47]
	v_mfma_f32_16x16x32_bf16 v[36:39], v[156:159], v[188:191], v[36:39]
	v_mfma_f32_16x16x32_bf16 v[28:31], v[168:171], v[188:191], v[28:31]
	v_mfma_f32_16x16x32_bf16 v[20:23], v[156:159], v[196:199], v[20:23]
	v_mfma_f32_16x16x32_bf16 v[12:15], v[168:171], v[196:199], v[12:15]
	v_mfma_f32_16x16x32_bf16 v[4:7], v[156:159], v[210:213], v[4:7]
	v_mfma_f32_16x16x32_bf16 v[0:3], v[168:171], v[210:213], v[0:3]
	v_mfma_f32_16x16x32_bf16 v[52:55], v[164:167], v[184:187], v[52:55]
	v_mfma_f32_16x16x32_bf16 v[44:47], v[176:179], v[184:187], v[44:47]
	v_mfma_f32_16x16x32_bf16 v[36:39], v[164:167], v[192:195], v[36:39]
	v_mfma_f32_16x16x32_bf16 v[28:31], v[176:179], v[192:195], v[28:31]
	v_mfma_f32_16x16x32_bf16 v[20:23], v[164:167], v[206:209], v[20:23]
	v_mfma_f32_16x16x32_bf16 v[12:15], v[176:179], v[206:209], v[12:15]
	v_mfma_f32_16x16x32_bf16 v[4:7], v[164:167], v[214:217], v[4:7]
	v_mfma_f32_16x16x32_bf16 v[0:3], v[176:179], v[214:217], v[0:3]
	s_barrier
	s_setprio 0
	s_add_i32 s54, s54, 2
	s_add_u32 s58, s58, 0x100
	s_addc_u32 s59, s59, 0
	s_add_u32 s39, s39, 0x100
	s_addc_u32 s47, s47, 0
	s_cmp_gt_u32 s54, 13
	s_cbranch_scc0 .LBB0_983
	s_branch .Lpeel_x_983
.LBB0_983:
	s_add_u32 s18, s58, 0xfffc0080
	s_addc_u32 s19, s59, -1
	s_add_i32 s20, 0, 0x10000
	s_cmp_eq_u32 s54, 12
	s_cselect_b32 s61, s15, s19
	s_cselect_b32 s60, s16, s18
	s_cselect_b32 s51, s17, s47
	s_cselect_b32 s50, s37, s39
	s_add_i32 s21, 0, 0x14000
	v_add_u32_e32 v140, s20, v174
	v_add_u32_e32 v162, s21, v174
	ds_read_b128 v[128:131], v140
	ds_read_b128 v[132:135], v140 offset:1024
	ds_read_b128 v[136:139], v140 offset:2048
	ds_read_b128 v[140:143], v140 offset:3072
	ds_read_b128 v[156:159], v162
	ds_read_b128 v[164:167], v162 offset:1024
	ds_read_b128 v[168:171], v162 offset:2048
	ds_read_b128 v[176:179], v162 offset:3072
	v_lshl_add_u64 v[200:201], s[58:59], 0, v[152:153]
	s_add_i32 m0, s4, 0xc000
	ds_read_b128 v[180:183], v175
	ds_read_b128 v[184:187], v175 offset:1024
	ds_read_b128 v[188:191], v175 offset:2048
	ds_read_b128 v[192:195], v175 offset:3072
	ds_read_b128 v[196:199], v175 offset:4096
	ds_read_b128 v[206:209], v175 offset:5120
	ds_read_b128 v[210:213], v175 offset:6144
	ds_read_b128 v[214:217], v175 offset:7168
	global_load_lds_dwordx4 v[200:201], off
	v_lshl_add_u64 v[200:201], s[58:59], 0, v[154:155]
	s_add_i32 m0, s4, 0xe000
	s_nop 0
	global_load_lds_dwordx4 v[200:201], off
	s_waitcnt vmcnt(8)
	s_waitcnt lgkmcnt(0)
	s_setprio 1
	s_barrier
	v_mfma_f32_16x16x32_bf16 v[124:127], v[128:131], v[180:183], v[124:127]
	v_mfma_f32_16x16x32_bf16 v[120:123], v[136:139], v[180:183], v[120:123]
	v_mfma_f32_16x16x32_bf16 v[112:115], v[128:131], v[188:191], v[112:115]
	v_mfma_f32_16x16x32_bf16 v[104:107], v[136:139], v[188:191], v[104:107]
	v_mfma_f32_16x16x32_bf16 v[96:99], v[128:131], v[196:199], v[96:99]
	v_mfma_f32_16x16x32_bf16 v[88:91], v[136:139], v[196:199], v[88:91]
	v_mfma_f32_16x16x32_bf16 v[80:83], v[128:131], v[210:213], v[80:83]
	v_mfma_f32_16x16x32_bf16 v[72:75], v[136:139], v[210:213], v[72:75]
	v_mfma_f32_16x16x32_bf16 v[124:127], v[132:135], v[184:187], v[124:127]
	v_mfma_f32_16x16x32_bf16 v[120:123], v[140:143], v[184:187], v[120:123]
	v_mfma_f32_16x16x32_bf16 v[112:115], v[132:135], v[192:195], v[112:115]
	v_mfma_f32_16x16x32_bf16 v[104:107], v[140:143], v[192:195], v[104:107]
	v_mfma_f32_16x16x32_bf16 v[96:99], v[132:135], v[206:209], v[96:99]
	v_mfma_f32_16x16x32_bf16 v[88:91], v[140:143], v[206:209], v[88:91]
	v_mfma_f32_16x16x32_bf16 v[80:83], v[132:135], v[214:217], v[80:83]
	v_mfma_f32_16x16x32_bf16 v[72:75], v[140:143], v[214:217], v[72:75]
	s_setprio 0
	s_setprio 1
	v_mfma_f32_16x16x32_bf16 v[116:119], v[156:159], v[180:183], v[116:119]
	v_mfma_f32_16x16x32_bf16 v[108:111], v[168:171], v[180:183], v[108:111]
	v_mfma_f32_16x16x32_bf16 v[100:103], v[156:159], v[188:191], v[100:103]
	v_mfma_f32_16x16x32_bf16 v[92:95], v[168:171], v[188:191], v[92:95]
	v_mfma_f32_16x16x32_bf16 v[84:87], v[156:159], v[196:199], v[84:87]
	v_mfma_f32_16x16x32_bf16 v[76:79], v[168:171], v[196:199], v[76:79]
	v_mfma_f32_16x16x32_bf16 v[68:71], v[156:159], v[210:213], v[68:71]
	v_mfma_f32_16x16x32_bf16 v[64:67], v[168:171], v[210:213], v[64:67]
	v_mfma_f32_16x16x32_bf16 v[116:119], v[164:167], v[184:187], v[116:119]
	v_mfma_f32_16x16x32_bf16 v[108:111], v[176:179], v[184:187], v[108:111]
	v_mfma_f32_16x16x32_bf16 v[100:103], v[164:167], v[192:195], v[100:103]
	v_mfma_f32_16x16x32_bf16 v[92:95], v[176:179], v[192:195], v[92:95]
	v_mfma_f32_16x16x32_bf16 v[84:87], v[164:167], v[206:209], v[84:87]
	v_mfma_f32_16x16x32_bf16 v[76:79], v[176:179], v[206:209], v[76:79]
	v_mfma_f32_16x16x32_bf16 v[68:71], v[164:167], v[214:217], v[68:71]
	v_mfma_f32_16x16x32_bf16 v[64:67], v[176:179], v[214:217], v[64:67]
	s_barrier
	s_setprio 0
	s_add_i32 s18, s20, s46
	v_lshl_add_u64 v[200:201], s[50:51], 0, v[148:149]
	s_mov_b32 m0, s18
	ds_read_b128 v[180:183], v175 offset:16384
	ds_read_b128 v[184:187], v175 offset:17408
	ds_read_b128 v[188:191], v175 offset:18432
	ds_read_b128 v[192:195], v175 offset:19456
	ds_read_b128 v[196:199], v175 offset:20480
	ds_read_b128 v[206:209], v175 offset:21504
	ds_read_b128 v[210:213], v175 offset:22528
	ds_read_b128 v[214:217], v175 offset:23552
	global_load_lds_dwordx4 v[200:201], off
	s_add_i32 m0, s18, 0x2000
	s_add_u32 s18, s50, 0x40000
	v_lshl_add_u64 v[218:219], s[50:51], 0, v[144:145]
	s_addc_u32 s19, s51, 0
	s_add_i32 s20, s21, s46
	global_load_lds_dwordx4 v[218:219], off
	v_lshl_add_u64 v[220:221], s[18:19], 0, v[148:149]
	s_mov_b32 m0, s20
	v_lshl_add_u64 v[222:223], s[60:61], 0, v[146:147]
	global_load_lds_dwordx4 v[220:221], off
	v_lshl_add_u64 v[220:221], s[18:19], 0, v[144:145]
	s_add_i32 m0, s20, 0x2000
	s_nop 0
	global_load_lds_dwordx4 v[220:221], off
	v_lshl_add_u64 v[220:221], s[60:61], 0, v[150:151]
	s_mov_b32 m0, s4
	s_nop 0
	global_load_lds_dwordx4 v[220:221], off
	s_mov_b32 m0, s5
	s_nop 0
	global_load_lds_dwordx4 v[222:223], off
	s_waitcnt vmcnt(8)
	s_waitcnt lgkmcnt(0)
	s_setprio 1
	s_barrier
	v_mfma_f32_16x16x32_bf16 v[60:63], v[128:131], v[180:183], v[60:63]
	v_mfma_f32_16x16x32_bf16 v[56:59], v[136:139], v[180:183], v[56:59]
	v_mfma_f32_16x16x32_bf16 v[48:51], v[128:131], v[188:191], v[48:51]
	v_mfma_f32_16x16x32_bf16 v[40:43], v[136:139], v[188:191], v[40:43]
	v_mfma_f32_16x16x32_bf16 v[32:35], v[128:131], v[196:199], v[32:35]
	v_mfma_f32_16x16x32_bf16 v[24:27], v[136:139], v[196:199], v[24:27]
	v_mfma_f32_16x16x32_bf16 v[16:19], v[128:131], v[210:213], v[16:19]
	v_mfma_f32_16x16x32_bf16 v[8:11], v[136:139], v[210:213], v[8:11]
	v_mfma_f32_16x16x32_bf16 v[60:63], v[132:135], v[184:187], v[60:63]
	v_mfma_f32_16x16x32_bf16 v[56:59], v[140:143], v[184:187], v[56:59]
	v_mfma_f32_16x16x32_bf16 v[48:51], v[132:135], v[192:195], v[48:51]
	v_mfma_f32_16x16x32_bf16 v[40:43], v[140:143], v[192:195], v[40:43]
	v_mfma_f32_16x16x32_bf16 v[32:35], v[132:135], v[206:209], v[32:35]
	v_mfma_f32_16x16x32_bf16 v[24:27], v[140:143], v[206:209], v[24:27]
	v_mfma_f32_16x16x32_bf16 v[16:19], v[132:135], v[214:217], v[16:19]
	v_mfma_f32_16x16x32_bf16 v[8:11], v[140:143], v[214:217], v[8:11]
	s_setprio 0
	s_setprio 1
	v_mfma_f32_16x16x32_bf16 v[52:55], v[156:159], v[180:183], v[52:55]
	v_mfma_f32_16x16x32_bf16 v[44:47], v[168:171], v[180:183], v[44:47]
	v_mfma_f32_16x16x32_bf16 v[36:39], v[156:159], v[188:191], v[36:39]
	v_mfma_f32_16x16x32_bf16 v[28:31], v[168:171], v[188:191], v[28:31]
	v_mfma_f32_16x16x32_bf16 v[20:23], v[156:159], v[196:199], v[20:23]
	v_mfma_f32_16x16x32_bf16 v[12:15], v[168:171], v[196:199], v[12:15]
	v_mfma_f32_16x16x32_bf16 v[4:7], v[156:159], v[210:213], v[4:7]
	v_mfma_f32_16x16x32_bf16 v[0:3], v[168:171], v[210:213], v[0:3]
	v_mfma_f32_16x16x32_bf16 v[52:55], v[164:167], v[184:187], v[52:55]
	v_mfma_f32_16x16x32_bf16 v[44:47], v[176:179], v[184:187], v[44:47]
	v_mfma_f32_16x16x32_bf16 v[36:39], v[164:167], v[192:195], v[36:39]
	v_mfma_f32_16x16x32_bf16 v[28:31], v[176:179], v[192:195], v[28:31]
	v_mfma_f32_16x16x32_bf16 v[20:23], v[164:167], v[206:209], v[20:23]
	v_mfma_f32_16x16x32_bf16 v[12:15], v[176:179], v[206:209], v[12:15]
	v_mfma_f32_16x16x32_bf16 v[4:7], v[164:167], v[214:217], v[4:7]
	v_mfma_f32_16x16x32_bf16 v[0:3], v[176:179], v[214:217], v[0:3]
	s_barrier
	s_setprio 0
	s_add_i32 s20, 0, 0x18000
	s_add_i32 s21, 0, 0x1c000
	v_add_u32_e32 v140, s20, v174
	v_add_u32_e32 v162, s21, v174
	ds_read_b128 v[128:131], v140
	ds_read_b128 v[132:135], v140 offset:1024
	ds_read_b128 v[136:139], v140 offset:2048
	ds_read_b128 v[140:143], v140 offset:3072
	ds_read_b128 v[156:159], v162
	ds_read_b128 v[164:167], v162 offset:1024
	ds_read_b128 v[168:171], v162 offset:2048
	ds_read_b128 v[176:179], v162 offset:3072
	s_add_u32 s18, s60, 0x40000
	s_addc_u32 s19, s61, 0
	s_mov_b32 m0, s6
	v_lshl_add_u64 v[224:225], s[18:19], 0, v[150:151]
	ds_read_b128 v[180:183], v175 offset:32768
	ds_read_b128 v[184:187], v175 offset:33792
	ds_read_b128 v[188:191], v175 offset:34816
	ds_read_b128 v[192:195], v175 offset:35840
	ds_read_b128 v[196:199], v175 offset:36864
	ds_read_b128 v[206:209], v175 offset:37888
	ds_read_b128 v[210:213], v175 offset:38912
	ds_read_b128 v[214:217], v175 offset:39936
	global_load_lds_dwordx4 v[224:225], off
	v_lshl_add_u64 v[224:225], s[18:19], 0, v[146:147]
	s_mov_b32 m0, s7
	s_nop 0
	global_load_lds_dwordx4 v[224:225], off
	s_waitcnt vmcnt(8)
	s_waitcnt lgkmcnt(0)
	s_setprio 1
	s_barrier
	v_mfma_f32_16x16x32_bf16 v[124:127], v[128:131], v[180:183], v[124:127]
	v_mfma_f32_16x16x32_bf16 v[120:123], v[136:139], v[180:183], v[120:123]
	v_mfma_f32_16x16x32_bf16 v[112:115], v[128:131], v[188:191], v[112:115]
	v_mfma_f32_16x16x32_bf16 v[104:107], v[136:139], v[188:191], v[104:107]
	v_mfma_f32_16x16x32_bf16 v[96:99], v[128:131], v[196:199], v[96:99]
	v_mfma_f32_16x16x32_bf16 v[88:91], v[136:139], v[196:199], v[88:91]
	v_mfma_f32_16x16x32_bf16 v[80:83], v[128:131], v[210:213], v[80:83]
	v_mfma_f32_16x16x32_bf16 v[72:75], v[136:139], v[210:213], v[72:75]
	v_mfma_f32_16x16x32_bf16 v[124:127], v[132:135], v[184:187], v[124:127]
	v_mfma_f32_16x16x32_bf16 v[120:123], v[140:143], v[184:187], v[120:123]
	v_mfma_f32_16x16x32_bf16 v[112:115], v[132:135], v[192:195], v[112:115]
	v_mfma_f32_16x16x32_bf16 v[104:107], v[140:143], v[192:195], v[104:107]
	v_mfma_f32_16x16x32_bf16 v[96:99], v[132:135], v[206:209], v[96:99]
	v_mfma_f32_16x16x32_bf16 v[88:91], v[140:143], v[206:209], v[88:91]
	v_mfma_f32_16x16x32_bf16 v[80:83], v[132:135], v[214:217], v[80:83]
	v_mfma_f32_16x16x32_bf16 v[72:75], v[140:143], v[214:217], v[72:75]
	s_setprio 0
	s_setprio 1
	v_mfma_f32_16x16x32_bf16 v[116:119], v[156:159], v[180:183], v[116:119]
	v_mfma_f32_16x16x32_bf16 v[108:111], v[168:171], v[180:183], v[108:111]
	v_mfma_f32_16x16x32_bf16 v[100:103], v[156:159], v[188:191], v[100:103]
	v_mfma_f32_16x16x32_bf16 v[92:95], v[168:171], v[188:191], v[92:95]
	v_mfma_f32_16x16x32_bf16 v[84:87], v[156:159], v[196:199], v[84:87]
	v_mfma_f32_16x16x32_bf16 v[76:79], v[168:171], v[196:199], v[76:79]
	v_mfma_f32_16x16x32_bf16 v[68:71], v[156:159], v[210:213], v[68:71]
	v_mfma_f32_16x16x32_bf16 v[64:67], v[168:171], v[210:213], v[64:67]
	v_mfma_f32_16x16x32_bf16 v[116:119], v[164:167], v[184:187], v[116:119]
	v_mfma_f32_16x16x32_bf16 v[108:111], v[176:179], v[184:187], v[108:111]
	v_mfma_f32_16x16x32_bf16 v[100:103], v[164:167], v[192:195], v[100:103]
	v_mfma_f32_16x16x32_bf16 v[92:95], v[176:179], v[192:195], v[92:95]
	v_mfma_f32_16x16x32_bf16 v[84:87], v[164:167], v[206:209], v[84:87]
	v_mfma_f32_16x16x32_bf16 v[76:79], v[176:179], v[206:209], v[76:79]
	v_mfma_f32_16x16x32_bf16 v[68:71], v[164:167], v[214:217], v[68:71]
	v_mfma_f32_16x16x32_bf16 v[64:67], v[176:179], v[214:217], v[64:67]
	s_barrier
	s_setprio 0
	s_add_i32 s18, s20, s46
	v_lshl_add_u64 v[200:201], v[200:201], 0, s[76:77]
	s_mov_b32 m0, s18
	ds_read_b128 v[180:183], v175 offset:49152
	ds_read_b128 v[184:187], v175 offset:50176
	ds_read_b128 v[188:191], v175 offset:51200
	ds_read_b128 v[192:195], v175 offset:52224
	ds_read_b128 v[196:199], v175 offset:53248
	ds_read_b128 v[206:209], v175 offset:54272
	ds_read_b128 v[210:213], v175 offset:55296
	ds_read_b128 v[214:217], v175 offset:56320
	global_load_lds_dwordx4 v[200:201], off
	s_add_i32 m0, s18, 0x2000
	s_add_u32 s18, s50, 0x40080
	v_lshl_add_u64 v[200:201], v[218:219], 0, s[76:77]
	s_addc_u32 s19, s51, 0
	s_add_i32 s20, s21, s46
	global_load_lds_dwordx4 v[200:201], off
	v_lshl_add_u64 v[200:201], s[18:19], 0, v[148:149]
	s_mov_b32 m0, s20
	s_nop 0
	global_load_lds_dwordx4 v[200:201], off
	v_lshl_add_u64 v[200:201], s[18:19], 0, v[144:145]
	s_add_i32 m0, s20, 0x2000
	s_nop 0
	global_load_lds_dwordx4 v[200:201], off
	v_lshl_add_u64 v[200:201], v[220:221], 0, s[76:77]
	s_mov_b32 m0, s9
	s_nop 0
	global_load_lds_dwordx4 v[200:201], off
	v_lshl_add_u64 v[200:201], v[222:223], 0, s[76:77]
	s_mov_b32 m0, s10
	s_nop 0
	global_load_lds_dwordx4 v[200:201], off
	s_waitcnt vmcnt(8)
	s_waitcnt lgkmcnt(0)
	s_setprio 1
	s_barrier
	v_mfma_f32_16x16x32_bf16 v[60:63], v[128:131], v[180:183], v[60:63]
	v_mfma_f32_16x16x32_bf16 v[56:59], v[136:139], v[180:183], v[56:59]
	v_mfma_f32_16x16x32_bf16 v[48:51], v[128:131], v[188:191], v[48:51]
	v_mfma_f32_16x16x32_bf16 v[40:43], v[136:139], v[188:191], v[40:43]
	v_mfma_f32_16x16x32_bf16 v[32:35], v[128:131], v[196:199], v[32:35]
	v_mfma_f32_16x16x32_bf16 v[24:27], v[136:139], v[196:199], v[24:27]
	v_mfma_f32_16x16x32_bf16 v[16:19], v[128:131], v[210:213], v[16:19]
	v_mfma_f32_16x16x32_bf16 v[8:11], v[136:139], v[210:213], v[8:11]
	v_mfma_f32_16x16x32_bf16 v[60:63], v[132:135], v[184:187], v[60:63]
	v_mfma_f32_16x16x32_bf16 v[56:59], v[140:143], v[184:187], v[56:59]
	v_mfma_f32_16x16x32_bf16 v[48:51], v[132:135], v[192:195], v[48:51]
	v_mfma_f32_16x16x32_bf16 v[40:43], v[140:143], v[192:195], v[40:43]
	v_mfma_f32_16x16x32_bf16 v[32:35], v[132:135], v[206:209], v[32:35]
	v_mfma_f32_16x16x32_bf16 v[24:27], v[140:143], v[206:209], v[24:27]
	v_mfma_f32_16x16x32_bf16 v[16:19], v[132:135], v[214:217], v[16:19]
	v_mfma_f32_16x16x32_bf16 v[8:11], v[140:143], v[214:217], v[8:11]
	s_setprio 0
	s_setprio 1
	v_mfma_f32_16x16x32_bf16 v[52:55], v[156:159], v[180:183], v[52:55]
	v_mfma_f32_16x16x32_bf16 v[44:47], v[168:171], v[180:183], v[44:47]
	v_mfma_f32_16x16x32_bf16 v[36:39], v[156:159], v[188:191], v[36:39]
	v_mfma_f32_16x16x32_bf16 v[28:31], v[168:171], v[188:191], v[28:31]
	v_mfma_f32_16x16x32_bf16 v[20:23], v[156:159], v[196:199], v[20:23]
	v_mfma_f32_16x16x32_bf16 v[12:15], v[168:171], v[196:199], v[12:15]
	v_mfma_f32_16x16x32_bf16 v[4:7], v[156:159], v[210:213], v[4:7]
	v_mfma_f32_16x16x32_bf16 v[0:3], v[168:171], v[210:213], v[0:3]
	v_mfma_f32_16x16x32_bf16 v[52:55], v[164:167], v[184:187], v[52:55]
	v_mfma_f32_16x16x32_bf16 v[44:47], v[176:179], v[184:187], v[44:47]
	v_mfma_f32_16x16x32_bf16 v[36:39], v[164:167], v[192:195], v[36:39]
	v_mfma_f32_16x16x32_bf16 v[28:31], v[176:179], v[192:195], v[28:31]
	v_mfma_f32_16x16x32_bf16 v[20:23], v[164:167], v[206:209], v[20:23]
	v_mfma_f32_16x16x32_bf16 v[12:15], v[176:179], v[206:209], v[12:15]
	v_mfma_f32_16x16x32_bf16 v[4:7], v[164:167], v[214:217], v[4:7]
	v_mfma_f32_16x16x32_bf16 v[0:3], v[176:179], v[214:217], v[0:3]
	s_barrier
	s_setprio 0
	s_add_i32 s54, s54, 2
	s_add_u32 s58, s58, 0x100
	s_addc_u32 s59, s59, 0
	s_add_u32 s39, s39, 0x100
	s_addc_u32 s47, s47, 0
	s_cmp_gt_u32 s54, 13
	s_cbranch_scc0 .LBB0_983

.LBB0_1004:
	s_ashr_i32 s37, s36, 31
	s_lshl_b64 s[16:17], s[36:37], 19
	s_add_u32 s40, s94, s16
	s_addc_u32 s41, s95, s17
	s_and_b64 s[16:17], s[42:43], exec
	s_cselect_b32 s16, s41, s51
	s_cselect_b32 s17, s40, s50
	s_ashr_i32 s39, s38, 31
	s_lshl_b64 s[18:19], s[38:39], 19
	s_add_u32 s48, s22, s18
	s_addc_u32 s49, s23, s19
	s_and_b64 s[18:19], s[42:43], exec
	s_cselect_b32 s37, s49, s61
	s_cselect_b32 s39, s48, s60
	s_add_u32 s58, s50, 0x40080
	s_addc_u32 s59, s51, 0
	s_add_u32 s46, s60, 0x100
	s_addc_u32 s47, s61, 0
	s_mov_b32 s54, -2
	s_add_u32 s18, s58, 0xfffc0080
	s_addc_u32 s19, s59, -1
	s_add_i32 s20, 0, 0x10000
	s_cmp_eq_u32 s54, 12
	s_cselect_b32 s61, s16, s19
	s_cselect_b32 s60, s17, s18
	s_cselect_b32 s51, s37, s47
	s_cselect_b32 s50, s39, s46
	s_add_i32 s21, 0, 0x14000
	v_add_u32_e32 v140, s20, v170
	v_add_u32_e32 v162, s21, v170
	ds_read_b128 v[128:131], v140
	ds_read_b128 v[132:135], v140 offset:1024
	ds_read_b128 v[136:139], v140 offset:2048
	ds_read_b128 v[140:143], v140 offset:3072
	ds_read_b128 v[144:147], v162
	ds_read_b128 v[148:151], v162 offset:1024
	ds_read_b128 v[172:175], v162 offset:2048
	ds_read_b128 v[176:179], v162 offset:3072
	v_lshl_add_u64 v[200:201], s[58:59], 0, v[164:165]
	s_add_i32 m0, s5, 0xc000
	ds_read_b128 v[180:183], v171
	ds_read_b128 v[184:187], v171 offset:1024
	ds_read_b128 v[188:191], v171 offset:2048
	ds_read_b128 v[192:195], v171 offset:3072
	ds_read_b128 v[196:199], v171 offset:4096
	ds_read_b128 v[206:209], v171 offset:5120
	ds_read_b128 v[210:213], v171 offset:6144
	ds_read_b128 v[214:217], v171 offset:7168
	global_load_lds_dwordx4 v[200:201], off
	v_lshl_add_u64 v[200:201], s[58:59], 0, v[166:167]
	s_add_i32 m0, s5, 0xe000
	s_nop 0
	global_load_lds_dwordx4 v[200:201], off
	s_waitcnt vmcnt(8)
	s_waitcnt lgkmcnt(0)
	s_setprio 1
	s_barrier
	v_mfma_f32_16x16x32_bf16 v[124:127], v[128:131], v[180:183], 0
	v_mfma_f32_16x16x32_bf16 v[120:123], v[136:139], v[180:183], 0
	v_mfma_f32_16x16x32_bf16 v[116:119], v[128:131], v[188:191], 0
	v_mfma_f32_16x16x32_bf16 v[112:115], v[136:139], v[188:191], 0
	v_mfma_f32_16x16x32_bf16 v[104:107], v[128:131], v[196:199], 0
	v_mfma_f32_16x16x32_bf16 v[96:99], v[136:139], v[196:199], 0
	v_mfma_f32_16x16x32_bf16 v[80:83], v[128:131], v[210:213], 0
	v_mfma_f32_16x16x32_bf16 v[72:75], v[136:139], v[210:213], 0
	v_mfma_f32_16x16x32_bf16 v[124:127], v[132:135], v[184:187], v[124:127]
	v_mfma_f32_16x16x32_bf16 v[120:123], v[140:143], v[184:187], v[120:123]
	v_mfma_f32_16x16x32_bf16 v[116:119], v[132:135], v[192:195], v[116:119]
	v_mfma_f32_16x16x32_bf16 v[112:115], v[140:143], v[192:195], v[112:115]
	v_mfma_f32_16x16x32_bf16 v[104:107], v[132:135], v[206:209], v[104:107]
	v_mfma_f32_16x16x32_bf16 v[96:99], v[140:143], v[206:209], v[96:99]
	v_mfma_f32_16x16x32_bf16 v[80:83], v[132:135], v[214:217], v[80:83]
	v_mfma_f32_16x16x32_bf16 v[72:75], v[140:143], v[214:217], v[72:75]
	s_setprio 0
	s_setprio 1
	v_mfma_f32_16x16x32_bf16 v[108:111], v[144:147], v[180:183], 0
	v_mfma_f32_16x16x32_bf16 v[100:103], v[172:175], v[180:183], 0
	v_mfma_f32_16x16x32_bf16 v[92:95], v[144:147], v[188:191], 0
	v_mfma_f32_16x16x32_bf16 v[88:91], v[172:175], v[188:191], 0
	v_mfma_f32_16x16x32_bf16 v[84:87], v[144:147], v[196:199], 0
	v_mfma_f32_16x16x32_bf16 v[76:79], v[172:175], v[196:199], 0
	v_mfma_f32_16x16x32_bf16 v[68:71], v[144:147], v[210:213], 0
	v_mfma_f32_16x16x32_bf16 v[64:67], v[172:175], v[210:213], 0
	v_mfma_f32_16x16x32_bf16 v[108:111], v[148:151], v[184:187], v[108:111]
	v_mfma_f32_16x16x32_bf16 v[100:103], v[176:179], v[184:187], v[100:103]
	v_mfma_f32_16x16x32_bf16 v[92:95], v[148:151], v[192:195], v[92:95]
	v_mfma_f32_16x16x32_bf16 v[88:91], v[176:179], v[192:195], v[88:91]
	v_mfma_f32_16x16x32_bf16 v[84:87], v[148:151], v[206:209], v[84:87]
	v_mfma_f32_16x16x32_bf16 v[76:79], v[176:179], v[206:209], v[76:79]
	v_mfma_f32_16x16x32_bf16 v[68:71], v[148:151], v[214:217], v[68:71]
	v_mfma_f32_16x16x32_bf16 v[64:67], v[176:179], v[214:217], v[64:67]
	s_barrier
	s_setprio 0
	s_add_i32 s18, s20, s4
	v_lshl_add_u64 v[200:201], s[50:51], 0, v[156:157]
	s_mov_b32 m0, s18
	ds_read_b128 v[180:183], v171 offset:16384
	ds_read_b128 v[184:187], v171 offset:17408
	ds_read_b128 v[188:191], v171 offset:18432
	ds_read_b128 v[192:195], v171 offset:19456
	ds_read_b128 v[196:199], v171 offset:20480
	ds_read_b128 v[206:209], v171 offset:21504
	ds_read_b128 v[210:213], v171 offset:22528
	ds_read_b128 v[214:217], v171 offset:23552
	global_load_lds_dwordx4 v[200:201], off
	s_add_i32 m0, s18, 0x2000
	s_add_u32 s18, s50, 0x40000
	v_lshl_add_u64 v[218:219], s[50:51], 0, v[152:153]
	s_addc_u32 s19, s51, 0
	s_add_i32 s20, s21, s4
	global_load_lds_dwordx4 v[218:219], off
	v_lshl_add_u64 v[220:221], s[18:19], 0, v[156:157]
	s_mov_b32 m0, s20
	v_lshl_add_u64 v[222:223], s[60:61], 0, v[154:155]
	global_load_lds_dwordx4 v[220:221], off
	v_lshl_add_u64 v[220:221], s[18:19], 0, v[152:153]
	s_add_i32 m0, s20, 0x2000
	s_nop 0
	global_load_lds_dwordx4 v[220:221], off
	v_lshl_add_u64 v[220:221], s[60:61], 0, v[158:159]
	s_mov_b32 m0, s5
	s_nop 0
	global_load_lds_dwordx4 v[220:221], off
	s_mov_b32 m0, s6
	s_nop 0
	global_load_lds_dwordx4 v[222:223], off
	s_waitcnt vmcnt(8)
	s_waitcnt lgkmcnt(0)
	s_setprio 1
	s_barrier
	v_mfma_f32_16x16x32_bf16 v[60:63], v[128:131], v[180:183], 0
	v_mfma_f32_16x16x32_bf16 v[56:59], v[136:139], v[180:183], 0
	v_mfma_f32_16x16x32_bf16 v[52:55], v[128:131], v[188:191], 0
	v_mfma_f32_16x16x32_bf16 v[48:51], v[136:139], v[188:191], 0
	v_mfma_f32_16x16x32_bf16 v[28:31], v[128:131], v[196:199], 0
	v_mfma_f32_16x16x32_bf16 v[24:27], v[136:139], v[196:199], 0
	v_mfma_f32_16x16x32_bf16 v[16:19], v[128:131], v[210:213], 0
	v_mfma_f32_16x16x32_bf16 v[8:11], v[136:139], v[210:213], 0
	v_mfma_f32_16x16x32_bf16 v[60:63], v[132:135], v[184:187], v[60:63]
	v_mfma_f32_16x16x32_bf16 v[56:59], v[140:143], v[184:187], v[56:59]
	v_mfma_f32_16x16x32_bf16 v[52:55], v[132:135], v[192:195], v[52:55]
	v_mfma_f32_16x16x32_bf16 v[48:51], v[140:143], v[192:195], v[48:51]
	v_mfma_f32_16x16x32_bf16 v[28:31], v[132:135], v[206:209], v[28:31]
	v_mfma_f32_16x16x32_bf16 v[24:27], v[140:143], v[206:209], v[24:27]
	v_mfma_f32_16x16x32_bf16 v[16:19], v[132:135], v[214:217], v[16:19]
	v_mfma_f32_16x16x32_bf16 v[8:11], v[140:143], v[214:217], v[8:11]
	s_setprio 0
	s_setprio 1
	v_mfma_f32_16x16x32_bf16 v[44:47], v[144:147], v[180:183], 0
	v_mfma_f32_16x16x32_bf16 v[40:43], v[172:175], v[180:183], 0
	v_mfma_f32_16x16x32_bf16 v[36:39], v[144:147], v[188:191], 0
	v_mfma_f32_16x16x32_bf16 v[32:35], v[172:175], v[188:191], 0
	v_mfma_f32_16x16x32_bf16 v[20:23], v[144:147], v[196:199], 0
	v_mfma_f32_16x16x32_bf16 v[12:15], v[172:175], v[196:199], 0
	v_mfma_f32_16x16x32_bf16 v[4:7], v[144:147], v[210:213], 0
	v_mfma_f32_16x16x32_bf16 v[0:3], v[172:175], v[210:213], 0
	v_mfma_f32_16x16x32_bf16 v[44:47], v[148:151], v[184:187], v[44:47]
	v_mfma_f32_16x16x32_bf16 v[40:43], v[176:179], v[184:187], v[40:43]
	v_mfma_f32_16x16x32_bf16 v[36:39], v[148:151], v[192:195], v[36:39]
	v_mfma_f32_16x16x32_bf16 v[32:35], v[176:179], v[192:195], v[32:35]
	v_mfma_f32_16x16x32_bf16 v[20:23], v[148:151], v[206:209], v[20:23]
	v_mfma_f32_16x16x32_bf16 v[12:15], v[176:179], v[206:209], v[12:15]
	v_mfma_f32_16x16x32_bf16 v[4:7], v[148:151], v[214:217], v[4:7]
	v_mfma_f32_16x16x32_bf16 v[0:3], v[176:179], v[214:217], v[0:3]
	s_barrier
	s_setprio 0
	s_add_i32 s20, 0, 0x18000
	s_add_i32 s21, 0, 0x1c000
	v_add_u32_e32 v140, s20, v170
	v_add_u32_e32 v162, s21, v170
	ds_read_b128 v[128:131], v140
	ds_read_b128 v[132:135], v140 offset:1024
	ds_read_b128 v[136:139], v140 offset:2048
	ds_read_b128 v[140:143], v140 offset:3072
	ds_read_b128 v[144:147], v162
	ds_read_b128 v[148:151], v162 offset:1024
	ds_read_b128 v[172:175], v162 offset:2048
	ds_read_b128 v[176:179], v162 offset:3072
	s_add_u32 s18, s60, 0x40000
	s_addc_u32 s19, s61, 0
	s_mov_b32 m0, s7
	v_lshl_add_u64 v[224:225], s[18:19], 0, v[158:159]
	ds_read_b128 v[180:183], v171 offset:32768
	ds_read_b128 v[184:187], v171 offset:33792
	ds_read_b128 v[188:191], v171 offset:34816
	ds_read_b128 v[192:195], v171 offset:35840
	ds_read_b128 v[196:199], v171 offset:36864
	ds_read_b128 v[206:209], v171 offset:37888
	ds_read_b128 v[210:213], v171 offset:38912
	ds_read_b128 v[214:217], v171 offset:39936
	global_load_lds_dwordx4 v[224:225], off
	v_lshl_add_u64 v[224:225], s[18:19], 0, v[154:155]
	s_mov_b32 m0, s8
	s_nop 0
	global_load_lds_dwordx4 v[224:225], off
	s_waitcnt vmcnt(8)
	s_waitcnt lgkmcnt(0)
	s_setprio 1
	s_barrier
	v_mfma_f32_16x16x32_bf16 v[124:127], v[128:131], v[180:183], v[124:127]
	v_mfma_f32_16x16x32_bf16 v[120:123], v[136:139], v[180:183], v[120:123]
	v_mfma_f32_16x16x32_bf16 v[116:119], v[128:131], v[188:191], v[116:119]
	v_mfma_f32_16x16x32_bf16 v[112:115], v[136:139], v[188:191], v[112:115]
	v_mfma_f32_16x16x32_bf16 v[104:107], v[128:131], v[196:199], v[104:107]
	v_mfma_f32_16x16x32_bf16 v[96:99], v[136:139], v[196:199], v[96:99]
	v_mfma_f32_16x16x32_bf16 v[80:83], v[128:131], v[210:213], v[80:83]
	v_mfma_f32_16x16x32_bf16 v[72:75], v[136:139], v[210:213], v[72:75]
	v_mfma_f32_16x16x32_bf16 v[124:127], v[132:135], v[184:187], v[124:127]
	v_mfma_f32_16x16x32_bf16 v[120:123], v[140:143], v[184:187], v[120:123]
	v_mfma_f32_16x16x32_bf16 v[116:119], v[132:135], v[192:195], v[116:119]
	v_mfma_f32_16x16x32_bf16 v[112:115], v[140:143], v[192:195], v[112:115]
	v_mfma_f32_16x16x32_bf16 v[104:107], v[132:135], v[206:209], v[104:107]
	v_mfma_f32_16x16x32_bf16 v[96:99], v[140:143], v[206:209], v[96:99]
	v_mfma_f32_16x16x32_bf16 v[80:83], v[132:135], v[214:217], v[80:83]
	v_mfma_f32_16x16x32_bf16 v[72:75], v[140:143], v[214:217], v[72:75]
	s_setprio 0
	s_setprio 1
	v_mfma_f32_16x16x32_bf16 v[108:111], v[144:147], v[180:183], v[108:111]
	v_mfma_f32_16x16x32_bf16 v[100:103], v[172:175], v[180:183], v[100:103]
	v_mfma_f32_16x16x32_bf16 v[92:95], v[144:147], v[188:191], v[92:95]
	v_mfma_f32_16x16x32_bf16 v[88:91], v[172:175], v[188:191], v[88:91]
	v_mfma_f32_16x16x32_bf16 v[84:87], v[144:147], v[196:199], v[84:87]
	v_mfma_f32_16x16x32_bf16 v[76:79], v[172:175], v[196:199], v[76:79]
	v_mfma_f32_16x16x32_bf16 v[68:71], v[144:147], v[210:213], v[68:71]
	v_mfma_f32_16x16x32_bf16 v[64:67], v[172:175], v[210:213], v[64:67]
	v_mfma_f32_16x16x32_bf16 v[108:111], v[148:151], v[184:187], v[108:111]
	v_mfma_f32_16x16x32_bf16 v[100:103], v[176:179], v[184:187], v[100:103]
	v_mfma_f32_16x16x32_bf16 v[92:95], v[148:151], v[192:195], v[92:95]
	v_mfma_f32_16x16x32_bf16 v[88:91], v[176:179], v[192:195], v[88:91]
	v_mfma_f32_16x16x32_bf16 v[84:87], v[148:151], v[206:209], v[84:87]
	v_mfma_f32_16x16x32_bf16 v[76:79], v[176:179], v[206:209], v[76:79]
	v_mfma_f32_16x16x32_bf16 v[68:71], v[148:151], v[214:217], v[68:71]
	v_mfma_f32_16x16x32_bf16 v[64:67], v[176:179], v[214:217], v[64:67]
	s_barrier
	s_setprio 0
	s_add_i32 s18, s20, s4
	v_lshl_add_u64 v[200:201], v[200:201], 0, s[76:77]
	s_mov_b32 m0, s18
	ds_read_b128 v[180:183], v171 offset:49152
	ds_read_b128 v[184:187], v171 offset:50176
	ds_read_b128 v[188:191], v171 offset:51200
	ds_read_b128 v[192:195], v171 offset:52224
	ds_read_b128 v[196:199], v171 offset:53248
	ds_read_b128 v[206:209], v171 offset:54272
	ds_read_b128 v[210:213], v171 offset:55296
	ds_read_b128 v[214:217], v171 offset:56320
	global_load_lds_dwordx4 v[200:201], off
	s_add_i32 m0, s18, 0x2000
	s_add_u32 s18, s50, 0x40080
	v_lshl_add_u64 v[200:201], v[218:219], 0, s[76:77]
	s_addc_u32 s19, s51, 0
	s_add_i32 s20, s21, s4
	global_load_lds_dwordx4 v[200:201], off
	v_lshl_add_u64 v[200:201], s[18:19], 0, v[156:157]
	s_mov_b32 m0, s20
	s_nop 0
	global_load_lds_dwordx4 v[200:201], off
	v_lshl_add_u64 v[200:201], s[18:19], 0, v[152:153]
	s_add_i32 m0, s20, 0x2000
	s_nop 0
	global_load_lds_dwordx4 v[200:201], off
	v_lshl_add_u64 v[200:201], v[220:221], 0, s[76:77]
	s_mov_b32 m0, s10
	s_nop 0
	global_load_lds_dwordx4 v[200:201], off
	v_lshl_add_u64 v[200:201], v[222:223], 0, s[76:77]
	s_mov_b32 m0, s11
	s_nop 0
	global_load_lds_dwordx4 v[200:201], off
	s_waitcnt vmcnt(8)
	s_waitcnt lgkmcnt(0)
	s_setprio 1
	s_barrier
	v_mfma_f32_16x16x32_bf16 v[60:63], v[128:131], v[180:183], v[60:63]
	v_mfma_f32_16x16x32_bf16 v[56:59], v[136:139], v[180:183], v[56:59]
	v_mfma_f32_16x16x32_bf16 v[52:55], v[128:131], v[188:191], v[52:55]
	v_mfma_f32_16x16x32_bf16 v[48:51], v[136:139], v[188:191], v[48:51]
	v_mfma_f32_16x16x32_bf16 v[28:31], v[128:131], v[196:199], v[28:31]
	v_mfma_f32_16x16x32_bf16 v[24:27], v[136:139], v[196:199], v[24:27]
	v_mfma_f32_16x16x32_bf16 v[16:19], v[128:131], v[210:213], v[16:19]
	v_mfma_f32_16x16x32_bf16 v[8:11], v[136:139], v[210:213], v[8:11]
	v_mfma_f32_16x16x32_bf16 v[60:63], v[132:135], v[184:187], v[60:63]
	v_mfma_f32_16x16x32_bf16 v[56:59], v[140:143], v[184:187], v[56:59]
	v_mfma_f32_16x16x32_bf16 v[52:55], v[132:135], v[192:195], v[52:55]
	v_mfma_f32_16x16x32_bf16 v[48:51], v[140:143], v[192:195], v[48:51]
	v_mfma_f32_16x16x32_bf16 v[28:31], v[132:135], v[206:209], v[28:31]
	v_mfma_f32_16x16x32_bf16 v[24:27], v[140:143], v[206:209], v[24:27]
	v_mfma_f32_16x16x32_bf16 v[16:19], v[132:135], v[214:217], v[16:19]
	v_mfma_f32_16x16x32_bf16 v[8:11], v[140:143], v[214:217], v[8:11]
	s_setprio 0
	s_setprio 1
	v_mfma_f32_16x16x32_bf16 v[44:47], v[144:147], v[180:183], v[44:47]
	v_mfma_f32_16x16x32_bf16 v[40:43], v[172:175], v[180:183], v[40:43]
	v_mfma_f32_16x16x32_bf16 v[36:39], v[144:147], v[188:191], v[36:39]
	v_mfma_f32_16x16x32_bf16 v[32:35], v[172:175], v[188:191], v[32:35]
	v_mfma_f32_16x16x32_bf16 v[20:23], v[144:147], v[196:199], v[20:23]
	v_mfma_f32_16x16x32_bf16 v[12:15], v[172:175], v[196:199], v[12:15]
	v_mfma_f32_16x16x32_bf16 v[4:7], v[144:147], v[210:213], v[4:7]
	v_mfma_f32_16x16x32_bf16 v[0:3], v[172:175], v[210:213], v[0:3]
	v_mfma_f32_16x16x32_bf16 v[44:47], v[148:151], v[184:187], v[44:47]
	v_mfma_f32_16x16x32_bf16 v[40:43], v[176:179], v[184:187], v[40:43]
	v_mfma_f32_16x16x32_bf16 v[36:39], v[148:151], v[192:195], v[36:39]
	v_mfma_f32_16x16x32_bf16 v[32:35], v[176:179], v[192:195], v[32:35]
	v_mfma_f32_16x16x32_bf16 v[20:23], v[148:151], v[206:209], v[20:23]
	v_mfma_f32_16x16x32_bf16 v[12:15], v[176:179], v[206:209], v[12:15]
	v_mfma_f32_16x16x32_bf16 v[4:7], v[148:151], v[214:217], v[4:7]
	v_mfma_f32_16x16x32_bf16 v[0:3], v[176:179], v[214:217], v[0:3]
	s_barrier
	s_setprio 0
	s_add_i32 s54, s54, 2
	s_add_u32 s58, s58, 0x100
	s_addc_u32 s59, s59, 0
	s_add_u32 s46, s46, 0x100
	s_addc_u32 s47, s47, 0
	s_cmp_gt_u32 s54, 13
	s_cbranch_scc0 .LBB0_1005
	s_branch .Lpeel_x_1005
.LBB0_1005:
	s_add_u32 s18, s58, 0xfffc0080
	s_addc_u32 s19, s59, -1
	s_add_i32 s20, 0, 0x10000
	s_cmp_eq_u32 s54, 12
	s_cselect_b32 s61, s16, s19
	s_cselect_b32 s60, s17, s18
	s_cselect_b32 s51, s37, s47
	s_cselect_b32 s50, s39, s46
	s_add_i32 s21, 0, 0x14000
	v_add_u32_e32 v140, s20, v170
	v_add_u32_e32 v162, s21, v170
	ds_read_b128 v[128:131], v140
	ds_read_b128 v[132:135], v140 offset:1024
	ds_read_b128 v[136:139], v140 offset:2048
	ds_read_b128 v[140:143], v140 offset:3072
	ds_read_b128 v[144:147], v162
	ds_read_b128 v[148:151], v162 offset:1024
	ds_read_b128 v[172:175], v162 offset:2048
	ds_read_b128 v[176:179], v162 offset:3072
	v_lshl_add_u64 v[200:201], s[58:59], 0, v[164:165]
	s_add_i32 m0, s5, 0xc000
	ds_read_b128 v[180:183], v171
	ds_read_b128 v[184:187], v171 offset:1024
	ds_read_b128 v[188:191], v171 offset:2048
	ds_read_b128 v[192:195], v171 offset:3072
	ds_read_b128 v[196:199], v171 offset:4096
	ds_read_b128 v[206:209], v171 offset:5120
	ds_read_b128 v[210:213], v171 offset:6144
	ds_read_b128 v[214:217], v171 offset:7168
	global_load_lds_dwordx4 v[200:201], off
	v_lshl_add_u64 v[200:201], s[58:59], 0, v[166:167]
	s_add_i32 m0, s5, 0xe000
	s_nop 0
	global_load_lds_dwordx4 v[200:201], off
	s_waitcnt vmcnt(8)
	s_waitcnt lgkmcnt(0)
	s_setprio 1
	s_barrier
	v_mfma_f32_16x16x32_bf16 v[124:127], v[128:131], v[180:183], v[124:127]
	v_mfma_f32_16x16x32_bf16 v[120:123], v[136:139], v[180:183], v[120:123]
	v_mfma_f32_16x16x32_bf16 v[116:119], v[128:131], v[188:191], v[116:119]
	v_mfma_f32_16x16x32_bf16 v[112:115], v[136:139], v[188:191], v[112:115]
	v_mfma_f32_16x16x32_bf16 v[104:107], v[128:131], v[196:199], v[104:107]
	v_mfma_f32_16x16x32_bf16 v[96:99], v[136:139], v[196:199], v[96:99]
	v_mfma_f32_16x16x32_bf16 v[80:83], v[128:131], v[210:213], v[80:83]
	v_mfma_f32_16x16x32_bf16 v[72:75], v[136:139], v[210:213], v[72:75]
	v_mfma_f32_16x16x32_bf16 v[124:127], v[132:135], v[184:187], v[124:127]
	v_mfma_f32_16x16x32_bf16 v[120:123], v[140:143], v[184:187], v[120:123]
	v_mfma_f32_16x16x32_bf16 v[116:119], v[132:135], v[192:195], v[116:119]
	v_mfma_f32_16x16x32_bf16 v[112:115], v[140:143], v[192:195], v[112:115]
	v_mfma_f32_16x16x32_bf16 v[104:107], v[132:135], v[206:209], v[104:107]
	v_mfma_f32_16x16x32_bf16 v[96:99], v[140:143], v[206:209], v[96:99]
	v_mfma_f32_16x16x32_bf16 v[80:83], v[132:135], v[214:217], v[80:83]
	v_mfma_f32_16x16x32_bf16 v[72:75], v[140:143], v[214:217], v[72:75]
	s_setprio 0
	s_setprio 1
	v_mfma_f32_16x16x32_bf16 v[108:111], v[144:147], v[180:183], v[108:111]
	v_mfma_f32_16x16x32_bf16 v[100:103], v[172:175], v[180:183], v[100:103]
	v_mfma_f32_16x16x32_bf16 v[92:95], v[144:147], v[188:191], v[92:95]
	v_mfma_f32_16x16x32_bf16 v[88:91], v[172:175], v[188:191], v[88:91]
	v_mfma_f32_16x16x32_bf16 v[84:87], v[144:147], v[196:199], v[84:87]
	v_mfma_f32_16x16x32_bf16 v[76:79], v[172:175], v[196:199], v[76:79]
	v_mfma_f32_16x16x32_bf16 v[68:71], v[144:147], v[210:213], v[68:71]
	v_mfma_f32_16x16x32_bf16 v[64:67], v[172:175], v[210:213], v[64:67]
	v_mfma_f32_16x16x32_bf16 v[108:111], v[148:151], v[184:187], v[108:111]
	v_mfma_f32_16x16x32_bf16 v[100:103], v[176:179], v[184:187], v[100:103]
	v_mfma_f32_16x16x32_bf16 v[92:95], v[148:151], v[192:195], v[92:95]
	v_mfma_f32_16x16x32_bf16 v[88:91], v[176:179], v[192:195], v[88:91]
	v_mfma_f32_16x16x32_bf16 v[84:87], v[148:151], v[206:209], v[84:87]
	v_mfma_f32_16x16x32_bf16 v[76:79], v[176:179], v[206:209], v[76:79]
	v_mfma_f32_16x16x32_bf16 v[68:71], v[148:151], v[214:217], v[68:71]
	v_mfma_f32_16x16x32_bf16 v[64:67], v[176:179], v[214:217], v[64:67]
	s_barrier
	s_setprio 0
	s_add_i32 s18, s20, s4
	v_lshl_add_u64 v[200:201], s[50:51], 0, v[156:157]
	s_mov_b32 m0, s18
	ds_read_b128 v[180:183], v171 offset:16384
	ds_read_b128 v[184:187], v171 offset:17408
	ds_read_b128 v[188:191], v171 offset:18432
	ds_read_b128 v[192:195], v171 offset:19456
	ds_read_b128 v[196:199], v171 offset:20480
	ds_read_b128 v[206:209], v171 offset:21504
	ds_read_b128 v[210:213], v171 offset:22528
	ds_read_b128 v[214:217], v171 offset:23552
	global_load_lds_dwordx4 v[200:201], off
	s_add_i32 m0, s18, 0x2000
	s_add_u32 s18, s50, 0x40000
	v_lshl_add_u64 v[218:219], s[50:51], 0, v[152:153]
	s_addc_u32 s19, s51, 0
	s_add_i32 s20, s21, s4
	global_load_lds_dwordx4 v[218:219], off
	v_lshl_add_u64 v[220:221], s[18:19], 0, v[156:157]
	s_mov_b32 m0, s20
	v_lshl_add_u64 v[222:223], s[60:61], 0, v[154:155]
	global_load_lds_dwordx4 v[220:221], off
	v_lshl_add_u64 v[220:221], s[18:19], 0, v[152:153]
	s_add_i32 m0, s20, 0x2000
	s_nop 0
	global_load_lds_dwordx4 v[220:221], off
	v_lshl_add_u64 v[220:221], s[60:61], 0, v[158:159]
	s_mov_b32 m0, s5
	s_nop 0
	global_load_lds_dwordx4 v[220:221], off
	s_mov_b32 m0, s6
	s_nop 0
	global_load_lds_dwordx4 v[222:223], off
	s_waitcnt vmcnt(8)
	s_waitcnt lgkmcnt(0)
	s_setprio 1
	s_barrier
	v_mfma_f32_16x16x32_bf16 v[60:63], v[128:131], v[180:183], v[60:63]
	v_mfma_f32_16x16x32_bf16 v[56:59], v[136:139], v[180:183], v[56:59]
	v_mfma_f32_16x16x32_bf16 v[52:55], v[128:131], v[188:191], v[52:55]
	v_mfma_f32_16x16x32_bf16 v[48:51], v[136:139], v[188:191], v[48:51]
	v_mfma_f32_16x16x32_bf16 v[28:31], v[128:131], v[196:199], v[28:31]
	v_mfma_f32_16x16x32_bf16 v[24:27], v[136:139], v[196:199], v[24:27]
	v_mfma_f32_16x16x32_bf16 v[16:19], v[128:131], v[210:213], v[16:19]
	v_mfma_f32_16x16x32_bf16 v[8:11], v[136:139], v[210:213], v[8:11]
	v_mfma_f32_16x16x32_bf16 v[60:63], v[132:135], v[184:187], v[60:63]
	v_mfma_f32_16x16x32_bf16 v[56:59], v[140:143], v[184:187], v[56:59]
	v_mfma_f32_16x16x32_bf16 v[52:55], v[132:135], v[192:195], v[52:55]
	v_mfma_f32_16x16x32_bf16 v[48:51], v[140:143], v[192:195], v[48:51]
	v_mfma_f32_16x16x32_bf16 v[28:31], v[132:135], v[206:209], v[28:31]
	v_mfma_f32_16x16x32_bf16 v[24:27], v[140:143], v[206:209], v[24:27]
	v_mfma_f32_16x16x32_bf16 v[16:19], v[132:135], v[214:217], v[16:19]
	v_mfma_f32_16x16x32_bf16 v[8:11], v[140:143], v[214:217], v[8:11]
	s_setprio 0
	s_setprio 1
	v_mfma_f32_16x16x32_bf16 v[44:47], v[144:147], v[180:183], v[44:47]
	v_mfma_f32_16x16x32_bf16 v[40:43], v[172:175], v[180:183], v[40:43]
	v_mfma_f32_16x16x32_bf16 v[36:39], v[144:147], v[188:191], v[36:39]
	v_mfma_f32_16x16x32_bf16 v[32:35], v[172:175], v[188:191], v[32:35]
	v_mfma_f32_16x16x32_bf16 v[20:23], v[144:147], v[196:199], v[20:23]
	v_mfma_f32_16x16x32_bf16 v[12:15], v[172:175], v[196:199], v[12:15]
	v_mfma_f32_16x16x32_bf16 v[4:7], v[144:147], v[210:213], v[4:7]
	v_mfma_f32_16x16x32_bf16 v[0:3], v[172:175], v[210:213], v[0:3]
	v_mfma_f32_16x16x32_bf16 v[44:47], v[148:151], v[184:187], v[44:47]
	v_mfma_f32_16x16x32_bf16 v[40:43], v[176:179], v[184:187], v[40:43]
	v_mfma_f32_16x16x32_bf16 v[36:39], v[148:151], v[192:195], v[36:39]
	v_mfma_f32_16x16x32_bf16 v[32:35], v[176:179], v[192:195], v[32:35]
	v_mfma_f32_16x16x32_bf16 v[20:23], v[148:151], v[206:209], v[20:23]
	v_mfma_f32_16x16x32_bf16 v[12:15], v[176:179], v[206:209], v[12:15]
	v_mfma_f32_16x16x32_bf16 v[4:7], v[148:151], v[214:217], v[4:7]
	v_mfma_f32_16x16x32_bf16 v[0:3], v[176:179], v[214:217], v[0:3]
	s_barrier
	s_setprio 0
	s_add_i32 s20, 0, 0x18000
	s_add_i32 s21, 0, 0x1c000
	v_add_u32_e32 v140, s20, v170
	v_add_u32_e32 v162, s21, v170
	ds_read_b128 v[128:131], v140
	ds_read_b128 v[132:135], v140 offset:1024
	ds_read_b128 v[136:139], v140 offset:2048
	ds_read_b128 v[140:143], v140 offset:3072
	ds_read_b128 v[144:147], v162
	ds_read_b128 v[148:151], v162 offset:1024
	ds_read_b128 v[172:175], v162 offset:2048
	ds_read_b128 v[176:179], v162 offset:3072
	s_add_u32 s18, s60, 0x40000
	s_addc_u32 s19, s61, 0
	s_mov_b32 m0, s7
	v_lshl_add_u64 v[224:225], s[18:19], 0, v[158:159]
	ds_read_b128 v[180:183], v171 offset:32768
	ds_read_b128 v[184:187], v171 offset:33792
	ds_read_b128 v[188:191], v171 offset:34816
	ds_read_b128 v[192:195], v171 offset:35840
	ds_read_b128 v[196:199], v171 offset:36864
	ds_read_b128 v[206:209], v171 offset:37888
	ds_read_b128 v[210:213], v171 offset:38912
	ds_read_b128 v[214:217], v171 offset:39936
	global_load_lds_dwordx4 v[224:225], off
	v_lshl_add_u64 v[224:225], s[18:19], 0, v[154:155]
	s_mov_b32 m0, s8
	s_nop 0
	global_load_lds_dwordx4 v[224:225], off
	s_waitcnt vmcnt(8)
	s_waitcnt lgkmcnt(0)
	s_setprio 1
	s_barrier
	v_mfma_f32_16x16x32_bf16 v[124:127], v[128:131], v[180:183], v[124:127]
	v_mfma_f32_16x16x32_bf16 v[120:123], v[136:139], v[180:183], v[120:123]
	v_mfma_f32_16x16x32_bf16 v[116:119], v[128:131], v[188:191], v[116:119]
	v_mfma_f32_16x16x32_bf16 v[112:115], v[136:139], v[188:191], v[112:115]
	v_mfma_f32_16x16x32_bf16 v[104:107], v[128:131], v[196:199], v[104:107]
	v_mfma_f32_16x16x32_bf16 v[96:99], v[136:139], v[196:199], v[96:99]
	v_mfma_f32_16x16x32_bf16 v[80:83], v[128:131], v[210:213], v[80:83]
	v_mfma_f32_16x16x32_bf16 v[72:75], v[136:139], v[210:213], v[72:75]
	v_mfma_f32_16x16x32_bf16 v[124:127], v[132:135], v[184:187], v[124:127]
	v_mfma_f32_16x16x32_bf16 v[120:123], v[140:143], v[184:187], v[120:123]
	v_mfma_f32_16x16x32_bf16 v[116:119], v[132:135], v[192:195], v[116:119]
	v_mfma_f32_16x16x32_bf16 v[112:115], v[140:143], v[192:195], v[112:115]
	v_mfma_f32_16x16x32_bf16 v[104:107], v[132:135], v[206:209], v[104:107]
	v_mfma_f32_16x16x32_bf16 v[96:99], v[140:143], v[206:209], v[96:99]
	v_mfma_f32_16x16x32_bf16 v[80:83], v[132:135], v[214:217], v[80:83]
	v_mfma_f32_16x16x32_bf16 v[72:75], v[140:143], v[214:217], v[72:75]
	s_setprio 0
	s_setprio 1
	v_mfma_f32_16x16x32_bf16 v[108:111], v[144:147], v[180:183], v[108:111]
	v_mfma_f32_16x16x32_bf16 v[100:103], v[172:175], v[180:183], v[100:103]
	v_mfma_f32_16x16x32_bf16 v[92:95], v[144:147], v[188:191], v[92:95]
	v_mfma_f32_16x16x32_bf16 v[88:91], v[172:175], v[188:191], v[88:91]
	v_mfma_f32_16x16x32_bf16 v[84:87], v[144:147], v[196:199], v[84:87]
	v_mfma_f32_16x16x32_bf16 v[76:79], v[172:175], v[196:199], v[76:79]
	v_mfma_f32_16x16x32_bf16 v[68:71], v[144:147], v[210:213], v[68:71]
	v_mfma_f32_16x16x32_bf16 v[64:67], v[172:175], v[210:213], v[64:67]
	v_mfma_f32_16x16x32_bf16 v[108:111], v[148:151], v[184:187], v[108:111]
	v_mfma_f32_16x16x32_bf16 v[100:103], v[176:179], v[184:187], v[100:103]
	v_mfma_f32_16x16x32_bf16 v[92:95], v[148:151], v[192:195], v[92:95]
	v_mfma_f32_16x16x32_bf16 v[88:91], v[176:179], v[192:195], v[88:91]
	v_mfma_f32_16x16x32_bf16 v[84:87], v[148:151], v[206:209], v[84:87]
	v_mfma_f32_16x16x32_bf16 v[76:79], v[176:179], v[206:209], v[76:79]
	v_mfma_f32_16x16x32_bf16 v[68:71], v[148:151], v[214:217], v[68:71]
	v_mfma_f32_16x16x32_bf16 v[64:67], v[176:179], v[214:217], v[64:67]
	s_barrier
	s_setprio 0
	s_add_i32 s18, s20, s4
	v_lshl_add_u64 v[200:201], v[200:201], 0, s[76:77]
	s_mov_b32 m0, s18
	ds_read_b128 v[180:183], v171 offset:49152
	ds_read_b128 v[184:187], v171 offset:50176
	ds_read_b128 v[188:191], v171 offset:51200
	ds_read_b128 v[192:195], v171 offset:52224
	ds_read_b128 v[196:199], v171 offset:53248
	ds_read_b128 v[206:209], v171 offset:54272
	ds_read_b128 v[210:213], v171 offset:55296
	ds_read_b128 v[214:217], v171 offset:56320
	global_load_lds_dwordx4 v[200:201], off
	s_add_i32 m0, s18, 0x2000
	s_add_u32 s18, s50, 0x40080
	v_lshl_add_u64 v[200:201], v[218:219], 0, s[76:77]
	s_addc_u32 s19, s51, 0
	s_add_i32 s20, s21, s4
	global_load_lds_dwordx4 v[200:201], off
	v_lshl_add_u64 v[200:201], s[18:19], 0, v[156:157]
	s_mov_b32 m0, s20
	s_nop 0
	global_load_lds_dwordx4 v[200:201], off
	v_lshl_add_u64 v[200:201], s[18:19], 0, v[152:153]
	s_add_i32 m0, s20, 0x2000
	s_nop 0
	global_load_lds_dwordx4 v[200:201], off
	v_lshl_add_u64 v[200:201], v[220:221], 0, s[76:77]
	s_mov_b32 m0, s10
	s_nop 0
	global_load_lds_dwordx4 v[200:201], off
	v_lshl_add_u64 v[200:201], v[222:223], 0, s[76:77]
	s_mov_b32 m0, s11
	s_nop 0
	global_load_lds_dwordx4 v[200:201], off
	s_waitcnt vmcnt(8)
	s_waitcnt lgkmcnt(0)
	s_setprio 1
	s_barrier
	v_mfma_f32_16x16x32_bf16 v[60:63], v[128:131], v[180:183], v[60:63]
	v_mfma_f32_16x16x32_bf16 v[56:59], v[136:139], v[180:183], v[56:59]
	v_mfma_f32_16x16x32_bf16 v[52:55], v[128:131], v[188:191], v[52:55]
	v_mfma_f32_16x16x32_bf16 v[48:51], v[136:139], v[188:191], v[48:51]
	v_mfma_f32_16x16x32_bf16 v[28:31], v[128:131], v[196:199], v[28:31]
	v_mfma_f32_16x16x32_bf16 v[24:27], v[136:139], v[196:199], v[24:27]
	v_mfma_f32_16x16x32_bf16 v[16:19], v[128:131], v[210:213], v[16:19]
	v_mfma_f32_16x16x32_bf16 v[8:11], v[136:139], v[210:213], v[8:11]
	v_mfma_f32_16x16x32_bf16 v[60:63], v[132:135], v[184:187], v[60:63]
	v_mfma_f32_16x16x32_bf16 v[56:59], v[140:143], v[184:187], v[56:59]
	v_mfma_f32_16x16x32_bf16 v[52:55], v[132:135], v[192:195], v[52:55]
	v_mfma_f32_16x16x32_bf16 v[48:51], v[140:143], v[192:195], v[48:51]
	v_mfma_f32_16x16x32_bf16 v[28:31], v[132:135], v[206:209], v[28:31]
	v_mfma_f32_16x16x32_bf16 v[24:27], v[140:143], v[206:209], v[24:27]
	v_mfma_f32_16x16x32_bf16 v[16:19], v[132:135], v[214:217], v[16:19]
	v_mfma_f32_16x16x32_bf16 v[8:11], v[140:143], v[214:217], v[8:11]
	s_setprio 0
	s_setprio 1
	v_mfma_f32_16x16x32_bf16 v[44:47], v[144:147], v[180:183], v[44:47]
	v_mfma_f32_16x16x32_bf16 v[40:43], v[172:175], v[180:183], v[40:43]
	v_mfma_f32_16x16x32_bf16 v[36:39], v[144:147], v[188:191], v[36:39]
	v_mfma_f32_16x16x32_bf16 v[32:35], v[172:175], v[188:191], v[32:35]
	v_mfma_f32_16x16x32_bf16 v[20:23], v[144:147], v[196:199], v[20:23]
	v_mfma_f32_16x16x32_bf16 v[12:15], v[172:175], v[196:199], v[12:15]
	v_mfma_f32_16x16x32_bf16 v[4:7], v[144:147], v[210:213], v[4:7]
	v_mfma_f32_16x16x32_bf16 v[0:3], v[172:175], v[210:213], v[0:3]
	v_mfma_f32_16x16x32_bf16 v[44:47], v[148:151], v[184:187], v[44:47]
	v_mfma_f32_16x16x32_bf16 v[40:43], v[176:179], v[184:187], v[40:43]
	v_mfma_f32_16x16x32_bf16 v[36:39], v[148:151], v[192:195], v[36:39]
	v_mfma_f32_16x16x32_bf16 v[32:35], v[176:179], v[192:195], v[32:35]
	v_mfma_f32_16x16x32_bf16 v[20:23], v[148:151], v[206:209], v[20:23]
	v_mfma_f32_16x16x32_bf16 v[12:15], v[176:179], v[206:209], v[12:15]
	v_mfma_f32_16x16x32_bf16 v[4:7], v[148:151], v[214:217], v[4:7]
	v_mfma_f32_16x16x32_bf16 v[0:3], v[176:179], v[214:217], v[0:3]
	s_barrier
	s_setprio 0
	s_add_i32 s54, s54, 2
	s_add_u32 s58, s58, 0x100
	s_addc_u32 s59, s59, 0
	s_add_u32 s46, s46, 0x100
	s_addc_u32 s47, s47, 0
	s_cmp_gt_u32 s54, 13
	s_cbranch_scc0 .LBB0_1005

.LBB0_1137:
	s_ashr_i32 s37, s36, 31
	s_lshl_b64 s[18:19], s[36:37], 19
	s_add_u32 s40, s96, s18
	s_addc_u32 s41, s97, s19
	s_and_b64 s[18:19], s[42:43], exec
	s_cselect_b32 s17, s41, s59
	s_cselect_b32 s37, s40, s58
	s_ashr_i32 s39, s38, 31
	s_lshl_b64 s[18:19], s[38:39], 19
	s_add_u32 s48, s5, s18
	s_addc_u32 s49, s6, s19
	s_and_b64 s[18:19], s[42:43], exec
	s_cselect_b32 s39, s49, s51
	s_cselect_b32 s46, s48, s50
	s_add_u32 s58, s58, 0x40080
	s_addc_u32 s59, s59, 0
	s_add_u32 s47, s50, 0x100
	s_addc_u32 s62, s51, 0
	s_mov_b32 s63, -2
	s_add_u32 s18, s58, 0xfffc0080
	s_addc_u32 s19, s59, -1
	s_add_i32 s20, 0, 0x10000
	s_cmp_eq_u32 s63, 12
	s_cselect_b32 s61, s17, s19
	s_cselect_b32 s60, s37, s18
	v_add_u32_e32 v140, s20, v143
	s_cselect_b32 s51, s39, s62
	s_cselect_b32 s50, s46, s47
	s_add_i32 s21, 0, 0x14000
	ds_read_b128 v[146:149], v140
	ds_read_b128 v[150:153], v140 offset:1024
	ds_read_b128 v[154:157], v140 offset:2048
	ds_read_b128 v[164:167], v140 offset:3072
	v_add_u32_e32 v140, s21, v143
	ds_read_b128 v[168:171], v140
	ds_read_b128 v[172:175], v140 offset:1024
	ds_read_b128 v[176:179], v140 offset:2048
	ds_read_b128 v[180:183], v140 offset:3072
	v_lshl_add_u64 v[140:141], s[58:59], 0, v[136:137]
	s_add_i32 m0, s8, 0xc000
	ds_read_b128 v[184:187], v144
	ds_read_b128 v[188:191], v144 offset:1024
	ds_read_b128 v[192:195], v144 offset:2048
	ds_read_b128 v[196:199], v144 offset:3072
	ds_read_b128 v[206:209], v144 offset:4096
	ds_read_b128 v[210:213], v144 offset:5120
	ds_read_b128 v[214:217], v144 offset:6144
	ds_read_b128 v[218:221], v144 offset:7168
	global_load_lds_dwordx4 v[140:141], off
	v_lshl_add_u64 v[140:141], s[58:59], 0, v[138:139]
	s_add_i32 m0, s8, 0xe000
	s_nop 0
	global_load_lds_dwordx4 v[140:141], off
	s_waitcnt vmcnt(8)
	s_waitcnt lgkmcnt(0)
	s_setprio 1
	s_barrier
	v_mfma_f32_16x16x32_bf16 v[124:127], v[146:149], v[184:187], 0
	v_mfma_f32_16x16x32_bf16 v[120:123], v[154:157], v[184:187], 0
	v_mfma_f32_16x16x32_bf16 v[108:111], v[146:149], v[192:195], 0
	v_mfma_f32_16x16x32_bf16 v[104:107], v[154:157], v[192:195], 0
	v_mfma_f32_16x16x32_bf16 v[92:95], v[146:149], v[206:209], 0
	v_mfma_f32_16x16x32_bf16 v[88:91], v[154:157], v[206:209], 0
	v_mfma_f32_16x16x32_bf16 v[76:79], v[146:149], v[214:217], 0
	v_mfma_f32_16x16x32_bf16 v[72:75], v[154:157], v[214:217], 0
	v_mfma_f32_16x16x32_bf16 v[124:127], v[150:153], v[188:191], v[124:127]
	v_mfma_f32_16x16x32_bf16 v[120:123], v[164:167], v[188:191], v[120:123]
	v_mfma_f32_16x16x32_bf16 v[108:111], v[150:153], v[196:199], v[108:111]
	v_mfma_f32_16x16x32_bf16 v[104:107], v[164:167], v[196:199], v[104:107]
	v_mfma_f32_16x16x32_bf16 v[92:95], v[150:153], v[210:213], v[92:95]
	v_mfma_f32_16x16x32_bf16 v[88:91], v[164:167], v[210:213], v[88:91]
	v_mfma_f32_16x16x32_bf16 v[76:79], v[150:153], v[218:221], v[76:79]
	v_mfma_f32_16x16x32_bf16 v[72:75], v[164:167], v[218:221], v[72:75]
	s_setprio 0
	s_setprio 1
	v_mfma_f32_16x16x32_bf16 v[116:119], v[168:171], v[184:187], 0
	v_mfma_f32_16x16x32_bf16 v[112:115], v[176:179], v[184:187], 0
	v_mfma_f32_16x16x32_bf16 v[100:103], v[168:171], v[192:195], 0
	v_mfma_f32_16x16x32_bf16 v[96:99], v[176:179], v[192:195], 0
	v_mfma_f32_16x16x32_bf16 v[84:87], v[168:171], v[206:209], 0
	v_mfma_f32_16x16x32_bf16 v[80:83], v[176:179], v[206:209], 0
	v_mfma_f32_16x16x32_bf16 v[68:71], v[168:171], v[214:217], 0
	v_mfma_f32_16x16x32_bf16 v[64:67], v[176:179], v[214:217], 0
	v_mfma_f32_16x16x32_bf16 v[116:119], v[172:175], v[188:191], v[116:119]
	v_mfma_f32_16x16x32_bf16 v[112:115], v[180:183], v[188:191], v[112:115]
	v_mfma_f32_16x16x32_bf16 v[100:103], v[172:175], v[196:199], v[100:103]
	v_mfma_f32_16x16x32_bf16 v[96:99], v[180:183], v[196:199], v[96:99]
	v_mfma_f32_16x16x32_bf16 v[84:87], v[172:175], v[210:213], v[84:87]
	v_mfma_f32_16x16x32_bf16 v[80:83], v[180:183], v[210:213], v[80:83]
	v_mfma_f32_16x16x32_bf16 v[68:71], v[172:175], v[218:221], v[68:71]
	v_mfma_f32_16x16x32_bf16 v[64:67], v[180:183], v[218:221], v[64:67]
	s_barrier
	s_setprio 0
	s_add_i32 s18, s20, s7
	v_lshl_add_u64 v[140:141], s[50:51], 0, v[132:133]
	s_mov_b32 m0, s18
	ds_read_b128 v[184:187], v144 offset:16384
	ds_read_b128 v[188:191], v144 offset:17408
	ds_read_b128 v[192:195], v144 offset:18432
	ds_read_b128 v[196:199], v144 offset:19456
	ds_read_b128 v[206:209], v144 offset:20480
	ds_read_b128 v[210:213], v144 offset:21504
	ds_read_b128 v[214:217], v144 offset:22528
	ds_read_b128 v[218:221], v144 offset:23552
	global_load_lds_dwordx4 v[140:141], off
	s_add_i32 m0, s18, 0x2000
	s_add_u32 s18, s50, 0x40000
	v_lshl_add_u64 v[158:159], s[50:51], 0, v[128:129]
	s_addc_u32 s19, s51, 0
	s_add_i32 s20, s21, s7
	global_load_lds_dwordx4 v[158:159], off
	v_lshl_add_u64 v[200:201], s[18:19], 0, v[132:133]
	s_mov_b32 m0, s20
	v_lshl_add_u64 v[222:223], s[60:61], 0, v[130:131]
	global_load_lds_dwordx4 v[200:201], off
	v_lshl_add_u64 v[200:201], s[18:19], 0, v[128:129]
	s_add_i32 m0, s20, 0x2000
	s_nop 0
	global_load_lds_dwordx4 v[200:201], off
	v_lshl_add_u64 v[200:201], s[60:61], 0, v[134:135]
	s_mov_b32 m0, s8
	s_nop 0
	global_load_lds_dwordx4 v[200:201], off
	s_mov_b32 m0, s9
	s_nop 0
	global_load_lds_dwordx4 v[222:223], off
	s_waitcnt vmcnt(8)
	s_waitcnt lgkmcnt(0)
	s_setprio 1
	s_barrier
	v_mfma_f32_16x16x32_bf16 v[60:63], v[146:149], v[184:187], 0
	v_mfma_f32_16x16x32_bf16 v[56:59], v[154:157], v[184:187], 0
	v_mfma_f32_16x16x32_bf16 v[44:47], v[146:149], v[192:195], 0
	v_mfma_f32_16x16x32_bf16 v[40:43], v[154:157], v[192:195], 0
	v_mfma_f32_16x16x32_bf16 v[28:31], v[146:149], v[206:209], 0
	v_mfma_f32_16x16x32_bf16 v[24:27], v[154:157], v[206:209], 0
	v_mfma_f32_16x16x32_bf16 v[12:15], v[146:149], v[214:217], 0
	v_mfma_f32_16x16x32_bf16 v[8:11], v[154:157], v[214:217], 0
	v_mfma_f32_16x16x32_bf16 v[60:63], v[150:153], v[188:191], v[60:63]
	v_mfma_f32_16x16x32_bf16 v[56:59], v[164:167], v[188:191], v[56:59]
	v_mfma_f32_16x16x32_bf16 v[44:47], v[150:153], v[196:199], v[44:47]
	v_mfma_f32_16x16x32_bf16 v[40:43], v[164:167], v[196:199], v[40:43]
	v_mfma_f32_16x16x32_bf16 v[28:31], v[150:153], v[210:213], v[28:31]
	v_mfma_f32_16x16x32_bf16 v[24:27], v[164:167], v[210:213], v[24:27]
	v_mfma_f32_16x16x32_bf16 v[12:15], v[150:153], v[218:221], v[12:15]
	v_mfma_f32_16x16x32_bf16 v[8:11], v[164:167], v[218:221], v[8:11]
	s_setprio 0
	s_setprio 1
	v_mfma_f32_16x16x32_bf16 v[52:55], v[168:171], v[184:187], 0
	v_mfma_f32_16x16x32_bf16 v[48:51], v[176:179], v[184:187], 0
	v_mfma_f32_16x16x32_bf16 v[36:39], v[168:171], v[192:195], 0
	v_mfma_f32_16x16x32_bf16 v[32:35], v[176:179], v[192:195], 0
	v_mfma_f32_16x16x32_bf16 v[20:23], v[168:171], v[206:209], 0
	v_mfma_f32_16x16x32_bf16 v[16:19], v[176:179], v[206:209], 0
	v_mfma_f32_16x16x32_bf16 v[4:7], v[168:171], v[214:217], 0
	v_mfma_f32_16x16x32_bf16 v[0:3], v[176:179], v[214:217], 0
	v_mfma_f32_16x16x32_bf16 v[52:55], v[172:175], v[188:191], v[52:55]
	v_mfma_f32_16x16x32_bf16 v[48:51], v[180:183], v[188:191], v[48:51]
	v_mfma_f32_16x16x32_bf16 v[36:39], v[172:175], v[196:199], v[36:39]
	v_mfma_f32_16x16x32_bf16 v[32:35], v[180:183], v[196:199], v[32:35]
	v_mfma_f32_16x16x32_bf16 v[20:23], v[172:175], v[210:213], v[20:23]
	v_mfma_f32_16x16x32_bf16 v[16:19], v[180:183], v[210:213], v[16:19]
	v_mfma_f32_16x16x32_bf16 v[4:7], v[172:175], v[218:221], v[4:7]
	v_mfma_f32_16x16x32_bf16 v[0:3], v[180:183], v[218:221], v[0:3]
	s_barrier
	s_setprio 0
	s_add_i32 s20, 0, 0x18000
	v_add_u32_e32 v145, s20, v143
	s_add_i32 s21, 0, 0x1c000
	ds_read_b128 v[146:149], v145
	ds_read_b128 v[150:153], v145 offset:1024
	ds_read_b128 v[154:157], v145 offset:2048
	ds_read_b128 v[164:167], v145 offset:3072
	v_add_u32_e32 v145, s21, v143
	ds_read_b128 v[168:171], v145
	ds_read_b128 v[172:175], v145 offset:1024
	ds_read_b128 v[176:179], v145 offset:2048
	ds_read_b128 v[180:183], v145 offset:3072
	s_add_u32 s18, s60, 0x40000
	s_addc_u32 s19, s61, 0
	s_mov_b32 m0, s10
	v_lshl_add_u64 v[224:225], s[18:19], 0, v[134:135]
	ds_read_b128 v[184:187], v144 offset:32768
	ds_read_b128 v[188:191], v144 offset:33792
	ds_read_b128 v[192:195], v144 offset:34816
	ds_read_b128 v[196:199], v144 offset:35840
	ds_read_b128 v[206:209], v144 offset:36864
	ds_read_b128 v[210:213], v144 offset:37888
	ds_read_b128 v[214:217], v144 offset:38912
	ds_read_b128 v[218:221], v144 offset:39936
	global_load_lds_dwordx4 v[224:225], off
	v_lshl_add_u64 v[224:225], s[18:19], 0, v[130:131]
	s_mov_b32 m0, s11
	s_nop 0
	global_load_lds_dwordx4 v[224:225], off
	s_waitcnt vmcnt(8)
	s_waitcnt lgkmcnt(0)
	s_setprio 1
	s_barrier
	v_mfma_f32_16x16x32_bf16 v[124:127], v[146:149], v[184:187], v[124:127]
	v_mfma_f32_16x16x32_bf16 v[120:123], v[154:157], v[184:187], v[120:123]
	v_mfma_f32_16x16x32_bf16 v[108:111], v[146:149], v[192:195], v[108:111]
	v_mfma_f32_16x16x32_bf16 v[104:107], v[154:157], v[192:195], v[104:107]
	v_mfma_f32_16x16x32_bf16 v[92:95], v[146:149], v[206:209], v[92:95]
	v_mfma_f32_16x16x32_bf16 v[88:91], v[154:157], v[206:209], v[88:91]
	v_mfma_f32_16x16x32_bf16 v[76:79], v[146:149], v[214:217], v[76:79]
	v_mfma_f32_16x16x32_bf16 v[72:75], v[154:157], v[214:217], v[72:75]
	v_mfma_f32_16x16x32_bf16 v[124:127], v[150:153], v[188:191], v[124:127]
	v_mfma_f32_16x16x32_bf16 v[120:123], v[164:167], v[188:191], v[120:123]
	v_mfma_f32_16x16x32_bf16 v[108:111], v[150:153], v[196:199], v[108:111]
	v_mfma_f32_16x16x32_bf16 v[104:107], v[164:167], v[196:199], v[104:107]
	v_mfma_f32_16x16x32_bf16 v[92:95], v[150:153], v[210:213], v[92:95]
	v_mfma_f32_16x16x32_bf16 v[88:91], v[164:167], v[210:213], v[88:91]
	v_mfma_f32_16x16x32_bf16 v[76:79], v[150:153], v[218:221], v[76:79]
	v_mfma_f32_16x16x32_bf16 v[72:75], v[164:167], v[218:221], v[72:75]
	s_setprio 0
	s_setprio 1
	v_mfma_f32_16x16x32_bf16 v[116:119], v[168:171], v[184:187], v[116:119]
	v_mfma_f32_16x16x32_bf16 v[112:115], v[176:179], v[184:187], v[112:115]
	v_mfma_f32_16x16x32_bf16 v[100:103], v[168:171], v[192:195], v[100:103]
	v_mfma_f32_16x16x32_bf16 v[96:99], v[176:179], v[192:195], v[96:99]
	v_mfma_f32_16x16x32_bf16 v[84:87], v[168:171], v[206:209], v[84:87]
	v_mfma_f32_16x16x32_bf16 v[80:83], v[176:179], v[206:209], v[80:83]
	v_mfma_f32_16x16x32_bf16 v[68:71], v[168:171], v[214:217], v[68:71]
	v_mfma_f32_16x16x32_bf16 v[64:67], v[176:179], v[214:217], v[64:67]
	v_mfma_f32_16x16x32_bf16 v[116:119], v[172:175], v[188:191], v[116:119]
	v_mfma_f32_16x16x32_bf16 v[112:115], v[180:183], v[188:191], v[112:115]
	v_mfma_f32_16x16x32_bf16 v[100:103], v[172:175], v[196:199], v[100:103]
	v_mfma_f32_16x16x32_bf16 v[96:99], v[180:183], v[196:199], v[96:99]
	v_mfma_f32_16x16x32_bf16 v[84:87], v[172:175], v[210:213], v[84:87]
	v_mfma_f32_16x16x32_bf16 v[80:83], v[180:183], v[210:213], v[80:83]
	v_mfma_f32_16x16x32_bf16 v[68:71], v[172:175], v[218:221], v[68:71]
	v_mfma_f32_16x16x32_bf16 v[64:67], v[180:183], v[218:221], v[64:67]
	s_barrier
	s_setprio 0
	s_add_i32 s18, s20, s7
	v_lshl_add_u64 v[140:141], v[140:141], 0, s[76:77]
	s_mov_b32 m0, s18
	ds_read_b128 v[184:187], v144 offset:49152
	ds_read_b128 v[188:191], v144 offset:50176
	ds_read_b128 v[192:195], v144 offset:51200
	ds_read_b128 v[196:199], v144 offset:52224
	ds_read_b128 v[206:209], v144 offset:53248
	ds_read_b128 v[210:213], v144 offset:54272
	ds_read_b128 v[214:217], v144 offset:55296
	ds_read_b128 v[218:221], v144 offset:56320
	global_load_lds_dwordx4 v[140:141], off
	s_add_i32 m0, s18, 0x2000
	s_add_u32 s18, s50, 0x40080
	v_lshl_add_u64 v[140:141], v[158:159], 0, s[76:77]
	s_addc_u32 s19, s51, 0
	s_add_i32 s20, s21, s7
	global_load_lds_dwordx4 v[140:141], off
	v_lshl_add_u64 v[140:141], s[18:19], 0, v[132:133]
	s_mov_b32 m0, s20
	s_nop 0
	global_load_lds_dwordx4 v[140:141], off
	v_lshl_add_u64 v[140:141], s[18:19], 0, v[128:129]
	s_add_i32 m0, s20, 0x2000
	s_nop 0
	global_load_lds_dwordx4 v[140:141], off
	v_lshl_add_u64 v[140:141], v[200:201], 0, s[76:77]
	s_mov_b32 m0, s12
	s_nop 0
	global_load_lds_dwordx4 v[140:141], off
	v_lshl_add_u64 v[140:141], v[222:223], 0, s[76:77]
	s_mov_b32 m0, s13
	s_nop 0
	global_load_lds_dwordx4 v[140:141], off
	s_waitcnt vmcnt(8)
	s_waitcnt lgkmcnt(0)
	s_setprio 1
	s_barrier
	v_mfma_f32_16x16x32_bf16 v[60:63], v[146:149], v[184:187], v[60:63]
	v_mfma_f32_16x16x32_bf16 v[56:59], v[154:157], v[184:187], v[56:59]
	v_mfma_f32_16x16x32_bf16 v[44:47], v[146:149], v[192:195], v[44:47]
	v_mfma_f32_16x16x32_bf16 v[40:43], v[154:157], v[192:195], v[40:43]
	v_mfma_f32_16x16x32_bf16 v[28:31], v[146:149], v[206:209], v[28:31]
	v_mfma_f32_16x16x32_bf16 v[24:27], v[154:157], v[206:209], v[24:27]
	v_mfma_f32_16x16x32_bf16 v[12:15], v[146:149], v[214:217], v[12:15]
	v_mfma_f32_16x16x32_bf16 v[8:11], v[154:157], v[214:217], v[8:11]
	v_mfma_f32_16x16x32_bf16 v[60:63], v[150:153], v[188:191], v[60:63]
	v_mfma_f32_16x16x32_bf16 v[56:59], v[164:167], v[188:191], v[56:59]
	v_mfma_f32_16x16x32_bf16 v[44:47], v[150:153], v[196:199], v[44:47]
	v_mfma_f32_16x16x32_bf16 v[40:43], v[164:167], v[196:199], v[40:43]
	v_mfma_f32_16x16x32_bf16 v[28:31], v[150:153], v[210:213], v[28:31]
	v_mfma_f32_16x16x32_bf16 v[24:27], v[164:167], v[210:213], v[24:27]
	v_mfma_f32_16x16x32_bf16 v[12:15], v[150:153], v[218:221], v[12:15]
	v_mfma_f32_16x16x32_bf16 v[8:11], v[164:167], v[218:221], v[8:11]
	s_setprio 0
	s_setprio 1
	v_mfma_f32_16x16x32_bf16 v[52:55], v[168:171], v[184:187], v[52:55]
	v_mfma_f32_16x16x32_bf16 v[48:51], v[176:179], v[184:187], v[48:51]
	v_mfma_f32_16x16x32_bf16 v[36:39], v[168:171], v[192:195], v[36:39]
	v_mfma_f32_16x16x32_bf16 v[32:35], v[176:179], v[192:195], v[32:35]
	v_mfma_f32_16x16x32_bf16 v[20:23], v[168:171], v[206:209], v[20:23]
	v_mfma_f32_16x16x32_bf16 v[16:19], v[176:179], v[206:209], v[16:19]
	v_mfma_f32_16x16x32_bf16 v[4:7], v[168:171], v[214:217], v[4:7]
	v_mfma_f32_16x16x32_bf16 v[0:3], v[176:179], v[214:217], v[0:3]
	v_mfma_f32_16x16x32_bf16 v[52:55], v[172:175], v[188:191], v[52:55]
	v_mfma_f32_16x16x32_bf16 v[48:51], v[180:183], v[188:191], v[48:51]
	v_mfma_f32_16x16x32_bf16 v[36:39], v[172:175], v[196:199], v[36:39]
	v_mfma_f32_16x16x32_bf16 v[32:35], v[180:183], v[196:199], v[32:35]
	v_mfma_f32_16x16x32_bf16 v[20:23], v[172:175], v[210:213], v[20:23]
	v_mfma_f32_16x16x32_bf16 v[16:19], v[180:183], v[210:213], v[16:19]
	v_mfma_f32_16x16x32_bf16 v[4:7], v[172:175], v[218:221], v[4:7]
	v_mfma_f32_16x16x32_bf16 v[0:3], v[180:183], v[218:221], v[0:3]
	s_barrier
	s_setprio 0
	s_add_i32 s63, s63, 2
	s_add_u32 s58, s58, 0x100
	s_addc_u32 s59, s59, 0
	s_add_u32 s47, s47, 0x100
	s_addc_u32 s62, s62, 0
	s_cmp_gt_u32 s63, 13
	s_cbranch_scc0 .LBB0_1138
	s_branch .Lpeel_x_1138
.LBB0_1138:
	s_add_u32 s18, s58, 0xfffc0080
	s_addc_u32 s19, s59, -1
	s_add_i32 s20, 0, 0x10000
	s_cmp_eq_u32 s63, 12
	s_cselect_b32 s61, s17, s19
	s_cselect_b32 s60, s37, s18
	v_add_u32_e32 v140, s20, v143
	s_cselect_b32 s51, s39, s62
	s_cselect_b32 s50, s46, s47
	s_add_i32 s21, 0, 0x14000
	ds_read_b128 v[146:149], v140
	ds_read_b128 v[150:153], v140 offset:1024
	ds_read_b128 v[154:157], v140 offset:2048
	ds_read_b128 v[164:167], v140 offset:3072
	v_add_u32_e32 v140, s21, v143
	ds_read_b128 v[168:171], v140
	ds_read_b128 v[172:175], v140 offset:1024
	ds_read_b128 v[176:179], v140 offset:2048
	ds_read_b128 v[180:183], v140 offset:3072
	v_lshl_add_u64 v[140:141], s[58:59], 0, v[136:137]
	s_add_i32 m0, s8, 0xc000
	ds_read_b128 v[184:187], v144
	ds_read_b128 v[188:191], v144 offset:1024
	ds_read_b128 v[192:195], v144 offset:2048
	ds_read_b128 v[196:199], v144 offset:3072
	ds_read_b128 v[206:209], v144 offset:4096
	ds_read_b128 v[210:213], v144 offset:5120
	ds_read_b128 v[214:217], v144 offset:6144
	ds_read_b128 v[218:221], v144 offset:7168
	global_load_lds_dwordx4 v[140:141], off
	v_lshl_add_u64 v[140:141], s[58:59], 0, v[138:139]
	s_add_i32 m0, s8, 0xe000
	s_nop 0
	global_load_lds_dwordx4 v[140:141], off
	s_waitcnt vmcnt(8)
	s_waitcnt lgkmcnt(0)
	s_setprio 1
	s_barrier
	v_mfma_f32_16x16x32_bf16 v[124:127], v[146:149], v[184:187], v[124:127]
	v_mfma_f32_16x16x32_bf16 v[120:123], v[154:157], v[184:187], v[120:123]
	v_mfma_f32_16x16x32_bf16 v[108:111], v[146:149], v[192:195], v[108:111]
	v_mfma_f32_16x16x32_bf16 v[104:107], v[154:157], v[192:195], v[104:107]
	v_mfma_f32_16x16x32_bf16 v[92:95], v[146:149], v[206:209], v[92:95]
	v_mfma_f32_16x16x32_bf16 v[88:91], v[154:157], v[206:209], v[88:91]
	v_mfma_f32_16x16x32_bf16 v[76:79], v[146:149], v[214:217], v[76:79]
	v_mfma_f32_16x16x32_bf16 v[72:75], v[154:157], v[214:217], v[72:75]
	v_mfma_f32_16x16x32_bf16 v[124:127], v[150:153], v[188:191], v[124:127]
	v_mfma_f32_16x16x32_bf16 v[120:123], v[164:167], v[188:191], v[120:123]
	v_mfma_f32_16x16x32_bf16 v[108:111], v[150:153], v[196:199], v[108:111]
	v_mfma_f32_16x16x32_bf16 v[104:107], v[164:167], v[196:199], v[104:107]
	v_mfma_f32_16x16x32_bf16 v[92:95], v[150:153], v[210:213], v[92:95]
	v_mfma_f32_16x16x32_bf16 v[88:91], v[164:167], v[210:213], v[88:91]
	v_mfma_f32_16x16x32_bf16 v[76:79], v[150:153], v[218:221], v[76:79]
	v_mfma_f32_16x16x32_bf16 v[72:75], v[164:167], v[218:221], v[72:75]
	s_setprio 0
	s_setprio 1
	v_mfma_f32_16x16x32_bf16 v[116:119], v[168:171], v[184:187], v[116:119]
	v_mfma_f32_16x16x32_bf16 v[112:115], v[176:179], v[184:187], v[112:115]
	v_mfma_f32_16x16x32_bf16 v[100:103], v[168:171], v[192:195], v[100:103]
	v_mfma_f32_16x16x32_bf16 v[96:99], v[176:179], v[192:195], v[96:99]
	v_mfma_f32_16x16x32_bf16 v[84:87], v[168:171], v[206:209], v[84:87]
	v_mfma_f32_16x16x32_bf16 v[80:83], v[176:179], v[206:209], v[80:83]
	v_mfma_f32_16x16x32_bf16 v[68:71], v[168:171], v[214:217], v[68:71]
	v_mfma_f32_16x16x32_bf16 v[64:67], v[176:179], v[214:217], v[64:67]
	v_mfma_f32_16x16x32_bf16 v[116:119], v[172:175], v[188:191], v[116:119]
	v_mfma_f32_16x16x32_bf16 v[112:115], v[180:183], v[188:191], v[112:115]
	v_mfma_f32_16x16x32_bf16 v[100:103], v[172:175], v[196:199], v[100:103]
	v_mfma_f32_16x16x32_bf16 v[96:99], v[180:183], v[196:199], v[96:99]
	v_mfma_f32_16x16x32_bf16 v[84:87], v[172:175], v[210:213], v[84:87]
	v_mfma_f32_16x16x32_bf16 v[80:83], v[180:183], v[210:213], v[80:83]
	v_mfma_f32_16x16x32_bf16 v[68:71], v[172:175], v[218:221], v[68:71]
	v_mfma_f32_16x16x32_bf16 v[64:67], v[180:183], v[218:221], v[64:67]
	s_barrier
	s_setprio 0
	s_add_i32 s18, s20, s7
	v_lshl_add_u64 v[140:141], s[50:51], 0, v[132:133]
	s_mov_b32 m0, s18
	ds_read_b128 v[184:187], v144 offset:16384
	ds_read_b128 v[188:191], v144 offset:17408
	ds_read_b128 v[192:195], v144 offset:18432
	ds_read_b128 v[196:199], v144 offset:19456
	ds_read_b128 v[206:209], v144 offset:20480
	ds_read_b128 v[210:213], v144 offset:21504
	ds_read_b128 v[214:217], v144 offset:22528
	ds_read_b128 v[218:221], v144 offset:23552
	global_load_lds_dwordx4 v[140:141], off
	s_add_i32 m0, s18, 0x2000
	s_add_u32 s18, s50, 0x40000
	v_lshl_add_u64 v[158:159], s[50:51], 0, v[128:129]
	s_addc_u32 s19, s51, 0
	s_add_i32 s20, s21, s7
	global_load_lds_dwordx4 v[158:159], off
	v_lshl_add_u64 v[200:201], s[18:19], 0, v[132:133]
	s_mov_b32 m0, s20
	v_lshl_add_u64 v[222:223], s[60:61], 0, v[130:131]
	global_load_lds_dwordx4 v[200:201], off
	v_lshl_add_u64 v[200:201], s[18:19], 0, v[128:129]
	s_add_i32 m0, s20, 0x2000
	s_nop 0
	global_load_lds_dwordx4 v[200:201], off
	v_lshl_add_u64 v[200:201], s[60:61], 0, v[134:135]
	s_mov_b32 m0, s8
	s_nop 0
	global_load_lds_dwordx4 v[200:201], off
	s_mov_b32 m0, s9
	s_nop 0
	global_load_lds_dwordx4 v[222:223], off
	s_waitcnt vmcnt(8)
	s_waitcnt lgkmcnt(0)
	s_setprio 1
	s_barrier
	v_mfma_f32_16x16x32_bf16 v[60:63], v[146:149], v[184:187], v[60:63]
	v_mfma_f32_16x16x32_bf16 v[56:59], v[154:157], v[184:187], v[56:59]
	v_mfma_f32_16x16x32_bf16 v[44:47], v[146:149], v[192:195], v[44:47]
	v_mfma_f32_16x16x32_bf16 v[40:43], v[154:157], v[192:195], v[40:43]
	v_mfma_f32_16x16x32_bf16 v[28:31], v[146:149], v[206:209], v[28:31]
	v_mfma_f32_16x16x32_bf16 v[24:27], v[154:157], v[206:209], v[24:27]
	v_mfma_f32_16x16x32_bf16 v[12:15], v[146:149], v[214:217], v[12:15]
	v_mfma_f32_16x16x32_bf16 v[8:11], v[154:157], v[214:217], v[8:11]
	v_mfma_f32_16x16x32_bf16 v[60:63], v[150:153], v[188:191], v[60:63]
	v_mfma_f32_16x16x32_bf16 v[56:59], v[164:167], v[188:191], v[56:59]
	v_mfma_f32_16x16x32_bf16 v[44:47], v[150:153], v[196:199], v[44:47]
	v_mfma_f32_16x16x32_bf16 v[40:43], v[164:167], v[196:199], v[40:43]
	v_mfma_f32_16x16x32_bf16 v[28:31], v[150:153], v[210:213], v[28:31]
	v_mfma_f32_16x16x32_bf16 v[24:27], v[164:167], v[210:213], v[24:27]
	v_mfma_f32_16x16x32_bf16 v[12:15], v[150:153], v[218:221], v[12:15]
	v_mfma_f32_16x16x32_bf16 v[8:11], v[164:167], v[218:221], v[8:11]
	s_setprio 0
	s_setprio 1
	v_mfma_f32_16x16x32_bf16 v[52:55], v[168:171], v[184:187], v[52:55]
	v_mfma_f32_16x16x32_bf16 v[48:51], v[176:179], v[184:187], v[48:51]
	v_mfma_f32_16x16x32_bf16 v[36:39], v[168:171], v[192:195], v[36:39]
	v_mfma_f32_16x16x32_bf16 v[32:35], v[176:179], v[192:195], v[32:35]
	v_mfma_f32_16x16x32_bf16 v[20:23], v[168:171], v[206:209], v[20:23]
	v_mfma_f32_16x16x32_bf16 v[16:19], v[176:179], v[206:209], v[16:19]
	v_mfma_f32_16x16x32_bf16 v[4:7], v[168:171], v[214:217], v[4:7]
	v_mfma_f32_16x16x32_bf16 v[0:3], v[176:179], v[214:217], v[0:3]
	v_mfma_f32_16x16x32_bf16 v[52:55], v[172:175], v[188:191], v[52:55]
	v_mfma_f32_16x16x32_bf16 v[48:51], v[180:183], v[188:191], v[48:51]
	v_mfma_f32_16x16x32_bf16 v[36:39], v[172:175], v[196:199], v[36:39]
	v_mfma_f32_16x16x32_bf16 v[32:35], v[180:183], v[196:199], v[32:35]
	v_mfma_f32_16x16x32_bf16 v[20:23], v[172:175], v[210:213], v[20:23]
	v_mfma_f32_16x16x32_bf16 v[16:19], v[180:183], v[210:213], v[16:19]
	v_mfma_f32_16x16x32_bf16 v[4:7], v[172:175], v[218:221], v[4:7]
	v_mfma_f32_16x16x32_bf16 v[0:3], v[180:183], v[218:221], v[0:3]
	s_barrier
	s_setprio 0
	s_add_i32 s20, 0, 0x18000
	v_add_u32_e32 v145, s20, v143
	s_add_i32 s21, 0, 0x1c000
	ds_read_b128 v[146:149], v145
	ds_read_b128 v[150:153], v145 offset:1024
	ds_read_b128 v[154:157], v145 offset:2048
	ds_read_b128 v[164:167], v145 offset:3072
	v_add_u32_e32 v145, s21, v143
	ds_read_b128 v[168:171], v145
	ds_read_b128 v[172:175], v145 offset:1024
	ds_read_b128 v[176:179], v145 offset:2048
	ds_read_b128 v[180:183], v145 offset:3072
	s_add_u32 s18, s60, 0x40000
	s_addc_u32 s19, s61, 0
	s_mov_b32 m0, s10
	v_lshl_add_u64 v[224:225], s[18:19], 0, v[134:135]
	ds_read_b128 v[184:187], v144 offset:32768
	ds_read_b128 v[188:191], v144 offset:33792
	ds_read_b128 v[192:195], v144 offset:34816
	ds_read_b128 v[196:199], v144 offset:35840
	ds_read_b128 v[206:209], v144 offset:36864
	ds_read_b128 v[210:213], v144 offset:37888
	ds_read_b128 v[214:217], v144 offset:38912
	ds_read_b128 v[218:221], v144 offset:39936
	global_load_lds_dwordx4 v[224:225], off
	v_lshl_add_u64 v[224:225], s[18:19], 0, v[130:131]
	s_mov_b32 m0, s11
	s_nop 0
	global_load_lds_dwordx4 v[224:225], off
	s_waitcnt vmcnt(8)
	s_waitcnt lgkmcnt(0)
	s_setprio 1
	s_barrier
	v_mfma_f32_16x16x32_bf16 v[124:127], v[146:149], v[184:187], v[124:127]
	v_mfma_f32_16x16x32_bf16 v[120:123], v[154:157], v[184:187], v[120:123]
	v_mfma_f32_16x16x32_bf16 v[108:111], v[146:149], v[192:195], v[108:111]
	v_mfma_f32_16x16x32_bf16 v[104:107], v[154:157], v[192:195], v[104:107]
	v_mfma_f32_16x16x32_bf16 v[92:95], v[146:149], v[206:209], v[92:95]
	v_mfma_f32_16x16x32_bf16 v[88:91], v[154:157], v[206:209], v[88:91]
	v_mfma_f32_16x16x32_bf16 v[76:79], v[146:149], v[214:217], v[76:79]
	v_mfma_f32_16x16x32_bf16 v[72:75], v[154:157], v[214:217], v[72:75]
	v_mfma_f32_16x16x32_bf16 v[124:127], v[150:153], v[188:191], v[124:127]
	v_mfma_f32_16x16x32_bf16 v[120:123], v[164:167], v[188:191], v[120:123]
	v_mfma_f32_16x16x32_bf16 v[108:111], v[150:153], v[196:199], v[108:111]
	v_mfma_f32_16x16x32_bf16 v[104:107], v[164:167], v[196:199], v[104:107]
	v_mfma_f32_16x16x32_bf16 v[92:95], v[150:153], v[210:213], v[92:95]
	v_mfma_f32_16x16x32_bf16 v[88:91], v[164:167], v[210:213], v[88:91]
	v_mfma_f32_16x16x32_bf16 v[76:79], v[150:153], v[218:221], v[76:79]
	v_mfma_f32_16x16x32_bf16 v[72:75], v[164:167], v[218:221], v[72:75]
	s_setprio 0
	s_setprio 1
	v_mfma_f32_16x16x32_bf16 v[116:119], v[168:171], v[184:187], v[116:119]
	v_mfma_f32_16x16x32_bf16 v[112:115], v[176:179], v[184:187], v[112:115]
	v_mfma_f32_16x16x32_bf16 v[100:103], v[168:171], v[192:195], v[100:103]
	v_mfma_f32_16x16x32_bf16 v[96:99], v[176:179], v[192:195], v[96:99]
	v_mfma_f32_16x16x32_bf16 v[84:87], v[168:171], v[206:209], v[84:87]
	v_mfma_f32_16x16x32_bf16 v[80:83], v[176:179], v[206:209], v[80:83]
	v_mfma_f32_16x16x32_bf16 v[68:71], v[168:171], v[214:217], v[68:71]
	v_mfma_f32_16x16x32_bf16 v[64:67], v[176:179], v[214:217], v[64:67]
	v_mfma_f32_16x16x32_bf16 v[116:119], v[172:175], v[188:191], v[116:119]
	v_mfma_f32_16x16x32_bf16 v[112:115], v[180:183], v[188:191], v[112:115]
	v_mfma_f32_16x16x32_bf16 v[100:103], v[172:175], v[196:199], v[100:103]
	v_mfma_f32_16x16x32_bf16 v[96:99], v[180:183], v[196:199], v[96:99]
	v_mfma_f32_16x16x32_bf16 v[84:87], v[172:175], v[210:213], v[84:87]
	v_mfma_f32_16x16x32_bf16 v[80:83], v[180:183], v[210:213], v[80:83]
	v_mfma_f32_16x16x32_bf16 v[68:71], v[172:175], v[218:221], v[68:71]
	v_mfma_f32_16x16x32_bf16 v[64:67], v[180:183], v[218:221], v[64:67]
	s_barrier
	s_setprio 0
	s_add_i32 s18, s20, s7
	v_lshl_add_u64 v[140:141], v[140:141], 0, s[76:77]
	s_mov_b32 m0, s18
	ds_read_b128 v[184:187], v144 offset:49152
	ds_read_b128 v[188:191], v144 offset:50176
	ds_read_b128 v[192:195], v144 offset:51200
	ds_read_b128 v[196:199], v144 offset:52224
	ds_read_b128 v[206:209], v144 offset:53248
	ds_read_b128 v[210:213], v144 offset:54272
	ds_read_b128 v[214:217], v144 offset:55296
	ds_read_b128 v[218:221], v144 offset:56320
	global_load_lds_dwordx4 v[140:141], off
	s_add_i32 m0, s18, 0x2000
	s_add_u32 s18, s50, 0x40080
	v_lshl_add_u64 v[140:141], v[158:159], 0, s[76:77]
	s_addc_u32 s19, s51, 0
	s_add_i32 s20, s21, s7
	global_load_lds_dwordx4 v[140:141], off
	v_lshl_add_u64 v[140:141], s[18:19], 0, v[132:133]
	s_mov_b32 m0, s20
	s_nop 0
	global_load_lds_dwordx4 v[140:141], off
	v_lshl_add_u64 v[140:141], s[18:19], 0, v[128:129]
	s_add_i32 m0, s20, 0x2000
	s_nop 0
	global_load_lds_dwordx4 v[140:141], off
	v_lshl_add_u64 v[140:141], v[200:201], 0, s[76:77]
	s_mov_b32 m0, s12
	s_nop 0
	global_load_lds_dwordx4 v[140:141], off
	v_lshl_add_u64 v[140:141], v[222:223], 0, s[76:77]
	s_mov_b32 m0, s13
	s_nop 0
	global_load_lds_dwordx4 v[140:141], off
	s_waitcnt vmcnt(8)
	s_waitcnt lgkmcnt(0)
	s_setprio 1
	s_barrier
	v_mfma_f32_16x16x32_bf16 v[60:63], v[146:149], v[184:187], v[60:63]
	v_mfma_f32_16x16x32_bf16 v[56:59], v[154:157], v[184:187], v[56:59]
	v_mfma_f32_16x16x32_bf16 v[44:47], v[146:149], v[192:195], v[44:47]
	v_mfma_f32_16x16x32_bf16 v[40:43], v[154:157], v[192:195], v[40:43]
	v_mfma_f32_16x16x32_bf16 v[28:31], v[146:149], v[206:209], v[28:31]
	v_mfma_f32_16x16x32_bf16 v[24:27], v[154:157], v[206:209], v[24:27]
	v_mfma_f32_16x16x32_bf16 v[12:15], v[146:149], v[214:217], v[12:15]
	v_mfma_f32_16x16x32_bf16 v[8:11], v[154:157], v[214:217], v[8:11]
	v_mfma_f32_16x16x32_bf16 v[60:63], v[150:153], v[188:191], v[60:63]
	v_mfma_f32_16x16x32_bf16 v[56:59], v[164:167], v[188:191], v[56:59]
	v_mfma_f32_16x16x32_bf16 v[44:47], v[150:153], v[196:199], v[44:47]
	v_mfma_f32_16x16x32_bf16 v[40:43], v[164:167], v[196:199], v[40:43]
	v_mfma_f32_16x16x32_bf16 v[28:31], v[150:153], v[210:213], v[28:31]
	v_mfma_f32_16x16x32_bf16 v[24:27], v[164:167], v[210:213], v[24:27]
	v_mfma_f32_16x16x32_bf16 v[12:15], v[150:153], v[218:221], v[12:15]
	v_mfma_f32_16x16x32_bf16 v[8:11], v[164:167], v[218:221], v[8:11]
	s_setprio 0
	s_setprio 1
	v_mfma_f32_16x16x32_bf16 v[52:55], v[168:171], v[184:187], v[52:55]
	v_mfma_f32_16x16x32_bf16 v[48:51], v[176:179], v[184:187], v[48:51]
	v_mfma_f32_16x16x32_bf16 v[36:39], v[168:171], v[192:195], v[36:39]
	v_mfma_f32_16x16x32_bf16 v[32:35], v[176:179], v[192:195], v[32:35]
	v_mfma_f32_16x16x32_bf16 v[20:23], v[168:171], v[206:209], v[20:23]
	v_mfma_f32_16x16x32_bf16 v[16:19], v[176:179], v[206:209], v[16:19]
	v_mfma_f32_16x16x32_bf16 v[4:7], v[168:171], v[214:217], v[4:7]
	v_mfma_f32_16x16x32_bf16 v[0:3], v[176:179], v[214:217], v[0:3]
	v_mfma_f32_16x16x32_bf16 v[52:55], v[172:175], v[188:191], v[52:55]
	v_mfma_f32_16x16x32_bf16 v[48:51], v[180:183], v[188:191], v[48:51]
	v_mfma_f32_16x16x32_bf16 v[36:39], v[172:175], v[196:199], v[36:39]
	v_mfma_f32_16x16x32_bf16 v[32:35], v[180:183], v[196:199], v[32:35]
	v_mfma_f32_16x16x32_bf16 v[20:23], v[172:175], v[210:213], v[20:23]
	v_mfma_f32_16x16x32_bf16 v[16:19], v[180:183], v[210:213], v[16:19]
	v_mfma_f32_16x16x32_bf16 v[4:7], v[172:175], v[218:221], v[4:7]
	v_mfma_f32_16x16x32_bf16 v[0:3], v[180:183], v[218:221], v[0:3]
	s_barrier
	s_setprio 0
	s_add_i32 s63, s63, 2
	s_add_u32 s58, s58, 0x100
	s_addc_u32 s59, s59, 0
	s_add_u32 s47, s47, 0x100
	s_addc_u32 s62, s62, 0
	s_cmp_gt_u32 s63, 13
	s_cbranch_scc0 .LBB0_1138

.LBB0_1209:
	s_add_u32 s54, s48, 0x100
	s_addc_u32 s60, s49, 0
	s_mov_b32 s61, -2
	s_add_u32 s48, s42, 0x100
	s_addc_u32 s49, s43, 0
	s_add_i32 s18, 0, 0x10000
	s_cmp_eq_u32 s61, 40
	s_cselect_b32 s59, s39, s49
	s_cselect_b32 s58, s38, s48
	s_cselect_b32 s51, s41, s60
	s_cselect_b32 s50, s40, s54
	s_add_i32 s20, 0, 0x14000
	v_add_u32_e32 v140, s18, v174
	v_add_u32_e32 v162, s20, v174
	ds_read_b128 v[128:131], v140
	ds_read_b128 v[132:135], v140 offset:1024
	ds_read_b128 v[136:139], v140 offset:2048
	ds_read_b128 v[140:143], v140 offset:3072
	ds_read_b128 v[156:159], v162
	ds_read_b128 v[164:167], v162 offset:1024
	ds_read_b128 v[168:171], v162 offset:2048
	ds_read_b128 v[176:179], v162 offset:3072
	v_lshl_add_u64 v[200:201], s[42:43], 0, v[152:153]
	s_add_i32 m0, s4, 0xc000
	ds_read_b128 v[180:183], v175
	ds_read_b128 v[184:187], v175 offset:1024
	ds_read_b128 v[188:191], v175 offset:2048
	ds_read_b128 v[192:195], v175 offset:3072
	ds_read_b128 v[196:199], v175 offset:4096
	ds_read_b128 v[206:209], v175 offset:5120
	ds_read_b128 v[210:213], v175 offset:6144
	ds_read_b128 v[214:217], v175 offset:7168
	global_load_lds_dwordx4 v[200:201], off
	v_lshl_add_u64 v[200:201], s[42:43], 0, v[154:155]
	s_add_i32 m0, s4, 0xe000
	s_nop 0
	global_load_lds_dwordx4 v[200:201], off
	s_waitcnt vmcnt(8)
	s_waitcnt lgkmcnt(0)
	s_setprio 1
	s_barrier
	v_mfma_f32_16x16x32_bf16 v[124:127], v[128:131], v[180:183], 0
	v_mfma_f32_16x16x32_bf16 v[120:123], v[136:139], v[180:183], 0
	v_mfma_f32_16x16x32_bf16 v[112:115], v[128:131], v[188:191], 0
	v_mfma_f32_16x16x32_bf16 v[104:107], v[136:139], v[188:191], 0
	v_mfma_f32_16x16x32_bf16 v[96:99], v[128:131], v[196:199], 0
	v_mfma_f32_16x16x32_bf16 v[88:91], v[136:139], v[196:199], 0
	v_mfma_f32_16x16x32_bf16 v[80:83], v[128:131], v[210:213], 0
	v_mfma_f32_16x16x32_bf16 v[72:75], v[136:139], v[210:213], 0
	v_mfma_f32_16x16x32_bf16 v[124:127], v[132:135], v[184:187], v[124:127]
	v_mfma_f32_16x16x32_bf16 v[120:123], v[140:143], v[184:187], v[120:123]
	v_mfma_f32_16x16x32_bf16 v[112:115], v[132:135], v[192:195], v[112:115]
	v_mfma_f32_16x16x32_bf16 v[104:107], v[140:143], v[192:195], v[104:107]
	v_mfma_f32_16x16x32_bf16 v[96:99], v[132:135], v[206:209], v[96:99]
	v_mfma_f32_16x16x32_bf16 v[88:91], v[140:143], v[206:209], v[88:91]
	v_mfma_f32_16x16x32_bf16 v[80:83], v[132:135], v[214:217], v[80:83]
	v_mfma_f32_16x16x32_bf16 v[72:75], v[140:143], v[214:217], v[72:75]
	s_setprio 0
	s_setprio 1
	v_mfma_f32_16x16x32_bf16 v[116:119], v[156:159], v[180:183], 0
	v_mfma_f32_16x16x32_bf16 v[108:111], v[168:171], v[180:183], 0
	v_mfma_f32_16x16x32_bf16 v[100:103], v[156:159], v[188:191], 0
	v_mfma_f32_16x16x32_bf16 v[92:95], v[168:171], v[188:191], 0
	v_mfma_f32_16x16x32_bf16 v[84:87], v[156:159], v[196:199], 0
	v_mfma_f32_16x16x32_bf16 v[76:79], v[168:171], v[196:199], 0
	v_mfma_f32_16x16x32_bf16 v[68:71], v[156:159], v[210:213], 0
	v_mfma_f32_16x16x32_bf16 v[64:67], v[168:171], v[210:213], 0
	v_mfma_f32_16x16x32_bf16 v[116:119], v[164:167], v[184:187], v[116:119]
	v_mfma_f32_16x16x32_bf16 v[108:111], v[176:179], v[184:187], v[108:111]
	v_mfma_f32_16x16x32_bf16 v[100:103], v[164:167], v[192:195], v[100:103]
	v_mfma_f32_16x16x32_bf16 v[92:95], v[176:179], v[192:195], v[92:95]
	v_mfma_f32_16x16x32_bf16 v[84:87], v[164:167], v[206:209], v[84:87]
	v_mfma_f32_16x16x32_bf16 v[76:79], v[176:179], v[206:209], v[76:79]
	v_mfma_f32_16x16x32_bf16 v[68:71], v[164:167], v[214:217], v[68:71]
	v_mfma_f32_16x16x32_bf16 v[64:67], v[176:179], v[214:217], v[64:67]
	s_barrier
	s_setprio 0
	s_add_i32 s18, s18, s46
	v_lshl_add_u64 v[200:201], s[50:51], 0, v[148:149]
	s_mov_b32 m0, s18
	ds_read_b128 v[180:183], v175 offset:16384
	ds_read_b128 v[184:187], v175 offset:17408
	ds_read_b128 v[188:191], v175 offset:18432
	ds_read_b128 v[192:195], v175 offset:19456
	ds_read_b128 v[196:199], v175 offset:20480
	ds_read_b128 v[206:209], v175 offset:21504
	ds_read_b128 v[210:213], v175 offset:22528
	ds_read_b128 v[214:217], v175 offset:23552
	global_load_lds_dwordx4 v[200:201], off
	s_add_i32 m0, s18, 0x2000
	s_add_u32 s18, s50, 0xb0000
	v_lshl_add_u64 v[218:219], s[50:51], 0, v[144:145]
	s_addc_u32 s19, s51, 0
	s_add_i32 s20, s20, s46
	global_load_lds_dwordx4 v[218:219], off
	v_lshl_add_u64 v[220:221], s[18:19], 0, v[148:149]
	s_mov_b32 m0, s20
	v_lshl_add_u64 v[222:223], s[58:59], 0, v[146:147]
	global_load_lds_dwordx4 v[220:221], off
	v_lshl_add_u64 v[220:221], s[18:19], 0, v[144:145]
	s_add_i32 m0, s20, 0x2000
	s_nop 0
	global_load_lds_dwordx4 v[220:221], off
	v_lshl_add_u64 v[220:221], s[58:59], 0, v[150:151]
	s_mov_b32 m0, s4
	s_nop 0
	global_load_lds_dwordx4 v[220:221], off
	s_mov_b32 m0, s5
	s_nop 0
	global_load_lds_dwordx4 v[222:223], off
	s_waitcnt vmcnt(8)
	s_waitcnt lgkmcnt(0)
	s_setprio 1
	s_barrier
	v_mfma_f32_16x16x32_bf16 v[60:63], v[128:131], v[180:183], 0
	v_mfma_f32_16x16x32_bf16 v[56:59], v[136:139], v[180:183], 0
	v_mfma_f32_16x16x32_bf16 v[48:51], v[128:131], v[188:191], 0
	v_mfma_f32_16x16x32_bf16 v[40:43], v[136:139], v[188:191], 0
	v_mfma_f32_16x16x32_bf16 v[32:35], v[128:131], v[196:199], 0
	v_mfma_f32_16x16x32_bf16 v[24:27], v[136:139], v[196:199], 0
	v_mfma_f32_16x16x32_bf16 v[16:19], v[128:131], v[210:213], 0
	v_mfma_f32_16x16x32_bf16 v[8:11], v[136:139], v[210:213], 0
	v_mfma_f32_16x16x32_bf16 v[60:63], v[132:135], v[184:187], v[60:63]
	v_mfma_f32_16x16x32_bf16 v[56:59], v[140:143], v[184:187], v[56:59]
	v_mfma_f32_16x16x32_bf16 v[48:51], v[132:135], v[192:195], v[48:51]
	v_mfma_f32_16x16x32_bf16 v[40:43], v[140:143], v[192:195], v[40:43]
	v_mfma_f32_16x16x32_bf16 v[32:35], v[132:135], v[206:209], v[32:35]
	v_mfma_f32_16x16x32_bf16 v[24:27], v[140:143], v[206:209], v[24:27]
	v_mfma_f32_16x16x32_bf16 v[16:19], v[132:135], v[214:217], v[16:19]
	v_mfma_f32_16x16x32_bf16 v[8:11], v[140:143], v[214:217], v[8:11]
	s_setprio 0
	s_setprio 1
	v_mfma_f32_16x16x32_bf16 v[52:55], v[156:159], v[180:183], 0
	v_mfma_f32_16x16x32_bf16 v[44:47], v[168:171], v[180:183], 0
	v_mfma_f32_16x16x32_bf16 v[36:39], v[156:159], v[188:191], 0
	v_mfma_f32_16x16x32_bf16 v[28:31], v[168:171], v[188:191], 0
	v_mfma_f32_16x16x32_bf16 v[20:23], v[156:159], v[196:199], 0
	v_mfma_f32_16x16x32_bf16 v[12:15], v[168:171], v[196:199], 0
	v_mfma_f32_16x16x32_bf16 v[4:7], v[156:159], v[210:213], 0
	v_mfma_f32_16x16x32_bf16 v[0:3], v[168:171], v[210:213], 0
	v_mfma_f32_16x16x32_bf16 v[52:55], v[164:167], v[184:187], v[52:55]
	v_mfma_f32_16x16x32_bf16 v[44:47], v[176:179], v[184:187], v[44:47]
	v_mfma_f32_16x16x32_bf16 v[36:39], v[164:167], v[192:195], v[36:39]
	v_mfma_f32_16x16x32_bf16 v[28:31], v[176:179], v[192:195], v[28:31]
	v_mfma_f32_16x16x32_bf16 v[20:23], v[164:167], v[206:209], v[20:23]
	v_mfma_f32_16x16x32_bf16 v[12:15], v[176:179], v[206:209], v[12:15]
	v_mfma_f32_16x16x32_bf16 v[4:7], v[164:167], v[214:217], v[4:7]
	v_mfma_f32_16x16x32_bf16 v[0:3], v[176:179], v[214:217], v[0:3]
	s_barrier
	s_setprio 0
	s_add_i32 s20, 0, 0x18000
	s_add_i32 s21, 0, 0x1c000
	v_add_u32_e32 v140, s20, v174
	v_add_u32_e32 v162, s21, v174
	ds_read_b128 v[128:131], v140
	ds_read_b128 v[132:135], v140 offset:1024
	ds_read_b128 v[136:139], v140 offset:2048
	ds_read_b128 v[140:143], v140 offset:3072
	ds_read_b128 v[156:159], v162
	ds_read_b128 v[164:167], v162 offset:1024
	ds_read_b128 v[168:171], v162 offset:2048
	ds_read_b128 v[176:179], v162 offset:3072
	s_add_u32 s18, s58, 0xb0000
	s_addc_u32 s19, s59, 0
	s_mov_b32 m0, s6
	v_lshl_add_u64 v[224:225], s[18:19], 0, v[150:151]
	ds_read_b128 v[180:183], v175 offset:32768
	ds_read_b128 v[184:187], v175 offset:33792
	ds_read_b128 v[188:191], v175 offset:34816
	ds_read_b128 v[192:195], v175 offset:35840
	ds_read_b128 v[196:199], v175 offset:36864
	ds_read_b128 v[206:209], v175 offset:37888
	ds_read_b128 v[210:213], v175 offset:38912
	ds_read_b128 v[214:217], v175 offset:39936
	global_load_lds_dwordx4 v[224:225], off
	v_lshl_add_u64 v[224:225], s[18:19], 0, v[146:147]
	s_mov_b32 m0, s7
	s_nop 0
	global_load_lds_dwordx4 v[224:225], off
	s_waitcnt vmcnt(8)
	s_waitcnt lgkmcnt(0)
	s_setprio 1
	s_barrier
	v_mfma_f32_16x16x32_bf16 v[124:127], v[128:131], v[180:183], v[124:127]
	v_mfma_f32_16x16x32_bf16 v[120:123], v[136:139], v[180:183], v[120:123]
	v_mfma_f32_16x16x32_bf16 v[112:115], v[128:131], v[188:191], v[112:115]
	v_mfma_f32_16x16x32_bf16 v[104:107], v[136:139], v[188:191], v[104:107]
	v_mfma_f32_16x16x32_bf16 v[96:99], v[128:131], v[196:199], v[96:99]
	v_mfma_f32_16x16x32_bf16 v[88:91], v[136:139], v[196:199], v[88:91]
	v_mfma_f32_16x16x32_bf16 v[80:83], v[128:131], v[210:213], v[80:83]
	v_mfma_f32_16x16x32_bf16 v[72:75], v[136:139], v[210:213], v[72:75]
	v_mfma_f32_16x16x32_bf16 v[124:127], v[132:135], v[184:187], v[124:127]
	v_mfma_f32_16x16x32_bf16 v[120:123], v[140:143], v[184:187], v[120:123]
	v_mfma_f32_16x16x32_bf16 v[112:115], v[132:135], v[192:195], v[112:115]
	v_mfma_f32_16x16x32_bf16 v[104:107], v[140:143], v[192:195], v[104:107]
	v_mfma_f32_16x16x32_bf16 v[96:99], v[132:135], v[206:209], v[96:99]
	v_mfma_f32_16x16x32_bf16 v[88:91], v[140:143], v[206:209], v[88:91]
	v_mfma_f32_16x16x32_bf16 v[80:83], v[132:135], v[214:217], v[80:83]
	v_mfma_f32_16x16x32_bf16 v[72:75], v[140:143], v[214:217], v[72:75]
	s_setprio 0
	s_setprio 1
	v_mfma_f32_16x16x32_bf16 v[116:119], v[156:159], v[180:183], v[116:119]
	v_mfma_f32_16x16x32_bf16 v[108:111], v[168:171], v[180:183], v[108:111]
	v_mfma_f32_16x16x32_bf16 v[100:103], v[156:159], v[188:191], v[100:103]
	v_mfma_f32_16x16x32_bf16 v[92:95], v[168:171], v[188:191], v[92:95]
	v_mfma_f32_16x16x32_bf16 v[84:87], v[156:159], v[196:199], v[84:87]
	v_mfma_f32_16x16x32_bf16 v[76:79], v[168:171], v[196:199], v[76:79]
	v_mfma_f32_16x16x32_bf16 v[68:71], v[156:159], v[210:213], v[68:71]
	v_mfma_f32_16x16x32_bf16 v[64:67], v[168:171], v[210:213], v[64:67]
	v_mfma_f32_16x16x32_bf16 v[116:119], v[164:167], v[184:187], v[116:119]
	v_mfma_f32_16x16x32_bf16 v[108:111], v[176:179], v[184:187], v[108:111]
	v_mfma_f32_16x16x32_bf16 v[100:103], v[164:167], v[192:195], v[100:103]
	v_mfma_f32_16x16x32_bf16 v[92:95], v[176:179], v[192:195], v[92:95]
	v_mfma_f32_16x16x32_bf16 v[84:87], v[164:167], v[206:209], v[84:87]
	v_mfma_f32_16x16x32_bf16 v[76:79], v[176:179], v[206:209], v[76:79]
	v_mfma_f32_16x16x32_bf16 v[68:71], v[164:167], v[214:217], v[68:71]
	v_mfma_f32_16x16x32_bf16 v[64:67], v[176:179], v[214:217], v[64:67]
	s_barrier
	s_setprio 0
	s_add_i32 s18, s20, s46
	v_lshl_add_u64 v[200:201], v[200:201], 0, s[76:77]
	s_mov_b32 m0, s18
	ds_read_b128 v[180:183], v175 offset:49152
	ds_read_b128 v[184:187], v175 offset:50176
	ds_read_b128 v[188:191], v175 offset:51200
	ds_read_b128 v[192:195], v175 offset:52224
	ds_read_b128 v[196:199], v175 offset:53248
	ds_read_b128 v[206:209], v175 offset:54272
	ds_read_b128 v[210:213], v175 offset:55296
	ds_read_b128 v[214:217], v175 offset:56320
	global_load_lds_dwordx4 v[200:201], off
	s_add_i32 m0, s18, 0x2000
	s_add_u32 s18, s50, 0xb0080
	v_lshl_add_u64 v[200:201], v[218:219], 0, s[76:77]
	s_addc_u32 s19, s51, 0
	s_add_i32 s20, s21, s46
	global_load_lds_dwordx4 v[200:201], off
	v_lshl_add_u64 v[200:201], s[18:19], 0, v[148:149]
	s_mov_b32 m0, s20
	s_nop 0
	global_load_lds_dwordx4 v[200:201], off
	v_lshl_add_u64 v[200:201], s[18:19], 0, v[144:145]
	s_add_i32 m0, s20, 0x2000
	s_nop 0
	global_load_lds_dwordx4 v[200:201], off
	v_lshl_add_u64 v[200:201], v[220:221], 0, s[76:77]
	s_mov_b32 m0, s11
	s_nop 0
	global_load_lds_dwordx4 v[200:201], off
	v_lshl_add_u64 v[200:201], v[222:223], 0, s[76:77]
	s_mov_b32 m0, s12
	s_nop 0
	global_load_lds_dwordx4 v[200:201], off
	s_waitcnt vmcnt(8)
	s_waitcnt lgkmcnt(0)
	s_setprio 1
	s_barrier
	v_mfma_f32_16x16x32_bf16 v[60:63], v[128:131], v[180:183], v[60:63]
	v_mfma_f32_16x16x32_bf16 v[56:59], v[136:139], v[180:183], v[56:59]
	v_mfma_f32_16x16x32_bf16 v[48:51], v[128:131], v[188:191], v[48:51]
	v_mfma_f32_16x16x32_bf16 v[40:43], v[136:139], v[188:191], v[40:43]
	v_mfma_f32_16x16x32_bf16 v[32:35], v[128:131], v[196:199], v[32:35]
	v_mfma_f32_16x16x32_bf16 v[24:27], v[136:139], v[196:199], v[24:27]
	v_mfma_f32_16x16x32_bf16 v[16:19], v[128:131], v[210:213], v[16:19]
	v_mfma_f32_16x16x32_bf16 v[8:11], v[136:139], v[210:213], v[8:11]
	v_mfma_f32_16x16x32_bf16 v[60:63], v[132:135], v[184:187], v[60:63]
	v_mfma_f32_16x16x32_bf16 v[56:59], v[140:143], v[184:187], v[56:59]
	v_mfma_f32_16x16x32_bf16 v[48:51], v[132:135], v[192:195], v[48:51]
	v_mfma_f32_16x16x32_bf16 v[40:43], v[140:143], v[192:195], v[40:43]
	v_mfma_f32_16x16x32_bf16 v[32:35], v[132:135], v[206:209], v[32:35]
	v_mfma_f32_16x16x32_bf16 v[24:27], v[140:143], v[206:209], v[24:27]
	v_mfma_f32_16x16x32_bf16 v[16:19], v[132:135], v[214:217], v[16:19]
	v_mfma_f32_16x16x32_bf16 v[8:11], v[140:143], v[214:217], v[8:11]
	s_setprio 0
	s_setprio 1
	v_mfma_f32_16x16x32_bf16 v[52:55], v[156:159], v[180:183], v[52:55]
	v_mfma_f32_16x16x32_bf16 v[44:47], v[168:171], v[180:183], v[44:47]
	v_mfma_f32_16x16x32_bf16 v[36:39], v[156:159], v[188:191], v[36:39]
	v_mfma_f32_16x16x32_bf16 v[28:31], v[168:171], v[188:191], v[28:31]
	v_mfma_f32_16x16x32_bf16 v[20:23], v[156:159], v[196:199], v[20:23]
	v_mfma_f32_16x16x32_bf16 v[12:15], v[168:171], v[196:199], v[12:15]
	v_mfma_f32_16x16x32_bf16 v[4:7], v[156:159], v[210:213], v[4:7]
	v_mfma_f32_16x16x32_bf16 v[0:3], v[168:171], v[210:213], v[0:3]
	v_mfma_f32_16x16x32_bf16 v[52:55], v[164:167], v[184:187], v[52:55]
	v_mfma_f32_16x16x32_bf16 v[44:47], v[176:179], v[184:187], v[44:47]
	v_mfma_f32_16x16x32_bf16 v[36:39], v[164:167], v[192:195], v[36:39]
	v_mfma_f32_16x16x32_bf16 v[28:31], v[176:179], v[192:195], v[28:31]
	v_mfma_f32_16x16x32_bf16 v[20:23], v[164:167], v[206:209], v[20:23]
	v_mfma_f32_16x16x32_bf16 v[12:15], v[176:179], v[206:209], v[12:15]
	v_mfma_f32_16x16x32_bf16 v[4:7], v[164:167], v[214:217], v[4:7]
	v_mfma_f32_16x16x32_bf16 v[0:3], v[176:179], v[214:217], v[0:3]
	s_barrier
	s_setprio 0
	s_add_i32 s61, s61, 2
	s_add_u32 s54, s54, 0x100
	s_addc_u32 s60, s60, 0
	s_cmp_gt_u32 s61, 41
	s_mov_b64 s[42:43], s[48:49]
	s_cbranch_scc0 .LBB0_1210
	s_branch .Lpeel_x_1210
.LBB0_1210:
	s_add_u32 s48, s42, 0x100
	s_addc_u32 s49, s43, 0
	s_add_i32 s18, 0, 0x10000
	s_cmp_eq_u32 s61, 40
	s_cselect_b32 s59, s39, s49
	s_cselect_b32 s58, s38, s48
	s_cselect_b32 s51, s41, s60
	s_cselect_b32 s50, s40, s54
	s_add_i32 s20, 0, 0x14000
	v_add_u32_e32 v140, s18, v174
	v_add_u32_e32 v162, s20, v174
	ds_read_b128 v[128:131], v140
	ds_read_b128 v[132:135], v140 offset:1024
	ds_read_b128 v[136:139], v140 offset:2048
	ds_read_b128 v[140:143], v140 offset:3072
	ds_read_b128 v[156:159], v162
	ds_read_b128 v[164:167], v162 offset:1024
	ds_read_b128 v[168:171], v162 offset:2048
	ds_read_b128 v[176:179], v162 offset:3072
	v_lshl_add_u64 v[200:201], s[42:43], 0, v[152:153]
	s_add_i32 m0, s4, 0xc000
	ds_read_b128 v[180:183], v175
	ds_read_b128 v[184:187], v175 offset:1024
	ds_read_b128 v[188:191], v175 offset:2048
	ds_read_b128 v[192:195], v175 offset:3072
	ds_read_b128 v[196:199], v175 offset:4096
	ds_read_b128 v[206:209], v175 offset:5120
	ds_read_b128 v[210:213], v175 offset:6144
	ds_read_b128 v[214:217], v175 offset:7168
	global_load_lds_dwordx4 v[200:201], off
	v_lshl_add_u64 v[200:201], s[42:43], 0, v[154:155]
	s_add_i32 m0, s4, 0xe000
	s_nop 0
	global_load_lds_dwordx4 v[200:201], off
	s_waitcnt vmcnt(8)
	s_waitcnt lgkmcnt(0)
	s_setprio 1
	s_barrier
	v_mfma_f32_16x16x32_bf16 v[124:127], v[128:131], v[180:183], v[124:127]
	v_mfma_f32_16x16x32_bf16 v[120:123], v[136:139], v[180:183], v[120:123]
	v_mfma_f32_16x16x32_bf16 v[112:115], v[128:131], v[188:191], v[112:115]
	v_mfma_f32_16x16x32_bf16 v[104:107], v[136:139], v[188:191], v[104:107]
	v_mfma_f32_16x16x32_bf16 v[96:99], v[128:131], v[196:199], v[96:99]
	v_mfma_f32_16x16x32_bf16 v[88:91], v[136:139], v[196:199], v[88:91]
	v_mfma_f32_16x16x32_bf16 v[80:83], v[128:131], v[210:213], v[80:83]
	v_mfma_f32_16x16x32_bf16 v[72:75], v[136:139], v[210:213], v[72:75]
	v_mfma_f32_16x16x32_bf16 v[124:127], v[132:135], v[184:187], v[124:127]
	v_mfma_f32_16x16x32_bf16 v[120:123], v[140:143], v[184:187], v[120:123]
	v_mfma_f32_16x16x32_bf16 v[112:115], v[132:135], v[192:195], v[112:115]
	v_mfma_f32_16x16x32_bf16 v[104:107], v[140:143], v[192:195], v[104:107]
	v_mfma_f32_16x16x32_bf16 v[96:99], v[132:135], v[206:209], v[96:99]
	v_mfma_f32_16x16x32_bf16 v[88:91], v[140:143], v[206:209], v[88:91]
	v_mfma_f32_16x16x32_bf16 v[80:83], v[132:135], v[214:217], v[80:83]
	v_mfma_f32_16x16x32_bf16 v[72:75], v[140:143], v[214:217], v[72:75]
	s_setprio 0
	s_setprio 1
	v_mfma_f32_16x16x32_bf16 v[116:119], v[156:159], v[180:183], v[116:119]
	v_mfma_f32_16x16x32_bf16 v[108:111], v[168:171], v[180:183], v[108:111]
	v_mfma_f32_16x16x32_bf16 v[100:103], v[156:159], v[188:191], v[100:103]
	v_mfma_f32_16x16x32_bf16 v[92:95], v[168:171], v[188:191], v[92:95]
	v_mfma_f32_16x16x32_bf16 v[84:87], v[156:159], v[196:199], v[84:87]
	v_mfma_f32_16x16x32_bf16 v[76:79], v[168:171], v[196:199], v[76:79]
	v_mfma_f32_16x16x32_bf16 v[68:71], v[156:159], v[210:213], v[68:71]
	v_mfma_f32_16x16x32_bf16 v[64:67], v[168:171], v[210:213], v[64:67]
	v_mfma_f32_16x16x32_bf16 v[116:119], v[164:167], v[184:187], v[116:119]
	v_mfma_f32_16x16x32_bf16 v[108:111], v[176:179], v[184:187], v[108:111]
	v_mfma_f32_16x16x32_bf16 v[100:103], v[164:167], v[192:195], v[100:103]
	v_mfma_f32_16x16x32_bf16 v[92:95], v[176:179], v[192:195], v[92:95]
	v_mfma_f32_16x16x32_bf16 v[84:87], v[164:167], v[206:209], v[84:87]
	v_mfma_f32_16x16x32_bf16 v[76:79], v[176:179], v[206:209], v[76:79]
	v_mfma_f32_16x16x32_bf16 v[68:71], v[164:167], v[214:217], v[68:71]
	v_mfma_f32_16x16x32_bf16 v[64:67], v[176:179], v[214:217], v[64:67]
	s_barrier
	s_setprio 0
	s_add_i32 s18, s18, s46
	v_lshl_add_u64 v[200:201], s[50:51], 0, v[148:149]
	s_mov_b32 m0, s18
	ds_read_b128 v[180:183], v175 offset:16384
	ds_read_b128 v[184:187], v175 offset:17408
	ds_read_b128 v[188:191], v175 offset:18432
	ds_read_b128 v[192:195], v175 offset:19456
	ds_read_b128 v[196:199], v175 offset:20480
	ds_read_b128 v[206:209], v175 offset:21504
	ds_read_b128 v[210:213], v175 offset:22528
	ds_read_b128 v[214:217], v175 offset:23552
	global_load_lds_dwordx4 v[200:201], off
	s_add_i32 m0, s18, 0x2000
	s_add_u32 s18, s50, 0xb0000
	v_lshl_add_u64 v[218:219], s[50:51], 0, v[144:145]
	s_addc_u32 s19, s51, 0
	s_add_i32 s20, s20, s46
	global_load_lds_dwordx4 v[218:219], off
	v_lshl_add_u64 v[220:221], s[18:19], 0, v[148:149]
	s_mov_b32 m0, s20
	v_lshl_add_u64 v[222:223], s[58:59], 0, v[146:147]
	global_load_lds_dwordx4 v[220:221], off
	v_lshl_add_u64 v[220:221], s[18:19], 0, v[144:145]
	s_add_i32 m0, s20, 0x2000
	s_nop 0
	global_load_lds_dwordx4 v[220:221], off
	v_lshl_add_u64 v[220:221], s[58:59], 0, v[150:151]
	s_mov_b32 m0, s4
	s_nop 0
	global_load_lds_dwordx4 v[220:221], off
	s_mov_b32 m0, s5
	s_nop 0
	global_load_lds_dwordx4 v[222:223], off
	s_waitcnt vmcnt(8)
	s_waitcnt lgkmcnt(0)
	s_setprio 1
	s_barrier
	v_mfma_f32_16x16x32_bf16 v[60:63], v[128:131], v[180:183], v[60:63]
	v_mfma_f32_16x16x32_bf16 v[56:59], v[136:139], v[180:183], v[56:59]
	v_mfma_f32_16x16x32_bf16 v[48:51], v[128:131], v[188:191], v[48:51]
	v_mfma_f32_16x16x32_bf16 v[40:43], v[136:139], v[188:191], v[40:43]
	v_mfma_f32_16x16x32_bf16 v[32:35], v[128:131], v[196:199], v[32:35]
	v_mfma_f32_16x16x32_bf16 v[24:27], v[136:139], v[196:199], v[24:27]
	v_mfma_f32_16x16x32_bf16 v[16:19], v[128:131], v[210:213], v[16:19]
	v_mfma_f32_16x16x32_bf16 v[8:11], v[136:139], v[210:213], v[8:11]
	v_mfma_f32_16x16x32_bf16 v[60:63], v[132:135], v[184:187], v[60:63]
	v_mfma_f32_16x16x32_bf16 v[56:59], v[140:143], v[184:187], v[56:59]
	v_mfma_f32_16x16x32_bf16 v[48:51], v[132:135], v[192:195], v[48:51]
	v_mfma_f32_16x16x32_bf16 v[40:43], v[140:143], v[192:195], v[40:43]
	v_mfma_f32_16x16x32_bf16 v[32:35], v[132:135], v[206:209], v[32:35]
	v_mfma_f32_16x16x32_bf16 v[24:27], v[140:143], v[206:209], v[24:27]
	v_mfma_f32_16x16x32_bf16 v[16:19], v[132:135], v[214:217], v[16:19]
	v_mfma_f32_16x16x32_bf16 v[8:11], v[140:143], v[214:217], v[8:11]
	s_setprio 0
	s_setprio 1
	v_mfma_f32_16x16x32_bf16 v[52:55], v[156:159], v[180:183], v[52:55]
	v_mfma_f32_16x16x32_bf16 v[44:47], v[168:171], v[180:183], v[44:47]
	v_mfma_f32_16x16x32_bf16 v[36:39], v[156:159], v[188:191], v[36:39]
	v_mfma_f32_16x16x32_bf16 v[28:31], v[168:171], v[188:191], v[28:31]
	v_mfma_f32_16x16x32_bf16 v[20:23], v[156:159], v[196:199], v[20:23]
	v_mfma_f32_16x16x32_bf16 v[12:15], v[168:171], v[196:199], v[12:15]
	v_mfma_f32_16x16x32_bf16 v[4:7], v[156:159], v[210:213], v[4:7]
	v_mfma_f32_16x16x32_bf16 v[0:3], v[168:171], v[210:213], v[0:3]
	v_mfma_f32_16x16x32_bf16 v[52:55], v[164:167], v[184:187], v[52:55]
	v_mfma_f32_16x16x32_bf16 v[44:47], v[176:179], v[184:187], v[44:47]
	v_mfma_f32_16x16x32_bf16 v[36:39], v[164:167], v[192:195], v[36:39]
	v_mfma_f32_16x16x32_bf16 v[28:31], v[176:179], v[192:195], v[28:31]
	v_mfma_f32_16x16x32_bf16 v[20:23], v[164:167], v[206:209], v[20:23]
	v_mfma_f32_16x16x32_bf16 v[12:15], v[176:179], v[206:209], v[12:15]
	v_mfma_f32_16x16x32_bf16 v[4:7], v[164:167], v[214:217], v[4:7]
	v_mfma_f32_16x16x32_bf16 v[0:3], v[176:179], v[214:217], v[0:3]
	s_barrier
	s_setprio 0
	s_add_i32 s20, 0, 0x18000
	s_add_i32 s21, 0, 0x1c000
	v_add_u32_e32 v140, s20, v174
	v_add_u32_e32 v162, s21, v174
	ds_read_b128 v[128:131], v140
	ds_read_b128 v[132:135], v140 offset:1024
	ds_read_b128 v[136:139], v140 offset:2048
	ds_read_b128 v[140:143], v140 offset:3072
	ds_read_b128 v[156:159], v162
	ds_read_b128 v[164:167], v162 offset:1024
	ds_read_b128 v[168:171], v162 offset:2048
	ds_read_b128 v[176:179], v162 offset:3072
	s_add_u32 s18, s58, 0xb0000
	s_addc_u32 s19, s59, 0
	s_mov_b32 m0, s6
	v_lshl_add_u64 v[224:225], s[18:19], 0, v[150:151]
	ds_read_b128 v[180:183], v175 offset:32768
	ds_read_b128 v[184:187], v175 offset:33792
	ds_read_b128 v[188:191], v175 offset:34816
	ds_read_b128 v[192:195], v175 offset:35840
	ds_read_b128 v[196:199], v175 offset:36864
	ds_read_b128 v[206:209], v175 offset:37888
	ds_read_b128 v[210:213], v175 offset:38912
	ds_read_b128 v[214:217], v175 offset:39936
	global_load_lds_dwordx4 v[224:225], off
	v_lshl_add_u64 v[224:225], s[18:19], 0, v[146:147]
	s_mov_b32 m0, s7
	s_nop 0
	global_load_lds_dwordx4 v[224:225], off
	s_waitcnt vmcnt(8)
	s_waitcnt lgkmcnt(0)
	s_setprio 1
	s_barrier
	v_mfma_f32_16x16x32_bf16 v[124:127], v[128:131], v[180:183], v[124:127]
	v_mfma_f32_16x16x32_bf16 v[120:123], v[136:139], v[180:183], v[120:123]
	v_mfma_f32_16x16x32_bf16 v[112:115], v[128:131], v[188:191], v[112:115]
	v_mfma_f32_16x16x32_bf16 v[104:107], v[136:139], v[188:191], v[104:107]
	v_mfma_f32_16x16x32_bf16 v[96:99], v[128:131], v[196:199], v[96:99]
	v_mfma_f32_16x16x32_bf16 v[88:91], v[136:139], v[196:199], v[88:91]
	v_mfma_f32_16x16x32_bf16 v[80:83], v[128:131], v[210:213], v[80:83]
	v_mfma_f32_16x16x32_bf16 v[72:75], v[136:139], v[210:213], v[72:75]
	v_mfma_f32_16x16x32_bf16 v[124:127], v[132:135], v[184:187], v[124:127]
	v_mfma_f32_16x16x32_bf16 v[120:123], v[140:143], v[184:187], v[120:123]
	v_mfma_f32_16x16x32_bf16 v[112:115], v[132:135], v[192:195], v[112:115]
	v_mfma_f32_16x16x32_bf16 v[104:107], v[140:143], v[192:195], v[104:107]
	v_mfma_f32_16x16x32_bf16 v[96:99], v[132:135], v[206:209], v[96:99]
	v_mfma_f32_16x16x32_bf16 v[88:91], v[140:143], v[206:209], v[88:91]
	v_mfma_f32_16x16x32_bf16 v[80:83], v[132:135], v[214:217], v[80:83]
	v_mfma_f32_16x16x32_bf16 v[72:75], v[140:143], v[214:217], v[72:75]
	s_setprio 0
	s_setprio 1
	v_mfma_f32_16x16x32_bf16 v[116:119], v[156:159], v[180:183], v[116:119]
	v_mfma_f32_16x16x32_bf16 v[108:111], v[168:171], v[180:183], v[108:111]
	v_mfma_f32_16x16x32_bf16 v[100:103], v[156:159], v[188:191], v[100:103]
	v_mfma_f32_16x16x32_bf16 v[92:95], v[168:171], v[188:191], v[92:95]
	v_mfma_f32_16x16x32_bf16 v[84:87], v[156:159], v[196:199], v[84:87]
	v_mfma_f32_16x16x32_bf16 v[76:79], v[168:171], v[196:199], v[76:79]
	v_mfma_f32_16x16x32_bf16 v[68:71], v[156:159], v[210:213], v[68:71]
	v_mfma_f32_16x16x32_bf16 v[64:67], v[168:171], v[210:213], v[64:67]
	v_mfma_f32_16x16x32_bf16 v[116:119], v[164:167], v[184:187], v[116:119]
	v_mfma_f32_16x16x32_bf16 v[108:111], v[176:179], v[184:187], v[108:111]
	v_mfma_f32_16x16x32_bf16 v[100:103], v[164:167], v[192:195], v[100:103]
	v_mfma_f32_16x16x32_bf16 v[92:95], v[176:179], v[192:195], v[92:95]
	v_mfma_f32_16x16x32_bf16 v[84:87], v[164:167], v[206:209], v[84:87]
	v_mfma_f32_16x16x32_bf16 v[76:79], v[176:179], v[206:209], v[76:79]
	v_mfma_f32_16x16x32_bf16 v[68:71], v[164:167], v[214:217], v[68:71]
	v_mfma_f32_16x16x32_bf16 v[64:67], v[176:179], v[214:217], v[64:67]
	s_barrier
	s_setprio 0
	s_add_i32 s18, s20, s46
	v_lshl_add_u64 v[200:201], v[200:201], 0, s[76:77]
	s_mov_b32 m0, s18
	ds_read_b128 v[180:183], v175 offset:49152
	ds_read_b128 v[184:187], v175 offset:50176
	ds_read_b128 v[188:191], v175 offset:51200
	ds_read_b128 v[192:195], v175 offset:52224
	ds_read_b128 v[196:199], v175 offset:53248
	ds_read_b128 v[206:209], v175 offset:54272
	ds_read_b128 v[210:213], v175 offset:55296
	ds_read_b128 v[214:217], v175 offset:56320
	global_load_lds_dwordx4 v[200:201], off
	s_add_i32 m0, s18, 0x2000
	s_add_u32 s18, s50, 0xb0080
	v_lshl_add_u64 v[200:201], v[218:219], 0, s[76:77]
	s_addc_u32 s19, s51, 0
	s_add_i32 s20, s21, s46
	global_load_lds_dwordx4 v[200:201], off
	v_lshl_add_u64 v[200:201], s[18:19], 0, v[148:149]
	s_mov_b32 m0, s20
	s_nop 0
	global_load_lds_dwordx4 v[200:201], off
	v_lshl_add_u64 v[200:201], s[18:19], 0, v[144:145]
	s_add_i32 m0, s20, 0x2000
	s_nop 0
	global_load_lds_dwordx4 v[200:201], off
	v_lshl_add_u64 v[200:201], v[220:221], 0, s[76:77]
	s_mov_b32 m0, s11
	s_nop 0
	global_load_lds_dwordx4 v[200:201], off
	v_lshl_add_u64 v[200:201], v[222:223], 0, s[76:77]
	s_mov_b32 m0, s12
	s_nop 0
	global_load_lds_dwordx4 v[200:201], off
	s_waitcnt vmcnt(8)
	s_waitcnt lgkmcnt(0)
	s_setprio 1
	s_barrier
	v_mfma_f32_16x16x32_bf16 v[60:63], v[128:131], v[180:183], v[60:63]
	v_mfma_f32_16x16x32_bf16 v[56:59], v[136:139], v[180:183], v[56:59]
	v_mfma_f32_16x16x32_bf16 v[48:51], v[128:131], v[188:191], v[48:51]
	v_mfma_f32_16x16x32_bf16 v[40:43], v[136:139], v[188:191], v[40:43]
	v_mfma_f32_16x16x32_bf16 v[32:35], v[128:131], v[196:199], v[32:35]
	v_mfma_f32_16x16x32_bf16 v[24:27], v[136:139], v[196:199], v[24:27]
	v_mfma_f32_16x16x32_bf16 v[16:19], v[128:131], v[210:213], v[16:19]
	v_mfma_f32_16x16x32_bf16 v[8:11], v[136:139], v[210:213], v[8:11]
	v_mfma_f32_16x16x32_bf16 v[60:63], v[132:135], v[184:187], v[60:63]
	v_mfma_f32_16x16x32_bf16 v[56:59], v[140:143], v[184:187], v[56:59]
	v_mfma_f32_16x16x32_bf16 v[48:51], v[132:135], v[192:195], v[48:51]
	v_mfma_f32_16x16x32_bf16 v[40:43], v[140:143], v[192:195], v[40:43]
	v_mfma_f32_16x16x32_bf16 v[32:35], v[132:135], v[206:209], v[32:35]
	v_mfma_f32_16x16x32_bf16 v[24:27], v[140:143], v[206:209], v[24:27]
	v_mfma_f32_16x16x32_bf16 v[16:19], v[132:135], v[214:217], v[16:19]
	v_mfma_f32_16x16x32_bf16 v[8:11], v[140:143], v[214:217], v[8:11]
	s_setprio 0
	s_setprio 1
	v_mfma_f32_16x16x32_bf16 v[52:55], v[156:159], v[180:183], v[52:55]
	v_mfma_f32_16x16x32_bf16 v[44:47], v[168:171], v[180:183], v[44:47]
	v_mfma_f32_16x16x32_bf16 v[36:39], v[156:159], v[188:191], v[36:39]
	v_mfma_f32_16x16x32_bf16 v[28:31], v[168:171], v[188:191], v[28:31]
	v_mfma_f32_16x16x32_bf16 v[20:23], v[156:159], v[196:199], v[20:23]
	v_mfma_f32_16x16x32_bf16 v[12:15], v[168:171], v[196:199], v[12:15]
	v_mfma_f32_16x16x32_bf16 v[4:7], v[156:159], v[210:213], v[4:7]
	v_mfma_f32_16x16x32_bf16 v[0:3], v[168:171], v[210:213], v[0:3]
	v_mfma_f32_16x16x32_bf16 v[52:55], v[164:167], v[184:187], v[52:55]
	v_mfma_f32_16x16x32_bf16 v[44:47], v[176:179], v[184:187], v[44:47]
	v_mfma_f32_16x16x32_bf16 v[36:39], v[164:167], v[192:195], v[36:39]
	v_mfma_f32_16x16x32_bf16 v[28:31], v[176:179], v[192:195], v[28:31]
	v_mfma_f32_16x16x32_bf16 v[20:23], v[164:167], v[206:209], v[20:23]
	v_mfma_f32_16x16x32_bf16 v[12:15], v[176:179], v[206:209], v[12:15]
	v_mfma_f32_16x16x32_bf16 v[4:7], v[164:167], v[214:217], v[4:7]
	v_mfma_f32_16x16x32_bf16 v[0:3], v[176:179], v[214:217], v[0:3]
	s_barrier
	s_setprio 0
	s_add_i32 s61, s61, 2
	s_add_u32 s54, s54, 0x100
	s_addc_u32 s60, s60, 0
	s_cmp_gt_u32 s61, 41
	s_mov_b64 s[42:43], s[48:49]
	s_cbranch_scc0 .LBB0_1210

.LBB0_1234:
	s_add_u32 s43, s58, 0x100
	s_addc_u32 s46, s59, 0
	s_mov_b32 s47, -2
	s_add_u32 s58, s48, 0x100
	s_addc_u32 s59, s49, 0
	s_add_i32 s18, 0, 0x10000
	s_cmp_eq_u32 s47, 18
	s_cselect_b32 s61, s39, s59
	s_cselect_b32 s60, s38, s58
	v_add_u32_e32 v158, s18, v152
	s_cselect_b32 s51, s41, s46
	s_cselect_b32 s50, s40, s43
	s_add_i32 s20, 0, 0x14000
	ds_read_b128 v[154:157], v158
	ds_read_b128 v[164:167], v158 offset:1024
	ds_read_b128 v[168:171], v158 offset:2048
	ds_read_b128 v[172:175], v158 offset:3072
	v_add_u32_e32 v158, s20, v152
	ds_read_b128 v[176:179], v158
	ds_read_b128 v[180:183], v158 offset:1024
	ds_read_b128 v[184:187], v158 offset:2048
	ds_read_b128 v[188:191], v158 offset:3072
	v_lshl_add_u64 v[158:159], s[48:49], 0, v[148:149]
	s_add_i32 m0, s5, 0xc000
	ds_read_b128 v[192:195], v153
	ds_read_b128 v[196:199], v153 offset:1024
	ds_read_b128 v[206:209], v153 offset:2048
	ds_read_b128 v[210:213], v153 offset:3072
	ds_read_b128 v[214:217], v153 offset:4096
	ds_read_b128 v[218:221], v153 offset:5120
	ds_read_b128 v[222:225], v153 offset:6144
	ds_read_b128 v[226:229], v153 offset:7168
	global_load_lds_dwordx4 v[158:159], off
	v_lshl_add_u64 v[158:159], s[48:49], 0, v[150:151]
	s_add_i32 m0, s5, 0xe000
	s_nop 0
	global_load_lds_dwordx4 v[158:159], off
	s_waitcnt vmcnt(8)
	s_waitcnt lgkmcnt(0)
	s_setprio 1
	s_barrier
	v_mfma_f32_16x16x32_bf16 v[124:127], v[154:157], v[192:195], 0
	v_mfma_f32_16x16x32_bf16 v[120:123], v[168:171], v[192:195], 0
	v_mfma_f32_16x16x32_bf16 v[116:119], v[154:157], v[206:209], 0
	v_mfma_f32_16x16x32_bf16 v[112:115], v[168:171], v[206:209], 0
	v_mfma_f32_16x16x32_bf16 v[108:111], v[154:157], v[214:217], 0
	v_mfma_f32_16x16x32_bf16 v[104:107], v[168:171], v[214:217], 0
	v_mfma_f32_16x16x32_bf16 v[96:99], v[154:157], v[222:225], 0
	v_mfma_f32_16x16x32_bf16 v[88:91], v[168:171], v[222:225], 0
	v_mfma_f32_16x16x32_bf16 v[124:127], v[164:167], v[196:199], v[124:127]
	v_mfma_f32_16x16x32_bf16 v[120:123], v[172:175], v[196:199], v[120:123]
	v_mfma_f32_16x16x32_bf16 v[116:119], v[164:167], v[210:213], v[116:119]
	v_mfma_f32_16x16x32_bf16 v[112:115], v[172:175], v[210:213], v[112:115]
	v_mfma_f32_16x16x32_bf16 v[108:111], v[164:167], v[218:221], v[108:111]
	v_mfma_f32_16x16x32_bf16 v[104:107], v[172:175], v[218:221], v[104:107]
	v_mfma_f32_16x16x32_bf16 v[96:99], v[164:167], v[226:229], v[96:99]
	v_mfma_f32_16x16x32_bf16 v[88:91], v[172:175], v[226:229], v[88:91]
	s_setprio 0
	s_setprio 1
	v_mfma_f32_16x16x32_bf16 v[100:103], v[176:179], v[192:195], 0
	v_mfma_f32_16x16x32_bf16 v[92:95], v[184:187], v[192:195], 0
	v_mfma_f32_16x16x32_bf16 v[84:87], v[176:179], v[206:209], 0
	v_mfma_f32_16x16x32_bf16 v[80:83], v[184:187], v[206:209], 0
	v_mfma_f32_16x16x32_bf16 v[76:79], v[176:179], v[214:217], 0
	v_mfma_f32_16x16x32_bf16 v[72:75], v[184:187], v[214:217], 0
	v_mfma_f32_16x16x32_bf16 v[68:71], v[176:179], v[222:225], 0
	v_mfma_f32_16x16x32_bf16 v[64:67], v[184:187], v[222:225], 0
	v_mfma_f32_16x16x32_bf16 v[100:103], v[180:183], v[196:199], v[100:103]
	v_mfma_f32_16x16x32_bf16 v[92:95], v[188:191], v[196:199], v[92:95]
	v_mfma_f32_16x16x32_bf16 v[84:87], v[180:183], v[210:213], v[84:87]
	v_mfma_f32_16x16x32_bf16 v[80:83], v[188:191], v[210:213], v[80:83]
	v_mfma_f32_16x16x32_bf16 v[76:79], v[180:183], v[218:221], v[76:79]
	v_mfma_f32_16x16x32_bf16 v[72:75], v[188:191], v[218:221], v[72:75]
	v_mfma_f32_16x16x32_bf16 v[68:71], v[180:183], v[226:229], v[68:71]
	v_mfma_f32_16x16x32_bf16 v[64:67], v[188:191], v[226:229], v[64:67]
	s_barrier
	s_setprio 0
	s_add_i32 s18, s18, s4
	v_lshl_add_u64 v[158:159], s[50:51], 0, v[130:131]
	s_mov_b32 m0, s18
	ds_read_b128 v[192:195], v153 offset:16384
	ds_read_b128 v[196:199], v153 offset:17408
	ds_read_b128 v[206:209], v153 offset:18432
	ds_read_b128 v[210:213], v153 offset:19456
	ds_read_b128 v[214:217], v153 offset:20480
	ds_read_b128 v[218:221], v153 offset:21504
	ds_read_b128 v[222:225], v153 offset:22528
	ds_read_b128 v[226:229], v153 offset:23552
	global_load_lds_dwordx4 v[158:159], off
	s_add_i32 m0, s18, 0x2000
	s_add_u32 s18, s50, 0xb0000
	v_lshl_add_u64 v[200:201], s[50:51], 0, v[128:129]
	s_addc_u32 s19, s51, 0
	s_add_i32 s20, s20, s4
	global_load_lds_dwordx4 v[200:201], off
	v_lshl_add_u64 v[230:231], s[18:19], 0, v[130:131]
	s_mov_b32 m0, s20
	v_lshl_add_u64 v[232:233], s[60:61], 0, v[128:129]
	global_load_lds_dwordx4 v[230:231], off
	v_lshl_add_u64 v[230:231], s[18:19], 0, v[128:129]
	s_add_i32 m0, s20, 0x2000
	s_nop 0
	global_load_lds_dwordx4 v[230:231], off
	v_lshl_add_u64 v[230:231], s[60:61], 0, v[130:131]
	s_mov_b32 m0, s5
	s_nop 0
	global_load_lds_dwordx4 v[230:231], off
	s_mov_b32 m0, s6
	s_nop 0
	global_load_lds_dwordx4 v[232:233], off
	s_waitcnt vmcnt(8)
	s_waitcnt lgkmcnt(0)
	s_setprio 1
	s_barrier
	v_mfma_f32_16x16x32_bf16 v[60:63], v[154:157], v[192:195], 0
	v_mfma_f32_16x16x32_bf16 v[56:59], v[168:171], v[192:195], 0
	v_mfma_f32_16x16x32_bf16 v[52:55], v[154:157], v[206:209], 0
	v_mfma_f32_16x16x32_bf16 v[48:51], v[168:171], v[206:209], 0
	v_mfma_f32_16x16x32_bf16 v[44:47], v[154:157], v[214:217], 0
	v_mfma_f32_16x16x32_bf16 v[40:43], v[168:171], v[214:217], 0
	v_mfma_f32_16x16x32_bf16 v[32:35], v[154:157], v[222:225], 0
	v_mfma_f32_16x16x32_bf16 v[24:27], v[168:171], v[222:225], 0
	v_mfma_f32_16x16x32_bf16 v[60:63], v[164:167], v[196:199], v[60:63]
	v_mfma_f32_16x16x32_bf16 v[56:59], v[172:175], v[196:199], v[56:59]
	v_mfma_f32_16x16x32_bf16 v[52:55], v[164:167], v[210:213], v[52:55]
	v_mfma_f32_16x16x32_bf16 v[48:51], v[172:175], v[210:213], v[48:51]
	v_mfma_f32_16x16x32_bf16 v[44:47], v[164:167], v[218:221], v[44:47]
	v_mfma_f32_16x16x32_bf16 v[40:43], v[172:175], v[218:221], v[40:43]
	v_mfma_f32_16x16x32_bf16 v[32:35], v[164:167], v[226:229], v[32:35]
	v_mfma_f32_16x16x32_bf16 v[24:27], v[172:175], v[226:229], v[24:27]
	s_setprio 0
	s_setprio 1
	v_mfma_f32_16x16x32_bf16 v[36:39], v[176:179], v[192:195], 0
	v_mfma_f32_16x16x32_bf16 v[28:31], v[184:187], v[192:195], 0
	v_mfma_f32_16x16x32_bf16 v[20:23], v[176:179], v[206:209], 0
	v_mfma_f32_16x16x32_bf16 v[16:19], v[184:187], v[206:209], 0
	v_mfma_f32_16x16x32_bf16 v[12:15], v[176:179], v[214:217], 0
	v_mfma_f32_16x16x32_bf16 v[8:11], v[184:187], v[214:217], 0
	v_mfma_f32_16x16x32_bf16 v[4:7], v[176:179], v[222:225], 0
	v_mfma_f32_16x16x32_bf16 v[0:3], v[184:187], v[222:225], 0
	v_mfma_f32_16x16x32_bf16 v[36:39], v[180:183], v[196:199], v[36:39]
	v_mfma_f32_16x16x32_bf16 v[28:31], v[188:191], v[196:199], v[28:31]
	v_mfma_f32_16x16x32_bf16 v[20:23], v[180:183], v[210:213], v[20:23]
	v_mfma_f32_16x16x32_bf16 v[16:19], v[188:191], v[210:213], v[16:19]
	v_mfma_f32_16x16x32_bf16 v[12:15], v[180:183], v[218:221], v[12:15]
	v_mfma_f32_16x16x32_bf16 v[8:11], v[188:191], v[218:221], v[8:11]
	v_mfma_f32_16x16x32_bf16 v[4:7], v[180:183], v[226:229], v[4:7]
	v_mfma_f32_16x16x32_bf16 v[0:3], v[188:191], v[226:229], v[0:3]
	s_barrier
	s_setprio 0
	s_add_i32 s20, 0, 0x18000
	s_add_i32 s21, 0, 0x1c000
	v_add_u32_e32 v172, s20, v152
	v_add_u32_e32 v188, s21, v152
	ds_read_b128 v[154:157], v172
	ds_read_b128 v[164:167], v172 offset:1024
	ds_read_b128 v[168:171], v172 offset:2048
	ds_read_b128 v[172:175], v172 offset:3072
	ds_read_b128 v[176:179], v188
	ds_read_b128 v[180:183], v188 offset:1024
	ds_read_b128 v[184:187], v188 offset:2048
	ds_read_b128 v[188:191], v188 offset:3072
	s_add_u32 s18, s60, 0xb0000
	s_addc_u32 s19, s61, 0
	s_mov_b32 m0, s7
	v_lshl_add_u64 v[234:235], s[18:19], 0, v[130:131]
	ds_read_b128 v[192:195], v153 offset:32768
	ds_read_b128 v[196:199], v153 offset:33792
	ds_read_b128 v[206:209], v153 offset:34816
	ds_read_b128 v[210:213], v153 offset:35840
	ds_read_b128 v[214:217], v153 offset:36864
	ds_read_b128 v[218:221], v153 offset:37888
	ds_read_b128 v[222:225], v153 offset:38912
	ds_read_b128 v[226:229], v153 offset:39936
	global_load_lds_dwordx4 v[234:235], off
	v_lshl_add_u64 v[234:235], s[18:19], 0, v[128:129]
	s_mov_b32 m0, s8
	s_nop 0
	global_load_lds_dwordx4 v[234:235], off
	s_waitcnt vmcnt(8)
	s_waitcnt lgkmcnt(0)
	s_setprio 1
	s_barrier
	v_mfma_f32_16x16x32_bf16 v[124:127], v[154:157], v[192:195], v[124:127]
	v_mfma_f32_16x16x32_bf16 v[120:123], v[168:171], v[192:195], v[120:123]
	v_mfma_f32_16x16x32_bf16 v[116:119], v[154:157], v[206:209], v[116:119]
	v_mfma_f32_16x16x32_bf16 v[112:115], v[168:171], v[206:209], v[112:115]
	v_mfma_f32_16x16x32_bf16 v[108:111], v[154:157], v[214:217], v[108:111]
	v_mfma_f32_16x16x32_bf16 v[104:107], v[168:171], v[214:217], v[104:107]
	v_mfma_f32_16x16x32_bf16 v[96:99], v[154:157], v[222:225], v[96:99]
	v_mfma_f32_16x16x32_bf16 v[88:91], v[168:171], v[222:225], v[88:91]
	v_mfma_f32_16x16x32_bf16 v[124:127], v[164:167], v[196:199], v[124:127]
	v_mfma_f32_16x16x32_bf16 v[120:123], v[172:175], v[196:199], v[120:123]
	v_mfma_f32_16x16x32_bf16 v[116:119], v[164:167], v[210:213], v[116:119]
	v_mfma_f32_16x16x32_bf16 v[112:115], v[172:175], v[210:213], v[112:115]
	v_mfma_f32_16x16x32_bf16 v[108:111], v[164:167], v[218:221], v[108:111]
	v_mfma_f32_16x16x32_bf16 v[104:107], v[172:175], v[218:221], v[104:107]
	v_mfma_f32_16x16x32_bf16 v[96:99], v[164:167], v[226:229], v[96:99]
	v_mfma_f32_16x16x32_bf16 v[88:91], v[172:175], v[226:229], v[88:91]
	s_setprio 0
	s_setprio 1
	v_mfma_f32_16x16x32_bf16 v[100:103], v[176:179], v[192:195], v[100:103]
	v_mfma_f32_16x16x32_bf16 v[92:95], v[184:187], v[192:195], v[92:95]
	v_mfma_f32_16x16x32_bf16 v[84:87], v[176:179], v[206:209], v[84:87]
	v_mfma_f32_16x16x32_bf16 v[80:83], v[184:187], v[206:209], v[80:83]
	v_mfma_f32_16x16x32_bf16 v[76:79], v[176:179], v[214:217], v[76:79]
	v_mfma_f32_16x16x32_bf16 v[72:75], v[184:187], v[214:217], v[72:75]
	v_mfma_f32_16x16x32_bf16 v[68:71], v[176:179], v[222:225], v[68:71]
	v_mfma_f32_16x16x32_bf16 v[64:67], v[184:187], v[222:225], v[64:67]
	v_mfma_f32_16x16x32_bf16 v[100:103], v[180:183], v[196:199], v[100:103]
	v_mfma_f32_16x16x32_bf16 v[92:95], v[188:191], v[196:199], v[92:95]
	v_mfma_f32_16x16x32_bf16 v[84:87], v[180:183], v[210:213], v[84:87]
	v_mfma_f32_16x16x32_bf16 v[80:83], v[188:191], v[210:213], v[80:83]
	v_mfma_f32_16x16x32_bf16 v[76:79], v[180:183], v[218:221], v[76:79]
	v_mfma_f32_16x16x32_bf16 v[72:75], v[188:191], v[218:221], v[72:75]
	v_mfma_f32_16x16x32_bf16 v[68:71], v[180:183], v[226:229], v[68:71]
	v_mfma_f32_16x16x32_bf16 v[64:67], v[188:191], v[226:229], v[64:67]
	s_barrier
	s_setprio 0
	s_add_i32 s18, s20, s4
	v_lshl_add_u64 v[158:159], v[158:159], 0, s[76:77]
	s_mov_b32 m0, s18
	ds_read_b128 v[192:195], v153 offset:49152
	ds_read_b128 v[196:199], v153 offset:50176
	ds_read_b128 v[206:209], v153 offset:51200
	ds_read_b128 v[210:213], v153 offset:52224
	ds_read_b128 v[214:217], v153 offset:53248
	ds_read_b128 v[218:221], v153 offset:54272
	ds_read_b128 v[222:225], v153 offset:55296
	ds_read_b128 v[226:229], v153 offset:56320
	global_load_lds_dwordx4 v[158:159], off
	s_add_i32 m0, s18, 0x2000
	s_add_u32 s18, s50, 0xb0080
	v_lshl_add_u64 v[158:159], v[200:201], 0, s[76:77]
	s_addc_u32 s19, s51, 0
	s_add_i32 s20, s21, s4
	global_load_lds_dwordx4 v[158:159], off
	v_lshl_add_u64 v[158:159], s[18:19], 0, v[130:131]
	s_mov_b32 m0, s20
	s_nop 0
	global_load_lds_dwordx4 v[158:159], off
	v_lshl_add_u64 v[158:159], s[18:19], 0, v[128:129]
	s_add_i32 m0, s20, 0x2000
	s_nop 0
	global_load_lds_dwordx4 v[158:159], off
	v_lshl_add_u64 v[158:159], v[230:231], 0, s[76:77]
	s_mov_b32 m0, s9
	s_nop 0
	global_load_lds_dwordx4 v[158:159], off
	v_lshl_add_u64 v[158:159], v[232:233], 0, s[76:77]
	s_mov_b32 m0, s10
	s_nop 0
	global_load_lds_dwordx4 v[158:159], off
	s_waitcnt vmcnt(8)
	s_waitcnt lgkmcnt(0)
	s_setprio 1
	s_barrier
	v_mfma_f32_16x16x32_bf16 v[60:63], v[154:157], v[192:195], v[60:63]
	v_mfma_f32_16x16x32_bf16 v[56:59], v[168:171], v[192:195], v[56:59]
	v_mfma_f32_16x16x32_bf16 v[52:55], v[154:157], v[206:209], v[52:55]
	v_mfma_f32_16x16x32_bf16 v[48:51], v[168:171], v[206:209], v[48:51]
	v_mfma_f32_16x16x32_bf16 v[44:47], v[154:157], v[214:217], v[44:47]
	v_mfma_f32_16x16x32_bf16 v[40:43], v[168:171], v[214:217], v[40:43]
	v_mfma_f32_16x16x32_bf16 v[32:35], v[154:157], v[222:225], v[32:35]
	v_mfma_f32_16x16x32_bf16 v[24:27], v[168:171], v[222:225], v[24:27]
	v_mfma_f32_16x16x32_bf16 v[60:63], v[164:167], v[196:199], v[60:63]
	v_mfma_f32_16x16x32_bf16 v[56:59], v[172:175], v[196:199], v[56:59]
	v_mfma_f32_16x16x32_bf16 v[52:55], v[164:167], v[210:213], v[52:55]
	v_mfma_f32_16x16x32_bf16 v[48:51], v[172:175], v[210:213], v[48:51]
	v_mfma_f32_16x16x32_bf16 v[44:47], v[164:167], v[218:221], v[44:47]
	v_mfma_f32_16x16x32_bf16 v[40:43], v[172:175], v[218:221], v[40:43]
	v_mfma_f32_16x16x32_bf16 v[32:35], v[164:167], v[226:229], v[32:35]
	v_mfma_f32_16x16x32_bf16 v[24:27], v[172:175], v[226:229], v[24:27]
	s_setprio 0
	s_setprio 1
	v_mfma_f32_16x16x32_bf16 v[36:39], v[176:179], v[192:195], v[36:39]
	v_mfma_f32_16x16x32_bf16 v[28:31], v[184:187], v[192:195], v[28:31]
	v_mfma_f32_16x16x32_bf16 v[20:23], v[176:179], v[206:209], v[20:23]
	v_mfma_f32_16x16x32_bf16 v[16:19], v[184:187], v[206:209], v[16:19]
	v_mfma_f32_16x16x32_bf16 v[12:15], v[176:179], v[214:217], v[12:15]
	v_mfma_f32_16x16x32_bf16 v[8:11], v[184:187], v[214:217], v[8:11]
	v_mfma_f32_16x16x32_bf16 v[4:7], v[176:179], v[222:225], v[4:7]
	v_mfma_f32_16x16x32_bf16 v[0:3], v[184:187], v[222:225], v[0:3]
	v_mfma_f32_16x16x32_bf16 v[36:39], v[180:183], v[196:199], v[36:39]
	v_mfma_f32_16x16x32_bf16 v[28:31], v[188:191], v[196:199], v[28:31]
	v_mfma_f32_16x16x32_bf16 v[20:23], v[180:183], v[210:213], v[20:23]
	v_mfma_f32_16x16x32_bf16 v[16:19], v[188:191], v[210:213], v[16:19]
	v_mfma_f32_16x16x32_bf16 v[12:15], v[180:183], v[218:221], v[12:15]
	v_mfma_f32_16x16x32_bf16 v[8:11], v[188:191], v[218:221], v[8:11]
	v_mfma_f32_16x16x32_bf16 v[4:7], v[180:183], v[226:229], v[4:7]
	v_mfma_f32_16x16x32_bf16 v[0:3], v[188:191], v[226:229], v[0:3]
	s_barrier
	s_setprio 0
	s_add_i32 s47, s47, 2
	s_add_u32 s43, s43, 0x100
	s_addc_u32 s46, s46, 0
	s_cmp_gt_u32 s47, 19
	s_mov_b64 s[48:49], s[58:59]
	s_cbranch_scc0 .LBB0_1235
	s_branch .Lpeel_x_1235
.LBB0_1235:
	s_add_u32 s58, s48, 0x100
	s_addc_u32 s59, s49, 0
	s_add_i32 s18, 0, 0x10000
	s_cmp_eq_u32 s47, 18
	s_cselect_b32 s61, s39, s59
	s_cselect_b32 s60, s38, s58
	v_add_u32_e32 v158, s18, v152
	s_cselect_b32 s51, s41, s46
	s_cselect_b32 s50, s40, s43
	s_add_i32 s20, 0, 0x14000
	ds_read_b128 v[154:157], v158
	ds_read_b128 v[164:167], v158 offset:1024
	ds_read_b128 v[168:171], v158 offset:2048
	ds_read_b128 v[172:175], v158 offset:3072
	v_add_u32_e32 v158, s20, v152
	ds_read_b128 v[176:179], v158
	ds_read_b128 v[180:183], v158 offset:1024
	ds_read_b128 v[184:187], v158 offset:2048
	ds_read_b128 v[188:191], v158 offset:3072
	v_lshl_add_u64 v[158:159], s[48:49], 0, v[148:149]
	s_add_i32 m0, s5, 0xc000
	ds_read_b128 v[192:195], v153
	ds_read_b128 v[196:199], v153 offset:1024
	ds_read_b128 v[206:209], v153 offset:2048
	ds_read_b128 v[210:213], v153 offset:3072
	ds_read_b128 v[214:217], v153 offset:4096
	ds_read_b128 v[218:221], v153 offset:5120
	ds_read_b128 v[222:225], v153 offset:6144
	ds_read_b128 v[226:229], v153 offset:7168
	global_load_lds_dwordx4 v[158:159], off
	v_lshl_add_u64 v[158:159], s[48:49], 0, v[150:151]
	s_add_i32 m0, s5, 0xe000
	s_nop 0
	global_load_lds_dwordx4 v[158:159], off
	s_waitcnt vmcnt(8)
	s_waitcnt lgkmcnt(0)
	s_setprio 1
	s_barrier
	v_mfma_f32_16x16x32_bf16 v[124:127], v[154:157], v[192:195], v[124:127]
	v_mfma_f32_16x16x32_bf16 v[120:123], v[168:171], v[192:195], v[120:123]
	v_mfma_f32_16x16x32_bf16 v[116:119], v[154:157], v[206:209], v[116:119]
	v_mfma_f32_16x16x32_bf16 v[112:115], v[168:171], v[206:209], v[112:115]
	v_mfma_f32_16x16x32_bf16 v[108:111], v[154:157], v[214:217], v[108:111]
	v_mfma_f32_16x16x32_bf16 v[104:107], v[168:171], v[214:217], v[104:107]
	v_mfma_f32_16x16x32_bf16 v[96:99], v[154:157], v[222:225], v[96:99]
	v_mfma_f32_16x16x32_bf16 v[88:91], v[168:171], v[222:225], v[88:91]
	v_mfma_f32_16x16x32_bf16 v[124:127], v[164:167], v[196:199], v[124:127]
	v_mfma_f32_16x16x32_bf16 v[120:123], v[172:175], v[196:199], v[120:123]
	v_mfma_f32_16x16x32_bf16 v[116:119], v[164:167], v[210:213], v[116:119]
	v_mfma_f32_16x16x32_bf16 v[112:115], v[172:175], v[210:213], v[112:115]
	v_mfma_f32_16x16x32_bf16 v[108:111], v[164:167], v[218:221], v[108:111]
	v_mfma_f32_16x16x32_bf16 v[104:107], v[172:175], v[218:221], v[104:107]
	v_mfma_f32_16x16x32_bf16 v[96:99], v[164:167], v[226:229], v[96:99]
	v_mfma_f32_16x16x32_bf16 v[88:91], v[172:175], v[226:229], v[88:91]
	s_setprio 0
	s_setprio 1
	v_mfma_f32_16x16x32_bf16 v[100:103], v[176:179], v[192:195], v[100:103]
	v_mfma_f32_16x16x32_bf16 v[92:95], v[184:187], v[192:195], v[92:95]
	v_mfma_f32_16x16x32_bf16 v[84:87], v[176:179], v[206:209], v[84:87]
	v_mfma_f32_16x16x32_bf16 v[80:83], v[184:187], v[206:209], v[80:83]
	v_mfma_f32_16x16x32_bf16 v[76:79], v[176:179], v[214:217], v[76:79]
	v_mfma_f32_16x16x32_bf16 v[72:75], v[184:187], v[214:217], v[72:75]
	v_mfma_f32_16x16x32_bf16 v[68:71], v[176:179], v[222:225], v[68:71]
	v_mfma_f32_16x16x32_bf16 v[64:67], v[184:187], v[222:225], v[64:67]
	v_mfma_f32_16x16x32_bf16 v[100:103], v[180:183], v[196:199], v[100:103]
	v_mfma_f32_16x16x32_bf16 v[92:95], v[188:191], v[196:199], v[92:95]
	v_mfma_f32_16x16x32_bf16 v[84:87], v[180:183], v[210:213], v[84:87]
	v_mfma_f32_16x16x32_bf16 v[80:83], v[188:191], v[210:213], v[80:83]
	v_mfma_f32_16x16x32_bf16 v[76:79], v[180:183], v[218:221], v[76:79]
	v_mfma_f32_16x16x32_bf16 v[72:75], v[188:191], v[218:221], v[72:75]
	v_mfma_f32_16x16x32_bf16 v[68:71], v[180:183], v[226:229], v[68:71]
	v_mfma_f32_16x16x32_bf16 v[64:67], v[188:191], v[226:229], v[64:67]
	s_barrier
	s_setprio 0
	s_add_i32 s18, s18, s4
	v_lshl_add_u64 v[158:159], s[50:51], 0, v[130:131]
	s_mov_b32 m0, s18
	ds_read_b128 v[192:195], v153 offset:16384
	ds_read_b128 v[196:199], v153 offset:17408
	ds_read_b128 v[206:209], v153 offset:18432
	ds_read_b128 v[210:213], v153 offset:19456
	ds_read_b128 v[214:217], v153 offset:20480
	ds_read_b128 v[218:221], v153 offset:21504
	ds_read_b128 v[222:225], v153 offset:22528
	ds_read_b128 v[226:229], v153 offset:23552
	global_load_lds_dwordx4 v[158:159], off
	s_add_i32 m0, s18, 0x2000
	s_add_u32 s18, s50, 0xb0000
	v_lshl_add_u64 v[200:201], s[50:51], 0, v[128:129]
	s_addc_u32 s19, s51, 0
	s_add_i32 s20, s20, s4
	global_load_lds_dwordx4 v[200:201], off
	v_lshl_add_u64 v[230:231], s[18:19], 0, v[130:131]
	s_mov_b32 m0, s20
	v_lshl_add_u64 v[232:233], s[60:61], 0, v[128:129]
	global_load_lds_dwordx4 v[230:231], off
	v_lshl_add_u64 v[230:231], s[18:19], 0, v[128:129]
	s_add_i32 m0, s20, 0x2000
	s_nop 0
	global_load_lds_dwordx4 v[230:231], off
	v_lshl_add_u64 v[230:231], s[60:61], 0, v[130:131]
	s_mov_b32 m0, s5
	s_nop 0
	global_load_lds_dwordx4 v[230:231], off
	s_mov_b32 m0, s6
	s_nop 0
	global_load_lds_dwordx4 v[232:233], off
	s_waitcnt vmcnt(8)
	s_waitcnt lgkmcnt(0)
	s_setprio 1
	s_barrier
	v_mfma_f32_16x16x32_bf16 v[60:63], v[154:157], v[192:195], v[60:63]
	v_mfma_f32_16x16x32_bf16 v[56:59], v[168:171], v[192:195], v[56:59]
	v_mfma_f32_16x16x32_bf16 v[52:55], v[154:157], v[206:209], v[52:55]
	v_mfma_f32_16x16x32_bf16 v[48:51], v[168:171], v[206:209], v[48:51]
	v_mfma_f32_16x16x32_bf16 v[44:47], v[154:157], v[214:217], v[44:47]
	v_mfma_f32_16x16x32_bf16 v[40:43], v[168:171], v[214:217], v[40:43]
	v_mfma_f32_16x16x32_bf16 v[32:35], v[154:157], v[222:225], v[32:35]
	v_mfma_f32_16x16x32_bf16 v[24:27], v[168:171], v[222:225], v[24:27]
	v_mfma_f32_16x16x32_bf16 v[60:63], v[164:167], v[196:199], v[60:63]
	v_mfma_f32_16x16x32_bf16 v[56:59], v[172:175], v[196:199], v[56:59]
	v_mfma_f32_16x16x32_bf16 v[52:55], v[164:167], v[210:213], v[52:55]
	v_mfma_f32_16x16x32_bf16 v[48:51], v[172:175], v[210:213], v[48:51]
	v_mfma_f32_16x16x32_bf16 v[44:47], v[164:167], v[218:221], v[44:47]
	v_mfma_f32_16x16x32_bf16 v[40:43], v[172:175], v[218:221], v[40:43]
	v_mfma_f32_16x16x32_bf16 v[32:35], v[164:167], v[226:229], v[32:35]
	v_mfma_f32_16x16x32_bf16 v[24:27], v[172:175], v[226:229], v[24:27]
	s_setprio 0
	s_setprio 1
	v_mfma_f32_16x16x32_bf16 v[36:39], v[176:179], v[192:195], v[36:39]
	v_mfma_f32_16x16x32_bf16 v[28:31], v[184:187], v[192:195], v[28:31]
	v_mfma_f32_16x16x32_bf16 v[20:23], v[176:179], v[206:209], v[20:23]
	v_mfma_f32_16x16x32_bf16 v[16:19], v[184:187], v[206:209], v[16:19]
	v_mfma_f32_16x16x32_bf16 v[12:15], v[176:179], v[214:217], v[12:15]
	v_mfma_f32_16x16x32_bf16 v[8:11], v[184:187], v[214:217], v[8:11]
	v_mfma_f32_16x16x32_bf16 v[4:7], v[176:179], v[222:225], v[4:7]
	v_mfma_f32_16x16x32_bf16 v[0:3], v[184:187], v[222:225], v[0:3]
	v_mfma_f32_16x16x32_bf16 v[36:39], v[180:183], v[196:199], v[36:39]
	v_mfma_f32_16x16x32_bf16 v[28:31], v[188:191], v[196:199], v[28:31]
	v_mfma_f32_16x16x32_bf16 v[20:23], v[180:183], v[210:213], v[20:23]
	v_mfma_f32_16x16x32_bf16 v[16:19], v[188:191], v[210:213], v[16:19]
	v_mfma_f32_16x16x32_bf16 v[12:15], v[180:183], v[218:221], v[12:15]
	v_mfma_f32_16x16x32_bf16 v[8:11], v[188:191], v[218:221], v[8:11]
	v_mfma_f32_16x16x32_bf16 v[4:7], v[180:183], v[226:229], v[4:7]
	v_mfma_f32_16x16x32_bf16 v[0:3], v[188:191], v[226:229], v[0:3]
	s_barrier
	s_setprio 0
	s_add_i32 s20, 0, 0x18000
	s_add_i32 s21, 0, 0x1c000
	v_add_u32_e32 v172, s20, v152
	v_add_u32_e32 v188, s21, v152
	ds_read_b128 v[154:157], v172
	ds_read_b128 v[164:167], v172 offset:1024
	ds_read_b128 v[168:171], v172 offset:2048
	ds_read_b128 v[172:175], v172 offset:3072
	ds_read_b128 v[176:179], v188
	ds_read_b128 v[180:183], v188 offset:1024
	ds_read_b128 v[184:187], v188 offset:2048
	ds_read_b128 v[188:191], v188 offset:3072
	s_add_u32 s18, s60, 0xb0000
	s_addc_u32 s19, s61, 0
	s_mov_b32 m0, s7
	v_lshl_add_u64 v[234:235], s[18:19], 0, v[130:131]
	ds_read_b128 v[192:195], v153 offset:32768
	ds_read_b128 v[196:199], v153 offset:33792
	ds_read_b128 v[206:209], v153 offset:34816
	ds_read_b128 v[210:213], v153 offset:35840
	ds_read_b128 v[214:217], v153 offset:36864
	ds_read_b128 v[218:221], v153 offset:37888
	ds_read_b128 v[222:225], v153 offset:38912
	ds_read_b128 v[226:229], v153 offset:39936
	global_load_lds_dwordx4 v[234:235], off
	v_lshl_add_u64 v[234:235], s[18:19], 0, v[128:129]
	s_mov_b32 m0, s8
	s_nop 0
	global_load_lds_dwordx4 v[234:235], off
	s_waitcnt vmcnt(8)
	s_waitcnt lgkmcnt(0)
	s_setprio 1
	s_barrier
	v_mfma_f32_16x16x32_bf16 v[124:127], v[154:157], v[192:195], v[124:127]
	v_mfma_f32_16x16x32_bf16 v[120:123], v[168:171], v[192:195], v[120:123]
	v_mfma_f32_16x16x32_bf16 v[116:119], v[154:157], v[206:209], v[116:119]
	v_mfma_f32_16x16x32_bf16 v[112:115], v[168:171], v[206:209], v[112:115]
	v_mfma_f32_16x16x32_bf16 v[108:111], v[154:157], v[214:217], v[108:111]
	v_mfma_f32_16x16x32_bf16 v[104:107], v[168:171], v[214:217], v[104:107]
	v_mfma_f32_16x16x32_bf16 v[96:99], v[154:157], v[222:225], v[96:99]
	v_mfma_f32_16x16x32_bf16 v[88:91], v[168:171], v[222:225], v[88:91]
	v_mfma_f32_16x16x32_bf16 v[124:127], v[164:167], v[196:199], v[124:127]
	v_mfma_f32_16x16x32_bf16 v[120:123], v[172:175], v[196:199], v[120:123]
	v_mfma_f32_16x16x32_bf16 v[116:119], v[164:167], v[210:213], v[116:119]
	v_mfma_f32_16x16x32_bf16 v[112:115], v[172:175], v[210:213], v[112:115]
	v_mfma_f32_16x16x32_bf16 v[108:111], v[164:167], v[218:221], v[108:111]
	v_mfma_f32_16x16x32_bf16 v[104:107], v[172:175], v[218:221], v[104:107]
	v_mfma_f32_16x16x32_bf16 v[96:99], v[164:167], v[226:229], v[96:99]
	v_mfma_f32_16x16x32_bf16 v[88:91], v[172:175], v[226:229], v[88:91]
	s_setprio 0
	s_setprio 1
	v_mfma_f32_16x16x32_bf16 v[100:103], v[176:179], v[192:195], v[100:103]
	v_mfma_f32_16x16x32_bf16 v[92:95], v[184:187], v[192:195], v[92:95]
	v_mfma_f32_16x16x32_bf16 v[84:87], v[176:179], v[206:209], v[84:87]
	v_mfma_f32_16x16x32_bf16 v[80:83], v[184:187], v[206:209], v[80:83]
	v_mfma_f32_16x16x32_bf16 v[76:79], v[176:179], v[214:217], v[76:79]
	v_mfma_f32_16x16x32_bf16 v[72:75], v[184:187], v[214:217], v[72:75]
	v_mfma_f32_16x16x32_bf16 v[68:71], v[176:179], v[222:225], v[68:71]
	v_mfma_f32_16x16x32_bf16 v[64:67], v[184:187], v[222:225], v[64:67]
	v_mfma_f32_16x16x32_bf16 v[100:103], v[180:183], v[196:199], v[100:103]
	v_mfma_f32_16x16x32_bf16 v[92:95], v[188:191], v[196:199], v[92:95]
	v_mfma_f32_16x16x32_bf16 v[84:87], v[180:183], v[210:213], v[84:87]
	v_mfma_f32_16x16x32_bf16 v[80:83], v[188:191], v[210:213], v[80:83]
	v_mfma_f32_16x16x32_bf16 v[76:79], v[180:183], v[218:221], v[76:79]
	v_mfma_f32_16x16x32_bf16 v[72:75], v[188:191], v[218:221], v[72:75]
	v_mfma_f32_16x16x32_bf16 v[68:71], v[180:183], v[226:229], v[68:71]
	v_mfma_f32_16x16x32_bf16 v[64:67], v[188:191], v[226:229], v[64:67]
	s_barrier
	s_setprio 0
	s_add_i32 s18, s20, s4
	v_lshl_add_u64 v[158:159], v[158:159], 0, s[76:77]
	s_mov_b32 m0, s18
	ds_read_b128 v[192:195], v153 offset:49152
	ds_read_b128 v[196:199], v153 offset:50176
	ds_read_b128 v[206:209], v153 offset:51200
	ds_read_b128 v[210:213], v153 offset:52224
	ds_read_b128 v[214:217], v153 offset:53248
	ds_read_b128 v[218:221], v153 offset:54272
	ds_read_b128 v[222:225], v153 offset:55296
	ds_read_b128 v[226:229], v153 offset:56320
	global_load_lds_dwordx4 v[158:159], off
	s_add_i32 m0, s18, 0x2000
	s_add_u32 s18, s50, 0xb0080
	v_lshl_add_u64 v[158:159], v[200:201], 0, s[76:77]
	s_addc_u32 s19, s51, 0
	s_add_i32 s20, s21, s4
	global_load_lds_dwordx4 v[158:159], off
	v_lshl_add_u64 v[158:159], s[18:19], 0, v[130:131]
	s_mov_b32 m0, s20
	s_nop 0
	global_load_lds_dwordx4 v[158:159], off
	v_lshl_add_u64 v[158:159], s[18:19], 0, v[128:129]
	s_add_i32 m0, s20, 0x2000
	s_nop 0
	global_load_lds_dwordx4 v[158:159], off
	v_lshl_add_u64 v[158:159], v[230:231], 0, s[76:77]
	s_mov_b32 m0, s9
	s_nop 0
	global_load_lds_dwordx4 v[158:159], off
	v_lshl_add_u64 v[158:159], v[232:233], 0, s[76:77]
	s_mov_b32 m0, s10
	s_nop 0
	global_load_lds_dwordx4 v[158:159], off
	s_waitcnt vmcnt(8)
	s_waitcnt lgkmcnt(0)
	s_setprio 1
	s_barrier
	v_mfma_f32_16x16x32_bf16 v[60:63], v[154:157], v[192:195], v[60:63]
	v_mfma_f32_16x16x32_bf16 v[56:59], v[168:171], v[192:195], v[56:59]
	v_mfma_f32_16x16x32_bf16 v[52:55], v[154:157], v[206:209], v[52:55]
	v_mfma_f32_16x16x32_bf16 v[48:51], v[168:171], v[206:209], v[48:51]
	v_mfma_f32_16x16x32_bf16 v[44:47], v[154:157], v[214:217], v[44:47]
	v_mfma_f32_16x16x32_bf16 v[40:43], v[168:171], v[214:217], v[40:43]
	v_mfma_f32_16x16x32_bf16 v[32:35], v[154:157], v[222:225], v[32:35]
	v_mfma_f32_16x16x32_bf16 v[24:27], v[168:171], v[222:225], v[24:27]
	v_mfma_f32_16x16x32_bf16 v[60:63], v[164:167], v[196:199], v[60:63]
	v_mfma_f32_16x16x32_bf16 v[56:59], v[172:175], v[196:199], v[56:59]
	v_mfma_f32_16x16x32_bf16 v[52:55], v[164:167], v[210:213], v[52:55]
	v_mfma_f32_16x16x32_bf16 v[48:51], v[172:175], v[210:213], v[48:51]
	v_mfma_f32_16x16x32_bf16 v[44:47], v[164:167], v[218:221], v[44:47]
	v_mfma_f32_16x16x32_bf16 v[40:43], v[172:175], v[218:221], v[40:43]
	v_mfma_f32_16x16x32_bf16 v[32:35], v[164:167], v[226:229], v[32:35]
	v_mfma_f32_16x16x32_bf16 v[24:27], v[172:175], v[226:229], v[24:27]
	s_setprio 0
	s_setprio 1
	v_mfma_f32_16x16x32_bf16 v[36:39], v[176:179], v[192:195], v[36:39]
	v_mfma_f32_16x16x32_bf16 v[28:31], v[184:187], v[192:195], v[28:31]
	v_mfma_f32_16x16x32_bf16 v[20:23], v[176:179], v[206:209], v[20:23]
	v_mfma_f32_16x16x32_bf16 v[16:19], v[184:187], v[206:209], v[16:19]
	v_mfma_f32_16x16x32_bf16 v[12:15], v[176:179], v[214:217], v[12:15]
	v_mfma_f32_16x16x32_bf16 v[8:11], v[184:187], v[214:217], v[8:11]
	v_mfma_f32_16x16x32_bf16 v[4:7], v[176:179], v[222:225], v[4:7]
	v_mfma_f32_16x16x32_bf16 v[0:3], v[184:187], v[222:225], v[0:3]
	v_mfma_f32_16x16x32_bf16 v[36:39], v[180:183], v[196:199], v[36:39]
	v_mfma_f32_16x16x32_bf16 v[28:31], v[188:191], v[196:199], v[28:31]
	v_mfma_f32_16x16x32_bf16 v[20:23], v[180:183], v[210:213], v[20:23]
	v_mfma_f32_16x16x32_bf16 v[16:19], v[188:191], v[210:213], v[16:19]
	v_mfma_f32_16x16x32_bf16 v[12:15], v[180:183], v[218:221], v[12:15]
	v_mfma_f32_16x16x32_bf16 v[8:11], v[188:191], v[218:221], v[8:11]
	v_mfma_f32_16x16x32_bf16 v[4:7], v[180:183], v[226:229], v[4:7]
	v_mfma_f32_16x16x32_bf16 v[0:3], v[188:191], v[226:229], v[0:3]
	s_barrier
	s_setprio 0
	s_add_i32 s47, s47, 2
	s_add_u32 s43, s43, 0x100
	s_addc_u32 s46, s46, 0
	s_cmp_gt_u32 s47, 19
	s_mov_b64 s[48:49], s[58:59]
	s_cbranch_scc0 .LBB0_1235
